# all packed fp32 VOP3P ops outside the A loop (v_pk_mul/fma/add_f32) split into two scalar fp32 ops, bit-identical math
# speedup vs baseline: 1.0865x; 1.0031x over previous
; template <int EPI>
; DI void gemm_tile(const Params& p, int layer, int mt, int nt, u16* sm, int wv) {
;     ...
;       const int vbase = (nt == 4) ? 0 : (nt == 5) ? 2 : (nt == 13) ? 4 : (nt == 22) ? 6 : 8;
;       const int bb = m0 / SEQ, s0 = m0 % SEQ;
;       constexpr int VSTR = 136;
; #pragma unroll
;       for (int i = 0; i < 8; ++i) {
;         float rs[4];
; #pragma unroll
;         for (int e = 0; e < 4; ++e) rs[e] = __builtin_amdgcn_rsqf(ssl[m0 + wm * 128 + 16 * i + 4 * fq + e] * (1.f / DM) + EPS);
;         const int pos = 16 * i + 8 * (fq & 1) + 4 * (fq >> 1);
; #pragma unroll
;         for (int j = 0; j < 4; ++j) {
;           u32x2 v = {pk2(acc[i][j][0] * rs[0], acc[i][j][1] * rs[1]), pk2(acc[i][j][2] * rs[2], acc[i][j][3] * rs[3])};
;           *(u32x2*)(stg + (16 * j + fr) * VSTR + pos) = v;
;         }
;       }
.LBB0_111:
	v_lshl_or_b32 v132, v134, 2, v139
	v_lshrrev_b32_e32 v133, 2, v138
	s_waitcnt vmcnt(6)
	v_and_b32_e32 v142, 8, v133
	v_ashrrev_i32_e32 v133, 31, v132
	v_lshl_add_u64 v[132:133], v[132:133], 2, s[0:1]
	global_load_dwordx4 v[138:141], v[132:133], off
	v_lshlrev_b32_e32 v0, 4, v134
	v_and_b32_e32 v0, 16, v0
	v_add_u32_e32 v0, v135, v0
	s_lshr_b32 s2, s19, 5
	s_mul_i32 s2, s2, 10
	s_add_i32 s2, s6, s2
	s_and_b32 s3, s21, 0x1f00
	s_mov_b32 s5, s25
	s_lshl_b32 s4, s3, 1
	s_waitcnt vmcnt(0)
	v_fmamk_f32 v138, v138, 0x3a800000, v188
	v_fmamk_f32 v139, v139, 0x3a800000, v188
	v_fmamk_f32 v140, v140, 0x3a800000, v188
	v_fmamk_f32 v141, v141, 0x3a800000, v188
	v_rsq_f32_e32 v138, v138
	v_rsq_f32_e32 v139, v139
	v_rsq_f32_e32 v140, v140
	v_rsq_f32_e32 v141, v141
	v_mul_f32_e32 v118, v118, v138
	v_mul_f32_e32 v119, v119, v139
	v_mul_f32_e32 v114, v114, v138
	v_mul_f32_e32 v115, v115, v139
	v_mul_f32_e32 v120, v120, v140
	v_mul_f32_e32 v121, v121, v141
	v_cvt_pk_bf16_f32 v118, v118, v119
	v_cvt_pk_bf16_f32 v119, v120, v121
	v_cvt_pk_bf16_f32 v120, v114, v115
	v_mul_f32_e32 v114, v116, v140
	v_mul_f32_e32 v115, v117, v141
	v_mul_f32_e32 v126, v126, v138
	v_mul_f32_e32 v127, v127, v139
	v_cvt_pk_bf16_f32 v121, v114, v115
	global_load_dwordx4 v[114:117], v[132:133], off offset:64
	v_mul_f32_e32 v128, v128, v140
	v_mul_f32_e32 v129, v129, v141
	v_cvt_pk_bf16_f32 v126, v126, v127
	v_cvt_pk_bf16_f32 v127, v128, v129
	v_mul_u32_u24_e32 v128, 0x110, v137
	v_add3_u32 v0, v0, v142, v128
	v_mul_f32_e32 v122, v122, v138
	v_mul_f32_e32 v123, v123, v139
	v_mul_f32_e32 v124, v124, v140
	v_mul_f32_e32 v125, v125, v141
	v_cvt_pk_bf16_f32 v122, v122, v123
	v_cvt_pk_bf16_f32 v123, v124, v125
	s_waitcnt vmcnt(0)
	v_fmamk_f32 v114, v114, 0x3a800000, v188
	v_fmamk_f32 v115, v115, 0x3a800000, v188
	v_fmamk_f32 v116, v116, 0x3a800000, v188
	v_fmamk_f32 v117, v117, 0x3a800000, v188
	v_rsq_f32_e32 v114, v114
	v_rsq_f32_e32 v115, v115
	v_rsq_f32_e32 v116, v116
	v_rsq_f32_e32 v117, v117
	v_mul_f32_e32 v110, v110, v114
	v_mul_f32_e32 v111, v111, v115
	s_nop 0
	v_cvt_pk_bf16_f32 v110, v110, v111
	v_mul_f32_e32 v112, v112, v116
	v_mul_f32_e32 v113, v113, v117
	v_mul_f32_e32 v106, v106, v114
	v_mul_f32_e32 v107, v107, v115
	v_cvt_pk_bf16_f32 v111, v112, v113
	v_mul_f32_e32 v102, v102, v114
	v_mul_f32_e32 v103, v103, v115
	ds_write2_b64 v0, v[126:127], v[110:111] offset1:4
	v_cvt_pk_bf16_f32 v110, v106, v107
	v_mul_f32_e32 v106, v108, v116
	v_mul_f32_e32 v107, v109, v117
	v_cvt_pk_bf16_f32 v108, v102, v103
	v_mul_f32_e32 v102, v104, v116
	v_mul_f32_e32 v103, v105, v117
	v_cvt_pk_bf16_f32 v111, v106, v107
	v_add_u32_e32 v106, 0x1000, v0
	v_cvt_pk_bf16_f32 v109, v102, v103
	v_add_u32_e32 v102, 0x2000, v0
	ds_write2_b64 v106, v[122:123], v[110:111] offset0:32 offset1:36
	ds_write2_b64 v102, v[118:119], v[108:109] offset0:64 offset1:68
	global_load_dwordx4 v[108:111], v[132:133], off offset:128
	v_mul_f32_e32 v98, v98, v114
	v_mul_f32_e32 v99, v99, v115
	s_nop 0
	v_cvt_pk_bf16_f32 v104, v98, v99
	v_mul_f32_e32 v98, v100, v116
	v_mul_f32_e32 v99, v101, v117
	s_nop 0
	v_cvt_pk_bf16_f32 v105, v98, v99
	v_add_u32_e32 v98, 0x3000, v0
	ds_write2_b64 v98, v[120:121], v[104:105] offset0:96 offset1:100
	s_waitcnt vmcnt(0)
	v_fmamk_f32 v99, v108, 0x3a800000, v188
	v_rsq_f32_e32 v100, v99
	v_fmamk_f32 v99, v109, 0x3a800000, v188
	v_rsq_f32_e32 v101, v99
	v_fmamk_f32 v99, v110, 0x3a800000, v188
	v_rsq_f32_e32 v104, v99
	v_fmamk_f32 v99, v111, 0x3a800000, v188
	v_rsq_f32_e32 v105, v99
	v_mul_f32_e32 v86, v86, v100
	v_mul_f32_e32 v87, v87, v101
	v_mul_f32_e32 v82, v82, v100
	v_mul_f32_e32 v83, v83, v101
	v_cvt_pk_bf16_f32 v86, v86, v87
	v_mul_f32_e32 v88, v88, v104
	v_mul_f32_e32 v89, v89, v105
	v_mul_f32_e32 v94, v94, v100
	v_mul_f32_e32 v95, v95, v101
	v_cvt_pk_bf16_f32 v87, v88, v89
	v_cvt_pk_bf16_f32 v88, v82, v83
	v_mul_f32_e32 v82, v84, v104
	v_mul_f32_e32 v83, v85, v105
	v_mul_f32_e32 v96, v96, v104
	v_mul_f32_e32 v97, v97, v105
	v_cvt_pk_bf16_f32 v89, v82, v83
	global_load_dwordx4 v[82:85], v[132:133], off offset:192
	v_cvt_pk_bf16_f32 v94, v94, v95
	v_cvt_pk_bf16_f32 v95, v96, v97
	v_mul_f32_e32 v90, v90, v100
	v_mul_f32_e32 v91, v91, v101
	v_mul_f32_e32 v92, v92, v104
	v_mul_f32_e32 v93, v93, v105
	v_cvt_pk_bf16_f32 v90, v90, v91
	v_cvt_pk_bf16_f32 v91, v92, v93
	s_waitcnt vmcnt(0)
	v_fmamk_f32 v82, v82, 0x3a800000, v188
	v_fmamk_f32 v83, v83, 0x3a800000, v188
	v_fmamk_f32 v84, v84, 0x3a800000, v188
	v_fmamk_f32 v85, v85, 0x3a800000, v188
	v_rsq_f32_e32 v82, v82
	v_rsq_f32_e32 v83, v83
	v_rsq_f32_e32 v84, v84
	v_rsq_f32_e32 v85, v85
	v_mul_f32_e32 v66, v66, v82
	v_mul_f32_e32 v67, v67, v83
	s_nop 0
	v_cvt_pk_bf16_f32 v66, v66, v67
	v_mul_f32_e32 v68, v68, v84
	v_mul_f32_e32 v69, v69, v85
	v_mul_f32_e32 v78, v78, v82
	v_mul_f32_e32 v79, v79, v83
	v_cvt_pk_bf16_f32 v67, v68, v69
	ds_write2_b64 v98, v[88:89], v[66:67] offset0:104 offset1:108
	global_load_dwordx4 v[66:69], v[132:133], off offset:256
	v_mul_f32_e32 v80, v80, v84
	v_mul_f32_e32 v81, v81, v85
	v_cvt_pk_bf16_f32 v78, v78, v79
	v_cvt_pk_bf16_f32 v79, v80, v81
	ds_write2_b64 v0, v[94:95], v[78:79] offset0:8 offset1:12
	v_mul_f32_e32 v74, v74, v82
	v_mul_f32_e32 v75, v75, v83
	v_mul_f32_e32 v76, v76, v84
	v_mul_f32_e32 v77, v77, v85
	v_mul_f32_e32 v70, v70, v82
	v_mul_f32_e32 v71, v71, v83
	v_mul_f32_e32 v72, v72, v84
	v_mul_f32_e32 v73, v73, v85
	v_cvt_pk_bf16_f32 v74, v74, v75
	v_cvt_pk_bf16_f32 v75, v76, v77
	v_cvt_pk_bf16_f32 v70, v70, v71
	v_cvt_pk_bf16_f32 v71, v72, v73
	ds_write2_b64 v106, v[90:91], v[74:75] offset0:40 offset1:44
	ds_write2_b64 v102, v[86:87], v[70:71] offset0:72 offset1:76
	s_waitcnt vmcnt(0)
; template <int EPI>
; DI void gemm_tile(const Params& p, int layer, int mt, int nt, u16* sm, int wv) {
;     ...
;       for (int i = 0; i < 8; ++i) {
;         float rs[4];
; #pragma unroll
;         for (int e = 0; e < 4; ++e) rs[e] = __builtin_amdgcn_rsqf(ssl[m0 + wm * 128 + 16 * i + 4 * fq + e] * (1.f / DM) + EPS);
;         const int pos = 16 * i + 8 * (fq & 1) + 4 * (fq >> 1);
; #pragma unroll
;         for (int j = 0; j < 4; ++j) {
;           u32x2 v = {pk2(acc[i][j][0] * rs[0], acc[i][j][1] * rs[1]), pk2(acc[i][j][2] * rs[2], acc[i][j][3] * rs[3])};
;           *(u32x2*)(stg + (16 * j + fr) * VSTR + pos) = v;
;         }
;       }
	v_fmamk_f32 v66, v66, 0x3a800000, v188
	v_fmamk_f32 v67, v67, 0x3a800000, v188
	v_fmamk_f32 v68, v68, 0x3a800000, v188
	v_fmamk_f32 v69, v69, 0x3a800000, v188
	v_rsq_f32_e32 v66, v66
	v_rsq_f32_e32 v67, v67
	v_rsq_f32_e32 v68, v68
	v_rsq_f32_e32 v69, v69
	v_mul_f32_e32 v54, v54, v66
	v_mul_f32_e32 v55, v55, v67
	v_mul_f32_e32 v50, v50, v66
	v_mul_f32_e32 v51, v51, v67
	v_mul_f32_e32 v56, v56, v68
	v_mul_f32_e32 v57, v57, v69
	v_cvt_pk_bf16_f32 v54, v54, v55
	v_cvt_pk_bf16_f32 v55, v56, v57
	v_cvt_pk_bf16_f32 v56, v50, v51
	v_mul_f32_e32 v50, v52, v68
	v_mul_f32_e32 v51, v53, v69
	v_mul_f32_e32 v62, v62, v66
	v_mul_f32_e32 v63, v63, v67
	v_cvt_pk_bf16_f32 v57, v50, v51
	global_load_dwordx4 v[50:53], v[132:133], off offset:320
	v_mul_f32_e32 v64, v64, v68
	v_mul_f32_e32 v65, v65, v69
	v_cvt_pk_bf16_f32 v62, v62, v63
	v_cvt_pk_bf16_f32 v63, v64, v65
	v_mul_f32_e32 v58, v58, v66
	v_mul_f32_e32 v59, v59, v67
	v_mul_f32_e32 v60, v60, v68
	v_mul_f32_e32 v61, v61, v69
	v_cvt_pk_bf16_f32 v58, v58, v59
	v_cvt_pk_bf16_f32 v59, v60, v61
	s_waitcnt vmcnt(0)
	v_fmamk_f32 v50, v50, 0x3a800000, v188
	v_fmamk_f32 v51, v51, 0x3a800000, v188
	v_fmamk_f32 v52, v52, 0x3a800000, v188
	v_fmamk_f32 v53, v53, 0x3a800000, v188
	v_rsq_f32_e32 v50, v50
	v_rsq_f32_e32 v51, v51
	v_rsq_f32_e32 v52, v52
	v_rsq_f32_e32 v53, v53
	v_mul_f32_e32 v34, v34, v50
	v_mul_f32_e32 v35, v35, v51
	s_nop 0
	v_cvt_pk_bf16_f32 v34, v34, v35
	v_mul_f32_e32 v36, v36, v52
	v_mul_f32_e32 v37, v37, v53
	v_mul_f32_e32 v46, v46, v50
	v_mul_f32_e32 v47, v47, v51
	v_cvt_pk_bf16_f32 v35, v36, v37
	ds_write2_b64 v98, v[56:57], v[34:35] offset0:112 offset1:116
	global_load_dwordx4 v[34:37], v[132:133], off offset:384
	v_mul_f32_e32 v48, v48, v52
	v_mul_f32_e32 v49, v49, v53
	v_cvt_pk_bf16_f32 v46, v46, v47
	v_cvt_pk_bf16_f32 v47, v48, v49
	ds_write2_b64 v0, v[62:63], v[46:47] offset0:16 offset1:20
	v_mul_f32_e32 v42, v42, v50
	v_mul_f32_e32 v43, v43, v51
	v_mul_f32_e32 v44, v44, v52
	v_mul_f32_e32 v45, v45, v53
	v_mul_f32_e32 v38, v38, v50
	v_mul_f32_e32 v39, v39, v51
	v_mul_f32_e32 v40, v40, v52
	v_mul_f32_e32 v41, v41, v53
	v_cvt_pk_bf16_f32 v42, v42, v43
	v_cvt_pk_bf16_f32 v43, v44, v45
	v_cvt_pk_bf16_f32 v38, v38, v39
	v_cvt_pk_bf16_f32 v39, v40, v41
	ds_write2_b64 v106, v[58:59], v[42:43] offset0:48 offset1:52
	ds_write2_b64 v102, v[54:55], v[38:39] offset0:80 offset1:84
	s_waitcnt vmcnt(0)
	v_fmamk_f32 v34, v34, 0x3a800000, v188
	v_fmamk_f32 v35, v35, 0x3a800000, v188
	v_fmamk_f32 v36, v36, 0x3a800000, v188
	v_fmamk_f32 v37, v37, 0x3a800000, v188
	v_rsq_f32_e32 v34, v34
	v_rsq_f32_e32 v35, v35
	v_rsq_f32_e32 v36, v36
	v_rsq_f32_e32 v37, v37
	v_mul_f32_e32 v30, v30, v34
	v_mul_f32_e32 v31, v31, v35
	s_nop 0
	v_cvt_pk_bf16_f32 v30, v30, v31
	v_mul_f32_e32 v32, v32, v36
	v_mul_f32_e32 v33, v33, v37
	v_mul_f32_e32 v26, v26, v34
	v_mul_f32_e32 v27, v27, v35
	v_cvt_pk_bf16_f32 v31, v32, v33
	v_mul_f32_e32 v22, v22, v34
	v_mul_f32_e32 v23, v23, v35
	v_mul_f32_e32 v18, v18, v34
	v_mul_f32_e32 v19, v19, v35
	global_load_dwordx4 v[32:35], v[132:133], off offset:448
	v_mul_f32_e32 v24, v24, v36
	v_mul_f32_e32 v25, v25, v37
	v_mul_f32_e32 v20, v20, v36
	v_mul_f32_e32 v21, v21, v37
	v_cvt_pk_bf16_f32 v22, v22, v23
	v_cvt_pk_bf16_f32 v23, v24, v25
	v_cvt_pk_bf16_f32 v18, v18, v19
	v_cvt_pk_bf16_f32 v19, v20, v21
	v_mul_f32_e32 v28, v28, v36
	v_mul_f32_e32 v29, v29, v37
	v_cvt_pk_bf16_f32 v26, v26, v27
	v_cvt_pk_bf16_f32 v27, v28, v29
	s_waitcnt vmcnt(0)
; template <int EPI>
; DI void gemm_tile(const Params& p, int layer, int mt, int nt, u16* sm, int wv) {
;     ...
;       for (int i = 0; i < 8; ++i) {
;         float rs[4];
; #pragma unroll
;         for (int e = 0; e < 4; ++e) rs[e] = __builtin_amdgcn_rsqf(ssl[m0 + wm * 128 + 16 * i + 4 * fq + e] * (1.f / DM) + EPS);
;         const int pos = 16 * i + 8 * (fq & 1) + 4 * (fq >> 1);
; #pragma unroll
;         for (int j = 0; j < 4; ++j) {
;           u32x2 v = {pk2(acc[i][j][0] * rs[0], acc[i][j][1] * rs[1]), pk2(acc[i][j][2] * rs[2], acc[i][j][3] * rs[3])};
;           *(u32x2*)(stg + (16 * j + fr) * VSTR + pos) = v;
;         }
;       }
;       u16* gdst = p.vt + ((size_t)(bb * NVH + vbase + wn) * 64) * SEQ + s0 + wm * 128;
; #pragma unroll
;       for (int t = 0; t < 16; ++t) {
;         const int c = lane + 64 * t, row = c >> 4, kc = c & 15;
;         const u32x4 v = *(const u32x4*)(stg + row * VSTR + kc * 8);
;         *(u32x4*)(gdst + (size_t)row * SEQ + kc * 8) = v;
;       }
	v_fmamk_f32 v20, v32, 0x3a800000, v188
	v_fmamk_f32 v21, v33, 0x3a800000, v188
	v_fmamk_f32 v24, v34, 0x3a800000, v188
	v_fmamk_f32 v25, v35, 0x3a800000, v188
	v_rsq_f32_e32 v20, v20
	v_rsq_f32_e32 v21, v21
	v_rsq_f32_e32 v24, v24
	v_rsq_f32_e32 v25, v25
	v_mul_f32_e32 v14, v14, v20
	v_mul_f32_e32 v15, v15, v21
	v_mul_f32_e32 v2, v2, v20
	v_mul_f32_e32 v3, v3, v21
	v_mul_f32_e32 v16, v16, v24
	v_mul_f32_e32 v17, v17, v25
	v_mul_f32_e32 v4, v4, v24
	v_mul_f32_e32 v5, v5, v25
	v_cvt_pk_bf16_f32 v14, v14, v15
	v_cvt_pk_bf16_f32 v15, v16, v17
	v_cvt_pk_bf16_f32 v2, v2, v3
	v_cvt_pk_bf16_f32 v3, v4, v5
	ds_write2_b64 v0, v[30:31], v[14:15] offset0:24 offset1:28
	ds_write2_b64 v102, v[22:23], v[2:3] offset0:88 offset1:92
	v_mul_f32_e32 v2, v10, v20
	v_mul_f32_e32 v3, v11, v21
	v_mul_f32_e32 v4, v12, v24
	v_mul_f32_e32 v5, v13, v25
	v_or_b32_e32 v0, s2, v131
	v_cvt_pk_bf16_f32 v2, v2, v3
	v_cvt_pk_bf16_f32 v3, v4, v5
	v_lshlrev_b32_e32 v0, 20, v0
	ds_write2_b64 v98, v[18:19], v[2:3] offset0:120 offset1:124
	v_lshl_add_u64 v[2:3], s[88:89], 0, v[0:1]
	v_lshl_add_u64 v[2:3], v[2:3], 0, s[4:5]
	v_ashrrev_i32_e32 v131, 31, v130
	v_mul_f32_e32 v6, v6, v20
	v_mul_f32_e32 v7, v7, v21
	v_mul_f32_e32 v8, v8, v24
	v_mul_f32_e32 v9, v9, v25
	v_lshl_add_u64 v[2:3], v[130:131], 1, v[2:3]
	v_and_b32_e32 v0, 0xf0, v136
	v_cvt_pk_bf16_f32 v6, v6, v7
	v_cvt_pk_bf16_f32 v7, v8, v9
	v_lshl_add_u64 v[132:133], v[2:3], 0, v[0:1]
	v_mul_u32_u24_e32 v2, 0x110, v134
	ds_write2_b64 v106, v[26:27], v[6:7] offset0:56 offset1:60
	v_add3_u32 v8, v135, v0, v2
	ds_read_b128 v[2:5], v8
	v_lshlrev_b32_e32 v0, 14, v134
	v_lshl_add_u64 v[6:7], v[132:133], 0, v[0:1]
	v_add_u32_e32 v140, 0x3fc0, v8
	s_waitcnt lgkmcnt(0)
	global_store_dwordx4 v[6:7], v[2:5], off
	ds_read_b128 v[2:5], v8 offset:1088
	v_or_b32_e32 v6, 0x10000, v0
	v_mov_b32_e32 v7, v1
	v_lshl_add_u64 v[6:7], v[132:133], 0, v[6:7]
	s_waitcnt lgkmcnt(0)
	global_store_dwordx4 v[6:7], v[2:5], off
	ds_read_b128 v[2:5], v8 offset:2176
	v_or_b32_e32 v6, 0x20000, v0
	v_mov_b32_e32 v7, v1
	v_lshl_add_u64 v[6:7], v[132:133], 0, v[6:7]
	s_waitcnt lgkmcnt(0)
	global_store_dwordx4 v[6:7], v[2:5], off
	ds_read_b128 v[2:5], v8 offset:3264
	v_or_b32_e32 v6, 0x30000, v0
	v_mov_b32_e32 v7, v1
	v_lshl_add_u64 v[6:7], v[132:133], 0, v[6:7]
	s_waitcnt lgkmcnt(0)
	global_store_dwordx4 v[6:7], v[2:5], off
	ds_read_b128 v[2:5], v8 offset:4352
	v_or_b32_e32 v6, 0x40000, v0
	v_mov_b32_e32 v7, v1
	v_lshl_add_u64 v[6:7], v[132:133], 0, v[6:7]
	s_waitcnt lgkmcnt(0)
	global_store_dwordx4 v[6:7], v[2:5], off
	ds_read_b128 v[2:5], v8 offset:5440
	v_or_b32_e32 v6, 0x50000, v0
	v_mov_b32_e32 v7, v1
	v_lshl_add_u64 v[6:7], v[132:133], 0, v[6:7]
	s_waitcnt lgkmcnt(0)
	global_store_dwordx4 v[6:7], v[2:5], off
	ds_read_b128 v[2:5], v8 offset:6528
	v_or_b32_e32 v6, 0x60000, v0
	v_mov_b32_e32 v7, v1
	v_lshl_add_u64 v[6:7], v[132:133], 0, v[6:7]
	s_waitcnt lgkmcnt(0)
	global_store_dwordx4 v[6:7], v[2:5], off
	ds_read_b128 v[2:5], v8 offset:7616
	v_or_b32_e32 v6, 0x70000, v0
	v_mov_b32_e32 v7, v1
	v_lshl_add_u64 v[6:7], v[132:133], 0, v[6:7]
	s_waitcnt lgkmcnt(0)
	global_store_dwordx4 v[6:7], v[2:5], off
	ds_read_b128 v[2:5], v8 offset:8704
	v_or_b32_e32 v6, 0x80000, v0
	v_mov_b32_e32 v7, v1
	v_lshl_add_u64 v[6:7], v[132:133], 0, v[6:7]
	s_waitcnt lgkmcnt(0)
	global_store_dwordx4 v[6:7], v[2:5], off
	ds_read_b128 v[2:5], v8 offset:9792
	v_or_b32_e32 v6, 0x90000, v0
	v_mov_b32_e32 v7, v1
	v_lshl_add_u64 v[6:7], v[132:133], 0, v[6:7]
	s_waitcnt lgkmcnt(0)
	global_store_dwordx4 v[6:7], v[2:5], off
	ds_read_b128 v[2:5], v8 offset:10880
	v_or_b32_e32 v6, 0xa0000, v0
	v_mov_b32_e32 v7, v1
	v_lshl_add_u64 v[6:7], v[132:133], 0, v[6:7]
	s_waitcnt lgkmcnt(0)
	global_store_dwordx4 v[6:7], v[2:5], off
	ds_read_b128 v[2:5], v8 offset:11968
	v_or_b32_e32 v6, 0xb0000, v0
	v_mov_b32_e32 v7, v1
	v_lshl_add_u64 v[6:7], v[132:133], 0, v[6:7]
	s_waitcnt lgkmcnt(0)
	global_store_dwordx4 v[6:7], v[2:5], off
	ds_read_b128 v[2:5], v8 offset:13056
	v_or_b32_e32 v6, 0xc0000, v0
	v_mov_b32_e32 v7, v1
	v_lshl_add_u64 v[6:7], v[132:133], 0, v[6:7]
	s_waitcnt lgkmcnt(0)
	global_store_dwordx4 v[6:7], v[2:5], off
	ds_read_b128 v[2:5], v8 offset:14144
	v_or_b32_e32 v6, 0xd0000, v0
	v_mov_b32_e32 v7, v1
	v_lshl_add_u64 v[6:7], v[132:133], 0, v[6:7]
	v_or_b32_e32 v0, 0xe0000, v0
	s_waitcnt lgkmcnt(0)
	global_store_dwordx4 v[6:7], v[2:5], off
	ds_read_b128 v[2:5], v8 offset:15232
	v_lshl_add_u64 v[6:7], v[132:133], 0, v[0:1]
	v_lshl_or_b32 v0, v134, 13, v194
	s_waitcnt lgkmcnt(0)
	global_store_dwordx4 v[6:7], v[2:5], off

; template <int EPI>
; DI void gemm_tile(const Params& p, int layer, int mt, int nt, u16* sm, int wv) {
;     ...
;   if (EPI == 0) {
;     const float* ssl = p.ss + (size_t)layer * MTOK;
;     __syncthreads();
;     u16* stg = sm + (wm * 2 + wn) * (128 * LSTR);
;     if (!vtile) {
;       const float qsc = (nt < 2) ? 0.17677669529663687f * LOG2E
;                         : ((nt >= 8 && nt < 12) || nt == 18 || nt == 19) ? 0.125f * LOG2E : 1.f;
; #pragma unroll
;       for (int i = 0; i < 8; ++i) {
;         const int m = m0 + wm * 128 + 16 * i + fr;
;         const float rs = __builtin_amdgcn_rsqf(ssl[m] * (1.f / DM) + EPS) * qsc;
;         u16* d = stg + (16 * i + fr) * LSTR + 4 * fq;
; #pragma unroll
;         for (int j = 0; j < 4; ++j) {
;           u32x2 v = {pk2(acc[i][j][0] * rs, acc[i][j][1] * rs), pk2(acc[i][j][2] * rs, acc[i][j][3] * rs)};
;           *(u32x2*)(d + 16 * j) = v;
;         }
;       }
.LBB0_124:
	s_waitcnt vmcnt(8)
	v_mbcnt_lo_u32_b32 v138, -1, 0
	v_mbcnt_hi_u32_b32 v138, -1, v138
	s_lshl_b32 s21, s21, 8
	v_add_u32_e32 v0, s33, v138
	v_bfe_u32 v130, v0, 6, 21
	s_waitcnt vmcnt(7)
	v_mul_u32_u24_e32 v135, 0x4800, v130
	v_and_b32_e32 v130, 0xffffff80, v0
	v_and_b32_e32 v137, 15, v138
	v_bfe_u32 v134, v138, 4, 2
	v_bfe_u32 v131, v0, 6, 1
	s_mov_b64 s[6:7], -1
	s_andn2_b64 vcc, exec, s[4:5]
	v_add_u32_e32 v139, s21, v130
	v_lshlrev_b32_e32 v136, 4, v138
	s_barrier
	s_cbranch_vccnz .LBB0_126
	v_or_b32_e32 v132, v139, v137
	v_ashrrev_i32_e32 v133, 31, v132
	v_lshl_add_u64 v[132:133], v[132:133], 2, s[0:1]
	global_load_dword v142, v[132:133], off
	global_load_dword v150, v[132:133], off offset:64
	global_load_dword v151, v[132:133], off offset:128
	global_load_dword v152, v[132:133], off offset:192
	global_load_dword v153, v[132:133], off offset:256
	global_load_dword v154, v[132:133], off offset:320
	global_load_dword v155, v[132:133], off offset:384
	global_load_dword v156, v[132:133], off offset:448
	s_and_b32 s4, s20, 0x7ffffffc
	s_cmp_eq_u32 s4, 8
	s_cselect_b64 s[4:5], -1, 0
	s_and_b32 s6, s18, -16
	s_cmpk_eq_i32 s6, 0x90
	s_cselect_b64 s[6:7], -1, 0
	s_or_b64 vcc, s[6:7], s[4:5]
	s_cmp_gt_i32 s20, 1
	v_cndmask_b32_e32 v0, 1.0, v191, vcc
	s_cselect_b64 vcc, -1, 0
	v_cndmask_b32_e32 v0, v192, v0, vcc
	s_waitcnt vmcnt(7)
	v_mul_u32_u24_e32 v143, 0x90, v137
	v_lshlrev_b32_e32 v141, 3, v134
	v_add3_u32 v141, v135, v141, v143
	v_and_b32_e32 v140, 63, v138
	s_mov_b64 s[6:7], 0
	s_waitcnt vmcnt(0)
	v_fmamk_f32 v142, v142, 0x3a800000, v188
	v_rsq_f32_e32 v142, v142
	s_nop 0
	v_mul_f32_e32 v142, v0, v142
	v_mul_f32_e32 v144, v126, v142
	v_mul_f32_e32 v145, v127, v142
	v_mul_f32_e32 v146, v128, v142
	v_mul_f32_e32 v147, v129, v142
	v_cvt_pk_bf16_f32 v144, v144, v145
	v_cvt_pk_bf16_f32 v145, v146, v147
	v_mul_f32_e32 v146, v122, v142
	v_mul_f32_e32 v147, v123, v142
	v_mul_f32_e32 v148, v124, v142
	v_mul_f32_e32 v149, v125, v142
	v_cvt_pk_bf16_f32 v146, v146, v147
	v_cvt_pk_bf16_f32 v147, v148, v149
	ds_write2_b64 v141, v[144:145], v[146:147] offset1:4
	v_mul_f32_e32 v144, v118, v142
	v_mul_f32_e32 v145, v119, v142
	v_mul_f32_e32 v146, v120, v142
	v_mul_f32_e32 v147, v121, v142
	v_cvt_pk_bf16_f32 v144, v144, v145
	v_cvt_pk_bf16_f32 v145, v146, v147
	v_mul_f32_e32 v146, v114, v142
	v_mul_f32_e32 v147, v115, v142
	v_mul_f32_e32 v143, v117, v142
	v_mul_f32_e32 v142, v116, v142
	v_cvt_pk_bf16_f32 v146, v146, v147
	v_cvt_pk_bf16_f32 v147, v142, v143
	v_mov_b32_e32 v142, v150
	ds_write2_b64 v141, v[144:145], v[146:147] offset0:8 offset1:12
	s_waitcnt vmcnt(0)
	v_fmamk_f32 v142, v142, 0x3a800000, v188
	v_rsq_f32_e32 v142, v142
	s_nop 0
	v_mul_f32_e32 v142, v0, v142
	v_mul_f32_e32 v144, v110, v142
	v_mul_f32_e32 v145, v111, v142
	v_mul_f32_e32 v146, v112, v142
	v_mul_f32_e32 v147, v113, v142
	v_cvt_pk_bf16_f32 v144, v144, v145
	v_cvt_pk_bf16_f32 v145, v146, v147
	v_mul_f32_e32 v146, v106, v142
	v_mul_f32_e32 v147, v107, v142
	v_mul_f32_e32 v148, v108, v142
	v_mul_f32_e32 v149, v109, v142
	v_cvt_pk_bf16_f32 v146, v146, v147
	v_cvt_pk_bf16_f32 v147, v148, v149
	v_add_u32_e32 v148, 0x800, v141
	ds_write2_b64 v148, v[144:145], v[146:147] offset0:32 offset1:36
	v_mul_f32_e32 v144, v102, v142
	v_mul_f32_e32 v145, v103, v142
	v_mul_f32_e32 v146, v104, v142
	v_mul_f32_e32 v147, v105, v142
	v_cvt_pk_bf16_f32 v144, v144, v145
	v_cvt_pk_bf16_f32 v145, v146, v147
	v_mul_f32_e32 v146, v98, v142
	v_mul_f32_e32 v147, v99, v142
	v_mul_f32_e32 v143, v101, v142
	v_mul_f32_e32 v142, v100, v142
	v_cvt_pk_bf16_f32 v146, v146, v147
	v_cvt_pk_bf16_f32 v147, v142, v143
	v_mov_b32_e32 v142, v151
	ds_write2_b64 v148, v[144:145], v[146:147] offset0:40 offset1:44
	s_waitcnt vmcnt(0)
	v_fmamk_f32 v142, v142, 0x3a800000, v188
	v_rsq_f32_e32 v142, v142
	s_nop 0
	v_mul_f32_e32 v142, v0, v142
	v_mul_f32_e32 v144, v94, v142
	v_mul_f32_e32 v145, v95, v142
	v_mul_f32_e32 v146, v96, v142
	v_mul_f32_e32 v147, v97, v142
	v_cvt_pk_bf16_f32 v144, v144, v145
	v_cvt_pk_bf16_f32 v145, v146, v147
	v_mul_f32_e32 v146, v90, v142
	v_mul_f32_e32 v147, v91, v142
	v_mul_f32_e32 v148, v92, v142
	v_mul_f32_e32 v149, v93, v142
	v_cvt_pk_bf16_f32 v146, v146, v147
	v_cvt_pk_bf16_f32 v147, v148, v149
	v_add_u32_e32 v148, 0x1000, v141
	ds_write2_b64 v148, v[144:145], v[146:147] offset0:64 offset1:68
	v_mul_f32_e32 v144, v86, v142
	v_mul_f32_e32 v145, v87, v142
	v_mul_f32_e32 v146, v88, v142
	v_mul_f32_e32 v147, v89, v142
	v_cvt_pk_bf16_f32 v144, v144, v145
	v_cvt_pk_bf16_f32 v145, v146, v147
	v_mul_f32_e32 v146, v82, v142
	v_mul_f32_e32 v147, v83, v142
	v_mul_f32_e32 v143, v85, v142
	v_mul_f32_e32 v142, v84, v142
	v_cvt_pk_bf16_f32 v146, v146, v147
	v_cvt_pk_bf16_f32 v147, v142, v143
	v_mov_b32_e32 v142, v152
	ds_write2_b64 v148, v[144:145], v[146:147] offset0:72 offset1:76
	s_waitcnt vmcnt(0)
	v_fmamk_f32 v142, v142, 0x3a800000, v188
	v_rsq_f32_e32 v142, v142
	s_nop 0
	v_mul_f32_e32 v142, v0, v142
	v_mul_f32_e32 v144, v78, v142
	v_mul_f32_e32 v145, v79, v142
	v_mul_f32_e32 v146, v80, v142
	v_mul_f32_e32 v147, v81, v142
	v_cvt_pk_bf16_f32 v144, v144, v145
	v_cvt_pk_bf16_f32 v145, v146, v147
	v_mul_f32_e32 v146, v74, v142
	v_mul_f32_e32 v147, v75, v142
	v_mul_f32_e32 v148, v76, v142
	v_mul_f32_e32 v149, v77, v142
	v_cvt_pk_bf16_f32 v146, v146, v147
	v_cvt_pk_bf16_f32 v147, v148, v149
	v_add_u32_e32 v148, 0x1800, v141
	ds_write2_b64 v148, v[144:145], v[146:147] offset0:96 offset1:100
	v_mul_f32_e32 v144, v70, v142
	v_mul_f32_e32 v145, v71, v142
	v_mul_f32_e32 v146, v72, v142
	v_mul_f32_e32 v147, v73, v142
	v_cvt_pk_bf16_f32 v144, v144, v145
	v_cvt_pk_bf16_f32 v145, v146, v147
	v_mul_f32_e32 v146, v66, v142
	v_mul_f32_e32 v147, v67, v142
	v_mul_f32_e32 v143, v69, v142
	v_mul_f32_e32 v142, v68, v142
	v_cvt_pk_bf16_f32 v146, v146, v147
	v_cvt_pk_bf16_f32 v147, v142, v143
	v_mov_b32_e32 v142, v153
	ds_write2_b64 v148, v[144:145], v[146:147] offset0:104 offset1:108
	s_waitcnt vmcnt(0)
; template <int EPI>
; DI void gemm_tile(const Params& p, int layer, int mt, int nt, u16* sm, int wv) {
;     ...
;       for (int i = 0; i < 8; ++i) {
;         const int m = m0 + wm * 128 + 16 * i + fr;
;         const float rs = __builtin_amdgcn_rsqf(ssl[m] * (1.f / DM) + EPS) * qsc;
;         u16* d = stg + (16 * i + fr) * LSTR + 4 * fq;
; #pragma unroll
;         for (int j = 0; j < 4; ++j) {
;           u32x2 v = {pk2(acc[i][j][0] * rs, acc[i][j][1] * rs), pk2(acc[i][j][2] * rs, acc[i][j][3] * rs)};
;           *(u32x2*)(d + 16 * j) = v;
;         }
;       }
;       u16* gdst = p.proj + (size_t)(m0 + wm * 128) * DIN + n0 + wn * 64;
; #pragma unroll
;       for (int t = 0; t < 16; ++t) {
;         const int c = lane + 64 * t, row = c >> 3, kc = c & 7;
;         const u32x4 v = *(const u32x4*)(stg + row * LSTR + kc * 8);
;         *(u32x4*)(gdst + (size_t)row * DIN + kc * 8) = v;
;       }
	v_fmamk_f32 v142, v142, 0x3a800000, v188
	v_rsq_f32_e32 v142, v142
	s_nop 0
	v_mul_f32_e32 v142, v0, v142
	v_mul_f32_e32 v144, v62, v142
	v_mul_f32_e32 v145, v63, v142
	v_mul_f32_e32 v146, v64, v142
	v_mul_f32_e32 v147, v65, v142
	v_cvt_pk_bf16_f32 v144, v144, v145
	v_cvt_pk_bf16_f32 v145, v146, v147
	v_mul_f32_e32 v146, v58, v142
	v_mul_f32_e32 v147, v59, v142
	v_mul_f32_e32 v148, v60, v142
	v_mul_f32_e32 v149, v61, v142
	v_cvt_pk_bf16_f32 v146, v146, v147
	v_cvt_pk_bf16_f32 v147, v148, v149
	v_add_u32_e32 v148, 0x2000, v141
	ds_write2_b64 v148, v[144:145], v[146:147] offset0:128 offset1:132
	v_mul_f32_e32 v144, v54, v142
	v_mul_f32_e32 v145, v55, v142
	v_mul_f32_e32 v146, v56, v142
	v_mul_f32_e32 v147, v57, v142
	v_cvt_pk_bf16_f32 v144, v144, v145
	v_cvt_pk_bf16_f32 v145, v146, v147
	v_mul_f32_e32 v146, v50, v142
	v_mul_f32_e32 v147, v51, v142
	v_mul_f32_e32 v143, v53, v142
	v_mul_f32_e32 v142, v52, v142
	v_cvt_pk_bf16_f32 v146, v146, v147
	v_cvt_pk_bf16_f32 v147, v142, v143
	v_mov_b32_e32 v142, v154
	ds_write2_b64 v148, v[144:145], v[146:147] offset0:136 offset1:140
	s_waitcnt vmcnt(0)
	v_fmamk_f32 v142, v142, 0x3a800000, v188
	v_rsq_f32_e32 v142, v142
	s_nop 0
	v_mul_f32_e32 v142, v0, v142
	v_mul_f32_e32 v144, v46, v142
	v_mul_f32_e32 v145, v47, v142
	v_mul_f32_e32 v146, v48, v142
	v_mul_f32_e32 v147, v49, v142
	v_cvt_pk_bf16_f32 v144, v144, v145
	v_cvt_pk_bf16_f32 v145, v146, v147
	v_mul_f32_e32 v146, v42, v142
	v_mul_f32_e32 v147, v43, v142
	v_mul_f32_e32 v148, v44, v142
	v_mul_f32_e32 v149, v45, v142
	v_cvt_pk_bf16_f32 v146, v146, v147
	v_cvt_pk_bf16_f32 v147, v148, v149
	v_add_u32_e32 v148, 0x2800, v141
	ds_write2_b64 v148, v[144:145], v[146:147] offset0:160 offset1:164
	v_mul_f32_e32 v144, v38, v142
	v_mul_f32_e32 v145, v39, v142
	v_mul_f32_e32 v146, v40, v142
	v_mul_f32_e32 v147, v41, v142
	v_cvt_pk_bf16_f32 v144, v144, v145
	v_cvt_pk_bf16_f32 v145, v146, v147
	v_mul_f32_e32 v146, v34, v142
	v_mul_f32_e32 v147, v35, v142
	v_mul_f32_e32 v143, v37, v142
	v_mul_f32_e32 v142, v36, v142
	v_cvt_pk_bf16_f32 v146, v146, v147
	v_cvt_pk_bf16_f32 v147, v142, v143
	v_mov_b32_e32 v142, v155
	ds_write2_b64 v148, v[144:145], v[146:147] offset0:168 offset1:172
	v_mov_b32_e32 v132, v156
	s_waitcnt vmcnt(1)
	v_fmamk_f32 v142, v142, 0x3a800000, v188
	v_rsq_f32_e32 v142, v142
	s_waitcnt vmcnt(0)
	v_fmamk_f32 v132, v132, 0x3a800000, v188
	v_rsq_f32_e32 v132, v132
	v_mul_f32_e32 v142, v0, v142
	v_mul_f32_e32 v144, v30, v142
	v_mul_f32_e32 v145, v31, v142
	v_mul_f32_e32 v146, v32, v142
	v_mul_f32_e32 v147, v33, v142
	v_cvt_pk_bf16_f32 v144, v144, v145
	v_cvt_pk_bf16_f32 v145, v146, v147
	v_mul_f32_e32 v146, v26, v142
	v_mul_f32_e32 v147, v27, v142
	v_mul_f32_e32 v148, v28, v142
	v_mul_f32_e32 v149, v29, v142
	v_cvt_pk_bf16_f32 v146, v146, v147
	v_cvt_pk_bf16_f32 v147, v148, v149
	v_add_u32_e32 v148, 0x3000, v141
	ds_write2_b64 v148, v[144:145], v[146:147] offset0:192 offset1:196
	v_mul_f32_e32 v144, v22, v142
	v_mul_f32_e32 v145, v23, v142
	v_mul_f32_e32 v146, v24, v142
	v_mul_f32_e32 v147, v25, v142
	v_cvt_pk_bf16_f32 v144, v144, v145
	v_cvt_pk_bf16_f32 v145, v146, v147
	v_mul_f32_e32 v146, v18, v142
	v_mul_f32_e32 v147, v19, v142
	v_mul_f32_e32 v143, v21, v142
	v_mul_f32_e32 v142, v20, v142
	v_mul_f32_e32 v0, v0, v132
	v_cvt_pk_bf16_f32 v146, v146, v147
	v_cvt_pk_bf16_f32 v147, v142, v143
	v_mul_f32_e32 v132, v14, v0
	v_mul_f32_e32 v133, v15, v0
	v_mul_f32_e32 v142, v16, v0
	v_mul_f32_e32 v143, v17, v0
	ds_write2_b64 v148, v[144:145], v[146:147] offset0:200 offset1:204
	v_cvt_pk_bf16_f32 v132, v132, v133
	v_cvt_pk_bf16_f32 v133, v142, v143
	v_mul_f32_e32 v142, v6, v0
	v_mul_f32_e32 v143, v7, v0
	v_mul_f32_e32 v144, v8, v0
	v_mul_f32_e32 v145, v9, v0
	v_cvt_pk_bf16_f32 v142, v142, v143
	v_cvt_pk_bf16_f32 v143, v144, v145
	v_add_u32_e32 v141, 0x3800, v141
	ds_write2_b64 v141, v[132:133], v[142:143] offset0:224 offset1:228
	v_mul_f32_e32 v132, v2, v0
	v_mul_f32_e32 v133, v3, v0
	v_mul_f32_e32 v142, v4, v0
	v_mul_f32_e32 v143, v5, v0
	v_cvt_pk_bf16_f32 v132, v132, v133
	v_cvt_pk_bf16_f32 v133, v142, v143
	v_mul_f32_e32 v142, v10, v0
	v_mul_f32_e32 v143, v11, v0
	v_mul_f32_e32 v144, v12, v0
	v_mul_f32_e32 v145, v13, v0
	v_cvt_pk_bf16_f32 v142, v142, v143
	v_cvt_pk_bf16_f32 v143, v144, v145
	ds_write2_b64 v141, v[132:133], v[142:143] offset0:232 offset1:236
	v_mov_b64_e32 v[132:133], s[62:63]
	v_mad_i64_i32 v[132:133], s[4:5], v139, s8, v[132:133]
	v_lshl_add_u64 v[132:133], s[2:3], 1, v[132:133]
	v_lshlrev_b32_e32 v0, 7, v131
	v_lshrrev_b32_e32 v148, 3, v140
	v_lshl_add_u64 v[132:133], v[132:133], 0, v[0:1]
	v_and_b32_e32 v0, 0x70, v136
	v_mul_u32_u24_e32 v140, 0x90, v148
	v_add3_u32 v149, v135, v0, v140
	ds_read_b128 v[140:143], v149
	v_lshl_add_u64 v[132:133], v[132:133], 0, v[0:1]
	v_mul_u32_u24_e32 v0, 0xd00, v148
	v_lshlrev_b32_e32 v0, 1, v0
	v_lshl_add_u64 v[144:145], v[132:133], 0, v[0:1]
	s_cmp_eq_u32 s40, 2
	s_cbranch_scc1 .Lepi_hi_skip
	s_waitcnt lgkmcnt(0)
	global_store_dwordx4 v[144:145], v[140:143], off
	ds_read_b128 v[140:143], v149 offset:1152
	s_mov_b32 s2, 0xd000
	v_add_co_u32_e32 v146, vcc, s2, v144
	s_mov_b32 s2, 0x1a000
	s_nop 0
	v_addc_co_u32_e32 v147, vcc, 0, v145, vcc
	s_waitcnt lgkmcnt(0)
	global_store_dwordx4 v[146:147], v[140:143], off
	ds_read_b128 v[140:143], v149 offset:2304
	v_add_co_u32_e32 v146, vcc, s2, v144
	s_mov_b32 s2, 0x27000
	s_nop 0
	v_addc_co_u32_e32 v147, vcc, 0, v145, vcc
	s_waitcnt lgkmcnt(0)
	global_store_dwordx4 v[146:147], v[140:143], off
	ds_read_b128 v[140:143], v149 offset:3456
	v_add_co_u32_e32 v144, vcc, s2, v144
	s_movk_i32 s2, 0xd00
	s_nop 0
	v_addc_co_u32_e32 v145, vcc, 0, v145, vcc
	s_waitcnt lgkmcnt(0)
	global_store_dwordx4 v[144:145], v[140:143], off
	ds_read_b128 v[140:143], v149 offset:4608
	v_add_u32_e32 v144, 0x34000, v0
	v_mov_b32_e32 v145, v1
	v_lshl_add_u64 v[144:145], v[132:133], 0, v[144:145]
	s_waitcnt lgkmcnt(0)
	global_store_dwordx4 v[144:145], v[140:143], off
	ds_read_b128 v[140:143], v149 offset:5760
	v_add_u32_e32 v144, 0x41000, v0
	v_mov_b32_e32 v145, v1
	v_lshl_add_u64 v[144:145], v[132:133], 0, v[144:145]
	s_waitcnt lgkmcnt(0)
	global_store_dwordx4 v[144:145], v[140:143], off
	ds_read_b128 v[140:143], v149 offset:6912
	v_add_u32_e32 v144, 0x4e000, v0
	v_mov_b32_e32 v145, v1
	v_lshl_add_u64 v[144:145], v[132:133], 0, v[144:145]
	s_waitcnt lgkmcnt(0)
	global_store_dwordx4 v[144:145], v[140:143], off
	ds_read_b128 v[140:143], v149 offset:8064
	v_add_u32_e32 v144, 0x5b000, v0
	v_mov_b32_e32 v145, v1
	v_lshl_add_u64 v[144:145], v[132:133], 0, v[144:145]
	s_waitcnt lgkmcnt(0)
	global_store_dwordx4 v[144:145], v[140:143], off
	s_cmp_eq_u32 s40, 1
	s_cbranch_scc1 .Lgx_halfdone
	s_branch .Lepi_t8

; DI float ex2(float x) { return __builtin_amdgcn_exp2f(x); }
; DI float lg2(float x) { return __builtin_amdgcn_logf(x); }
; DI f32x16 mfma(bf16x8 a, bf16x8 b, f32x16 c) { return __builtin_amdgcn_mfma_f32_32x32x16_bf16(a, b, c, 0, 0, 0); }
; DI void stick_pv(f32x16& s0, f32x16& s1, float& R, f32x16& o0, f32x16& o1, const u16* Vs, int dl,
;                  bool need_mask, int r, int h) {
;     ...
;     for (int i = 0; i < 16; ++i) {
;       const int ci = 32 * t + (i & 3) + 8 * (i >> 2);
;       float a = t ? s1[i] : s0[i];
;       float z = __builtin_amdgcn_fmed3f(a, -126.f, 126.f);
;       float e = ex2(-z);
;       float lb = -lg2(1.f + e);
;       float xi = lb - z;
;       if (need_mask) {
;         bool valid = (ci < dl);
;         xi = valid ? xi : 0.f;
;         lb = valid ? lb : -INFINITY;
;       }
;       x[16 * t + i] = xi;
;       if (t) s1[i] = lb; else s0[i] = lb;
;     }
; template <int MODE>
; DI void attn_item(const Params& p, int layer, int b, int head, int qblk, u16* sm, volatile LAS int* s_done_, int wv) {
;     ...
;               f32x16 sa[2];
; #pragma unroll
;               for (int e = 0; e < 16; ++e) { sa[0][e] = 0.f; sa[1][e] = 0.f; }
; #pragma unroll
;               for (int t = 0; t < 2; ++t)
; #pragma unroll
;                 for (int ks = 0; ks < 4; ++ks) {
;                   bf16x8 kf = ldsv(Kc + (32 * t + r) * LSTR + ks * 16 + 8 * h);
;                   sa[t] = mfma(kf, qf[ks], sa[t]);
;                 }
;               stick_pv(sa[0], sa[1], R, o[0], o[1], Vc, dl, need_mask, r, h);
.LBB0_224:
	s_or_b64 exec, exec, s[6:7]
	s_waitcnt lgkmcnt(0)
	s_barrier
	s_and_saveexec_b64 s[6:7], s[2:3]
	s_cbranch_execz .LBB0_210
	v_cmp_lt_i32_e64 s[2:3], v164, v176
	v_cmp_eq_u32_e64 s[44:45], 0, v64
	s_and_b64 s[2:3], s[2:3], s[44:45]
	s_and_saveexec_b64 s[18:19], s[2:3]
	s_cbranch_execz .LBB0_234
	v_add_u32_e32 v0, 63, v164
	v_cmp_lt_i32_e64 s[44:45], v0, v148
	v_add_u32_e32 v0, v152, v181
	s_waitcnt vmcnt(3)
	ds_read_b128 v[48:51], v0
	s_waitcnt vmcnt(2)
	ds_read_b128 v[52:55], v0 offset:32
	ds_read_b128 v[204:207], v0 offset:4640
	v_cmp_lt_i32_e64 s[2:3], 0, v183
	s_waitcnt lgkmcnt(2)
	v_mfma_f32_32x32x16_bf16 v[64:79], v[48:51], v[88:91], 0
	ds_read_b128 v[48:51], v0 offset:64
	s_or_b64 s[2:3], s[44:45], s[2:3]
	v_add_f32_e32 v236, 0, v184
	s_waitcnt lgkmcnt(2)
	v_mfma_f32_32x32x16_bf16 v[64:79], v[52:55], v[80:83], v[64:79]
	s_waitcnt lgkmcnt(0)
	v_mfma_f32_32x32x16_bf16 v[64:79], v[48:51], v[84:87], v[64:79]
	ds_read_b128 v[48:51], v0 offset:96
	s_waitcnt lgkmcnt(0)
	v_mfma_f32_32x32x16_bf16 v[64:79], v[48:51], v[92:95], v[64:79]
	ds_read_b128 v[48:51], v0 offset:4608
	s_waitcnt vmcnt(0) lgkmcnt(0)
	v_mfma_f32_32x32x16_bf16 v[48:63], v[48:51], v[88:91], 0
	v_mfma_f32_32x32x16_bf16 v[48:63], v[204:207], v[80:83], v[48:63]
	ds_read_b128 v[204:207], v0 offset:4672
	s_waitcnt lgkmcnt(0)
	v_mfma_f32_32x32x16_bf16 v[48:63], v[204:207], v[84:87], v[48:63]
	ds_read_b128 v[204:207], v0 offset:4704
	s_nop 3
	v_med3_f32 v0, v64, s94, v198
	v_exp_f32_e64 v14, -v0
	s_nop 0
	v_add_f32_e32 v14, 1.0, v14
	v_log_f32_e32 v15, v14
	s_waitcnt lgkmcnt(0)
	v_mfma_f32_32x32x16_bf16 v[48:63], v[204:207], v[92:95], v[48:63]
	v_sub_f32_e64 v0, -v15, v0
	v_cndmask_b32_e64 v14, 0, v0, s[2:3]
	v_med3_f32 v0, v65, s94, v198
	v_cndmask_b32_e64 v165, v199, -v15, s[2:3]
	v_exp_f32_e64 v15, -v0
	v_cmp_lt_i32_e64 s[2:3], 1, v183
	s_or_b64 s[2:3], s[44:45], s[2:3]
	v_add_f32_e32 v15, 1.0, v15
	v_log_f32_e32 v15, v15
	s_nop 0
	v_sub_f32_e64 v0, -v15, v0
	v_cndmask_b32_e64 v64, 0, v0, s[2:3]
	v_med3_f32 v0, v66, s94, v198
	v_cndmask_b32_e64 v185, v199, -v15, s[2:3]
	v_exp_f32_e64 v15, -v0
	v_cmp_lt_i32_e64 s[2:3], 2, v183
	s_or_b64 s[2:3], s[44:45], s[2:3]
	v_add_f32_e32 v15, 1.0, v15
	v_log_f32_e32 v15, v15
	s_nop 0
	v_sub_f32_e64 v0, -v15, v0
	v_cndmask_b32_e64 v66, 0, v0, s[2:3]
	v_med3_f32 v0, v67, s94, v198
	v_cndmask_b32_e64 v186, v199, -v15, s[2:3]
	v_exp_f32_e64 v15, -v0
	v_cmp_lt_i32_e64 s[2:3], 3, v183
	s_or_b64 s[2:3], s[44:45], s[2:3]
	v_add_f32_e32 v15, 1.0, v15
	v_log_f32_e32 v15, v15
	s_nop 0
	v_sub_f32_e64 v0, -v15, v0
	v_cndmask_b32_e64 v166, 0, v0, s[2:3]
	v_med3_f32 v0, v68, s94, v198
	v_cndmask_b32_e64 v204, v199, -v15, s[2:3]
	v_exp_f32_e64 v15, -v0
	v_cmp_lt_i32_e64 s[2:3], 8, v183
	s_or_b64 s[2:3], s[44:45], s[2:3]
	v_add_f32_e32 v15, 1.0, v15
	v_log_f32_e32 v15, v15
	s_nop 0
	v_sub_f32_e64 v0, -v15, v0
	v_cndmask_b32_e64 v205, v199, -v15, s[2:3]
	v_med3_f32 v15, v69, s94, v198
	v_exp_f32_e64 v65, -v15
	v_cndmask_b32_e64 v0, 0, v0, s[2:3]
	v_cmp_lt_i32_e64 s[2:3], 9, v183
	s_or_b64 s[2:3], s[44:45], s[2:3]
	v_add_f32_e32 v65, 1.0, v65
	v_log_f32_e32 v65, v65
	s_nop 0
	v_sub_f32_e64 v15, -v65, v15
	v_cndmask_b32_e64 v207, 0, v15, s[2:3]
	v_med3_f32 v15, v70, s94, v198
	v_cndmask_b32_e64 v206, v199, -v65, s[2:3]
	v_exp_f32_e64 v65, -v15
	v_cmp_lt_i32_e64 s[2:3], 10, v183
	s_or_b64 s[2:3], s[44:45], s[2:3]
	v_add_f32_e32 v0, v0, v207
	v_add_f32_e32 v65, 1.0, v65
	v_log_f32_e32 v65, v65
	s_nop 0
	v_sub_f32_e64 v15, -v65, v15
	v_cndmask_b32_e64 v209, 0, v15, s[2:3]
	v_med3_f32 v15, v71, s94, v198
	v_cndmask_b32_e64 v208, v199, -v65, s[2:3]
	v_exp_f32_e64 v65, -v15
	v_cmp_lt_i32_e64 s[2:3], 11, v183
	s_or_b64 s[2:3], s[44:45], s[2:3]
	v_add_f32_e32 v65, 1.0, v65
	v_log_f32_e32 v65, v65
	s_nop 0
	v_sub_f32_e64 v15, -v65, v15
	v_cndmask_b32_e64 v211, 0, v15, s[2:3]
	v_med3_f32 v15, v72, s94, v198
	v_cndmask_b32_e64 v210, v199, -v65, s[2:3]
	v_exp_f32_e64 v65, -v15
	v_cmp_lt_i32_e64 s[2:3], 16, v183
	s_or_b64 s[2:3], s[44:45], s[2:3]
	v_add_f32_e32 v65, 1.0, v65
	v_log_f32_e32 v65, v65
	s_nop 0
	v_sub_f32_e64 v15, -v65, v15
	v_cndmask_b32_e64 v67, 0, v15, s[2:3]
	v_med3_f32 v15, v73, s94, v198
	v_cndmask_b32_e64 v212, v199, -v65, s[2:3]
	v_exp_f32_e64 v65, -v15
	v_cmp_lt_i32_e64 s[2:3], 17, v183
	s_or_b64 s[2:3], s[44:45], s[2:3]
	v_add_f32_e32 v65, 1.0, v65
	v_log_f32_e32 v65, v65
	s_nop 0
	v_sub_f32_e64 v15, -v65, v15
	v_cndmask_b32_e64 v214, 0, v15, s[2:3]
	v_med3_f32 v15, v74, s94, v198
	v_cndmask_b32_e64 v213, v199, -v65, s[2:3]
	v_exp_f32_e64 v65, -v15
	v_cmp_lt_i32_e64 s[2:3], 18, v183
	s_or_b64 s[2:3], s[44:45], s[2:3]
	v_add_f32_e32 v65, 1.0, v65
	v_log_f32_e32 v65, v65
	s_nop 0
	v_sub_f32_e64 v15, -v65, v15
	v_cndmask_b32_e64 v216, 0, v15, s[2:3]
	v_med3_f32 v15, v75, s94, v198
	v_cndmask_b32_e64 v215, v199, -v65, s[2:3]
	v_exp_f32_e64 v65, -v15
	v_cmp_lt_i32_e64 s[2:3], 19, v183
	s_or_b64 s[2:3], s[44:45], s[2:3]
	v_add_f32_e32 v65, 1.0, v65
	v_log_f32_e32 v65, v65
	s_nop 0
	v_sub_f32_e64 v15, -v65, v15
	v_cndmask_b32_e64 v218, 0, v15, s[2:3]
	v_med3_f32 v15, v76, s94, v198
	v_cndmask_b32_e64 v217, v199, -v65, s[2:3]
	v_exp_f32_e64 v65, -v15
	v_cmp_lt_i32_e64 s[2:3], 24, v183
	s_or_b64 s[2:3], s[44:45], s[2:3]
	v_add_f32_e32 v65, 1.0, v65
	v_log_f32_e32 v65, v65
	s_nop 0
	v_sub_f32_e64 v15, -v65, v15
	v_cndmask_b32_e64 v70, 0, v15, s[2:3]
	v_med3_f32 v15, v77, s94, v198
	v_cndmask_b32_e64 v76, v199, -v65, s[2:3]
	v_exp_f32_e64 v65, -v15
	v_cmp_lt_i32_e64 s[2:3], 25, v183
	s_or_b64 s[2:3], s[44:45], s[2:3]
	v_add_f32_e32 v65, 1.0, v65
	v_log_f32_e32 v65, v65
	s_nop 0
	v_sub_f32_e64 v15, -v65, v15
	v_cndmask_b32_e64 v68, 0, v15, s[2:3]
; DI float ex2(float x) { return __builtin_amdgcn_exp2f(x); }
; DI float lg2(float x) { return __builtin_amdgcn_logf(x); }
; DI void stick_pv(f32x16& s0, f32x16& s1, float& R, f32x16& o0, f32x16& o1, const u16* Vs, int dl,
;                  bool need_mask, int r, int h) {
;     ...
;     for (int i = 0; i < 16; ++i) {
;       const int ci = 32 * t + (i & 3) + 8 * (i >> 2);
;       float a = t ? s1[i] : s0[i];
;       float z = __builtin_amdgcn_fmed3f(a, -126.f, 126.f);
;       float e = ex2(-z);
;       float lb = -lg2(1.f + e);
;       float xi = lb - z;
;       if (need_mask) {
;         bool valid = (ci < dl);
;         xi = valid ? xi : 0.f;
;         lb = valid ? lb : -INFINITY;
;       }
;       x[16 * t + i] = xi;
;       if (t) s1[i] = lb; else s0[i] = lb;
;     }
;   float gs[8], pg[8], pr[8];
; #pragma unroll
;   for (int g = 0; g < 8; ++g) {
;     gs[g] = (x[4 * g] + x[4 * g + 1]) + (x[4 * g + 2] + x[4 * g + 3]);
;     pg[g] = shx(gs[g], r + 32 * h);
;     pr[g] = gs[g] + pg[g];
	v_med3_f32 v15, v78, s94, v198
	v_cndmask_b32_e64 v77, v199, -v65, s[2:3]
	v_exp_f32_e64 v65, -v15
	v_cmp_lt_i32_e64 s[2:3], 26, v183
	s_or_b64 s[2:3], s[44:45], s[2:3]
	v_add_f32_e32 v65, 1.0, v65
	v_log_f32_e32 v65, v65
	s_nop 0
	v_sub_f32_e64 v15, -v65, v15
	v_cndmask_b32_e64 v72, 0, v15, s[2:3]
	v_med3_f32 v15, v79, s94, v198
	v_cndmask_b32_e64 v78, v199, -v65, s[2:3]
	v_exp_f32_e64 v65, -v15
	v_cmp_lt_i32_e64 s[2:3], 27, v183
	s_or_b64 s[2:3], s[44:45], s[2:3]
	v_add_f32_e32 v65, 1.0, v65
	v_log_f32_e32 v65, v65
	s_nop 0
	v_sub_f32_e64 v15, -v65, v15
	v_cndmask_b32_e64 v74, 0, v15, s[2:3]
	v_med3_f32 v15, v48, s94, v198
	v_exp_f32_e64 v48, -v15
	v_cndmask_b32_e64 v79, v199, -v65, s[2:3]
	v_cmp_lt_i32_e64 s[2:3], 32, v183
	s_or_b64 s[2:3], s[44:45], s[2:3]
	v_add_f32_e32 v48, 1.0, v48
	v_log_f32_e32 v48, v48
	s_nop 0
	v_sub_f32_e64 v15, -v48, v15
	v_cndmask_b32_e64 v69, 0, v15, s[2:3]
	v_med3_f32 v15, v49, s94, v198
	v_cndmask_b32_e64 v167, v199, -v48, s[2:3]
	v_exp_f32_e64 v48, -v15
	v_cmp_lt_i32_e64 s[2:3], 33, v183
	s_or_b64 s[2:3], s[44:45], s[2:3]
	v_add_f32_e32 v48, 1.0, v48
	v_log_f32_e32 v48, v48
	s_nop 0
	v_sub_f32_e64 v15, -v48, v15
	v_cndmask_b32_e64 v220, 0, v15, s[2:3]
	v_med3_f32 v15, v50, s94, v198
	v_cndmask_b32_e64 v219, v199, -v48, s[2:3]
	v_exp_f32_e64 v48, -v15
	v_cmp_lt_i32_e64 s[2:3], 34, v183
	s_or_b64 s[2:3], s[44:45], s[2:3]
	v_add_f32_e32 v48, 1.0, v48
	v_log_f32_e32 v48, v48
	s_nop 0
	v_sub_f32_e64 v15, -v48, v15
	v_cndmask_b32_e64 v222, 0, v15, s[2:3]
	v_med3_f32 v15, v51, s94, v198
	v_cndmask_b32_e64 v221, v199, -v48, s[2:3]
	v_exp_f32_e64 v48, -v15
	v_cmp_lt_i32_e64 s[2:3], 35, v183
	s_or_b64 s[2:3], s[44:45], s[2:3]
	v_add_f32_e32 v48, 1.0, v48
	v_log_f32_e32 v48, v48
	s_nop 0
	v_sub_f32_e64 v15, -v48, v15
	v_cndmask_b32_e64 v224, 0, v15, s[2:3]
	v_med3_f32 v15, v52, s94, v198
	v_cndmask_b32_e64 v223, v199, -v48, s[2:3]
	v_exp_f32_e64 v48, -v15
	v_cmp_lt_i32_e64 s[2:3], 40, v183
	s_or_b64 s[2:3], s[44:45], s[2:3]
	v_add_f32_e32 v48, 1.0, v48
	v_log_f32_e32 v48, v48
	s_nop 0
	v_sub_f32_e64 v15, -v48, v15
	v_cndmask_b32_e64 v49, 0, v15, s[2:3]
	v_med3_f32 v15, v53, s94, v198
	v_cndmask_b32_e64 v52, v199, -v48, s[2:3]
	v_exp_f32_e64 v48, -v15
	v_cmp_lt_i32_e64 s[2:3], 41, v183
	s_or_b64 s[2:3], s[44:45], s[2:3]
	v_add_f32_e32 v48, 1.0, v48
	v_log_f32_e32 v48, v48
	s_nop 0
	v_sub_f32_e64 v15, -v48, v15
	v_cndmask_b32_e64 v53, 0, v15, s[2:3]
	v_med3_f32 v15, v54, s94, v198
	v_cndmask_b32_e64 v75, v199, -v48, s[2:3]
	v_exp_f32_e64 v48, -v15
	v_cmp_lt_i32_e64 s[2:3], 42, v183
	s_or_b64 s[2:3], s[44:45], s[2:3]
	v_add_f32_e32 v48, 1.0, v48
	v_log_f32_e32 v48, v48
	s_nop 0
	v_sub_f32_e64 v15, -v48, v15
	v_cndmask_b32_e64 v225, 0, v15, s[2:3]
	v_med3_f32 v15, v55, s94, v198
	v_cndmask_b32_e64 v226, v199, -v48, s[2:3]
	v_exp_f32_e64 v48, -v15
	v_cmp_lt_i32_e64 s[2:3], 43, v183
	s_or_b64 s[2:3], s[44:45], s[2:3]
	v_add_f32_e32 v48, 1.0, v48
	v_log_f32_e32 v48, v48
	s_nop 0
	v_sub_f32_e64 v15, -v48, v15
	v_cndmask_b32_e64 v227, 0, v15, s[2:3]
	v_med3_f32 v15, v56, s94, v198
	v_cndmask_b32_e64 v228, v199, -v48, s[2:3]
	v_exp_f32_e64 v48, -v15
	v_cmp_lt_i32_e64 s[2:3], 48, v183
	s_or_b64 s[2:3], s[44:45], s[2:3]
	v_add_f32_e32 v48, 1.0, v48
	v_log_f32_e32 v50, v48
	s_nop 0
	v_sub_f32_e64 v15, -v50, v15
	v_cndmask_b32_e64 v48, 0, v15, s[2:3]
	v_med3_f32 v15, v57, s94, v198
	v_cndmask_b32_e64 v56, v199, -v50, s[2:3]
	v_exp_f32_e64 v50, -v15
	v_cmp_lt_i32_e64 s[2:3], 49, v183
	s_or_b64 s[2:3], s[44:45], s[2:3]
	v_add_f32_e32 v50, 1.0, v50
	v_log_f32_e32 v51, v50
	s_nop 0
	v_sub_f32_e64 v15, -v51, v15
	v_cndmask_b32_e64 v50, 0, v15, s[2:3]
	v_med3_f32 v15, v58, s94, v198
	v_cndmask_b32_e64 v57, v199, -v51, s[2:3]
	v_exp_f32_e64 v51, -v15
	v_cmp_lt_i32_e64 s[2:3], 50, v183
	s_or_b64 s[2:3], s[44:45], s[2:3]
	v_add_f32_e32 v51, 1.0, v51
	v_log_f32_e32 v51, v51
	s_nop 0
	v_sub_f32_e64 v15, -v51, v15
	v_cndmask_b32_e64 v58, 0, v15, s[2:3]
	v_med3_f32 v15, v59, s94, v198
	v_cndmask_b32_e64 v229, v199, -v51, s[2:3]
	v_exp_f32_e64 v51, -v15
	v_cmp_lt_i32_e64 s[2:3], 51, v183
	s_or_b64 s[2:3], s[44:45], s[2:3]
	v_add_f32_e32 v51, 1.0, v51
	v_log_f32_e32 v51, v51
	s_nop 0
	v_sub_f32_e64 v15, -v51, v15
	v_cndmask_b32_e64 v59, 0, v15, s[2:3]
	v_med3_f32 v15, v60, s94, v198
	v_cndmask_b32_e64 v230, v199, -v51, s[2:3]
	v_exp_f32_e64 v51, -v15
	v_cmp_lt_i32_e64 s[2:3], 56, v183
	s_or_b64 s[2:3], s[44:45], s[2:3]
	v_add_f32_e32 v54, v58, v59
	v_add_f32_e32 v51, 1.0, v51
	v_log_f32_e32 v51, v51
	s_nop 0
	v_sub_f32_e64 v15, -v51, v15
	v_cndmask_b32_e64 v55, 0, v15, s[2:3]
	v_med3_f32 v15, v61, s94, v198
	v_cndmask_b32_e64 v60, v199, -v51, s[2:3]
	v_exp_f32_e64 v51, -v15
	v_cmp_lt_i32_e64 s[2:3], 57, v183
	s_or_b64 s[2:3], s[44:45], s[2:3]
	v_add_f32_e32 v51, 1.0, v51
	v_log_f32_e32 v51, v51
	s_nop 0
	v_sub_f32_e64 v15, -v51, v15
	v_cndmask_b32_e64 v61, 0, v15, s[2:3]
	v_med3_f32 v15, v62, s94, v198
	v_cndmask_b32_e64 v231, v199, -v51, s[2:3]
	v_exp_f32_e64 v51, -v15
	v_cmp_lt_i32_e64 s[2:3], 58, v183
	s_or_b64 s[2:3], s[44:45], s[2:3]
	v_add_f32_e32 v51, 1.0, v51
	v_log_f32_e32 v51, v51
	s_nop 0
	v_sub_f32_e64 v15, -v51, v15
	v_cndmask_b32_e64 v62, 0, v15, s[2:3]
	v_med3_f32 v15, v63, s94, v198
	v_cndmask_b32_e64 v232, v199, -v51, s[2:3]
	v_exp_f32_e64 v51, -v15
	v_cmp_lt_i32_e64 s[2:3], 59, v183
	s_or_b64 s[2:3], s[44:45], s[2:3]
	v_add_f32_e32 v51, 1.0, v51
	v_log_f32_e32 v51, v51
	s_nop 0
	v_sub_f32_e64 v15, -v51, v15
	v_cndmask_b32_e64 v63, 0, v15, s[2:3]
	v_add_f32_e32 v15, v209, v211
	v_cndmask_b32_e64 v233, v199, -v51, s[2:3]
	v_add_f32_e32 v15, v0, v15
	v_add_f32_e32 v0, v67, v214
	v_add_f32_e32 v51, v216, v218
	v_add_f32_e32 v0, v0, v51
	ds_bpermute_b32 v234, v180, v0
	v_add_f32_e32 v51, v222, v224
	ds_bpermute_b32 v65, v180, v15
	s_mov_b32 s2, 0xc3200000
	s_waitcnt lgkmcnt(1)
; DI float ex2(float x) { return __builtin_amdgcn_exp2f(x); }
; DI f32x16 mfma(bf16x8 a, bf16x8 b, f32x16 c) { return __builtin_amdgcn_mfma_f32_32x32x16_bf16(a, b, c, 0, 0, 0); }
; DI void stick_pv(f32x16& s0, f32x16& s1, float& R, f32x16& o0, f32x16& o1, const u16* Vs, int dl,
;                  bool need_mask, int r, int h) {
;     ...
;   for (int g = 0; g < 8; ++g) {
;     gs[g] = (x[4 * g] + x[4 * g + 1]) + (x[4 * g + 2] + x[4 * g + 3]);
;     pg[g] = shx(gs[g], r + 32 * h);
;     pr[g] = gs[g] + pg[g];
;   }
;   float suf = 0.f;
; #pragma unroll
;   for (int g = 7; g >= 0; --g) {
;     float base = R + suf + (h == 0 ? pg[g] : 0.f);
;     float t3 = base, t2 = t3 + x[4 * g + 3], t1 = t2 + x[4 * g + 2], t0 = t1 + x[4 * g + 1];
;     const int i = 4 * (g & 3);
;     if (g >= 4) {
;       s1[i] = ex2(s1[i] + t0); s1[i + 1] = ex2(s1[i + 1] + t1); s1[i + 2] = ex2(s1[i + 2] + t2); s1[i + 3] = ex2(s1[i + 3] + t3);
;     } else {
;       s0[i] = ex2(s0[i] + t0); s0[i + 1] = ex2(s0[i + 1] + t1); s0[i + 2] = ex2(s0[i + 2] + t2); s0[i + 3] = ex2(s0[i + 3] + t3);
;     }
;     suf += pr[g];
;   }
;   R += suf;
; #pragma unroll
;   for (int kk = 0; kk < 4; ++kk) {
;     const int s = kk & 1;
;     unsigned u0, u1, u2, u3;
;     if (kk < 2) {
;       u0 = pk2(s0[8 * s], s0[8 * s + 1]); u1 = pk2(s0[8 * s + 2], s0[8 * s + 3]);
;       u2 = pk2(s0[8 * s + 4], s0[8 * s + 5]); u3 = pk2(s0[8 * s + 6], s0[8 * s + 7]);
;     } else {
;       u0 = pk2(s1[8 * s], s1[8 * s + 1]); u1 = pk2(s1[8 * s + 2], s1[8 * s + 3]);
;       u2 = pk2(s1[8 * s + 4], s1[8 * s + 5]); u3 = pk2(s1[8 * s + 6], s1[8 * s + 7]);
;     }
;     u32x4 uu = {u0, u1, u2, u3};
;     bf16x8 pf = __builtin_bit_cast(bf16x8, uu);
;     bf16x8 v0 = ldsv(Vs + r * LSTR + kk * 16 + 8 * h);
;     bf16x8 v1 = ldsv(Vs + (32 + r) * LSTR + kk * 16 + 8 * h);
;     o0 = mfma(v0, pf, o0);
;     o1 = mfma(v1, pf, o1);
;   }
; template <int MODE>
; DI void attn_item(const Params& p, int layer, int b, int head, int qblk, u16* sm, volatile LAS int* s_done_, int wv) {
;     ...
;               wdone = __all(R < -160.f) ? 1 : 0;
	v_add_f32_e32 v67, v0, v234
	v_add_f32_e32 v0, v69, v220
	v_add_f32_e32 v71, v0, v51
	v_add_f32_e32 v0, v49, v53
	v_add_f32_e32 v49, v225, v227
	v_add_f32_e32 v0, v0, v49
	v_add_f32_e32 v49, v55, v61
	v_add_f32_e32 v51, v62, v63
	v_add_f32_e32 v48, v48, v50
	v_add_f32_e32 v49, v49, v51
	ds_bpermute_b32 v55, v180, v49
	ds_bpermute_b32 v235, v180, v0
	ds_bpermute_b32 v69, v180, v71
	s_waitcnt lgkmcnt(3)
	v_add_f32_e32 v14, v14, v64
	v_add_f32_e32 v15, v15, v65
	s_waitcnt lgkmcnt(2)
	v_add_f32_e32 v48, v48, v54
	v_add_f32_e32 v49, v49, v55
	s_waitcnt lgkmcnt(1)
	v_add_f32_e32 v73, v0, v235
	ds_bpermute_b32 v0, v180, v48
	v_cndmask_b32_e32 v51, 0, v55, vcc
	v_add_f32_e32 v51, v236, v51
	v_add_f32_e32 v54, v63, v51
	v_add_f32_e32 v51, v233, v51
	s_waitcnt lgkmcnt(0)
	v_add_f32_e32 v48, v48, v0
	v_add_f32_e32 v49, v49, v1
	v_exp_f32_e32 v233, v51
	v_add_f32_e32 v51, v184, v49
	v_cndmask_b32_e32 v0, 0, v0, vcc
	v_add_f32_e32 v0, v0, v51
	v_add_f32_e32 v55, v62, v54
	v_add_f32_e32 v54, v232, v54
	v_add_f32_e32 v51, v59, v0
	v_exp_f32_e32 v232, v54
	v_add_f32_e32 v54, v58, v51
	v_add_f32_e32 v50, v50, v54
	v_add_f32_e32 v50, v56, v50
	v_exp_f32_e32 v237, v50
	v_add_f32_e32 v50, v57, v54
	v_exp_f32_e32 v238, v50
	v_add_f32_e32 v50, v229, v51
	v_pk_add_f32 v[48:49], v[48:49], v[48:49] op_sel:[0,1] op_sel_hi:[1,0]
	v_exp_f32_e32 v229, v50
	v_add_f32_e32 v49, v184, v48
	v_cndmask_b32_e32 v50, 0, v235, vcc
	v_add_f32_e32 v49, v50, v49
	v_add_f32_e32 v50, v227, v49
	v_add_f32_e32 v51, v225, v50
	v_add_f32_e32 v53, v53, v51
	v_add_f32_e32 v51, v75, v51
	v_add_f32_e32 v50, v226, v50
	v_add_f32_e32 v49, v228, v49
	v_mov_b32_e32 v75, v48
	v_exp_f32_e32 v227, v51
	v_exp_f32_e32 v226, v50
	v_exp_f32_e32 v228, v49
	v_add_f32_e32 v50, v70, v68
	v_add_f32_e32 v51, v71, v69
	v_add_f32_e32 v48, v72, v74
	v_add_f32_e32 v49, v73, v75
	v_add_f32_e32 v52, v52, v53
	v_add_f32_e32 v50, v50, v48
	v_add_f32_e32 v51, v51, v49
	ds_bpermute_b32 v48, v180, v50
	v_exp_f32_e32 v225, v52
	v_cndmask_b32_e32 v52, 0, v69, vcc
	v_add_f32_e32 v49, v184, v49
	v_add_f32_e32 v49, v52, v49
	v_add_f32_e32 v52, v224, v49
	v_add_f32_e32 v49, v223, v49
	s_waitcnt lgkmcnt(0)
	v_add_f32_e32 v50, v50, v48
	v_exp_f32_e32 v73, v49
	v_add_f32_e32 v49, v184, v51
	v_cndmask_b32_e32 v48, 0, v48, vcc
	v_add_f32_e32 v53, v222, v52
	v_add_f32_e32 v48, v48, v49
	v_add_f32_e32 v54, v220, v53
	v_add_f32_e32 v52, v221, v52
	v_add_f32_e32 v49, v74, v48
	v_add_f32_e32 v54, v167, v54
	v_exp_f32_e32 v71, v52
	v_add_f32_e32 v52, v72, v49
	v_add_f32_e32 v49, v78, v49
	v_add_f32_e32 v48, v79, v48
	v_add_f32_e32 v167, v50, v51
	v_exp_f32_e32 v74, v49
	v_exp_f32_e32 v75, v48
	v_add_f32_e32 v48, v184, v167
	v_cndmask_b32_e32 v49, 0, v234, vcc
	v_add_f32_e32 v48, v49, v48
	v_add_f32_e32 v49, v218, v48
	v_add_f32_e32 v50, v216, v49
	v_add_f32_e32 v49, v215, v49
	v_add_f32_e32 v48, v217, v48
	v_exp_f32_e32 v78, v49
	v_exp_f32_e32 v79, v48
	v_add_f32_e32 v48, v66, v166
	v_add_f32_e32 v49, v67, v167
	v_add_f32_e32 v53, v219, v53
	v_add_f32_e32 v51, v214, v50
	v_add_f32_e32 v50, v213, v50
	v_add_f32_e32 v14, v14, v48
	v_add_f32_e32 v15, v15, v49
	v_exp_f32_e32 v70, v53
	v_add_f32_e32 v53, v68, v52
	v_add_f32_e32 v52, v77, v52
	v_exp_f32_e32 v77, v50
	v_cndmask_b32_e32 v50, 0, v65, vcc
	ds_bpermute_b32 v48, v180, v14
	v_add_f32_e32 v49, v184, v49
	v_add_f32_e32 v49, v50, v49
	v_add_f32_e32 v51, v212, v51
	v_add_f32_e32 v50, v211, v49
	v_add_f32_e32 v53, v76, v53
	v_exp_f32_e32 v76, v51
	v_add_f32_e32 v51, v209, v50
	v_exp_f32_e32 v72, v52
	v_add_f32_e32 v52, v207, v51
	v_add_f32_e32 v51, v206, v51
	v_exp_f32_e32 v68, v53
	s_waitcnt lgkmcnt(0)
	v_add_f32_e32 v14, v14, v48
	v_exp_f32_e32 v53, v51
	v_add_f32_e32 v51, v184, v15
	v_cndmask_b32_e32 v48, 0, v48, vcc
	v_add_f32_e32 v48, v48, v51
	v_add_f32_e32 v51, v166, v48
	v_add_f32_e32 v61, v61, v55
	v_add_f32_e32 v55, v231, v55
	v_exp_f32_e32 v69, v54
	v_add_f32_e32 v54, v66, v51
	v_exp_f32_e32 v231, v55
	v_add_f32_e32 v55, v64, v54
	v_add_f32_e32 v52, v205, v52
	v_add_f32_e32 v50, v208, v50
	v_add_f32_e32 v49, v210, v49
	v_add_f32_e32 v55, v165, v55
	v_add_f32_e32 v54, v185, v54
	v_add_f32_e32 v51, v186, v51
	v_add_f32_e32 v48, v204, v48
	v_exp_f32_e32 v52, v52
	v_exp_f32_e32 v50, v50
	v_exp_f32_e32 v49, v49
	v_exp_f32_e32 v55, v55
	v_exp_f32_e32 v54, v54
	v_exp_f32_e32 v56, v51
	v_exp_f32_e32 v48, v48
	v_add_f32_e32 v60, v60, v61
	v_exp_f32_e32 v236, v60
	v_cvt_pk_bf16_f32 v51, v50, v49
	v_cvt_pk_bf16_f32 v50, v52, v53
	v_cvt_pk_bf16_f32 v49, v56, v48
	v_cvt_pk_bf16_f32 v48, v55, v54
	ds_read_b128 v[52:55], v155 offset:13824
	ds_read_b128 v[56:59], v155 offset:9216
	ds_read_b128 v[60:63], v155 offset:9248
	s_waitcnt lgkmcnt(2)
	v_mfma_f32_32x32x16_bf16 v[16:31], v[52:55], v[48:51], v[16:31]
	ds_read_b128 v[52:55], v155 offset:13856
	v_add_f32_e32 v0, v230, v0
	v_exp_f32_e32 v0, v0
	v_add_f32_e32 v14, v14, v15
	v_add_f32_e32 v184, v184, v14
	v_cmp_gt_f32_e64 s[2:3], s2, v184
	s_cmp_eq_u64 s[2:3], exec
	s_waitcnt lgkmcnt(2)
	v_mfma_f32_32x32x16_bf16 v[32:47], v[56:59], v[48:51], v[32:47]
	v_cvt_pk_bf16_f32 v51, v74, v75
	v_cvt_pk_bf16_f32 v50, v68, v72
	v_cvt_pk_bf16_f32 v49, v78, v79
	v_cvt_pk_bf16_f32 v48, v76, v77
	s_cselect_b64 s[2:3], -1, 0
	v_cndmask_b32_e64 v64, 0, 1, s[2:3]
	s_waitcnt lgkmcnt(1)
	v_mfma_f32_32x32x16_bf16 v[32:47], v[60:63], v[48:51], v[32:47]
	s_waitcnt lgkmcnt(0)
	v_mfma_f32_32x32x16_bf16 v[16:31], v[52:55], v[48:51], v[16:31]
	ds_read_b128 v[52:55], v155 offset:9280
	ds_read_b128 v[56:59], v155 offset:13888
	v_cvt_pk_bf16_f32 v51, v226, v228
	v_cvt_pk_bf16_f32 v50, v225, v227
	v_cvt_pk_bf16_f32 v49, v71, v73
	v_cvt_pk_bf16_f32 v48, v69, v70
	s_waitcnt lgkmcnt(1)
	s_nop 0
	v_mfma_f32_32x32x16_bf16 v[32:47], v[52:55], v[48:51], v[32:47]
	s_waitcnt lgkmcnt(0)
	v_mfma_f32_32x32x16_bf16 v[16:31], v[56:59], v[48:51], v[16:31]
	ds_read_b128 v[52:55], v155 offset:9312
	ds_read_b128 v[56:59], v155 offset:13920
	v_cvt_pk_bf16_f32 v51, v232, v233
	v_cvt_pk_bf16_f32 v50, v236, v231
	v_cvt_pk_bf16_f32 v49, v229, v0
	v_cvt_pk_bf16_f32 v48, v237, v238
	s_waitcnt lgkmcnt(1)
	s_nop 0
	v_mfma_f32_32x32x16_bf16 v[32:47], v[52:55], v[48:51], v[32:47]
	s_waitcnt lgkmcnt(0)
	v_mfma_f32_32x32x16_bf16 v[16:31], v[56:59], v[48:51], v[16:31]
	s_or_b64 exec, exec, s[18:19]
	s_and_saveexec_b64 s[44:45], s[42:43]
	s_cbranch_execnz .LBB0_235

; DI float ex2(float x) { return __builtin_amdgcn_exp2f(x); }
; DI float lg2(float x) { return __builtin_amdgcn_logf(x); }
; DI f32x16 mfma(bf16x8 a, bf16x8 b, f32x16 c) { return __builtin_amdgcn_mfma_f32_32x32x16_bf16(a, b, c, 0, 0, 0); }
; DI void stick_pv(f32x16& s0, f32x16& s1, float& R, f32x16& o0, f32x16& o1, const u16* Vs, int dl,
;                  bool need_mask, int r, int h) {
;     ...
;     for (int i = 0; i < 16; ++i) {
;       const int ci = 32 * t + (i & 3) + 8 * (i >> 2);
;       float a = t ? s1[i] : s0[i];
;       float z = __builtin_amdgcn_fmed3f(a, -126.f, 126.f);
;       float e = ex2(-z);
;       float lb = -lg2(1.f + e);
;       float xi = lb - z;
;       if (need_mask) {
;         bool valid = (ci < dl);
;         xi = valid ? xi : 0.f;
;         lb = valid ? lb : -INFINITY;
;       }
;       x[16 * t + i] = xi;
;       if (t) s1[i] = lb; else s0[i] = lb;
;     }
; template <int MODE>
; DI void attn_item(const Params& p, int layer, int b, int head, int qblk, u16* sm, volatile LAS int* s_done_, int wv) {
;     ...
;       for (int c = 0; c < 4; ++c) {
;         const int it = base + c;
;         if (it >= it0 && it < ntiles) {
;           const u16* Kc = Ks + c * (2 * 64 * LSTR);
;           const u16* Vc = Vs + c * (2 * 64 * LSTR);
;           const int k0 = tile_k0(it);
;           bool skip, need_mask;
;           if (MODE == 1) { skip = (k0 > q0w + 31) || (k0 + 63 < q0w - 127); need_mask = true; }
;           else { skip = (k0 >= q0w + 31) || wdone; need_mask = (k0 + 63 >= q0w); }
;           if (!skip) {
;             const int dl = qpos - k0 - 4 * h;
;             if (MODE == 1) {
;               softmax_pv<1, 0, 4>(qf, Kc, Vc, m0, ls0, o[0], o[1], sl2, dl, need_mask, false, r, h, LSTR, lo);
;             } else {
;               f32x16 sa[2];
; #pragma unroll
;               for (int e = 0; e < 16; ++e) { sa[0][e] = 0.f; sa[1][e] = 0.f; }
; #pragma unroll
;               for (int t = 0; t < 2; ++t)
; #pragma unroll
;                 for (int ks = 0; ks < 4; ++ks) {
;                   bf16x8 kf = ldsv(Kc + (32 * t + r) * LSTR + ks * 16 + 8 * h);
;                   sa[t] = mfma(kf, qf[ks], sa[t]);
;                 }
;               stick_pv(sa[0], sa[1], R, o[0], o[1], Vc, dl, need_mask, r, h);
.LBB0_228:
	s_xor_b32 s2, s87, 0x3fffffd
	v_add_lshl_u32 v0, s2, v173, 6
	v_cmp_lt_i32_e64 s[2:3], v0, v176
	v_cmp_eq_u32_e64 s[40:41], 0, v64
	s_and_b64 s[2:3], s[2:3], s[40:41]
	s_and_saveexec_b64 s[18:19], s[2:3]
	s_cbranch_execz .LBB0_230
	v_or_b32_e32 v14, 63, v0
	v_cmp_lt_i32_e64 s[40:41], v14, v148
	v_add_u32_e32 v14, v152, v181
	s_waitcnt vmcnt(3)
	ds_read_b128 v[48:51], v14 offset:36864
	s_waitcnt vmcnt(2)
	ds_read_b128 v[52:55], v14 offset:36896
	ds_read_b128 v[204:207], v14 offset:41504
	v_or_b32_e32 v0, v0, v177
	s_waitcnt lgkmcnt(2)
	v_mfma_f32_32x32x16_bf16 v[64:79], v[48:51], v[88:91], 0
	ds_read_b128 v[48:51], v14 offset:36928
	v_sub_u32_e32 v0, v149, v0
	v_cmp_lt_i32_e64 s[2:3], 0, v0
	s_or_b64 s[2:3], s[40:41], s[2:3]
	v_add_f32_e32 v236, 0, v184
	s_waitcnt lgkmcnt(2)
	v_mfma_f32_32x32x16_bf16 v[64:79], v[52:55], v[80:83], v[64:79]
	s_waitcnt lgkmcnt(0)
	v_mfma_f32_32x32x16_bf16 v[64:79], v[48:51], v[84:87], v[64:79]
	ds_read_b128 v[48:51], v14 offset:36960
	s_waitcnt lgkmcnt(0)
	v_mfma_f32_32x32x16_bf16 v[64:79], v[48:51], v[92:95], v[64:79]
	ds_read_b128 v[48:51], v14 offset:41472
	s_waitcnt vmcnt(0) lgkmcnt(0)
	v_mfma_f32_32x32x16_bf16 v[48:63], v[48:51], v[88:91], 0
	v_mfma_f32_32x32x16_bf16 v[48:63], v[204:207], v[80:83], v[48:63]
	ds_read_b128 v[204:207], v14 offset:41536
	s_waitcnt lgkmcnt(0)
	v_mfma_f32_32x32x16_bf16 v[48:63], v[204:207], v[84:87], v[48:63]
	ds_read_b128 v[204:207], v14 offset:41568
	s_nop 3
	v_med3_f32 v14, v64, s94, v198
	v_exp_f32_e64 v15, -v14
	s_nop 0
	v_add_f32_e32 v15, 1.0, v15
	v_log_f32_e32 v15, v15
	s_waitcnt lgkmcnt(0)
	v_mfma_f32_32x32x16_bf16 v[48:63], v[204:207], v[92:95], v[48:63]
	v_sub_f32_e64 v14, -v15, v14
	v_cndmask_b32_e64 v165, v199, -v15, s[2:3]
	v_med3_f32 v15, v65, s94, v198
	v_exp_f32_e64 v64, -v15
	v_cndmask_b32_e64 v14, 0, v14, s[2:3]
	v_cmp_lt_i32_e64 s[2:3], 1, v0
	s_or_b64 s[2:3], s[40:41], s[2:3]
	v_add_f32_e32 v64, 1.0, v64
	v_log_f32_e32 v65, v64
	s_nop 2
	v_med3_f32 v48, v48, s94, v198
	v_sub_f32_e64 v15, -v65, v15
	v_cndmask_b32_e64 v64, 0, v15, s[2:3]
	v_med3_f32 v15, v66, s94, v198
	v_cndmask_b32_e64 v185, v199, -v65, s[2:3]
	v_exp_f32_e64 v65, -v15
	v_cmp_lt_i32_e64 s[2:3], 2, v0
	s_or_b64 s[2:3], s[40:41], s[2:3]
	v_add_f32_e32 v65, 1.0, v65
	v_log_f32_e32 v65, v65
	s_nop 0
	v_sub_f32_e64 v15, -v65, v15
	v_cndmask_b32_e64 v66, 0, v15, s[2:3]
	v_med3_f32 v15, v67, s94, v198
	v_cndmask_b32_e64 v186, v199, -v65, s[2:3]
	v_exp_f32_e64 v65, -v15
	v_cmp_lt_i32_e64 s[2:3], 3, v0
	s_or_b64 s[2:3], s[40:41], s[2:3]
	v_add_f32_e32 v65, 1.0, v65
	v_log_f32_e32 v65, v65
	s_nop 0
	v_sub_f32_e64 v15, -v65, v15
	v_cndmask_b32_e64 v166, 0, v15, s[2:3]
	v_med3_f32 v15, v68, s94, v198
	v_cndmask_b32_e64 v204, v199, -v65, s[2:3]
	v_exp_f32_e64 v65, -v15
	v_cmp_lt_i32_e64 s[2:3], 8, v0
	s_or_b64 s[2:3], s[40:41], s[2:3]
	v_add_f32_e32 v65, 1.0, v65
	v_log_f32_e32 v65, v65
	s_nop 0
	v_sub_f32_e64 v15, -v65, v15
	v_cndmask_b32_e64 v205, v199, -v65, s[2:3]
	v_med3_f32 v65, v69, s94, v198
	v_exp_f32_e64 v67, -v65
	v_cndmask_b32_e64 v15, 0, v15, s[2:3]
	v_cmp_lt_i32_e64 s[2:3], 9, v0
	s_or_b64 s[2:3], s[40:41], s[2:3]
	v_add_f32_e32 v67, 1.0, v67
	v_log_f32_e32 v67, v67
	s_nop 0
	v_sub_f32_e64 v65, -v67, v65
	v_cndmask_b32_e64 v207, 0, v65, s[2:3]
	v_med3_f32 v65, v70, s94, v198
	v_cndmask_b32_e64 v206, v199, -v67, s[2:3]
	v_exp_f32_e64 v67, -v65
	v_cmp_lt_i32_e64 s[2:3], 10, v0
	s_or_b64 s[2:3], s[40:41], s[2:3]
	v_add_f32_e32 v67, 1.0, v67
	v_log_f32_e32 v67, v67
	s_nop 0
	v_sub_f32_e64 v65, -v67, v65
	v_cndmask_b32_e64 v209, 0, v65, s[2:3]
	v_med3_f32 v65, v71, s94, v198
	v_cndmask_b32_e64 v208, v199, -v67, s[2:3]
	v_exp_f32_e64 v67, -v65
	v_cmp_lt_i32_e64 s[2:3], 11, v0
	s_or_b64 s[2:3], s[40:41], s[2:3]
	v_add_f32_e32 v67, 1.0, v67
	v_log_f32_e32 v67, v67
	s_nop 0
	v_sub_f32_e64 v65, -v67, v65
	v_cndmask_b32_e64 v211, 0, v65, s[2:3]
	v_med3_f32 v65, v72, s94, v198
	v_cndmask_b32_e64 v210, v199, -v67, s[2:3]
	v_exp_f32_e64 v67, -v65
	v_cmp_lt_i32_e64 s[2:3], 16, v0
	s_or_b64 s[2:3], s[40:41], s[2:3]
	v_add_f32_e32 v67, 1.0, v67
	v_log_f32_e32 v68, v67
	s_nop 0
	v_sub_f32_e64 v65, -v68, v65
	v_cndmask_b32_e64 v67, 0, v65, s[2:3]
	v_med3_f32 v65, v73, s94, v198
	v_cndmask_b32_e64 v212, v199, -v68, s[2:3]
	v_exp_f32_e64 v68, -v65
	v_cmp_lt_i32_e64 s[2:3], 17, v0
	s_or_b64 s[2:3], s[40:41], s[2:3]
	v_add_f32_e32 v68, 1.0, v68
	v_log_f32_e32 v68, v68
	s_nop 0
	v_sub_f32_e64 v65, -v68, v65
	v_cndmask_b32_e64 v214, 0, v65, s[2:3]
	v_med3_f32 v65, v74, s94, v198
	v_cndmask_b32_e64 v213, v199, -v68, s[2:3]
	v_exp_f32_e64 v68, -v65
	v_cmp_lt_i32_e64 s[2:3], 18, v0
	s_or_b64 s[2:3], s[40:41], s[2:3]
	v_add_f32_e32 v68, 1.0, v68
	v_log_f32_e32 v68, v68
	s_nop 0
	v_sub_f32_e64 v65, -v68, v65
	v_cndmask_b32_e64 v216, 0, v65, s[2:3]
	v_med3_f32 v65, v75, s94, v198
	v_cndmask_b32_e64 v215, v199, -v68, s[2:3]
	v_exp_f32_e64 v68, -v65
	v_cmp_lt_i32_e64 s[2:3], 19, v0
	s_or_b64 s[2:3], s[40:41], s[2:3]
	v_add_f32_e32 v68, 1.0, v68
	v_log_f32_e32 v68, v68
	s_nop 0
	v_sub_f32_e64 v65, -v68, v65
	v_cndmask_b32_e64 v218, 0, v65, s[2:3]
	v_med3_f32 v65, v76, s94, v198
	v_cndmask_b32_e64 v217, v199, -v68, s[2:3]
	v_exp_f32_e64 v68, -v65
	v_cmp_lt_i32_e64 s[2:3], 24, v0
	s_or_b64 s[2:3], s[40:41], s[2:3]
	v_add_f32_e32 v68, 1.0, v68
	v_log_f32_e32 v68, v68
	s_nop 0
	v_sub_f32_e64 v65, -v68, v65
	v_cndmask_b32_e64 v70, 0, v65, s[2:3]
	v_med3_f32 v65, v77, s94, v198
	v_cndmask_b32_e64 v76, v199, -v68, s[2:3]
	v_exp_f32_e64 v68, -v65
	v_cmp_lt_i32_e64 s[2:3], 25, v0
	s_or_b64 s[2:3], s[40:41], s[2:3]
	v_add_f32_e32 v68, 1.0, v68
	v_log_f32_e32 v69, v68
	s_nop 0
	v_sub_f32_e64 v65, -v69, v65
; DI float ex2(float x) { return __builtin_amdgcn_exp2f(x); }
; DI float lg2(float x) { return __builtin_amdgcn_logf(x); }
; DI void stick_pv(f32x16& s0, f32x16& s1, float& R, f32x16& o0, f32x16& o1, const u16* Vs, int dl,
;                  bool need_mask, int r, int h) {
;     ...
;     for (int i = 0; i < 16; ++i) {
;       const int ci = 32 * t + (i & 3) + 8 * (i >> 2);
;       float a = t ? s1[i] : s0[i];
;       float z = __builtin_amdgcn_fmed3f(a, -126.f, 126.f);
;       float e = ex2(-z);
;       float lb = -lg2(1.f + e);
;       float xi = lb - z;
;       if (need_mask) {
;         bool valid = (ci < dl);
;         xi = valid ? xi : 0.f;
;         lb = valid ? lb : -INFINITY;
;       }
;       x[16 * t + i] = xi;
;       if (t) s1[i] = lb; else s0[i] = lb;
;     }
;   float gs[8], pg[8], pr[8];
; #pragma unroll
;   for (int g = 0; g < 8; ++g) {
;     gs[g] = (x[4 * g] + x[4 * g + 1]) + (x[4 * g + 2] + x[4 * g + 3]);
;     pg[g] = shx(gs[g], r + 32 * h);
;     pr[g] = gs[g] + pg[g];
	v_cndmask_b32_e64 v68, 0, v65, s[2:3]
	v_med3_f32 v65, v78, s94, v198
	v_cndmask_b32_e64 v77, v199, -v69, s[2:3]
	v_exp_f32_e64 v69, -v65
	v_cmp_lt_i32_e64 s[2:3], 26, v0
	s_or_b64 s[2:3], s[40:41], s[2:3]
	v_add_f32_e32 v69, 1.0, v69
	v_log_f32_e32 v69, v69
	s_nop 0
	v_sub_f32_e64 v65, -v69, v65
	v_cndmask_b32_e64 v72, 0, v65, s[2:3]
	v_med3_f32 v65, v79, s94, v198
	v_cndmask_b32_e64 v78, v199, -v69, s[2:3]
	v_exp_f32_e64 v69, -v65
	v_cmp_lt_i32_e64 s[2:3], 27, v0
	s_or_b64 s[2:3], s[40:41], s[2:3]
	v_add_f32_e32 v69, 1.0, v69
	v_log_f32_e32 v69, v69
	s_nop 0
	v_sub_f32_e64 v65, -v69, v65
	v_cndmask_b32_e64 v74, 0, v65, s[2:3]
	v_exp_f32_e64 v65, -v48
	v_cndmask_b32_e64 v79, v199, -v69, s[2:3]
	v_cmp_lt_i32_e64 s[2:3], 32, v0
	s_or_b64 s[2:3], s[40:41], s[2:3]
	v_add_f32_e32 v65, 1.0, v65
	v_log_f32_e32 v65, v65
	s_nop 0
	v_sub_f32_e64 v48, -v65, v48
	v_cndmask_b32_e64 v69, 0, v48, s[2:3]
	v_med3_f32 v48, v49, s94, v198
	v_exp_f32_e64 v49, -v48
	v_cndmask_b32_e64 v167, v199, -v65, s[2:3]
	v_cmp_lt_i32_e64 s[2:3], 33, v0
	s_or_b64 s[2:3], s[40:41], s[2:3]
	v_add_f32_e32 v49, 1.0, v49
	v_log_f32_e32 v49, v49
	s_nop 0
	v_sub_f32_e64 v48, -v49, v48
	v_cndmask_b32_e64 v220, 0, v48, s[2:3]
	v_med3_f32 v48, v50, s94, v198
	v_cndmask_b32_e64 v219, v199, -v49, s[2:3]
	v_exp_f32_e64 v49, -v48
	v_cmp_lt_i32_e64 s[2:3], 34, v0
	s_or_b64 s[2:3], s[40:41], s[2:3]
	v_add_f32_e32 v49, 1.0, v49
	v_log_f32_e32 v49, v49
	s_nop 0
	v_sub_f32_e64 v48, -v49, v48
	v_cndmask_b32_e64 v222, 0, v48, s[2:3]
	v_med3_f32 v48, v51, s94, v198
	v_cndmask_b32_e64 v221, v199, -v49, s[2:3]
	v_exp_f32_e64 v49, -v48
	v_cmp_lt_i32_e64 s[2:3], 35, v0
	s_or_b64 s[2:3], s[40:41], s[2:3]
	v_add_f32_e32 v49, 1.0, v49
	v_log_f32_e32 v49, v49
	s_nop 0
	v_sub_f32_e64 v48, -v49, v48
	v_cndmask_b32_e64 v224, 0, v48, s[2:3]
	v_med3_f32 v48, v52, s94, v198
	v_cndmask_b32_e64 v223, v199, -v49, s[2:3]
	v_exp_f32_e64 v49, -v48
	v_cmp_lt_i32_e64 s[2:3], 40, v0
	s_or_b64 s[2:3], s[40:41], s[2:3]
	v_add_f32_e32 v49, 1.0, v49
	v_log_f32_e32 v49, v49
	s_nop 0
	v_sub_f32_e64 v48, -v49, v48
	v_cndmask_b32_e64 v51, 0, v48, s[2:3]
	v_med3_f32 v48, v53, s94, v198
	v_cndmask_b32_e64 v52, v199, -v49, s[2:3]
	v_exp_f32_e64 v49, -v48
	v_cmp_lt_i32_e64 s[2:3], 41, v0
	s_or_b64 s[2:3], s[40:41], s[2:3]
	v_add_f32_e32 v49, 1.0, v49
	v_log_f32_e32 v49, v49
	s_nop 0
	v_sub_f32_e64 v48, -v49, v48
	v_cndmask_b32_e64 v53, 0, v48, s[2:3]
	v_med3_f32 v48, v54, s94, v198
	v_cndmask_b32_e64 v75, v199, -v49, s[2:3]
	v_exp_f32_e64 v49, -v48
	v_cmp_lt_i32_e64 s[2:3], 42, v0
	s_or_b64 s[2:3], s[40:41], s[2:3]
	v_add_f32_e32 v49, 1.0, v49
	v_log_f32_e32 v49, v49
	s_nop 0
	v_sub_f32_e64 v48, -v49, v48
	v_cndmask_b32_e64 v225, 0, v48, s[2:3]
	v_med3_f32 v48, v55, s94, v198
	v_cndmask_b32_e64 v226, v199, -v49, s[2:3]
	v_exp_f32_e64 v49, -v48
	v_cmp_lt_i32_e64 s[2:3], 43, v0
	s_or_b64 s[2:3], s[40:41], s[2:3]
	v_add_f32_e32 v49, 1.0, v49
	v_log_f32_e32 v49, v49
	s_nop 0
	v_sub_f32_e64 v48, -v49, v48
	v_cndmask_b32_e64 v227, 0, v48, s[2:3]
	v_med3_f32 v48, v56, s94, v198
	v_cndmask_b32_e64 v228, v199, -v49, s[2:3]
	v_exp_f32_e64 v49, -v48
	v_cmp_lt_i32_e64 s[2:3], 48, v0
	s_or_b64 s[2:3], s[40:41], s[2:3]
	v_add_f32_e32 v49, 1.0, v49
	v_log_f32_e32 v49, v49
	s_nop 0
	v_sub_f32_e64 v48, -v49, v48
	v_cndmask_b32_e64 v56, v199, -v49, s[2:3]
	v_med3_f32 v49, v57, s94, v198
	v_exp_f32_e64 v50, -v49
	v_cndmask_b32_e64 v48, 0, v48, s[2:3]
	v_cmp_lt_i32_e64 s[2:3], 49, v0
	s_or_b64 s[2:3], s[40:41], s[2:3]
	v_add_f32_e32 v50, 1.0, v50
	v_log_f32_e32 v54, v50
	s_nop 0
	v_sub_f32_e64 v49, -v54, v49
	v_cndmask_b32_e64 v50, 0, v49, s[2:3]
	v_med3_f32 v49, v58, s94, v198
	v_cndmask_b32_e64 v57, v199, -v54, s[2:3]
	v_exp_f32_e64 v54, -v49
	v_cmp_lt_i32_e64 s[2:3], 50, v0
	s_or_b64 s[2:3], s[40:41], s[2:3]
	v_add_f32_e32 v54, 1.0, v54
	v_log_f32_e32 v54, v54
	s_nop 0
	v_sub_f32_e64 v49, -v54, v49
	v_cndmask_b32_e64 v58, 0, v49, s[2:3]
	v_med3_f32 v49, v59, s94, v198
	v_cndmask_b32_e64 v229, v199, -v54, s[2:3]
	v_exp_f32_e64 v54, -v49
	v_cmp_lt_i32_e64 s[2:3], 51, v0
	s_or_b64 s[2:3], s[40:41], s[2:3]
	v_add_f32_e32 v54, 1.0, v54
	v_log_f32_e32 v54, v54
	s_nop 0
	v_sub_f32_e64 v49, -v54, v49
	v_cndmask_b32_e64 v59, 0, v49, s[2:3]
	v_med3_f32 v49, v60, s94, v198
	v_cndmask_b32_e64 v230, v199, -v54, s[2:3]
	v_exp_f32_e64 v54, -v49
	v_cmp_lt_i32_e64 s[2:3], 56, v0
	s_or_b64 s[2:3], s[40:41], s[2:3]
	v_add_f32_e32 v54, 1.0, v54
	v_log_f32_e32 v54, v54
	s_nop 0
	v_sub_f32_e64 v49, -v54, v49
	v_cndmask_b32_e64 v60, v199, -v54, s[2:3]
	v_med3_f32 v54, v61, s94, v198
	v_exp_f32_e64 v55, -v54
	v_cndmask_b32_e64 v49, 0, v49, s[2:3]
	v_cmp_lt_i32_e64 s[2:3], 57, v0
	s_or_b64 s[2:3], s[40:41], s[2:3]
	v_add_f32_e32 v55, 1.0, v55
	v_log_f32_e32 v55, v55
	s_nop 0
	v_sub_f32_e64 v54, -v55, v54
	v_cndmask_b32_e64 v61, 0, v54, s[2:3]
	v_med3_f32 v54, v62, s94, v198
	v_cndmask_b32_e64 v231, v199, -v55, s[2:3]
	v_exp_f32_e64 v55, -v54
	v_cmp_lt_i32_e64 s[2:3], 58, v0
	s_or_b64 s[2:3], s[40:41], s[2:3]
	v_add_f32_e32 v49, v49, v61
	v_add_f32_e32 v55, 1.0, v55
	v_log_f32_e32 v55, v55
	s_nop 0
	v_sub_f32_e64 v54, -v55, v54
	v_cndmask_b32_e64 v62, 0, v54, s[2:3]
	v_med3_f32 v54, v63, s94, v198
	v_cndmask_b32_e64 v232, v199, -v55, s[2:3]
	v_exp_f32_e64 v55, -v54
	v_cmp_lt_i32_e64 s[2:3], 59, v0
	s_or_b64 s[2:3], s[40:41], s[2:3]
	v_add_f32_e32 v0, v15, v207
	v_add_f32_e32 v55, 1.0, v55
	v_log_f32_e32 v55, v55
	v_add_f32_e32 v15, v209, v211
	v_add_f32_e32 v15, v0, v15
	v_add_f32_e32 v0, v67, v214
	v_sub_f32_e64 v54, -v55, v54
	v_cndmask_b32_e64 v63, 0, v54, s[2:3]
	v_add_f32_e32 v54, v216, v218
	v_add_f32_e32 v0, v0, v54
	ds_bpermute_b32 v234, v180, v0
	v_add_f32_e32 v54, v222, v224
	v_cndmask_b32_e64 v233, v199, -v55, s[2:3]
	ds_bpermute_b32 v65, v180, v15
	s_mov_b32 s2, 0xc3200000
	s_waitcnt lgkmcnt(1)
; DI float ex2(float x) { return __builtin_amdgcn_exp2f(x); }
; DI f32x16 mfma(bf16x8 a, bf16x8 b, f32x16 c) { return __builtin_amdgcn_mfma_f32_32x32x16_bf16(a, b, c, 0, 0, 0); }
; DI void stick_pv(f32x16& s0, f32x16& s1, float& R, f32x16& o0, f32x16& o1, const u16* Vs, int dl,
;                  bool need_mask, int r, int h) {
;     ...
;   for (int g = 0; g < 8; ++g) {
;     gs[g] = (x[4 * g] + x[4 * g + 1]) + (x[4 * g + 2] + x[4 * g + 3]);
;     pg[g] = shx(gs[g], r + 32 * h);
;     pr[g] = gs[g] + pg[g];
;   }
;   float suf = 0.f;
; #pragma unroll
;   for (int g = 7; g >= 0; --g) {
;     float base = R + suf + (h == 0 ? pg[g] : 0.f);
;     float t3 = base, t2 = t3 + x[4 * g + 3], t1 = t2 + x[4 * g + 2], t0 = t1 + x[4 * g + 1];
;     const int i = 4 * (g & 3);
;     if (g >= 4) {
;       s1[i] = ex2(s1[i] + t0); s1[i + 1] = ex2(s1[i + 1] + t1); s1[i + 2] = ex2(s1[i + 2] + t2); s1[i + 3] = ex2(s1[i + 3] + t3);
;     } else {
;       s0[i] = ex2(s0[i] + t0); s0[i + 1] = ex2(s0[i + 1] + t1); s0[i + 2] = ex2(s0[i + 2] + t2); s0[i + 3] = ex2(s0[i + 3] + t3);
;     }
;     suf += pr[g];
;   }
;   R += suf;
; #pragma unroll
;   for (int kk = 0; kk < 4; ++kk) {
;     const int s = kk & 1;
;     unsigned u0, u1, u2, u3;
;     if (kk < 2) {
;       u0 = pk2(s0[8 * s], s0[8 * s + 1]); u1 = pk2(s0[8 * s + 2], s0[8 * s + 3]);
;       u2 = pk2(s0[8 * s + 4], s0[8 * s + 5]); u3 = pk2(s0[8 * s + 6], s0[8 * s + 7]);
;     } else {
;       u0 = pk2(s1[8 * s], s1[8 * s + 1]); u1 = pk2(s1[8 * s + 2], s1[8 * s + 3]);
;       u2 = pk2(s1[8 * s + 4], s1[8 * s + 5]); u3 = pk2(s1[8 * s + 6], s1[8 * s + 7]);
;     }
;     u32x4 uu = {u0, u1, u2, u3};
;     bf16x8 pf = __builtin_bit_cast(bf16x8, uu);
;     bf16x8 v0 = ldsv(Vs + r * LSTR + kk * 16 + 8 * h);
;     bf16x8 v1 = ldsv(Vs + (32 + r) * LSTR + kk * 16 + 8 * h);
;     o0 = mfma(v0, pf, o0);
;     o1 = mfma(v1, pf, o1);
;   }
; template <int MODE>
; DI void attn_item(const Params& p, int layer, int b, int head, int qblk, u16* sm, volatile LAS int* s_done_, int wv) {
;     ...
;               wdone = __all(R < -160.f) ? 1 : 0;
	v_add_f32_e32 v67, v0, v234
	v_add_f32_e32 v0, v69, v220
	v_add_f32_e32 v71, v0, v54
	v_add_f32_e32 v0, v51, v53
	v_add_f32_e32 v51, v225, v227
	v_add_f32_e32 v0, v0, v51
	v_add_f32_e32 v51, v62, v63
	v_add_f32_e32 v48, v48, v50
	v_add_f32_e32 v49, v49, v51
	ds_bpermute_b32 v55, v180, v49
	ds_bpermute_b32 v235, v180, v0
	v_add_f32_e32 v54, v58, v59
	ds_bpermute_b32 v69, v180, v71
	s_waitcnt lgkmcnt(3)
	v_add_f32_e32 v14, v14, v64
	v_add_f32_e32 v15, v15, v65
	s_waitcnt lgkmcnt(2)
	v_add_f32_e32 v48, v48, v54
	v_add_f32_e32 v49, v49, v55
	s_waitcnt lgkmcnt(1)
	v_add_f32_e32 v73, v0, v235
	ds_bpermute_b32 v0, v180, v48
	v_cndmask_b32_e32 v51, 0, v55, vcc
	v_add_f32_e32 v51, v236, v51
	v_add_f32_e32 v54, v63, v51
	v_add_f32_e32 v51, v233, v51
	s_waitcnt lgkmcnt(0)
	v_add_f32_e32 v48, v48, v0
	v_add_f32_e32 v49, v49, v1
	v_exp_f32_e32 v233, v51
	v_add_f32_e32 v51, v184, v49
	v_cndmask_b32_e32 v0, 0, v0, vcc
	v_add_f32_e32 v0, v0, v51
	v_add_f32_e32 v55, v62, v54
	v_add_f32_e32 v54, v232, v54
	v_add_f32_e32 v51, v59, v0
	v_exp_f32_e32 v232, v54
	v_add_f32_e32 v54, v58, v51
	v_add_f32_e32 v50, v50, v54
	v_add_f32_e32 v50, v56, v50
	v_exp_f32_e32 v237, v50
	v_add_f32_e32 v50, v57, v54
	v_exp_f32_e32 v238, v50
	v_add_f32_e32 v50, v229, v51
	v_pk_add_f32 v[48:49], v[48:49], v[48:49] op_sel:[0,1] op_sel_hi:[1,0]
	v_exp_f32_e32 v229, v50
	v_add_f32_e32 v49, v184, v48
	v_cndmask_b32_e32 v50, 0, v235, vcc
	v_add_f32_e32 v49, v50, v49
	v_add_f32_e32 v50, v227, v49
	v_add_f32_e32 v51, v225, v50
	v_add_f32_e32 v53, v53, v51
	v_add_f32_e32 v51, v75, v51
	v_add_f32_e32 v50, v226, v50
	v_add_f32_e32 v49, v228, v49
	v_mov_b32_e32 v75, v48
	v_exp_f32_e32 v227, v51
	v_exp_f32_e32 v226, v50
	v_exp_f32_e32 v228, v49
	v_add_f32_e32 v50, v70, v68
	v_add_f32_e32 v51, v71, v69
	v_add_f32_e32 v48, v72, v74
	v_add_f32_e32 v49, v73, v75
	v_add_f32_e32 v52, v52, v53
	v_add_f32_e32 v50, v50, v48
	v_add_f32_e32 v51, v51, v49
	ds_bpermute_b32 v48, v180, v50
	v_exp_f32_e32 v225, v52
	v_cndmask_b32_e32 v52, 0, v69, vcc
	v_add_f32_e32 v49, v184, v49
	v_add_f32_e32 v49, v52, v49
	v_add_f32_e32 v52, v224, v49
	v_add_f32_e32 v49, v223, v49
	s_waitcnt lgkmcnt(0)
	v_add_f32_e32 v50, v50, v48
	v_exp_f32_e32 v73, v49
	v_add_f32_e32 v49, v184, v51
	v_cndmask_b32_e32 v48, 0, v48, vcc
	v_add_f32_e32 v53, v222, v52
	v_add_f32_e32 v48, v48, v49
	v_add_f32_e32 v54, v220, v53
	v_add_f32_e32 v52, v221, v52
	v_add_f32_e32 v49, v74, v48
	v_add_f32_e32 v54, v167, v54
	v_exp_f32_e32 v71, v52
	v_add_f32_e32 v52, v72, v49
	v_add_f32_e32 v49, v78, v49
	v_add_f32_e32 v48, v79, v48
	v_add_f32_e32 v167, v50, v51
	v_exp_f32_e32 v74, v49
	v_exp_f32_e32 v75, v48
	v_add_f32_e32 v48, v184, v167
	v_cndmask_b32_e32 v49, 0, v234, vcc
	v_add_f32_e32 v48, v49, v48
	v_add_f32_e32 v49, v218, v48
	v_add_f32_e32 v50, v216, v49
	v_add_f32_e32 v49, v215, v49
	v_add_f32_e32 v48, v217, v48
	v_exp_f32_e32 v78, v49
	v_exp_f32_e32 v79, v48
	v_add_f32_e32 v48, v66, v166
	v_add_f32_e32 v49, v67, v167
	v_add_f32_e32 v53, v219, v53
	v_add_f32_e32 v51, v214, v50
	v_add_f32_e32 v50, v213, v50
	v_add_f32_e32 v14, v14, v48
	v_add_f32_e32 v15, v15, v49
	v_exp_f32_e32 v70, v53
	v_add_f32_e32 v53, v68, v52
	v_add_f32_e32 v52, v77, v52
	v_exp_f32_e32 v77, v50
	v_cndmask_b32_e32 v50, 0, v65, vcc
	ds_bpermute_b32 v48, v180, v14
	v_add_f32_e32 v49, v184, v49
	v_add_f32_e32 v49, v50, v49
	v_add_f32_e32 v51, v212, v51
	v_add_f32_e32 v50, v211, v49
	v_add_f32_e32 v53, v76, v53
	v_exp_f32_e32 v76, v51
	v_add_f32_e32 v51, v209, v50
	v_exp_f32_e32 v72, v52
	v_add_f32_e32 v52, v207, v51
	v_add_f32_e32 v51, v206, v51
	v_exp_f32_e32 v68, v53
	s_waitcnt lgkmcnt(0)
	v_add_f32_e32 v14, v14, v48
	v_exp_f32_e32 v53, v51
	v_add_f32_e32 v51, v184, v15
	v_cndmask_b32_e32 v48, 0, v48, vcc
	v_add_f32_e32 v48, v48, v51
	v_add_f32_e32 v51, v166, v48
	v_add_f32_e32 v61, v61, v55
	v_add_f32_e32 v55, v231, v55
	v_exp_f32_e32 v69, v54
	v_add_f32_e32 v54, v66, v51
	v_exp_f32_e32 v231, v55
	v_add_f32_e32 v55, v64, v54
	v_add_f32_e32 v52, v205, v52
	v_add_f32_e32 v50, v208, v50
	v_add_f32_e32 v49, v210, v49
	v_add_f32_e32 v55, v165, v55
	v_add_f32_e32 v54, v185, v54
	v_add_f32_e32 v51, v186, v51
	v_add_f32_e32 v48, v204, v48
	v_exp_f32_e32 v52, v52
	v_exp_f32_e32 v50, v50
	v_exp_f32_e32 v49, v49
	v_exp_f32_e32 v55, v55
	v_exp_f32_e32 v54, v54
	v_exp_f32_e32 v56, v51
	v_exp_f32_e32 v48, v48
	v_add_f32_e32 v60, v60, v61
	v_exp_f32_e32 v236, v60
	v_cvt_pk_bf16_f32 v51, v50, v49
	v_cvt_pk_bf16_f32 v50, v52, v53
	v_cvt_pk_bf16_f32 v49, v56, v48
	v_cvt_pk_bf16_f32 v48, v55, v54
	ds_read_b128 v[52:55], v155 offset:50688
	ds_read_b128 v[56:59], v155 offset:46080
	ds_read_b128 v[60:63], v155 offset:46112
	s_waitcnt lgkmcnt(2)
	v_mfma_f32_32x32x16_bf16 v[16:31], v[52:55], v[48:51], v[16:31]
	ds_read_b128 v[52:55], v155 offset:50720
	v_add_f32_e32 v0, v230, v0
	v_exp_f32_e32 v0, v0
	v_add_f32_e32 v14, v14, v15
	v_add_f32_e32 v184, v184, v14
	v_cmp_gt_f32_e64 s[2:3], s2, v184
	s_cmp_eq_u64 s[2:3], exec
	s_waitcnt lgkmcnt(2)
	v_mfma_f32_32x32x16_bf16 v[32:47], v[56:59], v[48:51], v[32:47]
	v_cvt_pk_bf16_f32 v51, v74, v75
	v_cvt_pk_bf16_f32 v50, v68, v72
	v_cvt_pk_bf16_f32 v49, v78, v79
	v_cvt_pk_bf16_f32 v48, v76, v77
	s_cselect_b64 s[2:3], -1, 0
	v_cndmask_b32_e64 v64, 0, 1, s[2:3]
	s_waitcnt lgkmcnt(1)
	v_mfma_f32_32x32x16_bf16 v[32:47], v[60:63], v[48:51], v[32:47]
	s_waitcnt lgkmcnt(0)
	v_mfma_f32_32x32x16_bf16 v[16:31], v[52:55], v[48:51], v[16:31]
	ds_read_b128 v[52:55], v155 offset:46144
	ds_read_b128 v[56:59], v155 offset:50752
	v_cvt_pk_bf16_f32 v51, v226, v228
	v_cvt_pk_bf16_f32 v50, v225, v227
	v_cvt_pk_bf16_f32 v49, v71, v73
	v_cvt_pk_bf16_f32 v48, v69, v70
	s_waitcnt lgkmcnt(1)
	s_nop 0
	v_mfma_f32_32x32x16_bf16 v[32:47], v[52:55], v[48:51], v[32:47]
	s_waitcnt lgkmcnt(0)
	v_mfma_f32_32x32x16_bf16 v[16:31], v[56:59], v[48:51], v[16:31]
	ds_read_b128 v[52:55], v155 offset:46176
	ds_read_b128 v[56:59], v155 offset:50784
	v_cvt_pk_bf16_f32 v51, v232, v233
	v_cvt_pk_bf16_f32 v50, v236, v231
	v_cvt_pk_bf16_f32 v49, v229, v0
	v_cvt_pk_bf16_f32 v48, v237, v238
	s_waitcnt lgkmcnt(1)
	s_nop 0
	v_mfma_f32_32x32x16_bf16 v[32:47], v[52:55], v[48:51], v[32:47]
	s_waitcnt lgkmcnt(0)
	v_mfma_f32_32x32x16_bf16 v[16:31], v[56:59], v[48:51], v[16:31]

; DI float ex2(float x) { return __builtin_amdgcn_exp2f(x); }
; DI float lg2(float x) { return __builtin_amdgcn_logf(x); }
; DI f32x16 mfma(bf16x8 a, bf16x8 b, f32x16 c) { return __builtin_amdgcn_mfma_f32_32x32x16_bf16(a, b, c, 0, 0, 0); }
; DI void stick_pv(f32x16& s0, f32x16& s1, float& R, f32x16& o0, f32x16& o1, const u16* Vs, int dl,
;                  bool need_mask, int r, int h) {
;     ...
;     for (int i = 0; i < 16; ++i) {
;       const int ci = 32 * t + (i & 3) + 8 * (i >> 2);
;       float a = t ? s1[i] : s0[i];
;       float z = __builtin_amdgcn_fmed3f(a, -126.f, 126.f);
;       float e = ex2(-z);
;       float lb = -lg2(1.f + e);
;       float xi = lb - z;
;       if (need_mask) {
;         bool valid = (ci < dl);
;         xi = valid ? xi : 0.f;
;         lb = valid ? lb : -INFINITY;
;       }
;       x[16 * t + i] = xi;
;       if (t) s1[i] = lb; else s0[i] = lb;
;     }
; template <int MODE>
; DI void attn_item(const Params& p, int layer, int b, int head, int qblk, u16* sm, volatile LAS int* s_done_, int wv) {
;     ...
;       for (int c = 0; c < 4; ++c) {
;         const int it = base + c;
;         if (it >= it0 && it < ntiles) {
;           const u16* Kc = Ks + c * (2 * 64 * LSTR);
;           const u16* Vc = Vs + c * (2 * 64 * LSTR);
;           const int k0 = tile_k0(it);
;           bool skip, need_mask;
;           if (MODE == 1) { skip = (k0 > q0w + 31) || (k0 + 63 < q0w - 127); need_mask = true; }
;           else { skip = (k0 >= q0w + 31) || wdone; need_mask = (k0 + 63 >= q0w); }
;           if (!skip) {
;             const int dl = qpos - k0 - 4 * h;
;             if (MODE == 1) {
;               softmax_pv<1, 0, 4>(qf, Kc, Vc, m0, ls0, o[0], o[1], sl2, dl, need_mask, false, r, h, LSTR, lo);
;             } else {
;               f32x16 sa[2];
; #pragma unroll
;               for (int e = 0; e < 16; ++e) { sa[0][e] = 0.f; sa[1][e] = 0.f; }
; #pragma unroll
;               for (int t = 0; t < 2; ++t)
; #pragma unroll
;                 for (int ks = 0; ks < 4; ++ks) {
;                   bf16x8 kf = ldsv(Kc + (32 * t + r) * LSTR + ks * 16 + 8 * h);
;                   sa[t] = mfma(kf, qf[ks], sa[t]);
;                 }
;               stick_pv(sa[0], sa[1], R, o[0], o[1], Vc, dl, need_mask, r, h);
.LBB0_235:
	s_xor_b32 s2, s87, 0x3fffffe
	v_add_lshl_u32 v0, s2, v173, 6
	v_cmp_lt_i32_e64 s[2:3], v0, v176
	v_cmp_eq_u32_e64 s[42:43], 0, v64
	s_and_b64 s[2:3], s[2:3], s[42:43]
	s_and_saveexec_b64 s[18:19], s[2:3]
	s_cbranch_execz .LBB0_237
	v_or_b32_e32 v14, 63, v0
	v_cmp_lt_i32_e64 s[42:43], v14, v148
	v_add_u32_e32 v14, v152, v181
	s_waitcnt vmcnt(3)
	ds_read_b128 v[48:51], v14 offset:18432
	s_waitcnt vmcnt(2)
	ds_read_b128 v[52:55], v14 offset:18464
	ds_read_b128 v[204:207], v14 offset:23072
	v_or_b32_e32 v0, v0, v177
	s_waitcnt lgkmcnt(2)
	v_mfma_f32_32x32x16_bf16 v[64:79], v[48:51], v[88:91], 0
	ds_read_b128 v[48:51], v14 offset:18496
	v_sub_u32_e32 v0, v149, v0
	v_cmp_lt_i32_e64 s[2:3], 0, v0
	s_or_b64 s[2:3], s[42:43], s[2:3]
	v_add_f32_e32 v236, 0, v184
	s_waitcnt lgkmcnt(2)
	v_mfma_f32_32x32x16_bf16 v[64:79], v[52:55], v[80:83], v[64:79]
	s_waitcnt lgkmcnt(0)
	v_mfma_f32_32x32x16_bf16 v[64:79], v[48:51], v[84:87], v[64:79]
	ds_read_b128 v[48:51], v14 offset:18528
	s_waitcnt lgkmcnt(0)
	v_mfma_f32_32x32x16_bf16 v[64:79], v[48:51], v[92:95], v[64:79]
	ds_read_b128 v[48:51], v14 offset:23040
	s_waitcnt vmcnt(0) lgkmcnt(0)
	v_mfma_f32_32x32x16_bf16 v[48:63], v[48:51], v[88:91], 0
	v_mfma_f32_32x32x16_bf16 v[48:63], v[204:207], v[80:83], v[48:63]
	ds_read_b128 v[204:207], v14 offset:23104
	s_waitcnt lgkmcnt(0)
	v_mfma_f32_32x32x16_bf16 v[48:63], v[204:207], v[84:87], v[48:63]
	ds_read_b128 v[204:207], v14 offset:23136
	s_nop 3
	v_med3_f32 v14, v64, s94, v198
	v_exp_f32_e64 v15, -v14
	s_nop 0
	v_add_f32_e32 v15, 1.0, v15
	v_log_f32_e32 v15, v15
	s_waitcnt lgkmcnt(0)
	v_mfma_f32_32x32x16_bf16 v[48:63], v[204:207], v[92:95], v[48:63]
	v_sub_f32_e64 v14, -v15, v14
	v_cndmask_b32_e64 v165, v199, -v15, s[2:3]
	v_med3_f32 v15, v65, s94, v198
	v_exp_f32_e64 v64, -v15
	v_cndmask_b32_e64 v14, 0, v14, s[2:3]
	v_cmp_lt_i32_e64 s[2:3], 1, v0
	s_or_b64 s[2:3], s[42:43], s[2:3]
	v_add_f32_e32 v64, 1.0, v64
	v_log_f32_e32 v65, v64
	s_nop 2
	v_med3_f32 v48, v48, s94, v198
	v_sub_f32_e64 v15, -v65, v15
	v_cndmask_b32_e64 v64, 0, v15, s[2:3]
	v_med3_f32 v15, v66, s94, v198
	v_cndmask_b32_e64 v185, v199, -v65, s[2:3]
	v_exp_f32_e64 v65, -v15
	v_cmp_lt_i32_e64 s[2:3], 2, v0
	s_or_b64 s[2:3], s[42:43], s[2:3]
	v_add_f32_e32 v65, 1.0, v65
	v_log_f32_e32 v65, v65
	s_nop 0
	v_sub_f32_e64 v15, -v65, v15
	v_cndmask_b32_e64 v66, 0, v15, s[2:3]
	v_med3_f32 v15, v67, s94, v198
	v_cndmask_b32_e64 v186, v199, -v65, s[2:3]
	v_exp_f32_e64 v65, -v15
	v_cmp_lt_i32_e64 s[2:3], 3, v0
	s_or_b64 s[2:3], s[42:43], s[2:3]
	v_add_f32_e32 v65, 1.0, v65
	v_log_f32_e32 v65, v65
	s_nop 0
	v_sub_f32_e64 v15, -v65, v15
	v_cndmask_b32_e64 v166, 0, v15, s[2:3]
	v_med3_f32 v15, v68, s94, v198
	v_cndmask_b32_e64 v204, v199, -v65, s[2:3]
	v_exp_f32_e64 v65, -v15
	v_cmp_lt_i32_e64 s[2:3], 8, v0
	s_or_b64 s[2:3], s[42:43], s[2:3]
	v_add_f32_e32 v65, 1.0, v65
	v_log_f32_e32 v65, v65
	s_nop 0
	v_sub_f32_e64 v15, -v65, v15
	v_cndmask_b32_e64 v205, v199, -v65, s[2:3]
	v_med3_f32 v65, v69, s94, v198
	v_exp_f32_e64 v67, -v65
	v_cndmask_b32_e64 v15, 0, v15, s[2:3]
	v_cmp_lt_i32_e64 s[2:3], 9, v0
	s_or_b64 s[2:3], s[42:43], s[2:3]
	v_add_f32_e32 v67, 1.0, v67
	v_log_f32_e32 v67, v67
	s_nop 0
	v_sub_f32_e64 v65, -v67, v65
	v_cndmask_b32_e64 v207, 0, v65, s[2:3]
	v_med3_f32 v65, v70, s94, v198
	v_cndmask_b32_e64 v206, v199, -v67, s[2:3]
	v_exp_f32_e64 v67, -v65
	v_cmp_lt_i32_e64 s[2:3], 10, v0
	s_or_b64 s[2:3], s[42:43], s[2:3]
	v_add_f32_e32 v67, 1.0, v67
	v_log_f32_e32 v67, v67
	s_nop 0
	v_sub_f32_e64 v65, -v67, v65
	v_cndmask_b32_e64 v209, 0, v65, s[2:3]
	v_med3_f32 v65, v71, s94, v198
	v_cndmask_b32_e64 v208, v199, -v67, s[2:3]
	v_exp_f32_e64 v67, -v65
	v_cmp_lt_i32_e64 s[2:3], 11, v0
	s_or_b64 s[2:3], s[42:43], s[2:3]
	v_add_f32_e32 v67, 1.0, v67
	v_log_f32_e32 v67, v67
	s_nop 0
	v_sub_f32_e64 v65, -v67, v65
	v_cndmask_b32_e64 v211, 0, v65, s[2:3]
	v_med3_f32 v65, v72, s94, v198
	v_cndmask_b32_e64 v210, v199, -v67, s[2:3]
	v_exp_f32_e64 v67, -v65
	v_cmp_lt_i32_e64 s[2:3], 16, v0
	s_or_b64 s[2:3], s[42:43], s[2:3]
	v_add_f32_e32 v67, 1.0, v67
	v_log_f32_e32 v68, v67
	s_nop 0
	v_sub_f32_e64 v65, -v68, v65
	v_cndmask_b32_e64 v67, 0, v65, s[2:3]
	v_med3_f32 v65, v73, s94, v198
	v_cndmask_b32_e64 v212, v199, -v68, s[2:3]
	v_exp_f32_e64 v68, -v65
	v_cmp_lt_i32_e64 s[2:3], 17, v0
	s_or_b64 s[2:3], s[42:43], s[2:3]
	v_add_f32_e32 v68, 1.0, v68
	v_log_f32_e32 v68, v68
	s_nop 0
	v_sub_f32_e64 v65, -v68, v65
	v_cndmask_b32_e64 v214, 0, v65, s[2:3]
	v_med3_f32 v65, v74, s94, v198
	v_cndmask_b32_e64 v213, v199, -v68, s[2:3]
	v_exp_f32_e64 v68, -v65
	v_cmp_lt_i32_e64 s[2:3], 18, v0
	s_or_b64 s[2:3], s[42:43], s[2:3]
	v_add_f32_e32 v68, 1.0, v68
	v_log_f32_e32 v68, v68
	s_nop 0
	v_sub_f32_e64 v65, -v68, v65
	v_cndmask_b32_e64 v216, 0, v65, s[2:3]
	v_med3_f32 v65, v75, s94, v198
	v_cndmask_b32_e64 v215, v199, -v68, s[2:3]
	v_exp_f32_e64 v68, -v65
	v_cmp_lt_i32_e64 s[2:3], 19, v0
	s_or_b64 s[2:3], s[42:43], s[2:3]
	v_add_f32_e32 v68, 1.0, v68
	v_log_f32_e32 v68, v68
	s_nop 0
	v_sub_f32_e64 v65, -v68, v65
	v_cndmask_b32_e64 v218, 0, v65, s[2:3]
	v_med3_f32 v65, v76, s94, v198
	v_cndmask_b32_e64 v217, v199, -v68, s[2:3]
	v_exp_f32_e64 v68, -v65
	v_cmp_lt_i32_e64 s[2:3], 24, v0
	s_or_b64 s[2:3], s[42:43], s[2:3]
	v_add_f32_e32 v68, 1.0, v68
	v_log_f32_e32 v68, v68
	s_nop 0
	v_sub_f32_e64 v65, -v68, v65
	v_cndmask_b32_e64 v70, 0, v65, s[2:3]
	v_med3_f32 v65, v77, s94, v198
	v_cndmask_b32_e64 v76, v199, -v68, s[2:3]
	v_exp_f32_e64 v68, -v65
	v_cmp_lt_i32_e64 s[2:3], 25, v0
	s_or_b64 s[2:3], s[42:43], s[2:3]
	v_add_f32_e32 v68, 1.0, v68
	v_log_f32_e32 v69, v68
	s_nop 0
	v_sub_f32_e64 v65, -v69, v65
; DI float ex2(float x) { return __builtin_amdgcn_exp2f(x); }
; DI float lg2(float x) { return __builtin_amdgcn_logf(x); }
; DI void stick_pv(f32x16& s0, f32x16& s1, float& R, f32x16& o0, f32x16& o1, const u16* Vs, int dl,
;                  bool need_mask, int r, int h) {
;     ...
;     for (int i = 0; i < 16; ++i) {
;       const int ci = 32 * t + (i & 3) + 8 * (i >> 2);
;       float a = t ? s1[i] : s0[i];
;       float z = __builtin_amdgcn_fmed3f(a, -126.f, 126.f);
;       float e = ex2(-z);
;       float lb = -lg2(1.f + e);
;       float xi = lb - z;
;       if (need_mask) {
;         bool valid = (ci < dl);
;         xi = valid ? xi : 0.f;
;         lb = valid ? lb : -INFINITY;
;       }
;       x[16 * t + i] = xi;
;       if (t) s1[i] = lb; else s0[i] = lb;
;     }
;   float gs[8], pg[8], pr[8];
; #pragma unroll
;   for (int g = 0; g < 8; ++g) {
;     gs[g] = (x[4 * g] + x[4 * g + 1]) + (x[4 * g + 2] + x[4 * g + 3]);
;     pg[g] = shx(gs[g], r + 32 * h);
;     pr[g] = gs[g] + pg[g];
	v_cndmask_b32_e64 v68, 0, v65, s[2:3]
	v_med3_f32 v65, v78, s94, v198
	v_cndmask_b32_e64 v77, v199, -v69, s[2:3]
	v_exp_f32_e64 v69, -v65
	v_cmp_lt_i32_e64 s[2:3], 26, v0
	s_or_b64 s[2:3], s[42:43], s[2:3]
	v_add_f32_e32 v69, 1.0, v69
	v_log_f32_e32 v69, v69
	s_nop 0
	v_sub_f32_e64 v65, -v69, v65
	v_cndmask_b32_e64 v72, 0, v65, s[2:3]
	v_med3_f32 v65, v79, s94, v198
	v_cndmask_b32_e64 v78, v199, -v69, s[2:3]
	v_exp_f32_e64 v69, -v65
	v_cmp_lt_i32_e64 s[2:3], 27, v0
	s_or_b64 s[2:3], s[42:43], s[2:3]
	v_add_f32_e32 v69, 1.0, v69
	v_log_f32_e32 v69, v69
	s_nop 0
	v_sub_f32_e64 v65, -v69, v65
	v_cndmask_b32_e64 v74, 0, v65, s[2:3]
	v_exp_f32_e64 v65, -v48
	v_cndmask_b32_e64 v79, v199, -v69, s[2:3]
	v_cmp_lt_i32_e64 s[2:3], 32, v0
	s_or_b64 s[2:3], s[42:43], s[2:3]
	v_add_f32_e32 v65, 1.0, v65
	v_log_f32_e32 v65, v65
	s_nop 0
	v_sub_f32_e64 v48, -v65, v48
	v_cndmask_b32_e64 v69, 0, v48, s[2:3]
	v_med3_f32 v48, v49, s94, v198
	v_exp_f32_e64 v49, -v48
	v_cndmask_b32_e64 v167, v199, -v65, s[2:3]
	v_cmp_lt_i32_e64 s[2:3], 33, v0
	s_or_b64 s[2:3], s[42:43], s[2:3]
	v_add_f32_e32 v49, 1.0, v49
	v_log_f32_e32 v49, v49
	s_nop 0
	v_sub_f32_e64 v48, -v49, v48
	v_cndmask_b32_e64 v220, 0, v48, s[2:3]
	v_med3_f32 v48, v50, s94, v198
	v_cndmask_b32_e64 v219, v199, -v49, s[2:3]
	v_exp_f32_e64 v49, -v48
	v_cmp_lt_i32_e64 s[2:3], 34, v0
	s_or_b64 s[2:3], s[42:43], s[2:3]
	v_add_f32_e32 v49, 1.0, v49
	v_log_f32_e32 v49, v49
	s_nop 0
	v_sub_f32_e64 v48, -v49, v48
	v_cndmask_b32_e64 v222, 0, v48, s[2:3]
	v_med3_f32 v48, v51, s94, v198
	v_cndmask_b32_e64 v221, v199, -v49, s[2:3]
	v_exp_f32_e64 v49, -v48
	v_cmp_lt_i32_e64 s[2:3], 35, v0
	s_or_b64 s[2:3], s[42:43], s[2:3]
	v_add_f32_e32 v49, 1.0, v49
	v_log_f32_e32 v49, v49
	s_nop 0
	v_sub_f32_e64 v48, -v49, v48
	v_cndmask_b32_e64 v224, 0, v48, s[2:3]
	v_med3_f32 v48, v52, s94, v198
	v_cndmask_b32_e64 v223, v199, -v49, s[2:3]
	v_exp_f32_e64 v49, -v48
	v_cmp_lt_i32_e64 s[2:3], 40, v0
	s_or_b64 s[2:3], s[42:43], s[2:3]
	v_add_f32_e32 v49, 1.0, v49
	v_log_f32_e32 v49, v49
	s_nop 0
	v_sub_f32_e64 v48, -v49, v48
	v_cndmask_b32_e64 v51, 0, v48, s[2:3]
	v_med3_f32 v48, v53, s94, v198
	v_cndmask_b32_e64 v52, v199, -v49, s[2:3]
	v_exp_f32_e64 v49, -v48
	v_cmp_lt_i32_e64 s[2:3], 41, v0
	s_or_b64 s[2:3], s[42:43], s[2:3]
	v_add_f32_e32 v49, 1.0, v49
	v_log_f32_e32 v49, v49
	s_nop 0
	v_sub_f32_e64 v48, -v49, v48
	v_cndmask_b32_e64 v53, 0, v48, s[2:3]
	v_med3_f32 v48, v54, s94, v198
	v_cndmask_b32_e64 v75, v199, -v49, s[2:3]
	v_exp_f32_e64 v49, -v48
	v_cmp_lt_i32_e64 s[2:3], 42, v0
	s_or_b64 s[2:3], s[42:43], s[2:3]
	v_add_f32_e32 v49, 1.0, v49
	v_log_f32_e32 v49, v49
	s_nop 0
	v_sub_f32_e64 v48, -v49, v48
	v_cndmask_b32_e64 v225, 0, v48, s[2:3]
	v_med3_f32 v48, v55, s94, v198
	v_cndmask_b32_e64 v226, v199, -v49, s[2:3]
	v_exp_f32_e64 v49, -v48
	v_cmp_lt_i32_e64 s[2:3], 43, v0
	s_or_b64 s[2:3], s[42:43], s[2:3]
	v_add_f32_e32 v49, 1.0, v49
	v_log_f32_e32 v49, v49
	s_nop 0
	v_sub_f32_e64 v48, -v49, v48
	v_cndmask_b32_e64 v227, 0, v48, s[2:3]
	v_med3_f32 v48, v56, s94, v198
	v_cndmask_b32_e64 v228, v199, -v49, s[2:3]
	v_exp_f32_e64 v49, -v48
	v_cmp_lt_i32_e64 s[2:3], 48, v0
	s_or_b64 s[2:3], s[42:43], s[2:3]
	v_add_f32_e32 v49, 1.0, v49
	v_log_f32_e32 v49, v49
	s_nop 0
	v_sub_f32_e64 v48, -v49, v48
	v_cndmask_b32_e64 v56, v199, -v49, s[2:3]
	v_med3_f32 v49, v57, s94, v198
	v_exp_f32_e64 v50, -v49
	v_cndmask_b32_e64 v48, 0, v48, s[2:3]
	v_cmp_lt_i32_e64 s[2:3], 49, v0
	s_or_b64 s[2:3], s[42:43], s[2:3]
	v_add_f32_e32 v50, 1.0, v50
	v_log_f32_e32 v54, v50
	s_nop 0
	v_sub_f32_e64 v49, -v54, v49
	v_cndmask_b32_e64 v50, 0, v49, s[2:3]
	v_med3_f32 v49, v58, s94, v198
	v_cndmask_b32_e64 v57, v199, -v54, s[2:3]
	v_exp_f32_e64 v54, -v49
	v_cmp_lt_i32_e64 s[2:3], 50, v0
	s_or_b64 s[2:3], s[42:43], s[2:3]
	v_add_f32_e32 v54, 1.0, v54
	v_log_f32_e32 v54, v54
	s_nop 0
	v_sub_f32_e64 v49, -v54, v49
	v_cndmask_b32_e64 v58, 0, v49, s[2:3]
	v_med3_f32 v49, v59, s94, v198
	v_cndmask_b32_e64 v229, v199, -v54, s[2:3]
	v_exp_f32_e64 v54, -v49
	v_cmp_lt_i32_e64 s[2:3], 51, v0
	s_or_b64 s[2:3], s[42:43], s[2:3]
	v_add_f32_e32 v54, 1.0, v54
	v_log_f32_e32 v54, v54
	s_nop 0
	v_sub_f32_e64 v49, -v54, v49
	v_cndmask_b32_e64 v59, 0, v49, s[2:3]
	v_med3_f32 v49, v60, s94, v198
	v_cndmask_b32_e64 v230, v199, -v54, s[2:3]
	v_exp_f32_e64 v54, -v49
	v_cmp_lt_i32_e64 s[2:3], 56, v0
	s_or_b64 s[2:3], s[42:43], s[2:3]
	v_add_f32_e32 v54, 1.0, v54
	v_log_f32_e32 v54, v54
	s_nop 0
	v_sub_f32_e64 v49, -v54, v49
	v_cndmask_b32_e64 v60, v199, -v54, s[2:3]
	v_med3_f32 v54, v61, s94, v198
	v_exp_f32_e64 v55, -v54
	v_cndmask_b32_e64 v49, 0, v49, s[2:3]
	v_cmp_lt_i32_e64 s[2:3], 57, v0
	s_or_b64 s[2:3], s[42:43], s[2:3]
	v_add_f32_e32 v55, 1.0, v55
	v_log_f32_e32 v55, v55
	s_nop 0
	v_sub_f32_e64 v54, -v55, v54
	v_cndmask_b32_e64 v61, 0, v54, s[2:3]
	v_med3_f32 v54, v62, s94, v198
	v_cndmask_b32_e64 v231, v199, -v55, s[2:3]
	v_exp_f32_e64 v55, -v54
	v_cmp_lt_i32_e64 s[2:3], 58, v0
	s_or_b64 s[2:3], s[42:43], s[2:3]
	v_add_f32_e32 v49, v49, v61
	v_add_f32_e32 v55, 1.0, v55
	v_log_f32_e32 v55, v55
	s_nop 0
	v_sub_f32_e64 v54, -v55, v54
	v_cndmask_b32_e64 v62, 0, v54, s[2:3]
	v_med3_f32 v54, v63, s94, v198
	v_cndmask_b32_e64 v232, v199, -v55, s[2:3]
	v_exp_f32_e64 v55, -v54
	v_cmp_lt_i32_e64 s[2:3], 59, v0
	s_or_b64 s[2:3], s[42:43], s[2:3]
	v_add_f32_e32 v0, v15, v207
	v_add_f32_e32 v55, 1.0, v55
	v_log_f32_e32 v55, v55
	v_add_f32_e32 v15, v209, v211
	v_add_f32_e32 v15, v0, v15
	v_add_f32_e32 v0, v67, v214
	v_sub_f32_e64 v54, -v55, v54
	v_cndmask_b32_e64 v63, 0, v54, s[2:3]
	v_add_f32_e32 v54, v216, v218
	v_add_f32_e32 v0, v0, v54
	ds_bpermute_b32 v234, v180, v0
	v_add_f32_e32 v54, v222, v224
	v_cndmask_b32_e64 v233, v199, -v55, s[2:3]
	ds_bpermute_b32 v65, v180, v15
	s_mov_b32 s2, 0xc3200000
	s_waitcnt lgkmcnt(1)
; DI float ex2(float x) { return __builtin_amdgcn_exp2f(x); }
; DI f32x16 mfma(bf16x8 a, bf16x8 b, f32x16 c) { return __builtin_amdgcn_mfma_f32_32x32x16_bf16(a, b, c, 0, 0, 0); }
; DI void stick_pv(f32x16& s0, f32x16& s1, float& R, f32x16& o0, f32x16& o1, const u16* Vs, int dl,
;                  bool need_mask, int r, int h) {
;     ...
;   for (int g = 0; g < 8; ++g) {
;     gs[g] = (x[4 * g] + x[4 * g + 1]) + (x[4 * g + 2] + x[4 * g + 3]);
;     pg[g] = shx(gs[g], r + 32 * h);
;     pr[g] = gs[g] + pg[g];
;   }
;   float suf = 0.f;
; #pragma unroll
;   for (int g = 7; g >= 0; --g) {
;     float base = R + suf + (h == 0 ? pg[g] : 0.f);
;     float t3 = base, t2 = t3 + x[4 * g + 3], t1 = t2 + x[4 * g + 2], t0 = t1 + x[4 * g + 1];
;     const int i = 4 * (g & 3);
;     if (g >= 4) {
;       s1[i] = ex2(s1[i] + t0); s1[i + 1] = ex2(s1[i + 1] + t1); s1[i + 2] = ex2(s1[i + 2] + t2); s1[i + 3] = ex2(s1[i + 3] + t3);
;     } else {
;       s0[i] = ex2(s0[i] + t0); s0[i + 1] = ex2(s0[i + 1] + t1); s0[i + 2] = ex2(s0[i + 2] + t2); s0[i + 3] = ex2(s0[i + 3] + t3);
;     }
;     suf += pr[g];
;   }
;   R += suf;
; #pragma unroll
;   for (int kk = 0; kk < 4; ++kk) {
;     const int s = kk & 1;
;     unsigned u0, u1, u2, u3;
;     if (kk < 2) {
;       u0 = pk2(s0[8 * s], s0[8 * s + 1]); u1 = pk2(s0[8 * s + 2], s0[8 * s + 3]);
;       u2 = pk2(s0[8 * s + 4], s0[8 * s + 5]); u3 = pk2(s0[8 * s + 6], s0[8 * s + 7]);
;     } else {
;       u0 = pk2(s1[8 * s], s1[8 * s + 1]); u1 = pk2(s1[8 * s + 2], s1[8 * s + 3]);
;       u2 = pk2(s1[8 * s + 4], s1[8 * s + 5]); u3 = pk2(s1[8 * s + 6], s1[8 * s + 7]);
;     }
;     u32x4 uu = {u0, u1, u2, u3};
;     bf16x8 pf = __builtin_bit_cast(bf16x8, uu);
;     bf16x8 v0 = ldsv(Vs + r * LSTR + kk * 16 + 8 * h);
;     bf16x8 v1 = ldsv(Vs + (32 + r) * LSTR + kk * 16 + 8 * h);
;     o0 = mfma(v0, pf, o0);
;     o1 = mfma(v1, pf, o1);
;   }
; template <int MODE>
; DI void attn_item(const Params& p, int layer, int b, int head, int qblk, u16* sm, volatile LAS int* s_done_, int wv) {
;     ...
;               wdone = __all(R < -160.f) ? 1 : 0;
	v_add_f32_e32 v67, v0, v234
	v_add_f32_e32 v0, v69, v220
	v_add_f32_e32 v71, v0, v54
	v_add_f32_e32 v0, v51, v53
	v_add_f32_e32 v51, v225, v227
	v_add_f32_e32 v0, v0, v51
	v_add_f32_e32 v51, v62, v63
	v_add_f32_e32 v48, v48, v50
	v_add_f32_e32 v49, v49, v51
	ds_bpermute_b32 v55, v180, v49
	ds_bpermute_b32 v235, v180, v0
	v_add_f32_e32 v54, v58, v59
	ds_bpermute_b32 v69, v180, v71
	s_waitcnt lgkmcnt(3)
	v_add_f32_e32 v14, v14, v64
	v_add_f32_e32 v15, v15, v65
	s_waitcnt lgkmcnt(2)
	v_add_f32_e32 v48, v48, v54
	v_add_f32_e32 v49, v49, v55
	s_waitcnt lgkmcnt(1)
	v_add_f32_e32 v73, v0, v235
	ds_bpermute_b32 v0, v180, v48
	v_cndmask_b32_e32 v51, 0, v55, vcc
	v_add_f32_e32 v51, v236, v51
	v_add_f32_e32 v54, v63, v51
	v_add_f32_e32 v51, v233, v51
	s_waitcnt lgkmcnt(0)
	v_add_f32_e32 v48, v48, v0
	v_add_f32_e32 v49, v49, v1
	v_exp_f32_e32 v233, v51
	v_add_f32_e32 v51, v184, v49
	v_cndmask_b32_e32 v0, 0, v0, vcc
	v_add_f32_e32 v0, v0, v51
	v_add_f32_e32 v55, v62, v54
	v_add_f32_e32 v54, v232, v54
	v_add_f32_e32 v51, v59, v0
	v_exp_f32_e32 v232, v54
	v_add_f32_e32 v54, v58, v51
	v_add_f32_e32 v50, v50, v54
	v_add_f32_e32 v50, v56, v50
	v_exp_f32_e32 v237, v50
	v_add_f32_e32 v50, v57, v54
	v_exp_f32_e32 v238, v50
	v_add_f32_e32 v50, v229, v51
	v_pk_add_f32 v[48:49], v[48:49], v[48:49] op_sel:[0,1] op_sel_hi:[1,0]
	v_exp_f32_e32 v229, v50
	v_add_f32_e32 v49, v184, v48
	v_cndmask_b32_e32 v50, 0, v235, vcc
	v_add_f32_e32 v49, v50, v49
	v_add_f32_e32 v50, v227, v49
	v_add_f32_e32 v51, v225, v50
	v_add_f32_e32 v53, v53, v51
	v_add_f32_e32 v51, v75, v51
	v_add_f32_e32 v50, v226, v50
	v_add_f32_e32 v49, v228, v49
	v_mov_b32_e32 v75, v48
	v_exp_f32_e32 v227, v51
	v_exp_f32_e32 v226, v50
	v_exp_f32_e32 v228, v49
	v_add_f32_e32 v50, v70, v68
	v_add_f32_e32 v51, v71, v69
	v_add_f32_e32 v48, v72, v74
	v_add_f32_e32 v49, v73, v75
	v_add_f32_e32 v52, v52, v53
	v_add_f32_e32 v50, v50, v48
	v_add_f32_e32 v51, v51, v49
	ds_bpermute_b32 v48, v180, v50
	v_exp_f32_e32 v225, v52
	v_cndmask_b32_e32 v52, 0, v69, vcc
	v_add_f32_e32 v49, v184, v49
	v_add_f32_e32 v49, v52, v49
	v_add_f32_e32 v52, v224, v49
	v_add_f32_e32 v49, v223, v49
	s_waitcnt lgkmcnt(0)
	v_add_f32_e32 v50, v50, v48
	v_exp_f32_e32 v73, v49
	v_add_f32_e32 v49, v184, v51
	v_cndmask_b32_e32 v48, 0, v48, vcc
	v_add_f32_e32 v53, v222, v52
	v_add_f32_e32 v48, v48, v49
	v_add_f32_e32 v54, v220, v53
	v_add_f32_e32 v52, v221, v52
	v_add_f32_e32 v49, v74, v48
	v_add_f32_e32 v54, v167, v54
	v_exp_f32_e32 v71, v52
	v_add_f32_e32 v52, v72, v49
	v_add_f32_e32 v49, v78, v49
	v_add_f32_e32 v48, v79, v48
	v_add_f32_e32 v167, v50, v51
	v_exp_f32_e32 v74, v49
	v_exp_f32_e32 v75, v48
	v_add_f32_e32 v48, v184, v167
	v_cndmask_b32_e32 v49, 0, v234, vcc
	v_add_f32_e32 v48, v49, v48
	v_add_f32_e32 v49, v218, v48
	v_add_f32_e32 v50, v216, v49
	v_add_f32_e32 v49, v215, v49
	v_add_f32_e32 v48, v217, v48
	v_exp_f32_e32 v78, v49
	v_exp_f32_e32 v79, v48
	v_add_f32_e32 v48, v66, v166
	v_add_f32_e32 v49, v67, v167
	v_add_f32_e32 v53, v219, v53
	v_add_f32_e32 v51, v214, v50
	v_add_f32_e32 v50, v213, v50
	v_add_f32_e32 v14, v14, v48
	v_add_f32_e32 v15, v15, v49
	v_exp_f32_e32 v70, v53
	v_add_f32_e32 v53, v68, v52
	v_add_f32_e32 v52, v77, v52
	v_exp_f32_e32 v77, v50
	v_cndmask_b32_e32 v50, 0, v65, vcc
	ds_bpermute_b32 v48, v180, v14
	v_add_f32_e32 v49, v184, v49
	v_add_f32_e32 v49, v50, v49
	v_add_f32_e32 v51, v212, v51
	v_add_f32_e32 v50, v211, v49
	v_add_f32_e32 v53, v76, v53
	v_exp_f32_e32 v76, v51
	v_add_f32_e32 v51, v209, v50
	v_exp_f32_e32 v72, v52
	v_add_f32_e32 v52, v207, v51
	v_add_f32_e32 v51, v206, v51
	v_exp_f32_e32 v68, v53
	s_waitcnt lgkmcnt(0)
	v_add_f32_e32 v14, v14, v48
	v_exp_f32_e32 v53, v51
	v_add_f32_e32 v51, v184, v15
	v_cndmask_b32_e32 v48, 0, v48, vcc
	v_add_f32_e32 v48, v48, v51
	v_add_f32_e32 v51, v166, v48
	v_add_f32_e32 v61, v61, v55
	v_add_f32_e32 v55, v231, v55
	v_exp_f32_e32 v69, v54
	v_add_f32_e32 v54, v66, v51
	v_exp_f32_e32 v231, v55
	v_add_f32_e32 v55, v64, v54
	v_add_f32_e32 v52, v205, v52
	v_add_f32_e32 v50, v208, v50
	v_add_f32_e32 v49, v210, v49
	v_add_f32_e32 v55, v165, v55
	v_add_f32_e32 v54, v185, v54
	v_add_f32_e32 v51, v186, v51
	v_add_f32_e32 v48, v204, v48
	v_exp_f32_e32 v52, v52
	v_exp_f32_e32 v50, v50
	v_exp_f32_e32 v49, v49
	v_exp_f32_e32 v55, v55
	v_exp_f32_e32 v54, v54
	v_exp_f32_e32 v56, v51
	v_exp_f32_e32 v48, v48
	v_add_f32_e32 v60, v60, v61
	v_exp_f32_e32 v236, v60
	v_cvt_pk_bf16_f32 v51, v50, v49
	v_cvt_pk_bf16_f32 v50, v52, v53
	v_cvt_pk_bf16_f32 v49, v56, v48
	v_cvt_pk_bf16_f32 v48, v55, v54
	ds_read_b128 v[52:55], v155 offset:32256
	ds_read_b128 v[56:59], v155 offset:27648
	ds_read_b128 v[60:63], v155 offset:27680
	s_waitcnt lgkmcnt(2)
	v_mfma_f32_32x32x16_bf16 v[16:31], v[52:55], v[48:51], v[16:31]
	ds_read_b128 v[52:55], v155 offset:32288
	v_add_f32_e32 v0, v230, v0
	v_exp_f32_e32 v0, v0
	v_add_f32_e32 v14, v14, v15
	v_add_f32_e32 v184, v184, v14
	v_cmp_gt_f32_e64 s[2:3], s2, v184
	s_cmp_eq_u64 s[2:3], exec
	s_waitcnt lgkmcnt(2)
	v_mfma_f32_32x32x16_bf16 v[32:47], v[56:59], v[48:51], v[32:47]
	v_cvt_pk_bf16_f32 v51, v74, v75
	v_cvt_pk_bf16_f32 v50, v68, v72
	v_cvt_pk_bf16_f32 v49, v78, v79
	v_cvt_pk_bf16_f32 v48, v76, v77
	s_cselect_b64 s[2:3], -1, 0
	v_cndmask_b32_e64 v64, 0, 1, s[2:3]
	s_waitcnt lgkmcnt(1)
	v_mfma_f32_32x32x16_bf16 v[32:47], v[60:63], v[48:51], v[32:47]
	s_waitcnt lgkmcnt(0)
	v_mfma_f32_32x32x16_bf16 v[16:31], v[52:55], v[48:51], v[16:31]
	ds_read_b128 v[52:55], v155 offset:27712
	ds_read_b128 v[56:59], v155 offset:32320
	v_cvt_pk_bf16_f32 v51, v226, v228
	v_cvt_pk_bf16_f32 v50, v225, v227
	v_cvt_pk_bf16_f32 v49, v71, v73
	v_cvt_pk_bf16_f32 v48, v69, v70
	s_waitcnt lgkmcnt(1)
	s_nop 0
	v_mfma_f32_32x32x16_bf16 v[32:47], v[52:55], v[48:51], v[32:47]
	s_waitcnt lgkmcnt(0)
	v_mfma_f32_32x32x16_bf16 v[16:31], v[56:59], v[48:51], v[16:31]
	ds_read_b128 v[52:55], v155 offset:27744
	ds_read_b128 v[56:59], v155 offset:32352
	v_cvt_pk_bf16_f32 v51, v232, v233
	v_cvt_pk_bf16_f32 v50, v236, v231
	v_cvt_pk_bf16_f32 v49, v229, v0
	v_cvt_pk_bf16_f32 v48, v237, v238
	s_waitcnt lgkmcnt(1)
	s_nop 0
	v_mfma_f32_32x32x16_bf16 v[32:47], v[52:55], v[48:51], v[32:47]
	s_waitcnt lgkmcnt(0)
	v_mfma_f32_32x32x16_bf16 v[16:31], v[56:59], v[48:51], v[16:31]

; DI float ex2(float x) { return __builtin_amdgcn_exp2f(x); }
; DI float lg2(float x) { return __builtin_amdgcn_logf(x); }
; DI f32x16 mfma(bf16x8 a, bf16x8 b, f32x16 c) { return __builtin_amdgcn_mfma_f32_32x32x16_bf16(a, b, c, 0, 0, 0); }
; DI void stick_pv(f32x16& s0, f32x16& s1, float& R, f32x16& o0, f32x16& o1, const u16* Vs, int dl,
;                  bool need_mask, int r, int h) {
;     ...
;     for (int i = 0; i < 16; ++i) {
;       const int ci = 32 * t + (i & 3) + 8 * (i >> 2);
;       float a = t ? s1[i] : s0[i];
;       float z = __builtin_amdgcn_fmed3f(a, -126.f, 126.f);
;       float e = ex2(-z);
;       float lb = -lg2(1.f + e);
;       float xi = lb - z;
;       if (need_mask) {
;         bool valid = (ci < dl);
;         xi = valid ? xi : 0.f;
;         lb = valid ? lb : -INFINITY;
;       }
;       x[16 * t + i] = xi;
;       if (t) s1[i] = lb; else s0[i] = lb;
;     }
; template <int MODE>
; DI void attn_item(const Params& p, int layer, int b, int head, int qblk, u16* sm, volatile LAS int* s_done_, int wv) {
;     ...
;       for (int c = 0; c < 4; ++c) {
;         const int it = base + c;
;         if (it >= it0 && it < ntiles) {
;           const u16* Kc = Ks + c * (2 * 64 * LSTR);
;           const u16* Vc = Vs + c * (2 * 64 * LSTR);
;           const int k0 = tile_k0(it);
;           bool skip, need_mask;
;           if (MODE == 1) { skip = (k0 > q0w + 31) || (k0 + 63 < q0w - 127); need_mask = true; }
;           else { skip = (k0 >= q0w + 31) || wdone; need_mask = (k0 + 63 >= q0w); }
;           if (!skip) {
;             const int dl = qpos - k0 - 4 * h;
;             if (MODE == 1) {
;               softmax_pv<1, 0, 4>(qf, Kc, Vc, m0, ls0, o[0], o[1], sl2, dl, need_mask, false, r, h, LSTR, lo);
;             } else {
;               f32x16 sa[2];
; #pragma unroll
;               for (int e = 0; e < 16; ++e) { sa[0][e] = 0.f; sa[1][e] = 0.f; }
; #pragma unroll
;               for (int t = 0; t < 2; ++t)
; #pragma unroll
;                 for (int ks = 0; ks < 4; ++ks) {
;                   bf16x8 kf = ldsv(Kc + (32 * t + r) * LSTR + ks * 16 + 8 * h);
;                   sa[t] = mfma(kf, qf[ks], sa[t]);
;                 }
;               stick_pv(sa[0], sa[1], R, o[0], o[1], Vc, dl, need_mask, r, h);
.LBB0_239:
	s_xor_b32 s2, s87, 0x3fffffc
	v_add_lshl_u32 v0, s2, v173, 6
	v_cmp_lt_i32_e64 s[2:3], v0, v176
	v_cmp_eq_u32_e64 s[38:39], 0, v64
	s_and_b64 s[2:3], s[2:3], s[38:39]
	s_and_saveexec_b64 s[18:19], s[2:3]
	s_cbranch_execz .LBB0_241
	v_or_b32_e32 v14, 63, v0
	v_cmp_lt_i32_e64 s[38:39], v14, v148
	v_add_u32_e32 v14, v152, v181
	s_waitcnt vmcnt(3)
	ds_read_b128 v[48:51], v14 offset:55296
	s_waitcnt vmcnt(2)
	ds_read_b128 v[52:55], v14 offset:55328
	ds_read_b128 v[204:207], v14 offset:59936
	v_or_b32_e32 v0, v0, v177
	s_waitcnt lgkmcnt(2)
	v_mfma_f32_32x32x16_bf16 v[64:79], v[48:51], v[88:91], 0
	ds_read_b128 v[48:51], v14 offset:55360
	v_sub_u32_e32 v0, v149, v0
	v_cmp_lt_i32_e64 s[2:3], 0, v0
	s_or_b64 s[2:3], s[38:39], s[2:3]
	v_add_f32_e32 v236, 0, v184
	s_waitcnt lgkmcnt(2)
	v_mfma_f32_32x32x16_bf16 v[64:79], v[52:55], v[80:83], v[64:79]
	s_waitcnt lgkmcnt(0)
	v_mfma_f32_32x32x16_bf16 v[64:79], v[48:51], v[84:87], v[64:79]
	ds_read_b128 v[48:51], v14 offset:55392
	s_waitcnt lgkmcnt(0)
	v_mfma_f32_32x32x16_bf16 v[64:79], v[48:51], v[92:95], v[64:79]
	ds_read_b128 v[48:51], v14 offset:59904
	s_waitcnt vmcnt(0) lgkmcnt(0)
	v_mfma_f32_32x32x16_bf16 v[48:63], v[48:51], v[88:91], 0
	v_mfma_f32_32x32x16_bf16 v[48:63], v[204:207], v[80:83], v[48:63]
	ds_read_b128 v[204:207], v14 offset:59968
	s_waitcnt lgkmcnt(0)
	v_mfma_f32_32x32x16_bf16 v[48:63], v[204:207], v[84:87], v[48:63]
	ds_read_b128 v[204:207], v14 offset:60000
	s_nop 3
	v_med3_f32 v14, v64, s94, v198
	v_exp_f32_e64 v15, -v14
	s_nop 0
	v_add_f32_e32 v15, 1.0, v15
	v_log_f32_e32 v15, v15
	s_waitcnt lgkmcnt(0)
	v_mfma_f32_32x32x16_bf16 v[48:63], v[204:207], v[92:95], v[48:63]
	v_sub_f32_e64 v14, -v15, v14
	v_cndmask_b32_e64 v165, v199, -v15, s[2:3]
	v_med3_f32 v15, v65, s94, v198
	v_exp_f32_e64 v64, -v15
	v_cndmask_b32_e64 v14, 0, v14, s[2:3]
	v_cmp_lt_i32_e64 s[2:3], 1, v0
	s_or_b64 s[2:3], s[38:39], s[2:3]
	v_add_f32_e32 v64, 1.0, v64
	v_log_f32_e32 v65, v64
	s_nop 2
	v_med3_f32 v48, v48, s94, v198
	v_sub_f32_e64 v15, -v65, v15
	v_cndmask_b32_e64 v64, 0, v15, s[2:3]
	v_med3_f32 v15, v66, s94, v198
	v_cndmask_b32_e64 v185, v199, -v65, s[2:3]
	v_exp_f32_e64 v65, -v15
	v_cmp_lt_i32_e64 s[2:3], 2, v0
	s_or_b64 s[2:3], s[38:39], s[2:3]
	v_add_f32_e32 v65, 1.0, v65
	v_log_f32_e32 v65, v65
	s_nop 0
	v_sub_f32_e64 v15, -v65, v15
	v_cndmask_b32_e64 v66, 0, v15, s[2:3]
	v_med3_f32 v15, v67, s94, v198
	v_cndmask_b32_e64 v186, v199, -v65, s[2:3]
	v_exp_f32_e64 v65, -v15
	v_cmp_lt_i32_e64 s[2:3], 3, v0
	s_or_b64 s[2:3], s[38:39], s[2:3]
	v_add_f32_e32 v65, 1.0, v65
	v_log_f32_e32 v65, v65
	s_nop 0
	v_sub_f32_e64 v15, -v65, v15
	v_cndmask_b32_e64 v166, 0, v15, s[2:3]
	v_med3_f32 v15, v68, s94, v198
	v_cndmask_b32_e64 v204, v199, -v65, s[2:3]
	v_exp_f32_e64 v65, -v15
	v_cmp_lt_i32_e64 s[2:3], 8, v0
	s_or_b64 s[2:3], s[38:39], s[2:3]
	v_add_f32_e32 v65, 1.0, v65
	v_log_f32_e32 v65, v65
	s_nop 0
	v_sub_f32_e64 v15, -v65, v15
	v_cndmask_b32_e64 v205, v199, -v65, s[2:3]
	v_med3_f32 v65, v69, s94, v198
	v_exp_f32_e64 v67, -v65
	v_cndmask_b32_e64 v15, 0, v15, s[2:3]
	v_cmp_lt_i32_e64 s[2:3], 9, v0
	s_or_b64 s[2:3], s[38:39], s[2:3]
	v_add_f32_e32 v67, 1.0, v67
	v_log_f32_e32 v67, v67
	s_nop 0
	v_sub_f32_e64 v65, -v67, v65
	v_cndmask_b32_e64 v207, 0, v65, s[2:3]
	v_med3_f32 v65, v70, s94, v198
	v_cndmask_b32_e64 v206, v199, -v67, s[2:3]
	v_exp_f32_e64 v67, -v65
	v_cmp_lt_i32_e64 s[2:3], 10, v0
	s_or_b64 s[2:3], s[38:39], s[2:3]
	v_add_f32_e32 v67, 1.0, v67
	v_log_f32_e32 v67, v67
	s_nop 0
	v_sub_f32_e64 v65, -v67, v65
	v_cndmask_b32_e64 v209, 0, v65, s[2:3]
	v_med3_f32 v65, v71, s94, v198
	v_cndmask_b32_e64 v208, v199, -v67, s[2:3]
	v_exp_f32_e64 v67, -v65
	v_cmp_lt_i32_e64 s[2:3], 11, v0
	s_or_b64 s[2:3], s[38:39], s[2:3]
	v_add_f32_e32 v67, 1.0, v67
	v_log_f32_e32 v67, v67
	s_nop 0
	v_sub_f32_e64 v65, -v67, v65
	v_cndmask_b32_e64 v211, 0, v65, s[2:3]
	v_med3_f32 v65, v72, s94, v198
	v_cndmask_b32_e64 v210, v199, -v67, s[2:3]
	v_exp_f32_e64 v67, -v65
	v_cmp_lt_i32_e64 s[2:3], 16, v0
	s_or_b64 s[2:3], s[38:39], s[2:3]
	v_add_f32_e32 v67, 1.0, v67
	v_log_f32_e32 v68, v67
	s_nop 0
	v_sub_f32_e64 v65, -v68, v65
	v_cndmask_b32_e64 v67, 0, v65, s[2:3]
	v_med3_f32 v65, v73, s94, v198
	v_cndmask_b32_e64 v212, v199, -v68, s[2:3]
	v_exp_f32_e64 v68, -v65
	v_cmp_lt_i32_e64 s[2:3], 17, v0
	s_or_b64 s[2:3], s[38:39], s[2:3]
	v_add_f32_e32 v68, 1.0, v68
	v_log_f32_e32 v68, v68
	s_nop 0
	v_sub_f32_e64 v65, -v68, v65
	v_cndmask_b32_e64 v214, 0, v65, s[2:3]
	v_med3_f32 v65, v74, s94, v198
	v_cndmask_b32_e64 v213, v199, -v68, s[2:3]
	v_exp_f32_e64 v68, -v65
	v_cmp_lt_i32_e64 s[2:3], 18, v0
	s_or_b64 s[2:3], s[38:39], s[2:3]
	v_add_f32_e32 v68, 1.0, v68
	v_log_f32_e32 v68, v68
	s_nop 0
	v_sub_f32_e64 v65, -v68, v65
	v_cndmask_b32_e64 v216, 0, v65, s[2:3]
	v_med3_f32 v65, v75, s94, v198
	v_cndmask_b32_e64 v215, v199, -v68, s[2:3]
	v_exp_f32_e64 v68, -v65
	v_cmp_lt_i32_e64 s[2:3], 19, v0
	s_or_b64 s[2:3], s[38:39], s[2:3]
	v_add_f32_e32 v68, 1.0, v68
	v_log_f32_e32 v68, v68
	s_nop 0
	v_sub_f32_e64 v65, -v68, v65
	v_cndmask_b32_e64 v218, 0, v65, s[2:3]
	v_med3_f32 v65, v76, s94, v198
	v_cndmask_b32_e64 v217, v199, -v68, s[2:3]
	v_exp_f32_e64 v68, -v65
	v_cmp_lt_i32_e64 s[2:3], 24, v0
	s_or_b64 s[2:3], s[38:39], s[2:3]
	v_add_f32_e32 v68, 1.0, v68
	v_log_f32_e32 v68, v68
	s_nop 0
	v_sub_f32_e64 v65, -v68, v65
	v_cndmask_b32_e64 v70, 0, v65, s[2:3]
	v_med3_f32 v65, v77, s94, v198
	v_cndmask_b32_e64 v76, v199, -v68, s[2:3]
	v_exp_f32_e64 v68, -v65
	v_cmp_lt_i32_e64 s[2:3], 25, v0
	s_or_b64 s[2:3], s[38:39], s[2:3]
	v_add_f32_e32 v68, 1.0, v68
	v_log_f32_e32 v69, v68
	s_nop 0
	v_sub_f32_e64 v65, -v69, v65
; DI float ex2(float x) { return __builtin_amdgcn_exp2f(x); }
; DI float lg2(float x) { return __builtin_amdgcn_logf(x); }
; DI void stick_pv(f32x16& s0, f32x16& s1, float& R, f32x16& o0, f32x16& o1, const u16* Vs, int dl,
;                  bool need_mask, int r, int h) {
;     ...
;     for (int i = 0; i < 16; ++i) {
;       const int ci = 32 * t + (i & 3) + 8 * (i >> 2);
;       float a = t ? s1[i] : s0[i];
;       float z = __builtin_amdgcn_fmed3f(a, -126.f, 126.f);
;       float e = ex2(-z);
;       float lb = -lg2(1.f + e);
;       float xi = lb - z;
;       if (need_mask) {
;         bool valid = (ci < dl);
;         xi = valid ? xi : 0.f;
;         lb = valid ? lb : -INFINITY;
;       }
;       x[16 * t + i] = xi;
;       if (t) s1[i] = lb; else s0[i] = lb;
;     }
;   float gs[8], pg[8], pr[8];
; #pragma unroll
;   for (int g = 0; g < 8; ++g) {
;     gs[g] = (x[4 * g] + x[4 * g + 1]) + (x[4 * g + 2] + x[4 * g + 3]);
;     pg[g] = shx(gs[g], r + 32 * h);
;     pr[g] = gs[g] + pg[g];
	v_cndmask_b32_e64 v68, 0, v65, s[2:3]
	v_med3_f32 v65, v78, s94, v198
	v_cndmask_b32_e64 v77, v199, -v69, s[2:3]
	v_exp_f32_e64 v69, -v65
	v_cmp_lt_i32_e64 s[2:3], 26, v0
	s_or_b64 s[2:3], s[38:39], s[2:3]
	v_add_f32_e32 v69, 1.0, v69
	v_log_f32_e32 v69, v69
	s_nop 0
	v_sub_f32_e64 v65, -v69, v65
	v_cndmask_b32_e64 v72, 0, v65, s[2:3]
	v_med3_f32 v65, v79, s94, v198
	v_cndmask_b32_e64 v78, v199, -v69, s[2:3]
	v_exp_f32_e64 v69, -v65
	v_cmp_lt_i32_e64 s[2:3], 27, v0
	s_or_b64 s[2:3], s[38:39], s[2:3]
	v_add_f32_e32 v69, 1.0, v69
	v_log_f32_e32 v69, v69
	s_nop 0
	v_sub_f32_e64 v65, -v69, v65
	v_cndmask_b32_e64 v74, 0, v65, s[2:3]
	v_exp_f32_e64 v65, -v48
	v_cndmask_b32_e64 v79, v199, -v69, s[2:3]
	v_cmp_lt_i32_e64 s[2:3], 32, v0
	s_or_b64 s[2:3], s[38:39], s[2:3]
	v_add_f32_e32 v65, 1.0, v65
	v_log_f32_e32 v65, v65
	s_nop 0
	v_sub_f32_e64 v48, -v65, v48
	v_cndmask_b32_e64 v69, 0, v48, s[2:3]
	v_med3_f32 v48, v49, s94, v198
	v_exp_f32_e64 v49, -v48
	v_cndmask_b32_e64 v167, v199, -v65, s[2:3]
	v_cmp_lt_i32_e64 s[2:3], 33, v0
	s_or_b64 s[2:3], s[38:39], s[2:3]
	v_add_f32_e32 v49, 1.0, v49
	v_log_f32_e32 v49, v49
	s_nop 0
	v_sub_f32_e64 v48, -v49, v48
	v_cndmask_b32_e64 v220, 0, v48, s[2:3]
	v_med3_f32 v48, v50, s94, v198
	v_cndmask_b32_e64 v219, v199, -v49, s[2:3]
	v_exp_f32_e64 v49, -v48
	v_cmp_lt_i32_e64 s[2:3], 34, v0
	s_or_b64 s[2:3], s[38:39], s[2:3]
	v_add_f32_e32 v49, 1.0, v49
	v_log_f32_e32 v49, v49
	s_nop 0
	v_sub_f32_e64 v48, -v49, v48
	v_cndmask_b32_e64 v222, 0, v48, s[2:3]
	v_med3_f32 v48, v51, s94, v198
	v_cndmask_b32_e64 v221, v199, -v49, s[2:3]
	v_exp_f32_e64 v49, -v48
	v_cmp_lt_i32_e64 s[2:3], 35, v0
	s_or_b64 s[2:3], s[38:39], s[2:3]
	v_add_f32_e32 v49, 1.0, v49
	v_log_f32_e32 v49, v49
	s_nop 0
	v_sub_f32_e64 v48, -v49, v48
	v_cndmask_b32_e64 v224, 0, v48, s[2:3]
	v_med3_f32 v48, v52, s94, v198
	v_cndmask_b32_e64 v223, v199, -v49, s[2:3]
	v_exp_f32_e64 v49, -v48
	v_cmp_lt_i32_e64 s[2:3], 40, v0
	s_or_b64 s[2:3], s[38:39], s[2:3]
	v_add_f32_e32 v49, 1.0, v49
	v_log_f32_e32 v49, v49
	s_nop 0
	v_sub_f32_e64 v48, -v49, v48
	v_cndmask_b32_e64 v51, 0, v48, s[2:3]
	v_med3_f32 v48, v53, s94, v198
	v_cndmask_b32_e64 v52, v199, -v49, s[2:3]
	v_exp_f32_e64 v49, -v48
	v_cmp_lt_i32_e64 s[2:3], 41, v0
	s_or_b64 s[2:3], s[38:39], s[2:3]
	v_add_f32_e32 v49, 1.0, v49
	v_log_f32_e32 v49, v49
	s_nop 0
	v_sub_f32_e64 v48, -v49, v48
	v_cndmask_b32_e64 v53, 0, v48, s[2:3]
	v_med3_f32 v48, v54, s94, v198
	v_cndmask_b32_e64 v75, v199, -v49, s[2:3]
	v_exp_f32_e64 v49, -v48
	v_cmp_lt_i32_e64 s[2:3], 42, v0
	s_or_b64 s[2:3], s[38:39], s[2:3]
	v_add_f32_e32 v49, 1.0, v49
	v_log_f32_e32 v49, v49
	s_nop 0
	v_sub_f32_e64 v48, -v49, v48
	v_cndmask_b32_e64 v225, 0, v48, s[2:3]
	v_med3_f32 v48, v55, s94, v198
	v_cndmask_b32_e64 v226, v199, -v49, s[2:3]
	v_exp_f32_e64 v49, -v48
	v_cmp_lt_i32_e64 s[2:3], 43, v0
	s_or_b64 s[2:3], s[38:39], s[2:3]
	v_add_f32_e32 v49, 1.0, v49
	v_log_f32_e32 v49, v49
	s_nop 0
	v_sub_f32_e64 v48, -v49, v48
	v_cndmask_b32_e64 v227, 0, v48, s[2:3]
	v_med3_f32 v48, v56, s94, v198
	v_cndmask_b32_e64 v228, v199, -v49, s[2:3]
	v_exp_f32_e64 v49, -v48
	v_cmp_lt_i32_e64 s[2:3], 48, v0
	s_or_b64 s[2:3], s[38:39], s[2:3]
	v_add_f32_e32 v49, 1.0, v49
	v_log_f32_e32 v49, v49
	s_nop 0
	v_sub_f32_e64 v48, -v49, v48
	v_cndmask_b32_e64 v56, v199, -v49, s[2:3]
	v_med3_f32 v49, v57, s94, v198
	v_exp_f32_e64 v50, -v49
	v_cndmask_b32_e64 v48, 0, v48, s[2:3]
	v_cmp_lt_i32_e64 s[2:3], 49, v0
	s_or_b64 s[2:3], s[38:39], s[2:3]
	v_add_f32_e32 v50, 1.0, v50
	v_log_f32_e32 v54, v50
	s_nop 0
	v_sub_f32_e64 v49, -v54, v49
	v_cndmask_b32_e64 v50, 0, v49, s[2:3]
	v_med3_f32 v49, v58, s94, v198
	v_cndmask_b32_e64 v57, v199, -v54, s[2:3]
	v_exp_f32_e64 v54, -v49
	v_cmp_lt_i32_e64 s[2:3], 50, v0
	s_or_b64 s[2:3], s[38:39], s[2:3]
	v_add_f32_e32 v54, 1.0, v54
	v_log_f32_e32 v54, v54
	s_nop 0
	v_sub_f32_e64 v49, -v54, v49
	v_cndmask_b32_e64 v58, 0, v49, s[2:3]
	v_med3_f32 v49, v59, s94, v198
	v_cndmask_b32_e64 v229, v199, -v54, s[2:3]
	v_exp_f32_e64 v54, -v49
	v_cmp_lt_i32_e64 s[2:3], 51, v0
	s_or_b64 s[2:3], s[38:39], s[2:3]
	v_add_f32_e32 v54, 1.0, v54
	v_log_f32_e32 v54, v54
	s_nop 0
	v_sub_f32_e64 v49, -v54, v49
	v_cndmask_b32_e64 v59, 0, v49, s[2:3]
	v_med3_f32 v49, v60, s94, v198
	v_cndmask_b32_e64 v230, v199, -v54, s[2:3]
	v_exp_f32_e64 v54, -v49
	v_cmp_lt_i32_e64 s[2:3], 56, v0
	s_or_b64 s[2:3], s[38:39], s[2:3]
	v_add_f32_e32 v54, 1.0, v54
	v_log_f32_e32 v54, v54
	s_nop 0
	v_sub_f32_e64 v49, -v54, v49
	v_cndmask_b32_e64 v60, v199, -v54, s[2:3]
	v_med3_f32 v54, v61, s94, v198
	v_exp_f32_e64 v55, -v54
	v_cndmask_b32_e64 v49, 0, v49, s[2:3]
	v_cmp_lt_i32_e64 s[2:3], 57, v0
	s_or_b64 s[2:3], s[38:39], s[2:3]
	v_add_f32_e32 v55, 1.0, v55
	v_log_f32_e32 v55, v55
	s_nop 0
	v_sub_f32_e64 v54, -v55, v54
	v_cndmask_b32_e64 v61, 0, v54, s[2:3]
	v_med3_f32 v54, v62, s94, v198
	v_cndmask_b32_e64 v231, v199, -v55, s[2:3]
	v_exp_f32_e64 v55, -v54
	v_cmp_lt_i32_e64 s[2:3], 58, v0
	s_or_b64 s[2:3], s[38:39], s[2:3]
	v_add_f32_e32 v49, v49, v61
	v_add_f32_e32 v55, 1.0, v55
	v_log_f32_e32 v55, v55
	s_nop 0
	v_sub_f32_e64 v54, -v55, v54
	v_cndmask_b32_e64 v62, 0, v54, s[2:3]
	v_med3_f32 v54, v63, s94, v198
	v_cndmask_b32_e64 v232, v199, -v55, s[2:3]
	v_exp_f32_e64 v55, -v54
	v_cmp_lt_i32_e64 s[2:3], 59, v0
	s_or_b64 s[2:3], s[38:39], s[2:3]
	v_add_f32_e32 v0, v15, v207
	v_add_f32_e32 v55, 1.0, v55
	v_log_f32_e32 v55, v55
	v_add_f32_e32 v15, v209, v211
	v_add_f32_e32 v15, v0, v15
	v_add_f32_e32 v0, v67, v214
	v_sub_f32_e64 v54, -v55, v54
	v_cndmask_b32_e64 v63, 0, v54, s[2:3]
	v_add_f32_e32 v54, v216, v218
	v_add_f32_e32 v0, v0, v54
	ds_bpermute_b32 v234, v180, v0
	v_add_f32_e32 v54, v222, v224
	v_cndmask_b32_e64 v233, v199, -v55, s[2:3]
	ds_bpermute_b32 v65, v180, v15
	s_mov_b32 s2, 0xc3200000
	s_waitcnt lgkmcnt(1)
; DI float ex2(float x) { return __builtin_amdgcn_exp2f(x); }
; DI f32x16 mfma(bf16x8 a, bf16x8 b, f32x16 c) { return __builtin_amdgcn_mfma_f32_32x32x16_bf16(a, b, c, 0, 0, 0); }
; DI void stick_pv(f32x16& s0, f32x16& s1, float& R, f32x16& o0, f32x16& o1, const u16* Vs, int dl,
;                  bool need_mask, int r, int h) {
;     ...
;   for (int g = 0; g < 8; ++g) {
;     gs[g] = (x[4 * g] + x[4 * g + 1]) + (x[4 * g + 2] + x[4 * g + 3]);
;     pg[g] = shx(gs[g], r + 32 * h);
;     pr[g] = gs[g] + pg[g];
;   }
;   float suf = 0.f;
; #pragma unroll
;   for (int g = 7; g >= 0; --g) {
;     float base = R + suf + (h == 0 ? pg[g] : 0.f);
;     float t3 = base, t2 = t3 + x[4 * g + 3], t1 = t2 + x[4 * g + 2], t0 = t1 + x[4 * g + 1];
;     const int i = 4 * (g & 3);
;     if (g >= 4) {
;       s1[i] = ex2(s1[i] + t0); s1[i + 1] = ex2(s1[i + 1] + t1); s1[i + 2] = ex2(s1[i + 2] + t2); s1[i + 3] = ex2(s1[i + 3] + t3);
;     } else {
;       s0[i] = ex2(s0[i] + t0); s0[i + 1] = ex2(s0[i + 1] + t1); s0[i + 2] = ex2(s0[i + 2] + t2); s0[i + 3] = ex2(s0[i + 3] + t3);
;     }
;     suf += pr[g];
;   }
;   R += suf;
; #pragma unroll
;   for (int kk = 0; kk < 4; ++kk) {
;     const int s = kk & 1;
;     unsigned u0, u1, u2, u3;
;     if (kk < 2) {
;       u0 = pk2(s0[8 * s], s0[8 * s + 1]); u1 = pk2(s0[8 * s + 2], s0[8 * s + 3]);
;       u2 = pk2(s0[8 * s + 4], s0[8 * s + 5]); u3 = pk2(s0[8 * s + 6], s0[8 * s + 7]);
;     } else {
;       u0 = pk2(s1[8 * s], s1[8 * s + 1]); u1 = pk2(s1[8 * s + 2], s1[8 * s + 3]);
;       u2 = pk2(s1[8 * s + 4], s1[8 * s + 5]); u3 = pk2(s1[8 * s + 6], s1[8 * s + 7]);
;     }
;     u32x4 uu = {u0, u1, u2, u3};
;     bf16x8 pf = __builtin_bit_cast(bf16x8, uu);
;     bf16x8 v0 = ldsv(Vs + r * LSTR + kk * 16 + 8 * h);
;     bf16x8 v1 = ldsv(Vs + (32 + r) * LSTR + kk * 16 + 8 * h);
;     o0 = mfma(v0, pf, o0);
;     o1 = mfma(v1, pf, o1);
;   }
; template <int MODE>
; DI void attn_item(const Params& p, int layer, int b, int head, int qblk, u16* sm, volatile LAS int* s_done_, int wv) {
;     ...
;               wdone = __all(R < -160.f) ? 1 : 0;
	v_add_f32_e32 v67, v0, v234
	v_add_f32_e32 v0, v69, v220
	v_add_f32_e32 v71, v0, v54
	v_add_f32_e32 v0, v51, v53
	v_add_f32_e32 v51, v225, v227
	v_add_f32_e32 v0, v0, v51
	v_add_f32_e32 v51, v62, v63
	v_add_f32_e32 v48, v48, v50
	v_add_f32_e32 v49, v49, v51
	ds_bpermute_b32 v55, v180, v49
	ds_bpermute_b32 v235, v180, v0
	v_add_f32_e32 v54, v58, v59
	ds_bpermute_b32 v69, v180, v71
	s_waitcnt lgkmcnt(3)
	v_add_f32_e32 v14, v14, v64
	v_add_f32_e32 v15, v15, v65
	s_waitcnt lgkmcnt(2)
	v_add_f32_e32 v48, v48, v54
	v_add_f32_e32 v49, v49, v55
	s_waitcnt lgkmcnt(1)
	v_add_f32_e32 v73, v0, v235
	ds_bpermute_b32 v0, v180, v48
	v_cndmask_b32_e32 v51, 0, v55, vcc
	v_add_f32_e32 v51, v236, v51
	v_add_f32_e32 v54, v63, v51
	v_add_f32_e32 v51, v233, v51
	s_waitcnt lgkmcnt(0)
	v_add_f32_e32 v48, v48, v0
	v_add_f32_e32 v49, v49, v1
	v_exp_f32_e32 v233, v51
	v_add_f32_e32 v51, v184, v49
	v_cndmask_b32_e32 v0, 0, v0, vcc
	v_add_f32_e32 v0, v0, v51
	v_add_f32_e32 v55, v62, v54
	v_add_f32_e32 v54, v232, v54
	v_add_f32_e32 v51, v59, v0
	v_exp_f32_e32 v232, v54
	v_add_f32_e32 v54, v58, v51
	v_add_f32_e32 v50, v50, v54
	v_add_f32_e32 v50, v56, v50
	v_exp_f32_e32 v237, v50
	v_add_f32_e32 v50, v57, v54
	v_exp_f32_e32 v238, v50
	v_add_f32_e32 v50, v229, v51
	v_pk_add_f32 v[48:49], v[48:49], v[48:49] op_sel:[0,1] op_sel_hi:[1,0]
	v_exp_f32_e32 v229, v50
	v_add_f32_e32 v49, v184, v48
	v_cndmask_b32_e32 v50, 0, v235, vcc
	v_add_f32_e32 v49, v50, v49
	v_add_f32_e32 v50, v227, v49
	v_add_f32_e32 v51, v225, v50
	v_add_f32_e32 v53, v53, v51
	v_add_f32_e32 v51, v75, v51
	v_add_f32_e32 v50, v226, v50
	v_add_f32_e32 v49, v228, v49
	v_mov_b32_e32 v75, v48
	v_exp_f32_e32 v227, v51
	v_exp_f32_e32 v226, v50
	v_exp_f32_e32 v228, v49
	v_add_f32_e32 v50, v70, v68
	v_add_f32_e32 v51, v71, v69
	v_add_f32_e32 v48, v72, v74
	v_add_f32_e32 v49, v73, v75
	v_add_f32_e32 v52, v52, v53
	v_add_f32_e32 v50, v50, v48
	v_add_f32_e32 v51, v51, v49
	ds_bpermute_b32 v48, v180, v50
	v_exp_f32_e32 v225, v52
	v_cndmask_b32_e32 v52, 0, v69, vcc
	v_add_f32_e32 v49, v184, v49
	v_add_f32_e32 v49, v52, v49
	v_add_f32_e32 v52, v224, v49
	v_add_f32_e32 v49, v223, v49
	s_waitcnt lgkmcnt(0)
	v_add_f32_e32 v50, v50, v48
	v_exp_f32_e32 v73, v49
	v_add_f32_e32 v49, v184, v51
	v_cndmask_b32_e32 v48, 0, v48, vcc
	v_add_f32_e32 v53, v222, v52
	v_add_f32_e32 v48, v48, v49
	v_add_f32_e32 v54, v220, v53
	v_add_f32_e32 v52, v221, v52
	v_add_f32_e32 v49, v74, v48
	v_add_f32_e32 v54, v167, v54
	v_exp_f32_e32 v71, v52
	v_add_f32_e32 v52, v72, v49
	v_add_f32_e32 v49, v78, v49
	v_add_f32_e32 v48, v79, v48
	v_add_f32_e32 v167, v50, v51
	v_exp_f32_e32 v74, v49
	v_exp_f32_e32 v75, v48
	v_add_f32_e32 v48, v184, v167
	v_cndmask_b32_e32 v49, 0, v234, vcc
	v_add_f32_e32 v48, v49, v48
	v_add_f32_e32 v49, v218, v48
	v_add_f32_e32 v50, v216, v49
	v_add_f32_e32 v49, v215, v49
	v_add_f32_e32 v48, v217, v48
	v_exp_f32_e32 v78, v49
	v_exp_f32_e32 v79, v48
	v_add_f32_e32 v48, v66, v166
	v_add_f32_e32 v49, v67, v167
	v_add_f32_e32 v53, v219, v53
	v_add_f32_e32 v51, v214, v50
	v_add_f32_e32 v50, v213, v50
	v_add_f32_e32 v14, v14, v48
	v_add_f32_e32 v15, v15, v49
	v_exp_f32_e32 v70, v53
	v_add_f32_e32 v53, v68, v52
	v_add_f32_e32 v52, v77, v52
	v_exp_f32_e32 v77, v50
	v_cndmask_b32_e32 v50, 0, v65, vcc
	ds_bpermute_b32 v48, v180, v14
	v_add_f32_e32 v49, v184, v49
	v_add_f32_e32 v49, v50, v49
	v_add_f32_e32 v51, v212, v51
	v_add_f32_e32 v50, v211, v49
	v_add_f32_e32 v53, v76, v53
	v_exp_f32_e32 v76, v51
	v_add_f32_e32 v51, v209, v50
	v_exp_f32_e32 v72, v52
	v_add_f32_e32 v52, v207, v51
	v_add_f32_e32 v51, v206, v51
	v_exp_f32_e32 v68, v53
	s_waitcnt lgkmcnt(0)
	v_add_f32_e32 v14, v14, v48
	v_exp_f32_e32 v53, v51
	v_add_f32_e32 v51, v184, v15
	v_cndmask_b32_e32 v48, 0, v48, vcc
	v_add_f32_e32 v48, v48, v51
	v_add_f32_e32 v51, v166, v48
	v_add_f32_e32 v61, v61, v55
	v_add_f32_e32 v55, v231, v55
	v_exp_f32_e32 v69, v54
	v_add_f32_e32 v54, v66, v51
	v_exp_f32_e32 v231, v55
	v_add_f32_e32 v55, v64, v54
	v_add_f32_e32 v52, v205, v52
	v_add_f32_e32 v50, v208, v50
	v_add_f32_e32 v49, v210, v49
	v_add_f32_e32 v55, v165, v55
	v_add_f32_e32 v54, v185, v54
	v_add_f32_e32 v51, v186, v51
	v_add_f32_e32 v48, v204, v48
	v_exp_f32_e32 v52, v52
	v_exp_f32_e32 v50, v50
	v_exp_f32_e32 v49, v49
	v_exp_f32_e32 v55, v55
	v_exp_f32_e32 v54, v54
	v_exp_f32_e32 v56, v51
	v_exp_f32_e32 v48, v48
	v_cvt_pk_bf16_f32 v51, v50, v49
	v_cvt_pk_bf16_f32 v50, v52, v53
	v_add_f32_e32 v60, v60, v61
	v_cvt_pk_bf16_f32 v49, v56, v48
	v_cvt_pk_bf16_f32 v48, v55, v54
	ds_read_b128 v[52:55], v155 offset:64512
	ds_read_b128 v[56:59], v155 offset:64544
	v_exp_f32_e32 v236, v60
	s_waitcnt lgkmcnt(1)
	v_mfma_f32_32x32x16_bf16 v[32:47], v[52:55], v[48:51], v[32:47]
	ds_read_b128 v[52:55], v182 offset:59904
	ds_read_b128 v[60:63], v182 offset:59936
	v_add_f32_e32 v0, v230, v0
	v_exp_f32_e32 v0, v0
	v_add_f32_e32 v14, v14, v15
	v_add_f32_e32 v184, v184, v14
	v_cmp_gt_f32_e64 s[2:3], s2, v184
	s_cmp_eq_u64 s[2:3], exec
	s_waitcnt lgkmcnt(1)
	v_mfma_f32_32x32x16_bf16 v[16:31], v[52:55], v[48:51], v[16:31]
	v_cvt_pk_bf16_f32 v51, v74, v75
	v_cvt_pk_bf16_f32 v50, v68, v72
	v_cvt_pk_bf16_f32 v49, v78, v79
	v_cvt_pk_bf16_f32 v48, v76, v77
	s_cselect_b64 s[2:3], -1, 0
	v_cndmask_b32_e64 v64, 0, 1, s[2:3]
	v_mfma_f32_32x32x16_bf16 v[32:47], v[56:59], v[48:51], v[32:47]
	ds_read_b128 v[52:55], v155 offset:64576
	ds_read_b128 v[56:59], v182 offset:59968
	s_waitcnt lgkmcnt(2)
	v_mfma_f32_32x32x16_bf16 v[16:31], v[60:63], v[48:51], v[16:31]
	v_cvt_pk_bf16_f32 v51, v226, v228
	v_cvt_pk_bf16_f32 v50, v225, v227
	v_cvt_pk_bf16_f32 v49, v71, v73
	v_cvt_pk_bf16_f32 v48, v69, v70
	s_waitcnt lgkmcnt(1)
	s_nop 0
	v_mfma_f32_32x32x16_bf16 v[32:47], v[52:55], v[48:51], v[32:47]
	s_waitcnt lgkmcnt(0)
	v_mfma_f32_32x32x16_bf16 v[16:31], v[56:59], v[48:51], v[16:31]
	ds_read_b128 v[52:55], v155 offset:64608
	ds_read_b128 v[56:59], v182 offset:60000
	v_cvt_pk_bf16_f32 v51, v232, v233
	v_cvt_pk_bf16_f32 v50, v236, v231
	v_cvt_pk_bf16_f32 v49, v229, v0
	v_cvt_pk_bf16_f32 v48, v237, v238
	s_waitcnt lgkmcnt(1)
	s_nop 0
	v_mfma_f32_32x32x16_bf16 v[32:47], v[52:55], v[48:51], v[32:47]
	s_waitcnt lgkmcnt(0)
	v_mfma_f32_32x32x16_bf16 v[16:31], v[56:59], v[48:51], v[16:31]

; DI float bflo(unsigned v) { return __uint_as_float(v << 16); }
; DI float bfhi(unsigned v) { return __uint_as_float(v & 0xffff0000u); }
; DI float silu(float g) { return g * __builtin_amdgcn_rcpf(1.f + ex2(-g * LOG2E)); }
; DI void store_y(const f32x16& oa, const f32x16& ob, float mult, const float* sg, const u32x2 (&gv)[8], u16* yrow0, float* stg,
;                 int lane, int r, int h) {
; #pragma unroll
;   for (int dt = 0; dt < 2; ++dt)
; #pragma unroll
;     for (int g = 0; g < 4; ++g) {
;       f32x4 v;
;       v[0] = (dt ? ob[4 * g] : oa[4 * g]) * mult; v[1] = (dt ? ob[4 * g + 1] : oa[4 * g + 1]) * mult;
;       v[2] = (dt ? ob[4 * g + 2] : oa[4 * g + 2]) * mult; v[3] = (dt ? ob[4 * g + 3] : oa[4 * g + 3]) * mult;
;       *(f32x4*)(stg + r * 68 + 32 * dt + 8 * g + 4 * h) = v;
;     }
;   const int kc = lane & 15;
;   f32x4 sv = {1.f, 1.f, 1.f, 1.f};
;   if (sg) sv = *(const f32x4*)(sg + kc * 4);
; #pragma unroll
;   for (int t = 0; t < 8; ++t) {
;     const int row = (lane >> 4) + 4 * t;
;     const f32x4 v = *(const f32x4*)(stg + row * 68 + kc * 4);
;     float y0 = v[0] * sv[0] * silu(bflo(gv[t][0]));
;     float y1 = v[1] * sv[1] * silu(bfhi(gv[t][0]));
;     float y2 = v[2] * sv[2] * silu(bflo(gv[t][1]));
;     float y3 = v[3] * sv[3] * silu(bfhi(gv[t][1]));
;     u32x2 yo = {pk2(y0, y1), pk2(y2, y3)};
;     *(u32x2*)(yrow0 + (size_t)row * DM + kc * 4) = yo;
;   }
.LBB0_246:
	s_or_b64 exec, exec, s[0:1]
	v_readlane_b32 s0, v250, 9
	v_ashrrev_i32_e32 v149, 31, v148
	v_readlane_b32 s1, v250, 10
	s_waitcnt vmcnt(2)
	v_mul_u32_u24_e32 v4, 0x110, v169
	v_lshlrev_b32_e32 v8, 16, v150
	v_lshl_add_u64 v[2:3], v[148:149], 0, s[0:1]
	v_readlane_b32 s0, v250, 13
	v_lshlrev_b64 v[2:3], 11, v[2:3]
	v_readlane_b32 s1, v250, 14
	s_waitcnt lgkmcnt(0)
	s_barrier
	v_lshl_add_u64 v[2:3], s[0:1], 0, v[2:3]
	s_movk_i32 s0, 0x2200
	v_mul_lo_u32 v0, v168, s0
	v_add3_u32 v4, v0, v4, v152
	v_lshl_or_b32 v0, v170, 2, v0
	s_movk_i32 s0, 0x110
	ds_write_b128 v4, v[32:35] offset:36864
	ds_write_b128 v4, v[36:39] offset:36896
	ds_write_b128 v4, v[40:43] offset:36928
	ds_write_b128 v4, v[44:47] offset:36960
	ds_write_b128 v4, v[16:19] offset:36992
	ds_write_b128 v4, v[20:23] offset:37024
	ds_write_b128 v4, v[24:27] offset:37056
	ds_write_b128 v4, v[28:31] offset:37088
	v_mad_u32_u24 v20, v153, s0, v0
	v_and_b32_e32 v9, 0xffff0000, v150
	v_mul_f32_e32 v0, 0xbfb8aa3b, v8
	v_exp_f32_e32 v0, v0
	v_mul_f32_e32 v4, 0xbfb8aa3b, v9
	v_exp_f32_e32 v11, v4
	v_lshlrev_b32_e32 v12, 16, v151
	v_add_f32_e32 v0, 1.0, v0
	v_rcp_f32_e32 v10, v0
	v_add_f32_e32 v0, 1.0, v11
	v_and_b32_e32 v13, 0xffff0000, v151
	v_mul_f32_e32 v11, 0xbfb8aa3b, v12
	v_exp_f32_e32 v14, v11
	v_mul_f32_e32 v11, 0xbfb8aa3b, v13
	v_exp_f32_e32 v15, v11
	v_rcp_f32_e32 v11, v0
	v_add_f32_e32 v0, 1.0, v14
	v_rcp_f32_e32 v14, v0
	v_add_f32_e32 v0, 1.0, v15
	ds_read_b128 v[4:7], v20 offset:36864
	v_rcp_f32_e32 v15, v0
	v_mul_f32_e32 v16, v10, v8
	v_mul_f32_e32 v17, v11, v9
	ds_read_b128 v[8:11], v20 offset:37952
	v_mov_b32_e32 v147, v1
	v_mul_f32_e32 v12, v14, v12
	v_mul_f32_e32 v13, v15, v13
	s_waitcnt lgkmcnt(1)
	v_mul_f32_e32 v4, v16, v4
	v_mul_f32_e32 v5, v17, v5
	v_mul_f32_e32 v6, v12, v6
	v_mul_f32_e32 v7, v13, v7
	v_cvt_pk_bf16_f32 v4, v4, v5
	v_cvt_pk_bf16_f32 v5, v6, v7
	v_lshlrev_b32_e32 v6, 16, v144
	v_and_b32_e32 v7, 0xffff0000, v144
	v_mul_f32_e32 v12, 0xbfb8aa3b, v6
	v_lshlrev_b32_e32 v16, 16, v145
	v_and_b32_e32 v17, 0xffff0000, v145
	v_exp_f32_e32 v14, v12
	v_mul_f32_e32 v12, 0xbfb8aa3b, v7
	v_mul_f32_e32 v18, 0xbfb8aa3b, v16
	v_mul_f32_e32 v19, 0xbfb8aa3b, v17
	v_exp_f32_e32 v15, v12
	v_exp_f32_e32 v18, v18
	v_exp_f32_e32 v19, v19
	v_add_f32_e32 v14, 1.0, v14
	v_add_f32_e32 v15, 1.0, v15
	v_add_f32_e32 v18, 1.0, v18
	v_add_f32_e32 v19, 1.0, v19
	v_rcp_f32_e32 v14, v14
	v_rcp_f32_e32 v15, v15
	v_rcp_f32_e32 v18, v18
	v_rcp_f32_e32 v19, v19
	v_lshl_add_u64 v[2:3], v[2:3], 0, v[146:147]
	v_lshlrev_b32_e32 v0, 11, v153
	v_lshl_add_u64 v[12:13], v[2:3], 0, v[0:1]
	global_store_dwordx2 v[12:13], v[4:5], off offset:1536
	v_mul_f32_e32 v4, v14, v6
	v_mul_f32_e32 v5, v15, v7
	v_mul_f32_e32 v6, v18, v16
	v_mul_f32_e32 v7, v19, v17
	s_waitcnt lgkmcnt(0)
	v_mul_f32_e32 v4, v4, v8
	v_mul_f32_e32 v5, v5, v9
	v_mul_f32_e32 v6, v6, v10
	v_mul_f32_e32 v7, v7, v11
	v_cvt_pk_bf16_f32 v4, v4, v5
	v_cvt_pk_bf16_f32 v5, v6, v7
	v_or_b32_e32 v6, 0x2000, v0
	v_mov_b32_e32 v7, v1
	v_lshl_add_u64 v[6:7], v[2:3], 0, v[6:7]
	v_lshlrev_b32_e32 v8, 16, v142
	global_store_dwordx2 v[6:7], v[4:5], off offset:1536
	v_and_b32_e32 v9, 0xffff0000, v142
	v_mul_f32_e32 v4, 0xbfb8aa3b, v8
	v_lshlrev_b32_e32 v12, 16, v143
	v_and_b32_e32 v13, 0xffff0000, v143
	v_exp_f32_e32 v10, v4
	v_mul_f32_e32 v4, 0xbfb8aa3b, v9
	v_mul_f32_e32 v14, 0xbfb8aa3b, v12
	v_mul_f32_e32 v15, 0xbfb8aa3b, v13
	v_exp_f32_e32 v11, v4
	v_exp_f32_e32 v14, v14
	v_exp_f32_e32 v15, v15
	v_add_f32_e32 v10, 1.0, v10
	v_add_f32_e32 v11, 1.0, v11
	v_add_f32_e32 v14, 1.0, v14
	v_add_f32_e32 v15, 1.0, v15
	ds_read_b128 v[4:7], v20 offset:39040
	v_rcp_f32_e32 v10, v10
	v_rcp_f32_e32 v11, v11
	v_rcp_f32_e32 v14, v14
	v_rcp_f32_e32 v15, v15
	v_mul_f32_e32 v16, v10, v8
	v_mul_f32_e32 v17, v11, v9
	s_waitcnt lgkmcnt(0)
	v_mul_f32_e32 v4, v16, v4
	v_mul_f32_e32 v5, v17, v5
	v_mul_f32_e32 v12, v14, v12
	v_mul_f32_e32 v13, v15, v13
	v_lshlrev_b32_e32 v16, 16, v141
	v_mul_f32_e32 v6, v12, v6
	v_mul_f32_e32 v7, v13, v7
	v_lshlrev_b32_e32 v12, 16, v140
	v_and_b32_e32 v13, 0xffff0000, v140
	v_and_b32_e32 v17, 0xffff0000, v141
	v_mul_f32_e32 v14, 0xbfb8aa3b, v12
	v_mul_f32_e32 v15, 0xbfb8aa3b, v13
	v_mul_f32_e32 v18, 0xbfb8aa3b, v16
	v_mul_f32_e32 v19, 0xbfb8aa3b, v17
	v_exp_f32_e32 v14, v14
	v_exp_f32_e32 v15, v15
	v_exp_f32_e32 v18, v18
	v_exp_f32_e32 v19, v19
	v_add_f32_e32 v14, 1.0, v14
	v_add_f32_e32 v15, 1.0, v15
	v_add_f32_e32 v18, 1.0, v18
	v_add_f32_e32 v19, 1.0, v19
	ds_read_b128 v[8:11], v20 offset:40128
	v_rcp_f32_e32 v14, v14
	v_rcp_f32_e32 v15, v15
	v_rcp_f32_e32 v18, v18
	v_rcp_f32_e32 v19, v19
	v_cvt_pk_bf16_f32 v4, v4, v5
	v_cvt_pk_bf16_f32 v5, v6, v7
	v_or_b32_e32 v6, 0x4000, v0
	v_mov_b32_e32 v7, v1
	v_lshl_add_u64 v[6:7], v[2:3], 0, v[6:7]
	global_store_dwordx2 v[6:7], v[4:5], off offset:1536
	v_mul_f32_e32 v4, v14, v12
	v_mul_f32_e32 v5, v15, v13
	v_mul_f32_e32 v6, v18, v16
	v_mul_f32_e32 v7, v19, v17
	s_waitcnt lgkmcnt(0)
; DI float bflo(unsigned v) { return __uint_as_float(v << 16); }
; DI float bfhi(unsigned v) { return __uint_as_float(v & 0xffff0000u); }
; DI float silu(float g) { return g * __builtin_amdgcn_rcpf(1.f + ex2(-g * LOG2E)); }
; DI void store_y(const f32x16& oa, const f32x16& ob, float mult, const float* sg, const u32x2 (&gv)[8], u16* yrow0, float* stg,
;                 int lane, int r, int h) {
;     ...
; #pragma unroll
;   for (int t = 0; t < 8; ++t) {
;     const int row = (lane >> 4) + 4 * t;
;     const f32x4 v = *(const f32x4*)(stg + row * 68 + kc * 4);
;     float y0 = v[0] * sv[0] * silu(bflo(gv[t][0]));
;     float y1 = v[1] * sv[1] * silu(bfhi(gv[t][0]));
;     float y2 = v[2] * sv[2] * silu(bflo(gv[t][1]));
;     float y3 = v[3] * sv[3] * silu(bfhi(gv[t][1]));
;     u32x2 yo = {pk2(y0, y1), pk2(y2, y3)};
;     *(u32x2*)(yrow0 + (size_t)row * DM + kc * 4) = yo;
;   }
	v_mul_f32_e32 v4, v4, v8
	v_mul_f32_e32 v5, v5, v9
	v_mul_f32_e32 v6, v6, v10
	v_mul_f32_e32 v7, v7, v11
	v_cvt_pk_bf16_f32 v4, v4, v5
	v_cvt_pk_bf16_f32 v5, v6, v7
	v_or_b32_e32 v6, 0x6000, v0
	v_mov_b32_e32 v7, v1
	v_lshl_add_u64 v[6:7], v[2:3], 0, v[6:7]
	v_lshlrev_b32_e32 v8, 16, v138
	global_store_dwordx2 v[6:7], v[4:5], off offset:1536
	v_and_b32_e32 v9, 0xffff0000, v138
	v_mul_f32_e32 v4, 0xbfb8aa3b, v8
	v_lshlrev_b32_e32 v12, 16, v139
	v_and_b32_e32 v13, 0xffff0000, v139
	v_exp_f32_e32 v10, v4
	v_mul_f32_e32 v4, 0xbfb8aa3b, v9
	v_mul_f32_e32 v14, 0xbfb8aa3b, v12
	v_mul_f32_e32 v15, 0xbfb8aa3b, v13
	v_exp_f32_e32 v11, v4
	v_exp_f32_e32 v14, v14
	v_exp_f32_e32 v15, v15
	v_add_f32_e32 v10, 1.0, v10
	v_add_f32_e32 v11, 1.0, v11
	v_add_f32_e32 v14, 1.0, v14
	v_add_f32_e32 v15, 1.0, v15
	ds_read_b128 v[4:7], v20 offset:41216
	v_rcp_f32_e32 v10, v10
	v_rcp_f32_e32 v11, v11
	v_rcp_f32_e32 v14, v14
	v_rcp_f32_e32 v15, v15
	v_mul_f32_e32 v16, v10, v8
	v_mul_f32_e32 v17, v11, v9
	s_waitcnt lgkmcnt(0)
	v_mul_f32_e32 v4, v16, v4
	v_mul_f32_e32 v5, v17, v5
	v_mul_f32_e32 v12, v14, v12
	v_mul_f32_e32 v13, v15, v13
	v_lshlrev_b32_e32 v16, 16, v137
	v_mul_f32_e32 v6, v12, v6
	v_mul_f32_e32 v7, v13, v7
	v_lshlrev_b32_e32 v12, 16, v136
	v_and_b32_e32 v13, 0xffff0000, v136
	v_and_b32_e32 v17, 0xffff0000, v137
	v_mul_f32_e32 v14, 0xbfb8aa3b, v12
	v_mul_f32_e32 v15, 0xbfb8aa3b, v13
	v_mul_f32_e32 v18, 0xbfb8aa3b, v16
	v_mul_f32_e32 v19, 0xbfb8aa3b, v17
	v_exp_f32_e32 v14, v14
	v_exp_f32_e32 v15, v15
	v_exp_f32_e32 v18, v18
	v_exp_f32_e32 v19, v19
	v_add_f32_e32 v14, 1.0, v14
	v_add_f32_e32 v15, 1.0, v15
	v_add_f32_e32 v18, 1.0, v18
	v_add_f32_e32 v19, 1.0, v19
	ds_read_b128 v[8:11], v20 offset:42304
	v_rcp_f32_e32 v14, v14
	v_rcp_f32_e32 v15, v15
	v_rcp_f32_e32 v18, v18
	v_rcp_f32_e32 v19, v19
	v_cvt_pk_bf16_f32 v4, v4, v5
	v_cvt_pk_bf16_f32 v5, v6, v7
	v_or_b32_e32 v6, 0x8000, v0
	v_mov_b32_e32 v7, v1
	v_lshl_add_u64 v[6:7], v[2:3], 0, v[6:7]
	global_store_dwordx2 v[6:7], v[4:5], off offset:1536
	v_mul_f32_e32 v4, v14, v12
	v_mul_f32_e32 v5, v15, v13
	v_mul_f32_e32 v6, v18, v16
	v_mul_f32_e32 v7, v19, v17
	s_waitcnt lgkmcnt(0)
	v_mul_f32_e32 v4, v4, v8
	v_mul_f32_e32 v5, v5, v9
	v_mul_f32_e32 v6, v6, v10
	v_mul_f32_e32 v7, v7, v11
	v_cvt_pk_bf16_f32 v4, v4, v5
	v_cvt_pk_bf16_f32 v5, v6, v7
	v_or_b32_e32 v6, 0xa000, v0
	v_mov_b32_e32 v7, v1
	v_lshl_add_u64 v[6:7], v[2:3], 0, v[6:7]
	s_waitcnt vmcnt(6)
	v_lshlrev_b32_e32 v8, 16, v134
	global_store_dwordx2 v[6:7], v[4:5], off offset:1536
	v_and_b32_e32 v9, 0xffff0000, v134
	v_mul_f32_e32 v4, 0xbfb8aa3b, v8
	v_lshlrev_b32_e32 v12, 16, v135
	v_and_b32_e32 v13, 0xffff0000, v135
	v_exp_f32_e32 v10, v4
	v_mul_f32_e32 v4, 0xbfb8aa3b, v9
	v_mul_f32_e32 v14, 0xbfb8aa3b, v12
	v_mul_f32_e32 v15, 0xbfb8aa3b, v13
	v_exp_f32_e32 v11, v4
	v_exp_f32_e32 v14, v14
	v_exp_f32_e32 v15, v15
	v_add_f32_e32 v10, 1.0, v10
	v_add_f32_e32 v11, 1.0, v11
	v_add_f32_e32 v14, 1.0, v14
	v_add_f32_e32 v15, 1.0, v15
	ds_read_b128 v[4:7], v20 offset:43392
	v_rcp_f32_e32 v10, v10
	v_rcp_f32_e32 v11, v11
	v_rcp_f32_e32 v14, v14
	v_rcp_f32_e32 v15, v15
	v_mul_f32_e32 v16, v10, v8
	v_mul_f32_e32 v17, v11, v9
	s_waitcnt lgkmcnt(0)
	v_mul_f32_e32 v4, v16, v4
	v_mul_f32_e32 v5, v17, v5
	v_mul_f32_e32 v12, v14, v12
	v_mul_f32_e32 v13, v15, v13
	s_waitcnt vmcnt(6)
	v_lshlrev_b32_e32 v16, 16, v133
	v_mul_f32_e32 v6, v12, v6
	v_mul_f32_e32 v7, v13, v7
	v_lshlrev_b32_e32 v12, 16, v132
	v_and_b32_e32 v13, 0xffff0000, v132
	v_and_b32_e32 v17, 0xffff0000, v133
	v_mul_f32_e32 v14, 0xbfb8aa3b, v12
	v_mul_f32_e32 v15, 0xbfb8aa3b, v13
	v_mul_f32_e32 v18, 0xbfb8aa3b, v16
	v_mul_f32_e32 v19, 0xbfb8aa3b, v17
	v_exp_f32_e32 v14, v14
	v_exp_f32_e32 v15, v15
	v_exp_f32_e32 v18, v18
	v_exp_f32_e32 v19, v19
	v_add_f32_e32 v14, 1.0, v14
	v_add_f32_e32 v15, 1.0, v15
	v_add_f32_e32 v18, 1.0, v18
	v_add_f32_e32 v19, 1.0, v19
	ds_read_b128 v[8:11], v20 offset:44480
	v_rcp_f32_e32 v14, v14
	v_rcp_f32_e32 v15, v15
	v_rcp_f32_e32 v18, v18
	v_rcp_f32_e32 v19, v19
	v_cvt_pk_bf16_f32 v4, v4, v5
	v_cvt_pk_bf16_f32 v5, v6, v7
	v_or_b32_e32 v6, 0xc000, v0
	v_mov_b32_e32 v7, v1
	v_lshl_add_u64 v[6:7], v[2:3], 0, v[6:7]
	global_store_dwordx2 v[6:7], v[4:5], off offset:1536
	v_mul_f32_e32 v4, v14, v12
	v_mul_f32_e32 v5, v15, v13
	v_mul_f32_e32 v6, v18, v16
	v_mul_f32_e32 v7, v19, v17
	s_waitcnt lgkmcnt(0)
	v_mul_f32_e32 v4, v4, v8
	v_mul_f32_e32 v5, v5, v9
	v_mul_f32_e32 v6, v6, v10
	v_mul_f32_e32 v7, v7, v11
	v_or_b32_e32 v0, 0xe000, v0
	v_cvt_pk_bf16_f32 v4, v4, v5
	v_cvt_pk_bf16_f32 v5, v6, v7
	v_lshl_add_u64 v[2:3], v[2:3], 0, v[0:1]
	global_store_dwordx2 v[2:3], v[4:5], off offset:1536

; DI f32x16 mfma(bf16x8 a, bf16x8 b, f32x16 c) { return __builtin_amdgcn_mfma_f32_32x32x16_bf16(a, b, c, 0, 0, 0); }
; DI void diff_softmax_pv(const bf16x8 (&qf)[4], const u16* Ks, const u16* Vs, float& m, f32x4& ls0, f32x4& ls1, bf16x8 ones,
;                         f32x16 (&o)[2][2], float sl2, int dl, bool need_mask, bool first, int r, int h, int rs, const int (&lo)[4]) {
;     ...
;   const float nb = -sl2 * (float)dl - m;
; #pragma unroll
;   for (int i = 0; i < 16; ++i) {
;     const int ci = (i & 3) + 8 * (i >> 2);
;     b0[i] = fmaf(sl2, (float)ci, nb);
;     b1[i] = fmaf(sl2, (float)(ci + 32), nb);
;   }
;   {
;     __builtin_amdgcn_s_setprio(1);
;     f32x16 s0 = mfma(ldsv(Ks + lo[0]), qf[0], b0);
;     f32x16 s1 = mfma(ldsv(Ks + 32 * rs + lo[0]), qf[0], b1);
;     s0 = mfma(ldsv(Ks + lo[1]), qf[1], s0);
;     s1 = mfma(ldsv(Ks + 32 * rs + lo[1]), qf[1], s1);
;     __builtin_amdgcn_s_setprio(0);
;     if (need_mask) mask_causal(s0, s1, dl);
; DI void attn_item_A(const Params& p, int layer, int b, int head, int qb, u16* sm, float lam, float lam_init, int wv) {
;     ...
;   int lo[4];
; #pragma unroll
;   for (int c = 0; c < 4; ++c) lo[c] = r * 64 + (((2 * c + h) ^ ((r >> 1) & 7)) * 8);
;   const int t7 = tid & 127, wp = t7 >> 6;
;   const int csrc = (lane & 7) ^ ((4 * wp + (lane >> 4)) & 7);
;   const int row0 = wp * 8 + (lane >> 3);
;   const u16* kg = projb + koff + csrc * 8;
;   const u16* vg = p.vt + ((size_t)(b * NVH + vh) * 64) * SEQ + csrc * 8;
;   float zf = 0.f;
;   asm volatile("" : "+v"(zf));
;   f32x16 o[2][2];
; #pragma unroll
;   for (int a = 0; a < 2; ++a)
; #pragma unroll
;     for (int d = 0; d < 2; ++d)
; #pragma unroll
;       for (int e = 0; e < 16; ++e) o[a][d][e] = zf;
;   float m0 = 0.f, m1 = 0.f;
;   f32x4 ls0 = {zf, zf, zf, zf}, ls1 = {zf, zf, zf, zf};
;   const bf16x8 ones = rowsum_ones(lane);
.LBB0_259:
	s_or_b64 exec, exec, s[2:3]
	v_lshlrev_b32_e32 v18, 7, v73
	v_lshlrev_b32_e32 v125, 2, v171
	v_lshrrev_b32_e32 v19, 1, v175
	v_bitop3_b32 v181, v18, s95, v125 bitop3:0x36
	v_bitop3_b32 v182, v18, 64, v125 bitop3:0x36
	v_lshlrev_b32_e32 v18, 6, v171
	v_bfe_u32 v20, v175, 1, 3
	v_bitop3_b32 v19, v73, v19, 7 bitop3:0x78
	v_lshl_or_b32 v183, v19, 3, v18
	v_bitop3_b32 v19, v73, v20, 2 bitop3:0x36
	v_lshl_or_b32 v184, v19, 3, v18
	v_bitop3_b32 v19, v73, v20, 4 bitop3:0x36
	v_lshl_or_b32 v185, v19, 3, v18
	v_bitop3_b32 v19, v73, v20, 6 bitop3:0x36
	v_lshl_or_b32 v186, v19, 3, v18
	v_and_b32_e32 v18, 15, v175
	v_and_b32_e32 v19, 1, v170
	v_cmp_eq_u32_e64 s[2:3], v18, v19
	v_mov_b64_e32 v[156:157], v[152:153]
	v_mov_b64_e32 v[48:49], v[16:17]
	v_cndmask_b32_e64 v146, 0, v201, s[2:3]
	v_mov_b64_e32 v[64:65], v[16:17]
	v_mov_b64_e32 v[32:33], v[16:17]
	v_lshlrev_b32_e32 v124, 2, v73
	v_mov_b32_e32 v147, v146
	v_mov_b32_e32 v148, v146
	v_mov_b32_e32 v149, v146
	v_mov_b32_e32 v204, 0
	v_mov_b64_e32 v[154:155], v[150:151]
	v_mov_b64_e32 v[46:47], v[14:15]
	v_mov_b64_e32 v[44:45], v[12:13]
	v_mov_b64_e32 v[42:43], v[10:11]
	v_mov_b64_e32 v[40:41], v[8:9]
	v_mov_b64_e32 v[38:39], v[6:7]
	v_mov_b64_e32 v[36:37], v[4:5]
	v_mov_b64_e32 v[34:35], v[2:3]
	v_mov_b64_e32 v[62:63], v[14:15]
	v_mov_b64_e32 v[60:61], v[12:13]
	v_mov_b64_e32 v[58:59], v[10:11]
	v_mov_b64_e32 v[56:57], v[8:9]
	v_mov_b64_e32 v[54:55], v[6:7]
	v_mov_b64_e32 v[52:53], v[4:5]
	v_mov_b64_e32 v[50:51], v[2:3]
	v_mov_b64_e32 v[30:31], v[14:15]
	v_mov_b64_e32 v[28:29], v[12:13]
	v_mov_b64_e32 v[26:27], v[10:11]
	v_mov_b64_e32 v[24:25], v[8:9]
	v_mov_b64_e32 v[22:23], v[6:7]
	v_mov_b64_e32 v[20:21], v[4:5]
	v_mov_b64_e32 v[18:19], v[2:3]
	s_and_saveexec_b64 s[18:19], s[4:5]
	s_cbranch_execz .LBB0_276
	v_or_b32_e32 v3, v124, v66
	v_sub_u32_e32 v126, v72, v3
	v_cvt_f32_i32_e32 v3, v126
	s_mov_b32 s2, 2.0
	s_mov_b32 s3, 0x40400000
	v_cmp_eq_u32_e64 s[36:37], v74, v119
	v_mul_f32_e64 v4, -v178, v3
	v_fma_f32 v52, v178, s2, v4
	v_fma_f32 v53, v179, s3, v4
	s_mov_b32 s2, 0x41000000
	s_mov_b32 s3, 0x41100000
	v_fma_f32 v54, v178, s2, v4
	v_fma_f32 v55, v179, s3, v4
	s_mov_b32 s2, 0x41200000
	s_mov_b32 s3, 0x41300000
	v_fma_f32 v56, v178, s2, v4
	v_fma_f32 v57, v179, s3, v4
	s_mov_b32 s2, 0x41800000
	s_mov_b32 s3, 0x41880000
	v_fma_f32 v58, v178, s2, v4
	v_fma_f32 v59, v179, s3, v4
	s_mov_b32 s2, 0x42400000
	s_mov_b32 s3, 0x42440000
	v_fma_f32 v74, v178, s2, v4
	v_fma_f32 v75, v179, s3, v4
	s_mov_b32 s2, 0x41900000
	s_mov_b32 s3, 0x41980000
	v_fma_f32 v60, v178, s2, v4
	v_fma_f32 v61, v179, s3, v4
	s_mov_b32 s2, 0x42680000
	s_mov_b32 s3, 0x426c0000
	v_fma_f32 v51, -v178, v3, v178
	v_fma_f32 v50, 0, v178, v4
	v_fma_f32 v66, v178, s78, v4
	v_fma_f32 v67, v179, s79, v4
	v_fma_f32 v68, v178, s76, v4
	v_fma_f32 v69, v179, s77, v4
	v_fma_f32 v70, v178, s74, v4
	v_fma_f32 v71, v179, s75, v4
	v_fma_f32 v72, v178, s72, v4
	v_fma_f32 v73, v179, s73, v4
	v_fma_f32 v76, v178, s10, v4
	v_fma_f32 v77, v179, s11, v4
	v_fma_f32 v62, v178, s50, v4
	v_fma_f32 v63, v179, s51, v4
	v_fma_f32 v78, v178, s30, v4
	v_fma_f32 v79, v179, s31, v4
	v_fma_f32 v64, v178, s28, v4
	v_fma_f32 v65, v179, s29, v4
	v_fma_f32 v80, v178, s2, v4
	v_fma_f32 v81, v179, s3, v4
	s_setprio 1
	v_lshl_add_u32 v3, v183, 1, v176
	ds_read_b128 v[4:7], v3
	v_mov_b64_e32 v[34:35], v[50:51]
	v_mov_b64_e32 v[36:37], v[52:53]
	v_mov_b64_e32 v[38:39], v[54:55]
	v_mov_b64_e32 v[40:41], v[56:57]
	v_mov_b64_e32 v[42:43], v[58:59]
	v_mov_b64_e32 v[44:45], v[60:61]
	v_mov_b64_e32 v[46:47], v[62:63]
	v_mov_b64_e32 v[48:49], v[64:65]
	v_lshl_add_u32 v102, v184, 1, v176
	s_waitcnt lgkmcnt(0)
	v_mfma_f32_32x32x16_bf16 v[34:49], v[4:7], v[130:133], v[34:49]
	ds_read_b128 v[4:7], v3 offset:4096
	s_waitcnt lgkmcnt(0)
	v_mfma_f32_32x32x16_bf16 v[82:97], v[4:7], v[130:133], v[66:81]
	ds_read_b128 v[4:7], v102
	s_waitcnt lgkmcnt(0)
	v_mfma_f32_32x32x16_bf16 v[34:49], v[4:7], v[134:137], v[34:49]
	ds_read_b128 v[4:7], v102 offset:4096
	s_waitcnt lgkmcnt(0)
	v_mfma_f32_32x32x16_bf16 v[82:97], v[4:7], v[134:137], v[82:97]
	s_setprio 0
	s_and_saveexec_b64 s[38:39], s[36:37]
	s_cbranch_execz .LBB0_262
	v_cmp_lt_i32_e64 s[2:3], -1, v126
	s_nop 4
	v_cndmask_b32_e64 v34, v199, v34, s[2:3]
	v_cmp_lt_i32_e64 s[2:3], 31, v126
	s_nop 1
	v_cndmask_b32_e64 v82, v199, v82, s[2:3]
	v_cmp_lt_i32_e64 s[2:3], 0, v126
	s_nop 1
	v_cndmask_b32_e64 v35, v199, v35, s[2:3]
	v_cmp_lt_i32_e64 s[2:3], 32, v126
	s_nop 1
	v_cndmask_b32_e64 v83, v199, v83, s[2:3]
	v_cmp_lt_i32_e64 s[2:3], 1, v126
	s_nop 1
	v_cndmask_b32_e64 v36, v199, v36, s[2:3]
	v_cmp_lt_i32_e64 s[2:3], 33, v126
	s_nop 1
	v_cndmask_b32_e64 v84, v199, v84, s[2:3]
	v_cmp_lt_i32_e64 s[2:3], 2, v126
	s_nop 1
	v_cndmask_b32_e64 v37, v199, v37, s[2:3]
	v_cmp_lt_i32_e64 s[2:3], 34, v126
	s_nop 1
	v_cndmask_b32_e64 v85, v199, v85, s[2:3]
	v_cmp_lt_i32_e64 s[2:3], 7, v126
	s_nop 1
	v_cndmask_b32_e64 v38, v199, v38, s[2:3]
	v_cmp_lt_i32_e64 s[2:3], 39, v126
	s_nop 1
	v_cndmask_b32_e64 v86, v199, v86, s[2:3]
	v_cmp_lt_i32_e64 s[2:3], 8, v126
	s_nop 1
	v_cndmask_b32_e64 v39, v199, v39, s[2:3]
	v_cmp_lt_i32_e64 s[2:3], 40, v126
	s_nop 1
	v_cndmask_b32_e64 v87, v199, v87, s[2:3]
	v_cmp_lt_i32_e64 s[2:3], 9, v126
	s_nop 1
	v_cndmask_b32_e64 v40, v199, v40, s[2:3]
	v_cmp_lt_i32_e64 s[2:3], 41, v126
	s_nop 1
	v_cndmask_b32_e64 v88, v199, v88, s[2:3]
	v_cmp_lt_i32_e64 s[2:3], 10, v126
	s_nop 1
	v_cndmask_b32_e64 v41, v199, v41, s[2:3]
	v_cmp_lt_i32_e64 s[2:3], 42, v126
	s_nop 1
	v_cndmask_b32_e64 v89, v199, v89, s[2:3]
	v_cmp_lt_i32_e64 s[2:3], 15, v126
	s_nop 1
	v_cndmask_b32_e64 v42, v199, v42, s[2:3]
	v_cmp_lt_i32_e64 s[2:3], 47, v126
	s_nop 1
	v_cndmask_b32_e64 v90, v199, v90, s[2:3]
	v_cmp_lt_i32_e64 s[2:3], 16, v126
	s_nop 1
	v_cndmask_b32_e64 v43, v199, v43, s[2:3]
	v_cmp_lt_i32_e64 s[2:3], 48, v126
	s_nop 1
	v_cndmask_b32_e64 v91, v199, v91, s[2:3]
	v_cmp_lt_i32_e64 s[2:3], 17, v126
	s_nop 1
	v_cndmask_b32_e64 v44, v199, v44, s[2:3]
	v_cmp_lt_i32_e64 s[2:3], 49, v126
	s_nop 1
	v_cndmask_b32_e64 v92, v199, v92, s[2:3]
	v_cmp_lt_i32_e64 s[2:3], 18, v126
	s_nop 1
	v_cndmask_b32_e64 v45, v199, v45, s[2:3]
	v_cmp_lt_i32_e64 s[2:3], 50, v126
	s_nop 1
	v_cndmask_b32_e64 v93, v199, v93, s[2:3]
	v_cmp_lt_i32_e64 s[2:3], 23, v126
	s_nop 1
	v_cndmask_b32_e64 v46, v199, v46, s[2:3]
	v_cmp_lt_i32_e64 s[2:3], 55, v126
	s_nop 1
	v_cndmask_b32_e64 v94, v199, v94, s[2:3]
	v_cmp_lt_i32_e64 s[2:3], 24, v126
	s_nop 1
	v_cndmask_b32_e64 v47, v199, v47, s[2:3]
	v_cmp_lt_i32_e64 s[2:3], 56, v126
	s_nop 1
	v_cndmask_b32_e64 v95, v199, v95, s[2:3]
	v_cmp_lt_i32_e64 s[2:3], 25, v126
	s_nop 1
	v_cndmask_b32_e64 v48, v199, v48, s[2:3]
	v_cmp_lt_i32_e64 s[2:3], 57, v126
	s_nop 1
	v_cndmask_b32_e64 v96, v199, v96, s[2:3]
	v_cmp_lt_i32_e64 s[2:3], 26, v126
	s_nop 1
	v_cndmask_b32_e64 v49, v199, v49, s[2:3]
	v_cmp_lt_i32_e64 s[2:3], 58, v126
	s_nop 1
	v_cndmask_b32_e64 v97, v199, v97, s[2:3]
; DI float ex2(float x) { return __builtin_amdgcn_exp2f(x); }
; DI float lg2(float x) { return __builtin_amdgcn_logf(x); }
; DI void diff_softmax_pv(const bf16x8 (&qf)[4], const u16* Ks, const u16* Vs, float& m, f32x4& ls0, f32x4& ls1, bf16x8 ones,
;                         f32x16 (&o)[2][2], float sl2, int dl, bool need_mask, bool first, int r, int h, int rs, const int (&lo)[4]) {
;     ...
;     if (__any(first || !(ls0[0] <= 1.0e12f) || !(ls0[1] <= 1.0e12f) || !(ls1[0] <= 1.0e12f) || !(ls1[1] <= 1.0e12f))) {
;       float tmax = -INFINITY;
; #pragma unroll
;       for (int i = 0; i < 16; ++i) tmax = fmaxf(tmax, fmaxf(s0[i], s1[i]));
;       tmax = fmaxf(tmax, shx(tmax, r + 32 * h));
;       const float lmx = fmaxf(own_rowsum(ls0, r), own_rowsum(ls1, r));
;       const float lref = (lmx > 1.f) ? lg2(lmx) : 0.f;
;       const float delta = first ? tmax : fmaxf(fmaxf(tmax, lref), 0.f);
;       m += delta;
;       const float alpha = ex2(-delta);
;       const float alpha_hi = shx(alpha, r + 32 * h, 16);
;       ls0[0] *= alpha; ls0[1] *= alpha_hi; ls1[0] *= alpha; ls1[1] *= alpha_hi;
; #pragma unroll
;       for (int e = 0; e < 16; ++e) {
;         o[0][0][e] *= alpha; o[0][1][e] *= alpha; o[1][0][e] *= alpha; o[1][1][e] *= alpha;
;         s0[e] -= delta; s1[e] -= delta; b0[e] -= delta; b1[e] -= delta;
;       }
;     }
.LBB0_262:
	s_or_b64 exec, exec, s[38:39]
	s_cmp_eq_u64 exec, 0
	s_cbranch_scc1 .LBB0_272
	s_nop 5
	v_max_f32_e32 v4, v82, v82
	v_max_f32_e32 v5, v34, v34
	v_max_f32_e32 v4, v5, v4
	v_max_f32_e32 v5, v83, v83
	v_max_f32_e32 v6, v35, v35
	v_max_f32_e32 v5, v6, v5
	s_mov_b32 s2, 0xff800000
	v_max3_f32 v4, v4, s2, v5
	v_max_f32_e32 v5, v84, v84
	v_max_f32_e32 v6, v36, v36
	v_max_f32_e32 v5, v6, v5
	v_max_f32_e32 v6, v85, v85
	v_max_f32_e32 v7, v37, v37
	v_max_f32_e32 v6, v7, v6
	v_max3_f32 v4, v4, v5, v6
	v_max_f32_e32 v5, v86, v86
	v_max_f32_e32 v6, v38, v38
	v_max_f32_e32 v5, v6, v5
	v_max_f32_e32 v6, v87, v87
	v_max_f32_e32 v7, v39, v39
	v_max_f32_e32 v6, v7, v6
	v_max3_f32 v4, v4, v5, v6
	v_max_f32_e32 v5, v88, v88
	v_max_f32_e32 v6, v40, v40
	v_max_f32_e32 v5, v6, v5
	v_max_f32_e32 v6, v89, v89
	v_max_f32_e32 v7, v41, v41
	v_max_f32_e32 v6, v7, v6
	v_max3_f32 v4, v4, v5, v6
	v_max_f32_e32 v5, v90, v90
	v_max_f32_e32 v6, v42, v42
	v_max_f32_e32 v5, v6, v5
	v_max_f32_e32 v6, v91, v91
	v_max_f32_e32 v7, v43, v43
	v_max_f32_e32 v6, v7, v6
	v_max3_f32 v4, v4, v5, v6
	v_max_f32_e32 v5, v92, v92
	v_max_f32_e32 v6, v44, v44
	v_max_f32_e32 v5, v6, v5
	v_max_f32_e32 v6, v93, v93
	v_max_f32_e32 v7, v45, v45
	v_max_f32_e32 v6, v7, v6
	v_max3_f32 v4, v4, v5, v6
	v_max_f32_e32 v5, v94, v94
	v_max_f32_e32 v6, v46, v46
	v_max_f32_e32 v5, v6, v5
	v_max_f32_e32 v6, v95, v95
	v_max_f32_e32 v7, v47, v47
	v_max_f32_e32 v6, v7, v6
	v_max3_f32 v4, v4, v5, v6
	v_max_f32_e32 v5, v96, v96
	v_max_f32_e32 v6, v48, v48
	v_max_f32_e32 v5, v6, v5
	v_max_f32_e32 v6, v97, v97
	v_max_f32_e32 v7, v49, v49
	v_max_f32_e32 v6, v7, v6
	v_max3_f32 v4, v4, v5, v6
	ds_bpermute_b32 v5, v181, v4
	v_mov_b32_e32 v100, v152
	v_mov_b32_e32 v101, v153
	s_waitcnt lgkmcnt(0)
	v_max_f32_e32 v5, v5, v5
	v_max_f32_e32 v6, v4, v5
	v_exp_f32_e64 v4, -v6
	v_add_f32_e32 v204, 0, v6
	v_sub_f32_e32 v49, v49, v6
	v_sub_f32_e32 v48, v48, v6
	ds_bpermute_b32 v5, v182, v4
	v_mul_f32_e32 v18, v2, v4
	v_sub_f32_e32 v47, v47, v6
	v_sub_f32_e32 v46, v46, v6
	v_sub_f32_e32 v45, v45, v6
	s_waitcnt lgkmcnt(0)
	v_mul_f32_e32 v150, v150, v4
	v_mul_f32_e32 v151, v151, v5
	v_sub_f32_e32 v44, v44, v6
	v_sub_f32_e32 v43, v43, v6
	v_sub_f32_e32 v42, v42, v6
	v_sub_f32_e32 v41, v41, v6
	v_sub_f32_e32 v40, v40, v6
	v_sub_f32_e32 v39, v39, v6
	v_sub_f32_e32 v38, v38, v6
	v_sub_f32_e32 v37, v37, v6
	v_sub_f32_e32 v36, v36, v6
	v_sub_f32_e32 v35, v35, v6
	v_sub_f32_e32 v34, v34, v6
	v_sub_f32_e32 v97, v97, v6
	v_sub_f32_e32 v96, v96, v6
	v_sub_f32_e32 v95, v95, v6
	v_sub_f32_e32 v94, v94, v6
	v_sub_f32_e32 v93, v93, v6
	v_sub_f32_e32 v92, v92, v6
	v_sub_f32_e32 v91, v91, v6
	v_sub_f32_e32 v90, v90, v6
	v_sub_f32_e32 v89, v89, v6
	v_sub_f32_e32 v88, v88, v6
	v_sub_f32_e32 v87, v87, v6
	v_sub_f32_e32 v86, v86, v6
	v_sub_f32_e32 v85, v85, v6
	v_sub_f32_e32 v84, v84, v6
	v_sub_f32_e32 v83, v83, v6
	v_sub_f32_e32 v82, v82, v6
	v_sub_f32_e32 v65, v65, v6
	v_sub_f32_e32 v64, v64, v6
	v_sub_f32_e32 v63, v63, v6
	v_sub_f32_e32 v62, v62, v6
	v_sub_f32_e32 v61, v61, v6
	v_sub_f32_e32 v60, v60, v6
	v_sub_f32_e32 v59, v59, v6
	v_sub_f32_e32 v58, v58, v6
	v_sub_f32_e32 v57, v57, v6
	v_sub_f32_e32 v56, v56, v6
	v_sub_f32_e32 v55, v55, v6
	v_sub_f32_e32 v54, v54, v6
	v_sub_f32_e32 v53, v53, v6
	v_sub_f32_e32 v52, v52, v6
	v_sub_f32_e32 v51, v51, v6
	v_sub_f32_e32 v50, v50, v6
	v_sub_f32_e32 v66, v66, v6
	v_sub_f32_e32 v67, v67, v6
	v_sub_f32_e32 v68, v68, v6
	v_sub_f32_e32 v69, v69, v6
	v_sub_f32_e32 v70, v70, v6
	v_sub_f32_e32 v71, v71, v6
	v_sub_f32_e32 v72, v72, v6
	v_sub_f32_e32 v73, v73, v6
	v_sub_f32_e32 v74, v74, v6
	v_sub_f32_e32 v75, v75, v6
	v_sub_f32_e32 v76, v76, v6
	v_sub_f32_e32 v77, v77, v6
	v_sub_f32_e32 v78, v78, v6
	v_sub_f32_e32 v79, v79, v6
	v_sub_f32_e32 v80, v80, v6
	v_sub_f32_e32 v81, v81, v6
	v_mov_b32_e32 v19, v18
	v_mov_b32_e32 v98, v150
	v_mov_b32_e32 v99, v151
	s_branch .LBB0_273

; DI void attn_item_B2(const Params& p, int layer, int b, int head0, int qblk, u16* sm, int wv) {
;     ...
;     __syncthreads();
; #pragma unroll
;     for (int c = 0; c < 4; ++c) {
;       if (c >= it0) {
; #pragma unroll
;         for (int i = 0; i < 2; ++i) {
;           *(u32x4*)(Ks + c * (2 * 64 * LSTR) + loff + i * 32 * LSTR) = rk[c][i];
;           *(u32x4*)(Vs + c * (2 * 64 * LSTR) + loff + i * 32 * LSTR) = rv[c][i];
;         }
;       }
;     }
;     __syncthreads();
;   }
;   float zf = 0.f, onef = 1.f;
;   asm volatile("" : "+v"(zf), "+v"(onef));
;   f32x16 o[2][2], ls[2];
;   float mref[2];
; #pragma unroll
;   for (int hh = 0; hh < 2; ++hh) {
;     const int head = head0 + hh;
;     const float sl2 = exp2f(-8.f * (float)(1 + head) / 12.f) * LOG2E;
; #pragma unroll
;     for (int e = 0; e < 16; ++e) { o[hh][0][e] = zf; o[hh][1][e] = zf; ls[hh][e] = onef; }
;     mref[hh] = p.sinks[layer * 8 + head] * LOG2E;
.LBB0_268:
	s_or_b64 exec, exec, s[0:1]
	s_waitcnt vmcnt(10)
	v_lshlrev_b32_e32 v3, 7, v66
	v_lshlrev_b32_e32 v4, 2, v205
	v_bitop3_b32 v185, v3, s95, v4 bitop3:0x36
	v_cvt_f32_i32_e32 v3, s2
	v_lshlrev_b32_e32 v2, 3, v66
	s_movk_i32 s0, 0x48
	s_mov_b32 s2, 0x41400000
	v_mul_f32_e32 v3, 0xc1000000, v3
	v_mad_u32_u24 v159, v205, s0, v2
	v_div_scale_f32 v4, s[0:1], s2, s2, v3
	v_rcp_f32_e32 v5, v4
	s_waitcnt vmcnt(7)
	ds_write_b128 v67, v[34:37] offset:36864
	s_waitcnt vmcnt(6)
	ds_write_b128 v67, v[38:41] offset:46080
	s_waitcnt vmcnt(4)
	ds_write_b128 v67, v[42:45] offset:41472
	ds_write_b128 v67, v[46:49] offset:50688
	s_waitcnt vmcnt(3)
	ds_write_b128 v67, v[50:53] offset:55296
	s_waitcnt vmcnt(2)
	ds_write_b128 v67, v[54:57] offset:64512
	s_waitcnt vmcnt(1)
	ds_write_b128 v67, v[58:61] offset:59904
	v_add_u32_e32 v2, 0x10e00, v67
	s_waitcnt vmcnt(0)
	ds_write_b128 v2, v[62:65]
	v_fma_f32 v6, -v4, v5, 1.0
	v_fmac_f32_e32 v5, v6, v5
	v_div_scale_f32 v6, vcc, v3, s2, v3
	v_mul_f32_e32 v7, v6, v5
	v_fma_f32 v8, -v4, v7, v6
	v_fmac_f32_e32 v7, v8, v5
	v_fma_f32 v4, -v4, v7, v6
	v_div_fmas_f32 v4, v4, v5, v7
	v_div_fixup_f32 v3, v4, s2, v3
	v_cmp_gt_f32_e32 vcc, s94, v3
	s_and_b64 s[0:1], vcc, exec
	s_cselect_b32 s0, 0xffffffc0, 0
	v_cndmask_b32_e32 v4, 0, v187, vcc
	v_add_f32_e32 v3, v3, v4
	v_exp_f32_e32 v3, v3
	v_mov_b32_e32 v2, v1
	v_mov_b32_e32 v18, 1.0
	s_waitcnt lgkmcnt(0)
	v_ldexp_f32 v34, v3, s0
	s_add_i32 s0, s18, s24
	s_ashr_i32 s1, s0, 31
	s_lshl_b64 s[0:1], s[0:1], 2
	s_add_u32 s0, s48, s0
	s_addc_u32 s1, s49, s1
	s_barrier
	v_mul_f32_e32 v186, 0x3fb8aa3b, v34
	global_load_dword v34, v1, s[0:1]
	v_mov_b32_e32 v16, v2
	v_mov_b32_e32 v17, v2
	v_mov_b32_e32 v32, v18
	v_mov_b32_e32 v33, v18
	v_mul_i32_i24_e32 v214, -4, v66
	v_mov_b32_e32 v3, v2
	v_mov_b32_e32 v4, v2
	v_mov_b32_e32 v5, v2
	v_mov_b32_e32 v6, v2
	v_mov_b32_e32 v7, v2
	v_mov_b32_e32 v8, v2
	v_mov_b32_e32 v9, v2
	v_mov_b32_e32 v10, v2
	v_mov_b32_e32 v11, v2
	v_mov_b32_e32 v12, v2
	v_mov_b32_e32 v13, v2
	v_mov_b32_e32 v14, v2
	v_mov_b32_e32 v15, v2
	v_mov_b32_e32 v19, v18
	v_mov_b32_e32 v20, v18
	v_mov_b32_e32 v21, v18
	v_mov_b32_e32 v22, v18
	v_mov_b32_e32 v23, v18
	v_mov_b32_e32 v24, v18
	v_mov_b32_e32 v25, v18
	v_mov_b32_e32 v26, v18
	v_mov_b32_e32 v27, v18
	v_mov_b32_e32 v28, v18
	v_mov_b32_e32 v29, v18
	v_mov_b32_e32 v30, v18
	v_mov_b32_e32 v31, v18
	v_mov_b64_e32 v[80:81], v[16:17]
	v_mov_b64_e32 v[64:65], v[32:33]
	v_ashrrev_i32_e32 v183, 31, v182
	v_sub_u32_e32 v213, 0x80, v184
	v_or_b32_e32 v210, 31, v182
	v_add_u32_e32 v211, 0xffffff81, v182
	v_or_b32_e32 v216, 63, v212
	v_mov_b64_e32 v[78:79], v[14:15]
	v_mov_b64_e32 v[76:77], v[12:13]
	v_mov_b64_e32 v[74:75], v[10:11]
	v_mov_b64_e32 v[72:73], v[8:9]
	v_mov_b64_e32 v[70:71], v[6:7]
	v_mov_b64_e32 v[68:69], v[4:5]
	v_mov_b64_e32 v[66:67], v[2:3]
	v_mov_b64_e32 v[62:63], v[30:31]
	v_mov_b64_e32 v[60:61], v[28:29]
	v_mov_b64_e32 v[58:59], v[26:27]
	v_mov_b64_e32 v[56:57], v[24:25]
	v_mov_b64_e32 v[54:55], v[22:23]
	v_mov_b64_e32 v[52:53], v[20:21]
	v_mov_b64_e32 v[50:51], v[18:19]
	s_waitcnt vmcnt(0)
	v_mul_f32_e32 v220, 0x3fb8aa3b, v34
	v_mov_b64_e32 v[48:49], v[16:17]
	v_mov_b64_e32 v[46:47], v[14:15]
	v_mov_b64_e32 v[44:45], v[12:13]
	v_mov_b64_e32 v[42:43], v[10:11]
	v_mov_b64_e32 v[40:41], v[8:9]
	v_mov_b64_e32 v[38:39], v[6:7]
	v_mov_b64_e32 v[36:37], v[4:5]
	v_mov_b64_e32 v[34:35], v[2:3]
	s_and_saveexec_b64 s[4:5], s[36:37]
	s_cbranch_execz .LBB0_305
	v_cmp_le_i32_e32 vcc, v212, v210
	v_cmp_ge_i32_e64 s[2:3], v216, v211
	v_mov_b64_e32 v[64:65], v[32:33]
	v_mov_b64_e32 v[80:81], v[16:17]
	v_mov_b64_e32 v[48:49], v[16:17]
	s_and_b64 s[6:7], vcc, s[2:3]
	v_mov_b64_e32 v[62:63], v[30:31]
	v_mov_b64_e32 v[60:61], v[28:29]
	v_mov_b64_e32 v[58:59], v[26:27]
	v_mov_b64_e32 v[56:57], v[24:25]
	v_mov_b64_e32 v[54:55], v[22:23]
	v_mov_b64_e32 v[52:53], v[20:21]
	v_mov_b64_e32 v[50:51], v[18:19]
	v_mov_b64_e32 v[78:79], v[14:15]
	v_mov_b64_e32 v[76:77], v[12:13]
	v_mov_b64_e32 v[74:75], v[10:11]
	v_mov_b64_e32 v[72:73], v[8:9]
	v_mov_b64_e32 v[70:71], v[6:7]
	v_mov_b64_e32 v[68:69], v[4:5]
	v_mov_b64_e32 v[66:67], v[2:3]
	v_mov_b64_e32 v[46:47], v[14:15]
	v_mov_b64_e32 v[44:45], v[12:13]
	v_mov_b64_e32 v[42:43], v[10:11]
	v_mov_b64_e32 v[40:41], v[8:9]
	v_mov_b64_e32 v[38:39], v[6:7]
	v_mov_b64_e32 v[36:37], v[4:5]
	v_mov_b64_e32 v[34:35], v[2:3]
	s_and_saveexec_b64 s[2:3], s[6:7]
	s_cbranch_execz .LBB0_304
; DI f32x16 mfma(bf16x8 a, bf16x8 b, f32x16 c) { return __builtin_amdgcn_mfma_f32_32x32x16_bf16(a, b, c, 0, 0, 0); }
; template <int MODE, int KS0, int NKS>
; DI void qk_scores(f32x16& s0, f32x16& s1, const u16* Ks, const bf16x8 (&qf)[4], float sl2, int dl, float mref,
;                   bool need_mask, int r, int h, int rs, const int (&lo)[4]) {
;   asm volatile("" : "+v"(dl));
;   const float nb = -sl2 * (float)dl - mref;
; #pragma unroll
;   for (int i = 0; i < 16; ++i) {
;     const int ci = (i & 3) + 8 * (i >> 2);
;     s0[i] = fmaf(sl2, (float)ci, nb);
;     s1[i] = fmaf(sl2, (float)(ci + 32), nb);
;   }
; #pragma unroll
;   for (int ks = 0; ks < NKS; ++ks) {
;     bf16x8 k0 = ldsv(Ks + lo[KS0 + ks]);
;     bf16x8 k1 = ldsv(Ks + 32 * rs + lo[KS0 + ks]);
;     s0 = mfma(k0, qf[KS0 + ks], s0);
;     s1 = mfma(k1, qf[KS0 + ks], s1);
;   }
;   if (need_mask) {
; #pragma unroll
;     for (int i = 0; i < 16; ++i) {
;       const int ci = (i & 3) + 8 * (i >> 2);
;       bool v0 = (MODE == 0) ? (ci <= dl) : (ci <= dl && ci > dl - 128);
;       bool v1 = (MODE == 0) ? (ci + 32 <= dl) : (ci + 32 <= dl && ci + 32 > dl - 128);
;       s0[i] = v0 ? s0[i] : -INFINITY;
;       s1[i] = v1 ? s1[i] : -INFINITY;
;     }
;   }
	v_add3_u32 v74, v214, v213, v208
	s_mov_b32 s6, 2.0
	v_cvt_f32_i32_e32 v34, v74
	s_mov_b32 s7, 0x40400000
	v_lshlrev_b32_e32 v86, 1, v159
	ds_read_b128 v[50:53], v86
	v_fma_f32 v70, -v186, v34, -v220
	v_fma_f32 v36, v186, s6, v70
	v_fma_f32 v37, v186, s7, v70
	s_mov_b32 s6, 0x41000000
	s_mov_b32 s7, 0x41100000
	v_fma_f32 v38, v186, s6, v70
	v_fma_f32 v39, v186, s7, v70
	s_mov_b32 s6, 0x41200000
	s_mov_b32 s7, 0x41300000
	v_fma_f32 v40, v186, s6, v70
	v_fma_f32 v41, v186, s7, v70
	s_mov_b32 s6, 0x41800000
	ds_read_b128 v[66:69], v86 offset:4608
	s_mov_b32 s7, 0x41880000
	v_fma_f32 v42, v186, s6, v70
	v_fma_f32 v43, v186, s7, v70
	s_mov_b32 s6, 0x41900000
	s_mov_b32 s7, 0x41980000
	v_fma_f32 v44, v186, s6, v70
	v_fma_f32 v45, v186, s7, v70
	s_mov_b32 s6, 0x42680000
	s_mov_b32 s7, 0x426c0000
	v_fma_f32 v64, v186, s6, v70
	v_fma_f32 v65, v186, s7, v70
	s_mov_b32 s6, 0x42400000
	v_fma_f32 v34, 0, v186, v70
	v_add_f32_e32 v35, v186, v70
	v_fma_f32 v46, v186, s50, v70
	v_fma_f32 v47, v186, s51, v70
	v_fma_f32 v48, v186, s28, v70
	v_fma_f32 v49, v186, s29, v70
	s_mov_b32 s7, 0x42440000
	v_fma_f32 v62, v186, s30, v70
	v_fma_f32 v63, v186, s31, v70
	s_waitcnt lgkmcnt(1)
	v_mfma_f32_32x32x16_bf16 v[34:49], v[50:53], v[126:129], v[34:49]
	v_fma_f32 v60, v186, s10, v70
	v_fma_f32 v61, v186, s11, v70
	v_fma_f32 v58, v186, s6, v70
	v_fma_f32 v59, v186, s7, v70
	v_fma_f32 v56, v186, s72, v70
	v_fma_f32 v57, v186, s73, v70
	v_fma_f32 v54, v186, s74, v70
	v_fma_f32 v55, v186, s75, v70
	v_fma_f32 v52, v186, s76, v70
	v_fma_f32 v53, v186, s77, v70
	v_fma_f32 v50, v186, s78, v70
	v_fma_f32 v51, v186, s79, v70
	v_add_u32_e32 v75, -1, v74
	v_cmp_gt_u32_e32 vcc, s95, v75
	s_waitcnt lgkmcnt(0)
	v_mfma_f32_32x32x16_bf16 v[50:65], v[66:69], v[126:129], v[50:65]
	ds_read_b128 v[66:69], v86 offset:32
	s_waitcnt lgkmcnt(0)
	v_mfma_f32_32x32x16_bf16 v[34:49], v[66:69], v[122:125], v[34:49]
	ds_read_b128 v[66:69], v86 offset:4640
	s_waitcnt lgkmcnt(0)
	v_mfma_f32_32x32x16_bf16 v[50:65], v[66:69], v[122:125], v[50:65]
	ds_read_b128 v[66:69], v86 offset:64
	s_waitcnt lgkmcnt(0)
	v_mfma_f32_32x32x16_bf16 v[34:49], v[66:69], v[118:121], v[34:49]
	ds_read_b128 v[66:69], v86 offset:4672
	s_waitcnt lgkmcnt(0)
	v_mfma_f32_32x32x16_bf16 v[50:65], v[66:69], v[118:121], v[50:65]
	ds_read_b128 v[66:69], v86 offset:96
	ds_read_b128 v[70:73], v86 offset:4704
	s_waitcnt lgkmcnt(1)
	v_mfma_f32_32x32x16_bf16 v[34:49], v[66:69], v[114:117], v[34:49]
	s_waitcnt lgkmcnt(0)
	v_mfma_f32_32x32x16_bf16 v[50:65], v[70:73], v[114:117], v[50:65]
	s_nop 9
	v_cndmask_b32_e32 v66, v199, v35, vcc
	v_cmp_gt_u32_e32 vcc, s95, v74
	v_subrev_u32_e32 v35, 32, v74
	s_nop 0
	v_cndmask_b32_e32 v67, v199, v34, vcc
	v_subrev_u32_e32 v34, 33, v74
	v_cmp_gt_u32_e32 vcc, s95, v34
	v_add_u32_e32 v34, -3, v74
	s_nop 0
	v_cndmask_b32_e32 v89, v199, v51, vcc
	v_cmp_gt_u32_e32 vcc, s95, v35
	v_add_u32_e32 v35, -2, v74
	s_nop 0
	v_cndmask_b32_e32 v94, v199, v50, vcc
	v_cmp_gt_u32_e32 vcc, s95, v34
	v_subrev_u32_e32 v34, 35, v74
	s_nop 0
	v_cndmask_b32_e32 v68, v199, v37, vcc
	v_cmp_gt_u32_e32 vcc, s95, v35
	v_subrev_u32_e32 v35, 34, v74
	s_nop 0
	v_cndmask_b32_e32 v69, v199, v36, vcc
	v_cmp_gt_u32_e32 vcc, s95, v34
	v_add_u32_e32 v34, -9, v74
	s_nop 0
	v_cndmask_b32_e32 v92, v199, v53, vcc
	v_cmp_gt_u32_e32 vcc, s95, v35
	v_add_u32_e32 v35, -8, v74
	s_nop 0
	v_cndmask_b32_e32 v95, v199, v52, vcc
	v_cmp_gt_u32_e32 vcc, s95, v34
	v_subrev_u32_e32 v34, 41, v74
	s_nop 0
	v_cndmask_b32_e32 v70, v199, v39, vcc
	v_cmp_gt_u32_e32 vcc, s95, v35
	v_subrev_u32_e32 v35, 40, v74
	s_nop 0
	v_cndmask_b32_e32 v71, v199, v38, vcc
	v_cmp_gt_u32_e32 vcc, s95, v34
	v_add_u32_e32 v34, -11, v74
	s_nop 0
	v_cndmask_b32_e32 v93, v199, v55, vcc
	v_cmp_gt_u32_e32 vcc, s95, v35
	v_add_u32_e32 v35, -10, v74
	s_nop 0
	v_cndmask_b32_e32 v96, v199, v54, vcc
	v_cmp_gt_u32_e32 vcc, s95, v34
	v_subrev_u32_e32 v34, 43, v74
	s_nop 0
	v_cndmask_b32_e32 v72, v199, v41, vcc
	v_cmp_gt_u32_e32 vcc, s95, v35
	v_subrev_u32_e32 v35, 42, v74
	s_nop 0
	v_cndmask_b32_e32 v73, v199, v40, vcc
	v_cmp_gt_u32_e32 vcc, s95, v34
	v_subrev_u32_e32 v34, 17, v74
	s_nop 0
	v_cndmask_b32_e32 v97, v199, v57, vcc
	v_cmp_gt_u32_e32 vcc, s95, v35
	v_add_u32_e32 v35, -16, v74
	s_nop 0
	v_cndmask_b32_e32 v98, v199, v56, vcc
	v_cmp_gt_u32_e32 vcc, s95, v34
	v_subrev_u32_e32 v34, 49, v74
	s_nop 0
	v_cndmask_b32_e32 v103, v199, v43, vcc
	v_cmp_gt_u32_e32 vcc, s95, v35
	v_subrev_u32_e32 v35, 48, v74
	s_nop 0
	v_cndmask_b32_e32 v82, v199, v42, vcc
	v_cmp_gt_u32_e32 vcc, s95, v34
	v_subrev_u32_e32 v34, 19, v74
	s_nop 0
	v_cndmask_b32_e32 v87, v199, v59, vcc
	v_cmp_gt_u32_e32 vcc, s95, v35
	v_subrev_u32_e32 v35, 18, v74
	s_nop 0
	v_cndmask_b32_e32 v88, v199, v58, vcc
	v_cmp_gt_u32_e32 vcc, s95, v34
	v_subrev_u32_e32 v34, 51, v74
	s_nop 0
	v_cndmask_b32_e32 v104, v199, v45, vcc
	v_cmp_gt_u32_e32 vcc, s95, v35
	v_subrev_u32_e32 v35, 50, v74
	s_nop 0
	v_cndmask_b32_e32 v83, v199, v44, vcc
	v_cmp_gt_u32_e32 vcc, s95, v34
	v_subrev_u32_e32 v34, 25, v74
	s_nop 0
	v_cndmask_b32_e32 v90, v199, v61, vcc
	v_cmp_gt_u32_e32 vcc, s95, v35
	v_subrev_u32_e32 v35, 24, v74
	s_nop 0
	v_cndmask_b32_e32 v91, v199, v60, vcc
	v_cmp_gt_u32_e32 vcc, s95, v34
	v_subrev_u32_e32 v34, 57, v74
	s_nop 0
	v_cndmask_b32_e32 v105, v199, v47, vcc
	v_cmp_gt_u32_e32 vcc, s95, v35
	v_subrev_u32_e32 v35, 56, v74
	s_nop 0
	v_cndmask_b32_e32 v106, v199, v46, vcc
	v_cmp_gt_u32_e32 vcc, s95, v34
	v_subrev_u32_e32 v34, 27, v74
	s_nop 0
	v_cndmask_b32_e32 v99, v199, v63, vcc
	v_cmp_gt_u32_e32 vcc, s95, v35
	v_subrev_u32_e32 v35, 26, v74
	s_nop 0
	v_cndmask_b32_e32 v100, v199, v62, vcc
	v_cmp_gt_u32_e32 vcc, s95, v34
	v_subrev_u32_e32 v34, 59, v74
	s_nop 0
	v_cndmask_b32_e32 v107, v199, v49, vcc
	v_cmp_gt_u32_e32 vcc, s95, v35
	v_subrev_u32_e32 v35, 58, v74
	s_nop 0
	v_cndmask_b32_e32 v108, v199, v48, vcc
	v_cmp_gt_u32_e32 vcc, s95, v34
	s_nop 1
	v_cndmask_b32_e32 v101, v199, v65, vcc
	v_cmp_gt_u32_e32 vcc, s95, v35
	s_nop 1
	v_cndmask_b32_e32 v102, v199, v64, vcc
	v_cmp_nge_f32_e32 vcc, s9, v18
	s_cbranch_vccz .LBB0_302
; DI float ex2(float x) { return __builtin_amdgcn_exp2f(x); }
; DI float lg2(float x) { return __builtin_amdgcn_logf(x); }
; template <int MODE, int KS0, int NKS>
; DI void softmax_pv(const bf16x8 (&qf)[4], const u16* Ks, const u16* Vs, float& m, f32x16& ls, f32x16& o0, f32x16& o1,
;                    float sl2, int dl, bool need_mask, bool first, int r, int h, int rs, const int (&lo)[4]) {
;     ...
;     float tmax = -INFINITY;
; #pragma unroll
;     for (int i = 0; i < 16; ++i) tmax = fmaxf(tmax, fmaxf(s0[i], s1[i]));
;     tmax = fmaxf(tmax, shx(tmax, r + 32 * h));
;     const float lref = (ls[0] > 1.f) ? lg2(ls[0]) : 0.f;
;     const float delta = first ? tmax : fmaxf(fmaxf(tmax, lref), 0.f);
;     m += delta;
;     const float alpha = ex2(-delta);
; #pragma unroll
;     for (int e = 0; e < 16; ++e) { o0[e] *= alpha; o1[e] *= alpha; ls[e] *= alpha; }
; #pragma unroll
;     for (int i = 0; i < 16; ++i) { s0[i] -= delta; s1[i] -= delta; }
	v_max_f32_e32 v34, v94, v94
	v_max_f32_e32 v35, v67, v67
	v_max_f32_e32 v34, v35, v34
	v_max_f32_e32 v35, v89, v89
	v_max_f32_e32 v36, v66, v66
	v_max_f32_e32 v35, v36, v35
	s_mov_b32 s6, 0xff800000
	v_max3_f32 v34, v34, s6, v35
	v_max_f32_e32 v35, v95, v95
	v_max_f32_e32 v36, v69, v69
	v_max_f32_e32 v35, v36, v35
	v_max_f32_e32 v36, v92, v92
	v_max_f32_e32 v37, v68, v68
	v_max_f32_e32 v36, v37, v36
	v_max3_f32 v34, v34, v35, v36
	v_max_f32_e32 v35, v96, v96
	v_max_f32_e32 v36, v71, v71
	v_max_f32_e32 v35, v36, v35
	v_max_f32_e32 v36, v93, v93
	v_max_f32_e32 v37, v70, v70
	v_max_f32_e32 v36, v37, v36
	v_max3_f32 v34, v34, v35, v36
	v_max_f32_e32 v35, v98, v98
	v_max_f32_e32 v36, v73, v73
	v_max_f32_e32 v35, v36, v35
	v_max_f32_e32 v36, v97, v97
	v_max_f32_e32 v37, v72, v72
	v_max_f32_e32 v36, v37, v36
	v_max3_f32 v34, v34, v35, v36
	v_max_f32_e32 v35, v88, v88
	v_max_f32_e32 v36, v82, v82
	v_max_f32_e32 v35, v36, v35
	v_max_f32_e32 v36, v87, v87
	v_max_f32_e32 v37, v103, v103
	v_max_f32_e32 v36, v37, v36
	v_max3_f32 v34, v34, v35, v36
	v_max_f32_e32 v35, v91, v91
	v_max_f32_e32 v36, v83, v83
	v_max_f32_e32 v35, v36, v35
	v_max_f32_e32 v36, v90, v90
	v_max_f32_e32 v37, v104, v104
	v_max_f32_e32 v36, v37, v36
	v_max3_f32 v34, v34, v35, v36
	v_max_f32_e32 v35, v100, v100
	v_max_f32_e32 v36, v106, v106
	v_max_f32_e32 v35, v36, v35
	v_max_f32_e32 v36, v99, v99
	v_max_f32_e32 v37, v105, v105
	v_max_f32_e32 v36, v37, v36
	v_max3_f32 v34, v34, v35, v36
	v_max_f32_e32 v35, v102, v102
	v_max_f32_e32 v36, v108, v108
	v_max_f32_e32 v35, v36, v35
	v_max_f32_e32 v36, v101, v101
	v_max_f32_e32 v37, v107, v107
	v_max_f32_e32 v36, v37, v36
	v_max3_f32 v34, v34, v35, v36
	ds_bpermute_b32 v35, v185, v34
	v_log_f32_e32 v36, v18
	v_cmp_lt_f32_e32 vcc, 1.0, v18
	s_waitcnt lgkmcnt(0)
	v_max_f32_e32 v35, v35, v35
	v_max_f32_e32 v34, v34, v35
	v_cndmask_b32_e32 v35, 0, v36, vcc
	v_max3_f32 v35, v34, v35, 0
	v_exp_f32_e64 v36, -v35
	v_add_f32_e32 v220, v220, v35
	v_sub_f32_e32 v67, v67, v35
	v_sub_f32_e32 v66, v66, v35
	v_mul_f32_e32 v34, v2, v36
	v_mul_f32_e32 v50, v18, v36
	v_sub_f32_e32 v69, v69, v35
	v_sub_f32_e32 v68, v68, v35
	v_sub_f32_e32 v71, v71, v35
	v_sub_f32_e32 v70, v70, v35
	v_sub_f32_e32 v73, v73, v35
	v_sub_f32_e32 v72, v72, v35
	v_sub_f32_e32 v82, v82, v35
	v_sub_f32_e32 v103, v103, v35
	v_sub_f32_e32 v83, v83, v35
	v_sub_f32_e32 v104, v104, v35
	v_sub_f32_e32 v106, v106, v35
	v_sub_f32_e32 v105, v105, v35
	v_sub_f32_e32 v108, v108, v35
	v_sub_f32_e32 v107, v107, v35
	v_sub_f32_e32 v94, v94, v35
	v_sub_f32_e32 v89, v89, v35
	v_sub_f32_e32 v95, v95, v35
	v_sub_f32_e32 v92, v92, v35
	v_sub_f32_e32 v96, v96, v35
	v_sub_f32_e32 v93, v93, v35
	v_sub_f32_e32 v98, v98, v35
	v_sub_f32_e32 v97, v97, v35
	v_sub_f32_e32 v88, v88, v35
	v_sub_f32_e32 v87, v87, v35
	v_sub_f32_e32 v91, v91, v35
	v_sub_f32_e32 v90, v90, v35
	v_sub_f32_e32 v100, v100, v35
	v_sub_f32_e32 v99, v99, v35
	v_sub_f32_e32 v102, v102, v35
	v_sub_f32_e32 v101, v101, v35
	v_mov_b32_e32 v35, v34
	v_mov_b32_e32 v51, v50
	s_branch .LBB0_303

; DI void attn_item_A(const Params& p, int layer, int b, int head, int qb, u16* sm, float lam, float lam_init, int wv) {
;     ...
;   const int npairs = (qb >> 1) + 1;
;   const int T0 = 2 * (npairs - 1) + kh;
;   const bool v0 = (T0 <= qb);
;   auto dma_tile = [&](int T, int c) {
;     const int k0 = 64 * T;
;     u16* Kd = Kb0 + c * (2 * 64 * 64) + wp * (8 * 64);
; #pragma unroll
;     for (int i = 0; i < 4; ++i) {
;       __builtin_amdgcn_global_load_lds((const unsigned*)(kg + (size_t)(k0 + row0 + 16 * i) * DIN), (unsigned*)(Kd + i * 16 * 64), 16, 0, 0);
;       __builtin_amdgcn_global_load_lds((const unsigned*)(vg + (size_t)(row0 + 16 * i) * SEQ + k0), (unsigned*)(Kd + 64 * 64 + i * 16 * 64), 16, 0, 0);
;     }
;   };
;   if (v0) dma_tile(T0, 0);
;   asm volatile("" :: "v"(qf[0]), "v"(qf[1]), "v"(qf[2]), "v"(qf[3]));
;   asm volatile("s_waitcnt vmcnt(0)" ::: "memory");
;   __syncthreads();
;   for (int j = 0; j < npairs; ++j) {
;     if (j + 1 < npairs) dma_tile(T0 - 2 * (j + 1), (j + 1) & 1);
.LBB0_276:
	s_or_b64 exec, exec, s[18:19]
	s_waitcnt vmcnt(0)
	v_and_b32_e32 v205, 60, v125
	s_waitcnt vmcnt(0) lgkmcnt(0)
	s_barrier
	s_and_saveexec_b64 s[18:19], vcc
	s_cbranch_execz .LBB0_292
	v_add_u32_e32 v66, v120, v171
	v_sub_u32_e32 v66, v66, v124
	v_lshlrev_b32_e32 v67, 6, v118
	v_sub_u32_e32 v66, v66, v67
	v_lshlrev_b32_e32 v206, 6, v173
	v_lshlrev_b32_e32 v67, 6, v119
	v_sub_u32_e32 v66, v66, v206
	v_and_b32_e32 v67, 0xffffff80, v67
	v_sub_u32_e32 v66, v66, v67
	v_add_u32_e32 v207, 0x2040, v66
	v_add_u32_e32 v66, v118, v173
	s_movk_i32 s2, 0xff7f
	v_add3_u32 v208, v66, v123, s2
	v_or_b32_e32 v66, v121, v67
	v_cmp_gt_u32_e64 s[36:37], 16, v171
	v_add_u32_e32 v209, v66, v122
	v_add_u32_e32 v210, 0xffffff00, v67
	v_add_u32_e32 v72, v206, v209
	v_add_u32_e32 v68, 0xffffff00, v72
	v_mad_i64_i32 v[68:69], s[38:39], v68, s8, v[160:161]
	v_readlane_b32 s22, v250, 19
	v_add_u32_e32 v66, v206, v210
	v_ashrrev_i32_e32 v67, 31, v66
	v_lshl_add_u64 v[68:69], v[68:69], 0, s[68:69]
	v_lshlrev_b64 v[66:67], 1, v[66:67]
	v_or_b32_e32 v74, v121, v122
	v_subrev_u32_e32 v75, s22, v160
	v_lshl_add_u64 v[70:71], v[162:163], 0, v[66:67]
	v_mul_u32_u24_e32 v76, 0x1a00, v74
	v_lshlrev_b32_e32 v77, 14, v74
	v_add_u32_e32 v76, v76, v75
	v_add_u32_e32 v77, v77, v75
	v_sub_co_u32_e32 v68, vcc, v68, v76
	s_nop 1
	v_subbrev_co_u32_e32 v69, vcc, 0, v69, vcc
	v_sub_co_u32_e32 v70, vcc, v70, v77
	s_nop 1
	v_subbrev_co_u32_e32 v71, vcc, 0, v71, vcc
	v_mov_b32_e32 v160, v76
	v_readfirstlane_b32 s98, v68
	v_readfirstlane_b32 s99, v69
	v_readfirstlane_b32 s100, v70
	v_readfirstlane_b32 s101, v71
	v_readfirstlane_b32 s87, v177
	v_add_u32_e32 v161, 0x1a000, v76
	v_add_u32_e32 v162, 0x34000, v76
	v_add_u32_e32 v163, 0x4e000, v76
	v_mov_b32_e32 v164, v77
	v_add_u32_e32 v165, 0x40000, v77
	v_add_u32_e32 v166, 0x80000, v77
	v_add_u32_e32 v167, 0xc0000, v77
	s_movk_i32 s64, 0x2000
	s_mov_b32 s65, 0
	s_mov_b64 s[40:41], 0
	s_mov_b64 s[42:43], s[4:5]
	s_branch .LBB0_279
	s_nop 0
	s_nop 0
	s_nop 0
	s_nop 0
	s_nop 0
	s_nop 0

; DI float ex2(float x) { return __builtin_amdgcn_exp2f(x); }
; DI void attn_item_A(const Params& p, int layer, int b, int head, int qb, u16* sm, float lam, float lam_init, int wv) {
;     ...
;   __syncthreads();
;   if (kh == 0) {
;     {
;       const float mb = cb[64 * 64], lb = cb[65 * 64];
;       const float mn = fmaxf(m0, mb), fa = ex2(m0 - mn), fb = ex2(mb - mn);
;       l0 = l0 * fa + lb * fb;
; #pragma unroll
;       for (int d = 0; d < 2; ++d)
; #pragma unroll
;         for (int e = 0; e < 16; ++e) o[0][d][e] = o[0][d][e] * fa + cb[((0 * 2 + d) * 16 + e) * 64] * fb;
;     }
;     {
;       const float mb = cb[66 * 64], lb = cb[67 * 64];
;       const float mn = fmaxf(m1, mb), fa = ex2(m1 - mn), fb = ex2(mb - mn);
;       l1 = l1 * fa + lb * fb;
; #pragma unroll
;       for (int d = 0; d < 2; ++d)
; #pragma unroll
;         for (int e = 0; e < 16; ++e) o[1][d][e] = o[1][d][e] * fa + cb[((1 * 2 + d) * 16 + e) * 64] * fb;
;     }
;     const float inv0 = 1.f / l0, inv1 = lam / l1;
.LBB0_299:
	s_or_b64 exec, exec, s[2:3]
	s_waitcnt lgkmcnt(0)
	s_barrier
	s_and_saveexec_b64 s[2:3], s[36:37]
	s_cbranch_execz .LBB0_195
	ds_read2st64_b32 v[116:117], v111 offset0:64 offset1:65
	v_max_f32_e32 v110, v67, v67
	ds_read2st64_b32 v[112:113], v111 offset1:1
	ds_read2st64_b32 v[108:109], v111 offset0:2 offset1:3
	ds_read2st64_b32 v[106:107], v111 offset0:4 offset1:5
	ds_read2st64_b32 v[104:105], v111 offset0:6 offset1:7
	ds_read2st64_b32 v[102:103], v111 offset0:8 offset1:9
	ds_read2st64_b32 v[100:101], v111 offset0:10 offset1:11
	ds_read2st64_b32 v[98:99], v111 offset0:12 offset1:13
	ds_read2st64_b32 v[96:97], v111 offset0:14 offset1:15
	ds_read2st64_b32 v[94:95], v111 offset0:16 offset1:17
	ds_read2st64_b32 v[92:93], v111 offset0:18 offset1:19
	ds_read2st64_b32 v[90:91], v111 offset0:20 offset1:21
	ds_read2st64_b32 v[88:89], v111 offset0:22 offset1:23
	ds_read2st64_b32 v[86:87], v111 offset0:24 offset1:25
	ds_read2st64_b32 v[128:129], v111 offset0:26 offset1:27
	ds_read2st64_b32 v[124:125], v111 offset0:28 offset1:29
	ds_read2st64_b32 v[118:119], v111 offset0:30 offset1:31
	ds_read2st64_b32 v[142:143], v111 offset0:66 offset1:67
	s_waitcnt lgkmcnt(14)
	v_max_f32_e32 v68, v116, v116
	v_max_f32_e32 v69, v110, v68
	v_sub_f32_e32 v68, v67, v69
	v_sub_f32_e32 v69, v116, v69
	v_exp_f32_e32 v68, v68
	v_exp_f32_e32 v115, v69
	v_mov_b32_e32 v69, v117
	ds_read2st64_b32 v[144:145], v111 offset0:32 offset1:33
	ds_read2st64_b32 v[146:147], v111 offset0:34 offset1:35
	ds_read2st64_b32 v[148:149], v111 offset0:36 offset1:37
	ds_read2st64_b32 v[150:151], v111 offset0:38 offset1:39
	ds_read2st64_b32 v[152:153], v111 offset0:40 offset1:41
	ds_read2st64_b32 v[136:137], v111 offset0:42 offset1:43
	ds_read2st64_b32 v[134:135], v111 offset0:44 offset1:45
	ds_read2st64_b32 v[132:133], v111 offset0:46 offset1:47
	ds_read2st64_b32 v[130:131], v111 offset0:48 offset1:49
	ds_read2st64_b32 v[126:127], v111 offset0:50 offset1:51
	ds_read2st64_b32 v[122:123], v111 offset0:52 offset1:53
	ds_read2st64_b32 v[120:121], v111 offset0:54 offset1:55
	ds_read2st64_b32 v[116:117], v111 offset0:56 offset1:57
	ds_read2st64_b32 v[154:155], v111 offset0:58 offset1:59
	ds_read2st64_b32 v[156:157], v111 offset0:60 offset1:61
	ds_read2st64_b32 v[160:161], v111 offset0:62 offset1:63
	s_waitcnt lgkmcnt(14)
	v_mov_b32_e32 v111, v143
	v_mul_f32_e32 v140, v68, v114
	v_mul_f32_e32 v141, v69, v115
	v_max_f32_e32 v69, v142, v142
	v_max_f32_e32 v69, v110, v69
	v_sub_f32_e32 v67, v67, v69
	v_exp_f32_e32 v110, v67
	v_sub_f32_e32 v67, v142, v69
	v_add_f32_e32 v69, v140, v141
	v_exp_f32_e32 v67, v67
	v_div_scale_f32 v114, s[4:5], v69, v69, 1.0
	v_rcp_f32_e32 v139, v114
	v_mul_f32_e32 v140, v110, v66
	v_mul_f32_e32 v141, v111, v67
	v_mov_b32_e32 v66, 1.0
	v_add_f32_e32 v111, v140, v141
	v_fma_f32 v140, -v114, v139, 1.0
	v_fmac_f32_e32 v139, v140, v139
	v_div_scale_f32 v140, vcc, 1.0, v69, 1.0
	v_mul_f32_e32 v141, v140, v139
	v_fma_f32 v142, -v114, v141, v140
	v_fmac_f32_e32 v141, v142, v139
	v_fma_f32 v114, -v114, v141, v140
	v_div_fmas_f32 v114, v114, v139, v141
	v_div_fixup_f32 v114, v114, v69, 1.0
	v_div_scale_f32 v69, s[4:5], v111, v111, v202
	v_rcp_f32_e32 v139, v69
	s_movk_i32 s4, 0x2200
	v_fma_f32 v140, -v69, v139, 1.0
	v_fmac_f32_e32 v139, v140, v139
	v_div_scale_f32 v140, vcc, v202, v111, v202
	v_mul_f32_e32 v141, v140, v139
	v_fma_f32 v142, -v69, v141, v140
	v_fmac_f32_e32 v141, v142, v139
	v_fma_f32 v69, -v69, v141, v140
	v_mov_b32_e32 v142, v115
	v_div_fmas_f32 v69, v69, v139, v141
	v_mul_f32_e32 v128, v142, v128
	v_mul_f32_e32 v129, v142, v129
	v_fma_f32 v44, v44, v68, v128
	v_fma_f32 v45, v45, v68, v129
	v_mov_b32_e32 v128, v67
	v_mul_f32_e32 v124, v142, v124
	v_mul_f32_e32 v125, v142, v125
	v_fma_f32 v46, v46, v68, v124
	v_fma_f32 v47, v47, v68, v125
	s_waitcnt lgkmcnt(1)
	v_mul_f32_e32 v124, v128, v156
	v_mul_f32_e32 v125, v128, v157
	v_div_fixup_f32 v140, v69, v111, v202
	v_fma_f32 v30, v30, v110, v124
	v_fma_f32 v31, v31, v110, v125
	v_mul_f32_e32 v154, v128, v154
	v_mul_f32_e32 v155, v128, v155
	v_mul_f32_e32 v30, v140, v30
	v_mul_f32_e32 v31, v140, v31
	v_fma_f32 v30, v114, v46, -v30
	v_fma_f32 v31, v114, v47, -v31
	v_mul_f32_e32 v46, v142, v118
	v_mul_f32_e32 v47, v142, v119
	v_fma_f32 v46, v48, v68, v46
	v_fma_f32 v47, v49, v68, v47
	s_waitcnt lgkmcnt(0)
; DI float ex2(float x) { return __builtin_amdgcn_exp2f(x); }
; DI void attn_item_A(const Params& p, int layer, int b, int head, int qb, u16* sm, float lam, float lam_init, int wv) {
;     ...
;       for (int d = 0; d < 2; ++d)
; #pragma unroll
;         for (int e = 0; e < 16; ++e) o[0][d][e] = o[0][d][e] * fa + cb[((0 * 2 + d) * 16 + e) * 64] * fb;
;     }
;     {
;       const float mb = cb[66 * 64], lb = cb[67 * 64];
;       const float mn = fmaxf(m1, mb), fa = ex2(m1 - mn), fb = ex2(mb - mn);
;       l1 = l1 * fa + lb * fb;
; #pragma unroll
;       for (int d = 0; d < 2; ++d)
; #pragma unroll
;         for (int e = 0; e < 16; ++e) o[1][d][e] = o[1][d][e] * fa + cb[((1 * 2 + d) * 16 + e) * 64] * fb;
;     }
;     const float inv0 = 1.f / l0, inv1 = lam / l1;
;     float sq = 0.f;
; #pragma unroll
;     for (int dt = 0; dt < 2; ++dt)
; #pragma unroll
;       for (int e = 0; e < 16; ++e) {
;         float v = o[0][dt][e] * inv0 - o[1][dt][e] * inv1;
;         o[0][dt][e] = v;
;         sq += v * v;
;       }
	v_mul_f32_e32 v48, v128, v160
	v_mul_f32_e32 v49, v128, v161
	v_fma_f32 v32, v32, v110, v48
	v_fma_f32 v33, v33, v110, v49
	v_mul_u32_u24_e32 v69, 0x110, v171
	v_mul_f32_e32 v32, v140, v32
	v_mul_f32_e32 v33, v140, v33
	v_fma_f32 v32, v114, v46, -v32
	v_fma_f32 v33, v114, v47, -v33
	v_mul_lo_u32 v46, v159, s4
	v_mul_f32_e32 v112, v112, v142
	v_mul_f32_e32 v113, v113, v142
	v_fma_f32 v28, v28, v110, v154
	v_fma_f32 v29, v29, v110, v155
	v_add3_u32 v111, v46, v69, v0
	v_fma_f32 v2, v2, v68, v112
	v_fma_f32 v3, v3, v68, v113
	v_mul_f32_e32 v112, v144, v128
	v_mul_f32_e32 v113, v145, v128
	v_mul_f32_e32 v108, v142, v108
	v_mul_f32_e32 v109, v142, v109
	v_fma_f32 v50, v50, v110, v112
	v_fma_f32 v51, v51, v110, v113
	v_fma_f32 v4, v4, v68, v108
	v_fma_f32 v5, v5, v68, v109
	v_mul_f32_e32 v108, v128, v146
	v_mul_f32_e32 v109, v128, v147
	v_mul_f32_e32 v50, v50, v140
	v_mul_f32_e32 v51, v51, v140
	v_fma_f32 v52, v52, v110, v108
	v_fma_f32 v53, v53, v110, v109
	v_mul_f32_e32 v106, v142, v106
	v_mul_f32_e32 v107, v142, v107
	v_fma_f32 v2, v2, v114, -v50
	v_fma_f32 v3, v3, v114, -v51
	v_mul_f32_e32 v52, v140, v52
	v_mul_f32_e32 v53, v140, v53
	v_fma_f32 v6, v6, v68, v106
	v_fma_f32 v7, v7, v68, v107
	v_mul_f32_e32 v106, v128, v148
	v_mul_f32_e32 v107, v128, v149
	v_mul_f32_e32 v50, v2, v2
	v_mul_f32_e32 v51, v3, v3
	v_fma_f32 v4, v114, v4, -v52
	v_fma_f32 v5, v114, v5, -v53
	v_fma_f32 v54, v54, v110, v106
	v_fma_f32 v55, v55, v110, v107
	v_mul_f32_e32 v104, v142, v104
	v_mul_f32_e32 v105, v142, v105
	v_mul_f32_e32 v52, v4, v4
	v_mul_f32_e32 v53, v5, v5
	v_mul_f32_e32 v54, v140, v54
	v_mul_f32_e32 v55, v140, v55
	v_fma_f32 v8, v8, v68, v104
	v_fma_f32 v9, v9, v68, v105
	v_mul_f32_e32 v104, v128, v150
	v_mul_f32_e32 v105, v128, v151
	v_add_f32_e32 v0, v50, v51
	v_fma_f32 v6, v114, v6, -v54
	v_fma_f32 v7, v114, v7, -v55
	v_fma_f32 v56, v56, v110, v104
	v_fma_f32 v57, v57, v110, v105
	v_mul_f32_e32 v102, v142, v102
	v_mul_f32_e32 v103, v142, v103
	v_add_f32_e32 v0, v52, v0
	v_mul_f32_e32 v54, v6, v6
	v_mul_f32_e32 v55, v7, v7
	v_mul_f32_e32 v56, v140, v56
	v_mul_f32_e32 v57, v140, v57
	v_fma_f32 v10, v10, v68, v102
	v_fma_f32 v11, v11, v68, v103
	v_mul_f32_e32 v102, v128, v152
	v_mul_f32_e32 v103, v128, v153
	v_add_f32_e32 v0, v53, v0
	v_fma_f32 v8, v114, v8, -v56
	v_fma_f32 v9, v114, v9, -v57
	v_fma_f32 v58, v58, v110, v102
	v_fma_f32 v59, v59, v110, v103
	v_mul_f32_e32 v100, v142, v100
	v_mul_f32_e32 v101, v142, v101
	v_add_f32_e32 v0, v54, v0
	v_mul_f32_e32 v56, v8, v8
	v_mul_f32_e32 v57, v9, v9
	v_mul_f32_e32 v58, v140, v58
	v_mul_f32_e32 v59, v140, v59
	v_fma_f32 v12, v12, v68, v100
	v_fma_f32 v13, v13, v68, v101
	v_mul_f32_e32 v100, v128, v136
	v_mul_f32_e32 v101, v128, v137
	v_add_f32_e32 v0, v55, v0
	v_fma_f32 v10, v114, v10, -v58
	v_fma_f32 v11, v114, v11, -v59
	v_fma_f32 v60, v60, v110, v100
	v_fma_f32 v61, v61, v110, v101
	v_mul_f32_e32 v98, v142, v98
	v_mul_f32_e32 v99, v142, v99
	v_add_f32_e32 v0, v56, v0
	v_mul_f32_e32 v58, v10, v10
	v_mul_f32_e32 v59, v11, v11
	v_mul_f32_e32 v60, v140, v60
	v_mul_f32_e32 v61, v140, v61
	v_fma_f32 v14, v14, v68, v98
	v_fma_f32 v15, v15, v68, v99
	v_mul_f32_e32 v98, v128, v134
	v_mul_f32_e32 v99, v128, v135
	v_add_f32_e32 v0, v57, v0
	v_fma_f32 v12, v114, v12, -v60
	v_fma_f32 v13, v114, v13, -v61
	v_fma_f32 v62, v62, v110, v98
	v_fma_f32 v63, v63, v110, v99
	v_mul_f32_e32 v96, v142, v96
	v_mul_f32_e32 v97, v142, v97
	v_add_f32_e32 v0, v58, v0
	v_mul_f32_e32 v60, v12, v12
	v_mul_f32_e32 v61, v13, v13
	v_mul_f32_e32 v62, v140, v62
	v_mul_f32_e32 v63, v140, v63
	v_fma_f32 v16, v16, v68, v96
	v_fma_f32 v17, v17, v68, v97
	v_mul_f32_e32 v96, v128, v132
	v_mul_f32_e32 v97, v128, v133
	v_add_f32_e32 v0, v59, v0
	v_fma_f32 v14, v114, v14, -v62
	v_fma_f32 v15, v114, v15, -v63
	v_fma_f32 v64, v64, v110, v96
	v_fma_f32 v65, v65, v110, v97
	v_mul_f32_e32 v94, v142, v94
	v_mul_f32_e32 v95, v142, v95
	v_add_f32_e32 v0, v60, v0
	v_mul_f32_e32 v62, v14, v14
	v_mul_f32_e32 v63, v15, v15
	v_mul_f32_e32 v64, v140, v64
	v_mul_f32_e32 v65, v140, v65
	v_fma_f32 v34, v34, v68, v94
	v_fma_f32 v35, v35, v68, v95
	v_mul_f32_e32 v94, v128, v130
	v_mul_f32_e32 v95, v128, v131
	v_add_f32_e32 v0, v61, v0
	v_fma_f32 v16, v114, v16, -v64
	v_fma_f32 v17, v114, v17, -v65
	v_fma_f32 v18, v18, v110, v94
	v_fma_f32 v19, v19, v110, v95
	v_mul_f32_e32 v92, v142, v92
	v_mul_f32_e32 v93, v142, v93
	v_add_f32_e32 v0, v62, v0
	v_mul_f32_e32 v64, v16, v16
; DI void store_y(const f32x16& oa, const f32x16& ob, float mult, const float* sg, const u32x2 (&gv)[8], u16* yrow0, float* stg,
;                 int lane, int r, int h) {
; #pragma unroll
;   for (int dt = 0; dt < 2; ++dt)
; #pragma unroll
;     for (int g = 0; g < 4; ++g) {
;       f32x4 v;
;       v[0] = (dt ? ob[4 * g] : oa[4 * g]) * mult; v[1] = (dt ? ob[4 * g + 1] : oa[4 * g + 1]) * mult;
;       v[2] = (dt ? ob[4 * g + 2] : oa[4 * g + 2]) * mult; v[3] = (dt ? ob[4 * g + 3] : oa[4 * g + 3]) * mult;
;       *(f32x4*)(stg + r * 68 + 32 * dt + 8 * g + 4 * h) = v;
;     }
;   const int kc = lane & 15;
;   f32x4 sv = {1.f, 1.f, 1.f, 1.f};
;   if (sg) sv = *(const f32x4*)(sg + kc * 4);
; DI void attn_item_A(const Params& p, int layer, int b, int head, int qb, u16* sm, float lam, float lam_init, int wv) {
;     ...
;     float sq = 0.f;
; #pragma unroll
;     for (int dt = 0; dt < 2; ++dt)
; #pragma unroll
;       for (int e = 0; e < 16; ++e) {
;         float v = o[0][dt][e] * inv0 - o[1][dt][e] * inv1;
;         o[0][dt][e] = v;
;         sq += v * v;
;       }
;     sq += shx(sq, lane);
;     const float mult = __builtin_amdgcn_rsqf(sq * (1.f / 64.f) + EPS) * (1.f - lam_init);
;     store_y(o[0][0], o[0][1], mult, p.subln_g + layer * 64, gate,
;             p.y + ((size_t)b * SEQ + q0w) * DM + yoff, (float*)sm + 9216 + w * 2176, lane, r, h);
	v_mul_f32_e32 v65, v17, v17
	v_mul_f32_e32 v18, v140, v18
	v_mul_f32_e32 v19, v140, v19
	v_fma_f32 v36, v36, v68, v92
	v_fma_f32 v37, v37, v68, v93
	v_mul_f32_e32 v92, v128, v126
	v_mul_f32_e32 v93, v128, v127
	v_add_f32_e32 v0, v63, v0
	v_fma_f32 v18, v114, v34, -v18
	v_fma_f32 v19, v114, v35, -v19
	v_fma_f32 v20, v20, v110, v92
	v_fma_f32 v21, v21, v110, v93
	v_mul_f32_e32 v90, v142, v90
	v_mul_f32_e32 v91, v142, v91
	v_add_f32_e32 v0, v64, v0
	v_mul_f32_e32 v34, v18, v18
	v_mul_f32_e32 v35, v19, v19
	v_mul_f32_e32 v20, v140, v20
	v_mul_f32_e32 v21, v140, v21
	v_fma_f32 v38, v38, v68, v90
	v_fma_f32 v39, v39, v68, v91
	v_mul_f32_e32 v90, v128, v122
	v_mul_f32_e32 v91, v128, v123
	v_add_f32_e32 v0, v65, v0
	v_fma_f32 v20, v114, v36, -v20
	v_fma_f32 v21, v114, v37, -v21
	v_fma_f32 v22, v22, v110, v90
	v_fma_f32 v23, v23, v110, v91
	v_mul_f32_e32 v88, v142, v88
	v_mul_f32_e32 v89, v142, v89
	v_add_f32_e32 v0, v34, v0
	v_mul_f32_e32 v36, v20, v20
	v_mul_f32_e32 v37, v21, v21
	v_mul_f32_e32 v22, v140, v22
	v_mul_f32_e32 v23, v140, v23
	v_fma_f32 v40, v40, v68, v88
	v_fma_f32 v41, v41, v68, v89
	v_mul_f32_e32 v88, v128, v120
	v_mul_f32_e32 v89, v128, v121
	v_add_f32_e32 v0, v35, v0
	v_fma_f32 v22, v114, v38, -v22
	v_fma_f32 v23, v114, v39, -v23
	v_fma_f32 v24, v24, v110, v88
	v_fma_f32 v25, v25, v110, v89
	v_mul_f32_e32 v86, v142, v86
	v_mul_f32_e32 v87, v142, v87
	v_add_f32_e32 v0, v36, v0
	v_mul_f32_e32 v38, v22, v22
	v_mul_f32_e32 v39, v23, v23
	v_mul_f32_e32 v24, v140, v24
	v_mul_f32_e32 v25, v140, v25
	v_fma_f32 v42, v42, v68, v86
	v_fma_f32 v43, v43, v68, v87
	v_mul_f32_e32 v68, v128, v116
	v_mul_f32_e32 v69, v128, v117
	v_add_f32_e32 v0, v37, v0
	v_fma_f32 v24, v114, v40, -v24
	v_fma_f32 v25, v114, v41, -v25
	v_fma_f32 v26, v26, v110, v68
	v_fma_f32 v27, v27, v110, v69
	v_add_f32_e32 v0, v38, v0
	v_mul_f32_e32 v40, v24, v24
	v_mul_f32_e32 v41, v25, v25
	v_mul_f32_e32 v26, v140, v26
	v_mul_f32_e32 v27, v140, v27
	v_add_f32_e32 v0, v39, v0
	v_fma_f32 v26, v114, v42, -v26
	v_fma_f32 v27, v114, v43, -v27
	v_add_f32_e32 v0, v40, v0
	v_mul_f32_e32 v28, v140, v28
	v_mul_f32_e32 v29, v140, v29
	v_mul_f32_e32 v42, v26, v26
	v_mul_f32_e32 v43, v27, v27
	v_add_f32_e32 v0, v41, v0
	v_fma_f32 v28, v114, v44, -v28
	v_fma_f32 v29, v114, v45, -v29
	v_add_f32_e32 v0, v42, v0
	v_mul_f32_e32 v44, v28, v28
	v_mul_f32_e32 v45, v29, v29
	v_add_f32_e32 v0, v43, v0
	v_add_f32_e32 v0, v44, v0
	v_mul_f32_e32 v124, v30, v30
	v_mul_f32_e32 v125, v31, v31
	v_add_f32_e32 v0, v45, v0
	v_add_f32_e32 v0, v124, v0
	v_mul_f32_e32 v48, v32, v32
	v_mul_f32_e32 v49, v33, v33
	v_add_f32_e32 v0, v125, v0
	v_lshlrev_b32_e32 v47, 2, v138
	v_add_f32_e32 v0, v48, v0
	v_xor_b32_e32 v67, 0x80, v47
	v_add_f32_e32 v0, v49, v0
	ds_bpermute_b32 v34, v67, v0
	v_readlane_b32 s4, v250, 15
	v_readlane_b32 s5, v250, 16
	s_andn2_b64 vcc, exec, s[4:5]
	v_mov_b32_e32 v67, 1.0
	s_waitcnt lgkmcnt(0)
	v_add_f32_e32 v0, v0, v34
	v_fmamk_f32 v0, v0, 0x3c800000, v188
	v_rsq_f32_e32 v0, v0
	v_mov_b32_e32 v68, 1.0
	v_mov_b32_e32 v69, 1.0
	v_mul_f32_e32 v0, v203, v0
	v_mul_f32_e32 v4, v4, v0
	v_mul_f32_e32 v5, v5, v0
	v_mul_f32_e32 v2, v2, v0
	v_mul_f32_e32 v3, v3, v0
	ds_write_b128 v111, v[2:5] offset:36864
	v_mul_f32_e32 v4, v8, v0
	v_mul_f32_e32 v5, v9, v0
	v_mul_f32_e32 v2, v6, v0
	v_mul_f32_e32 v3, v7, v0
	ds_write_b128 v111, v[2:5] offset:36896
	v_mul_f32_e32 v4, v12, v0
	v_mul_f32_e32 v5, v13, v0
	v_mul_f32_e32 v2, v10, v0
	v_mul_f32_e32 v3, v11, v0
	ds_write_b128 v111, v[2:5] offset:36928
	v_mul_f32_e32 v4, v16, v0
	v_mul_f32_e32 v5, v17, v0
	v_mul_f32_e32 v2, v14, v0
	v_mul_f32_e32 v3, v15, v0
	ds_write_b128 v111, v[2:5] offset:36960
	v_mul_f32_e32 v4, v20, v0
	v_mul_f32_e32 v5, v21, v0
	v_mul_f32_e32 v2, v18, v0
	v_mul_f32_e32 v3, v19, v0
	ds_write_b128 v111, v[2:5] offset:36992
	v_mul_f32_e32 v4, v24, v0
	v_mul_f32_e32 v5, v25, v0
	v_mul_f32_e32 v2, v22, v0
	v_mul_f32_e32 v3, v23, v0
	ds_write_b128 v111, v[2:5] offset:37024
	v_mul_f32_e32 v4, v28, v0
	v_mul_f32_e32 v5, v29, v0
	v_mul_f32_e32 v2, v26, v0
	v_mul_f32_e32 v3, v27, v0
	ds_write_b128 v111, v[2:5] offset:37056
	v_mul_f32_e32 v4, v32, v0
	v_mul_f32_e32 v5, v33, v0
	v_mul_f32_e32 v2, v30, v0
	v_mul_f32_e32 v3, v31, v0
	v_and_b32_e32 v0, 60, v47
	ds_write_b128 v111, v[2:5] offset:37088
	v_lshlrev_b32_e32 v4, 2, v0
	s_cbranch_vccnz .LBB0_194
	v_readlane_b32 s4, v250, 33
	v_readlane_b32 s5, v250, 34
	s_nop 4
	global_load_dwordx4 v[66:69], v4, s[4:5]
	s_branch .LBB0_194

; DI f32x16 mfma(bf16x8 a, bf16x8 b, f32x16 c) { return __builtin_amdgcn_mfma_f32_32x32x16_bf16(a, b, c, 0, 0, 0); }
; template <int MODE, int KS0, int NKS>
; DI void qk_scores(f32x16& s0, f32x16& s1, const u16* Ks, const bf16x8 (&qf)[4], float sl2, int dl, float mref,
;                   bool need_mask, int r, int h, int rs, const int (&lo)[4]) {
;   asm volatile("" : "+v"(dl));
;   const float nb = -sl2 * (float)dl - mref;
; #pragma unroll
;   for (int i = 0; i < 16; ++i) {
;     const int ci = (i & 3) + 8 * (i >> 2);
;     s0[i] = fmaf(sl2, (float)ci, nb);
;     s1[i] = fmaf(sl2, (float)(ci + 32), nb);
;   }
; #pragma unroll
;   for (int ks = 0; ks < NKS; ++ks) {
;     bf16x8 k0 = ldsv(Ks + lo[KS0 + ks]);
;     bf16x8 k1 = ldsv(Ks + 32 * rs + lo[KS0 + ks]);
;     s0 = mfma(k0, qf[KS0 + ks], s0);
;     s1 = mfma(k1, qf[KS0 + ks], s1);
;   }
;   if (need_mask) {
; #pragma unroll
;     for (int i = 0; i < 16; ++i) {
;       const int ci = (i & 3) + 8 * (i >> 2);
;       bool v0 = (MODE == 0) ? (ci <= dl) : (ci <= dl && ci > dl - 128);
;       bool v1 = (MODE == 0) ? (ci + 32 <= dl) : (ci + 32 <= dl && ci + 32 > dl - 128);
;       s0[i] = v0 ? s0[i] : -INFINITY;
;       s1[i] = v1 ? s1[i] : -INFINITY;
;     }
;   }
; DI void attn_item_B2(const Params& p, int layer, int b, int head0, int qblk, u16* sm, int wv) {
;     ...
;     for (int c = 0; c < 4; ++c) {
;       if (c >= it0) {
;         const int k0 = q0 - 128 + 64 * c;
;         const bool skip = (k0 > q0w + 31) || (k0 + 63 < q0w - 127);
;         if (!skip) {
;           const int dl = qpos - k0 - 4 * h;
;           softmax_pv<1, 0, 4>(qf[hh], Ks + c * (2 * 64 * LSTR), Vs + c * (2 * 64 * LSTR), mref[hh], ls[hh], o[hh][0], o[hh][1],
;                               sl2, dl, true, false, r, h, LSTR, lo);
.LBB0_305:
	s_or_b64 exec, exec, s[4:5]
	v_subrev_u32_e32 v217, 64, v184
	v_or_b32_e32 v218, 63, v217
	s_and_saveexec_b64 s[4:5], s[36:37]
	s_cbranch_execz .LBB0_311
	v_cmp_le_i32_e32 vcc, v217, v210
	v_cmp_ge_i32_e64 s[2:3], v218, v211
	s_and_b64 s[6:7], vcc, s[2:3]
	s_and_saveexec_b64 s[2:3], s[6:7]
	s_cbranch_execz .LBB0_310
	v_sub_u32_e32 v82, v214, v184
	v_add3_u32 v230, v82, v208, 64
	s_mov_b32 s6, 2.0
	v_cvt_f32_i32_e32 v82, v230
	s_mov_b32 s7, 0x40400000
	v_lshlrev_b32_e32 v209, 1, v159
	ds_read_b128 v[98:101], v209 offset:18432
	v_fma_f32 v226, -v186, v82, -v220
	v_fma_f32 v84, v186, s6, v226
	v_fma_f32 v85, v186, s7, v226
	s_mov_b32 s6, 0x41000000
	s_mov_b32 s7, 0x41100000
	v_fma_f32 v86, v186, s6, v226
	v_fma_f32 v87, v186, s7, v226
	s_mov_b32 s6, 0x41200000
	s_mov_b32 s7, 0x41300000
	v_fma_f32 v88, v186, s6, v226
	v_fma_f32 v89, v186, s7, v226
	s_mov_b32 s6, 0x41800000
	ds_read_b128 v[222:225], v209 offset:23040
	s_mov_b32 s7, 0x41880000
	v_fma_f32 v90, v186, s6, v226
	v_fma_f32 v91, v186, s7, v226
	s_mov_b32 s6, 0x41900000
	s_mov_b32 s7, 0x41980000
	v_fma_f32 v92, v186, s6, v226
	v_fma_f32 v93, v186, s7, v226
	s_mov_b32 s6, 0x42680000
	s_mov_b32 s7, 0x426c0000
	v_fma_f32 v112, v186, s6, v226
	v_fma_f32 v113, v186, s7, v226
	s_mov_b32 s6, 0x42400000
	v_fma_f32 v82, 0, v186, v226
	v_add_f32_e32 v83, v186, v226
	v_fma_f32 v94, v186, s50, v226
	v_fma_f32 v95, v186, s51, v226
	v_fma_f32 v96, v186, s28, v226
	v_fma_f32 v97, v186, s29, v226
	s_mov_b32 s7, 0x42440000
	v_fma_f32 v110, v186, s30, v226
	v_fma_f32 v111, v186, s31, v226
	s_waitcnt lgkmcnt(1)
	v_mfma_f32_32x32x16_bf16 v[82:97], v[98:101], v[126:129], v[82:97]
	v_fma_f32 v108, v186, s10, v226
	v_fma_f32 v109, v186, s11, v226
	v_fma_f32 v106, v186, s6, v226
	v_fma_f32 v107, v186, s7, v226
	v_fma_f32 v104, v186, s72, v226
	v_fma_f32 v105, v186, s73, v226
	v_fma_f32 v102, v186, s74, v226
	v_fma_f32 v103, v186, s75, v226
	v_fma_f32 v100, v186, s76, v226
	v_fma_f32 v101, v186, s77, v226
	v_fma_f32 v98, v186, s78, v226
	v_fma_f32 v99, v186, s79, v226
	v_add_u32_e32 v215, -1, v230
	v_cmp_gt_u32_e32 vcc, s95, v215
	s_waitcnt lgkmcnt(0)
	v_mfma_f32_32x32x16_bf16 v[98:113], v[222:225], v[126:129], v[98:113]
	ds_read_b128 v[222:225], v209 offset:18464
	v_subrev_u32_e32 v215, 33, v230
	v_subrev_u32_e32 v221, 32, v230
	s_waitcnt lgkmcnt(0)
	v_mfma_f32_32x32x16_bf16 v[82:97], v[222:225], v[122:125], v[82:97]
	ds_read_b128 v[222:225], v209 offset:23072
	s_waitcnt lgkmcnt(0)
	v_mfma_f32_32x32x16_bf16 v[98:113], v[222:225], v[122:125], v[98:113]
	ds_read_b128 v[222:225], v209 offset:18496
	s_waitcnt lgkmcnt(0)
	v_mfma_f32_32x32x16_bf16 v[82:97], v[222:225], v[118:121], v[82:97]
	ds_read_b128 v[222:225], v209 offset:23104
	s_waitcnt lgkmcnt(0)
	v_mfma_f32_32x32x16_bf16 v[98:113], v[222:225], v[118:121], v[98:113]
	ds_read_b128 v[222:225], v209 offset:18528
	ds_read_b128 v[226:229], v209 offset:23136
	s_waitcnt lgkmcnt(1)
	v_mfma_f32_32x32x16_bf16 v[82:97], v[222:225], v[114:117], v[82:97]
	s_waitcnt lgkmcnt(0)
	v_mfma_f32_32x32x16_bf16 v[98:113], v[226:229], v[114:117], v[98:113]
	s_nop 9
	v_cndmask_b32_e32 v83, v199, v83, vcc
	v_cmp_gt_u32_e32 vcc, s95, v230
	s_nop 1
	v_cndmask_b32_e32 v82, v199, v82, vcc
	v_cmp_gt_u32_e32 vcc, s95, v215
	s_nop 1
	v_cndmask_b32_e32 v99, v199, v99, vcc
	v_cmp_gt_u32_e32 vcc, s95, v221
	v_add_u32_e32 v221, -2, v230
	s_nop 0
	v_cndmask_b32_e32 v215, v199, v98, vcc
	v_add_u32_e32 v98, -3, v230
	v_cmp_gt_u32_e32 vcc, s95, v98
	v_subrev_u32_e32 v98, 35, v230
	s_nop 0
	v_cndmask_b32_e32 v85, v199, v85, vcc
	v_cmp_gt_u32_e32 vcc, s95, v221
	v_subrev_u32_e32 v221, 34, v230
	s_nop 0
	v_cndmask_b32_e32 v84, v199, v84, vcc
	v_cmp_gt_u32_e32 vcc, s95, v98
	s_nop 1
	v_cndmask_b32_e32 v98, v199, v101, vcc
	v_cmp_gt_u32_e32 vcc, s95, v221
	v_add_u32_e32 v221, -8, v230
	s_nop 0
	v_cndmask_b32_e32 v101, v199, v100, vcc
	v_add_u32_e32 v100, -9, v230
	v_cmp_gt_u32_e32 vcc, s95, v100
	s_nop 1
	v_cndmask_b32_e32 v222, v199, v87, vcc
	v_cmp_gt_u32_e32 vcc, s95, v221
	v_subrev_u32_e32 v87, 40, v230
	s_nop 0
	v_cndmask_b32_e32 v223, v199, v86, vcc
	v_subrev_u32_e32 v86, 41, v230
	v_cmp_gt_u32_e32 vcc, s95, v86
	v_add_u32_e32 v86, -11, v230
	s_nop 0
	v_cndmask_b32_e32 v100, v199, v103, vcc
	v_cmp_gt_u32_e32 vcc, s95, v87
	v_add_u32_e32 v87, -10, v230
	s_nop 0
	v_cndmask_b32_e32 v102, v199, v102, vcc
	v_cmp_gt_u32_e32 vcc, s95, v86
	v_subrev_u32_e32 v86, 43, v230
	s_nop 0
	v_cndmask_b32_e32 v224, v199, v89, vcc
	v_cmp_gt_u32_e32 vcc, s95, v87
	v_subrev_u32_e32 v87, 42, v230
	v_subrev_u32_e32 v89, 18, v230
	v_cndmask_b32_e32 v225, v199, v88, vcc
	v_cmp_gt_u32_e32 vcc, s95, v86
	v_subrev_u32_e32 v86, 17, v230
	v_subrev_u32_e32 v88, 19, v230
	v_cndmask_b32_e32 v103, v199, v105, vcc
	v_cmp_gt_u32_e32 vcc, s95, v87
	v_add_u32_e32 v87, -16, v230
	s_nop 0
	v_cndmask_b32_e32 v104, v199, v104, vcc
	v_cmp_gt_u32_e32 vcc, s95, v86
	v_subrev_u32_e32 v86, 49, v230
	s_nop 0
	v_cndmask_b32_e32 v105, v199, v91, vcc
	v_cmp_gt_u32_e32 vcc, s95, v87
	v_subrev_u32_e32 v87, 48, v230
	v_subrev_u32_e32 v91, 24, v230
	v_cndmask_b32_e32 v221, v199, v90, vcc
	v_cmp_gt_u32_e32 vcc, s95, v86
	v_subrev_u32_e32 v90, 25, v230
	s_nop 0
	v_cndmask_b32_e32 v86, v199, v107, vcc
	v_cmp_gt_u32_e32 vcc, s95, v87
	s_nop 1
	v_cndmask_b32_e32 v87, v199, v106, vcc
	v_cmp_gt_u32_e32 vcc, s95, v88
	v_subrev_u32_e32 v88, 51, v230
	s_nop 0
	v_cndmask_b32_e32 v106, v199, v93, vcc
	v_cmp_gt_u32_e32 vcc, s95, v89
	v_subrev_u32_e32 v89, 50, v230
	v_subrev_u32_e32 v93, 26, v230
	v_cndmask_b32_e32 v107, v199, v92, vcc
	v_cmp_gt_u32_e32 vcc, s95, v88
	v_subrev_u32_e32 v92, 27, v230
	s_nop 0
	v_cndmask_b32_e32 v88, v199, v109, vcc
	v_cmp_gt_u32_e32 vcc, s95, v89
	s_nop 1
	v_cndmask_b32_e32 v89, v199, v108, vcc
	v_cmp_gt_u32_e32 vcc, s95, v90
	v_subrev_u32_e32 v90, 57, v230
	s_nop 0
	v_cndmask_b32_e32 v95, v199, v95, vcc
	v_cmp_gt_u32_e32 vcc, s95, v91
	v_subrev_u32_e32 v91, 56, v230
	s_nop 0
	v_cndmask_b32_e32 v94, v199, v94, vcc
	v_cmp_gt_u32_e32 vcc, s95, v90
	s_nop 1
	v_cndmask_b32_e32 v90, v199, v111, vcc
	v_cmp_gt_u32_e32 vcc, s95, v91
	s_nop 1
	v_cndmask_b32_e32 v91, v199, v110, vcc
	v_cmp_gt_u32_e32 vcc, s95, v92
	v_subrev_u32_e32 v92, 59, v230
	s_nop 0
	v_cndmask_b32_e32 v97, v199, v97, vcc
	v_cmp_gt_u32_e32 vcc, s95, v93
	v_subrev_u32_e32 v93, 58, v230
	s_nop 0
	v_cndmask_b32_e32 v96, v199, v96, vcc
	v_cmp_gt_u32_e32 vcc, s95, v92
	s_nop 1
	v_cndmask_b32_e32 v92, v199, v113, vcc
	v_cmp_gt_u32_e32 vcc, s95, v93
	s_nop 1
	v_cndmask_b32_e32 v93, v199, v112, vcc
	v_cmp_nge_f32_e32 vcc, s9, v50
	s_cbranch_vccz .LBB0_309
; DI float ex2(float x) { return __builtin_amdgcn_exp2f(x); }
; DI float lg2(float x) { return __builtin_amdgcn_logf(x); }
; template <int MODE, int KS0, int NKS>
; DI void softmax_pv(const bf16x8 (&qf)[4], const u16* Ks, const u16* Vs, float& m, f32x16& ls, f32x16& o0, f32x16& o1,
;                    float sl2, int dl, bool need_mask, bool first, int r, int h, int rs, const int (&lo)[4]) {
;     ...
;   if (__any(first || !(ls[0] <= 1.0e12f))) {
;     float tmax = -INFINITY;
; #pragma unroll
;     for (int i = 0; i < 16; ++i) tmax = fmaxf(tmax, fmaxf(s0[i], s1[i]));
;     tmax = fmaxf(tmax, shx(tmax, r + 32 * h));
;     const float lref = (ls[0] > 1.f) ? lg2(ls[0]) : 0.f;
;     const float delta = first ? tmax : fmaxf(fmaxf(tmax, lref), 0.f);
;     m += delta;
;     const float alpha = ex2(-delta);
; #pragma unroll
;     for (int e = 0; e < 16; ++e) { o0[e] *= alpha; o1[e] *= alpha; ls[e] *= alpha; }
; #pragma unroll
;     for (int i = 0; i < 16; ++i) { s0[i] -= delta; s1[i] -= delta; }
;   }
	v_max_f32_e32 v108, v215, v215
	v_max_f32_e32 v109, v82, v82
	v_max_f32_e32 v108, v109, v108
	v_max_f32_e32 v109, v99, v99
	v_max_f32_e32 v110, v83, v83
	v_max_f32_e32 v109, v110, v109
	s_mov_b32 s6, 0xff800000
	v_max3_f32 v108, v108, s6, v109
	v_max_f32_e32 v109, v101, v101
	v_max_f32_e32 v110, v84, v84
	v_max_f32_e32 v109, v110, v109
	v_max_f32_e32 v110, v98, v98
	v_max_f32_e32 v111, v85, v85
	v_max_f32_e32 v110, v111, v110
	v_max3_f32 v108, v108, v109, v110
	v_max_f32_e32 v109, v102, v102
	v_max_f32_e32 v110, v223, v223
	v_max_f32_e32 v109, v110, v109
	v_max_f32_e32 v110, v100, v100
	v_max_f32_e32 v111, v222, v222
	v_max_f32_e32 v110, v111, v110
	v_max3_f32 v108, v108, v109, v110
	v_max_f32_e32 v109, v104, v104
	v_max_f32_e32 v110, v225, v225
	v_max_f32_e32 v109, v110, v109
	v_max_f32_e32 v110, v103, v103
	v_max_f32_e32 v111, v224, v224
	v_max_f32_e32 v110, v111, v110
	v_max3_f32 v108, v108, v109, v110
	v_max_f32_e32 v109, v87, v87
	v_max_f32_e32 v110, v221, v221
	v_max_f32_e32 v109, v110, v109
	v_max_f32_e32 v110, v86, v86
	v_max_f32_e32 v111, v105, v105
	v_max_f32_e32 v110, v111, v110
	v_max3_f32 v108, v108, v109, v110
	v_max_f32_e32 v109, v89, v89
	v_max_f32_e32 v110, v107, v107
	v_max_f32_e32 v109, v110, v109
	v_max_f32_e32 v110, v88, v88
	v_max_f32_e32 v111, v106, v106
	v_max_f32_e32 v110, v111, v110
	v_max3_f32 v108, v108, v109, v110
	v_max_f32_e32 v109, v91, v91
	v_max_f32_e32 v110, v94, v94
	v_max_f32_e32 v109, v110, v109
	v_max_f32_e32 v110, v90, v90
	v_max_f32_e32 v111, v95, v95
	v_max_f32_e32 v110, v111, v110
	v_max3_f32 v108, v108, v109, v110
	v_max_f32_e32 v109, v93, v93
	v_max_f32_e32 v110, v96, v96
	v_max_f32_e32 v109, v110, v109
	v_max_f32_e32 v110, v92, v92
	v_max_f32_e32 v111, v97, v97
	v_max_f32_e32 v110, v111, v110
	v_max3_f32 v108, v108, v109, v110
	ds_bpermute_b32 v109, v185, v108
	v_log_f32_e32 v110, v50
	v_cmp_lt_f32_e32 vcc, 1.0, v50
	s_waitcnt lgkmcnt(0)
	v_max_f32_e32 v109, v109, v109
	v_max_f32_e32 v108, v108, v109
	v_cndmask_b32_e32 v109, 0, v110, vcc
	v_max3_f32 v109, v108, v109, 0
	v_exp_f32_e64 v108, -v109
	v_add_f32_e32 v220, v220, v109
	v_sub_f32_e32 v82, v82, v109
	v_sub_f32_e32 v83, v83, v109
	v_mul_f32_e32 v80, v80, v108
	v_mul_f32_e32 v81, v81, v108
	v_mul_f32_e32 v78, v78, v108
	v_mul_f32_e32 v79, v79, v108
	v_mul_f32_e32 v76, v76, v108
	v_mul_f32_e32 v77, v77, v108
	v_mul_f32_e32 v74, v74, v108
	v_mul_f32_e32 v75, v75, v108
	v_mul_f32_e32 v72, v72, v108
	v_mul_f32_e32 v73, v73, v108
	v_mul_f32_e32 v70, v70, v108
	v_mul_f32_e32 v71, v71, v108
	v_mul_f32_e32 v68, v68, v108
	v_mul_f32_e32 v69, v69, v108
	v_mul_f32_e32 v66, v66, v108
	v_mul_f32_e32 v67, v67, v108
	v_mul_f32_e32 v48, v48, v108
	v_mul_f32_e32 v49, v49, v108
	v_mul_f32_e32 v46, v46, v108
	v_mul_f32_e32 v47, v47, v108
	v_mul_f32_e32 v44, v44, v108
	v_mul_f32_e32 v45, v45, v108
	v_mul_f32_e32 v42, v42, v108
	v_mul_f32_e32 v43, v43, v108
	v_mul_f32_e32 v40, v40, v108
	v_mul_f32_e32 v41, v41, v108
	v_mul_f32_e32 v38, v38, v108
	v_mul_f32_e32 v39, v39, v108
	v_mul_f32_e32 v36, v36, v108
	v_mul_f32_e32 v37, v37, v108
	v_mul_f32_e32 v34, v34, v108
	v_mul_f32_e32 v35, v35, v108
	v_mul_f32_e32 v64, v64, v108
	v_mul_f32_e32 v65, v65, v108
	v_mul_f32_e32 v62, v62, v108
	v_mul_f32_e32 v63, v63, v108
	v_mul_f32_e32 v60, v60, v108
	v_mul_f32_e32 v61, v61, v108
	v_mul_f32_e32 v58, v58, v108
	v_mul_f32_e32 v59, v59, v108
	v_mul_f32_e32 v56, v56, v108
	v_mul_f32_e32 v57, v57, v108
	v_mul_f32_e32 v54, v54, v108
	v_mul_f32_e32 v55, v55, v108
	v_mul_f32_e32 v52, v52, v108
	v_mul_f32_e32 v53, v53, v108
	v_mul_f32_e32 v50, v50, v108
	v_mul_f32_e32 v51, v51, v108
	v_sub_f32_e32 v84, v84, v109
	v_sub_f32_e32 v85, v85, v109
	v_sub_f32_e32 v223, v223, v109
	v_sub_f32_e32 v222, v222, v109
	v_sub_f32_e32 v225, v225, v109
	v_sub_f32_e32 v224, v224, v109
	v_sub_f32_e32 v221, v221, v109
	v_sub_f32_e32 v105, v105, v109
	v_sub_f32_e32 v107, v107, v109
	v_sub_f32_e32 v106, v106, v109
	v_sub_f32_e32 v94, v94, v109
	v_sub_f32_e32 v95, v95, v109
	v_sub_f32_e32 v96, v96, v109
	v_sub_f32_e32 v97, v97, v109
	v_sub_f32_e32 v215, v215, v109
	v_sub_f32_e32 v99, v99, v109
	v_sub_f32_e32 v101, v101, v109
	v_sub_f32_e32 v98, v98, v109
	v_sub_f32_e32 v102, v102, v109
	v_sub_f32_e32 v100, v100, v109
	v_sub_f32_e32 v104, v104, v109
	v_sub_f32_e32 v103, v103, v109
	v_sub_f32_e32 v87, v87, v109
	v_sub_f32_e32 v86, v86, v109
	v_sub_f32_e32 v89, v89, v109
	v_sub_f32_e32 v88, v88, v109
	v_sub_f32_e32 v91, v91, v109
	v_sub_f32_e32 v90, v90, v109
	v_sub_f32_e32 v93, v93, v109
	v_sub_f32_e32 v92, v92, v109

; DI f32x16 mfma(bf16x8 a, bf16x8 b, f32x16 c) { return __builtin_amdgcn_mfma_f32_32x32x16_bf16(a, b, c, 0, 0, 0); }
; template <int MODE, int KS0, int NKS>
; DI void qk_scores(f32x16& s0, f32x16& s1, const u16* Ks, const bf16x8 (&qf)[4], float sl2, int dl, float mref,
;                   bool need_mask, int r, int h, int rs, const int (&lo)[4]) {
;   asm volatile("" : "+v"(dl));
;   const float nb = -sl2 * (float)dl - mref;
; #pragma unroll
;   for (int i = 0; i < 16; ++i) {
;     const int ci = (i & 3) + 8 * (i >> 2);
;     s0[i] = fmaf(sl2, (float)ci, nb);
;     s1[i] = fmaf(sl2, (float)(ci + 32), nb);
;   }
; #pragma unroll
;   for (int ks = 0; ks < NKS; ++ks) {
;     bf16x8 k0 = ldsv(Ks + lo[KS0 + ks]);
;     bf16x8 k1 = ldsv(Ks + 32 * rs + lo[KS0 + ks]);
;     s0 = mfma(k0, qf[KS0 + ks], s0);
;     s1 = mfma(k1, qf[KS0 + ks], s1);
;   }
;   if (need_mask) {
; #pragma unroll
;     for (int i = 0; i < 16; ++i) {
;       const int ci = (i & 3) + 8 * (i >> 2);
;       bool v0 = (MODE == 0) ? (ci <= dl) : (ci <= dl && ci > dl - 128);
;       bool v1 = (MODE == 0) ? (ci + 32 <= dl) : (ci + 32 <= dl && ci + 32 > dl - 128);
;       s0[i] = v0 ? s0[i] : -INFINITY;
;       s1[i] = v1 ? s1[i] : -INFINITY;
;     }
;   }
; DI void attn_item_B2(const Params& p, int layer, int b, int head0, int qblk, u16* sm, int wv) {
;     ...
;     for (int c = 0; c < 4; ++c) {
;       if (c >= it0) {
;         const int k0 = q0 - 128 + 64 * c;
;         const bool skip = (k0 > q0w + 31) || (k0 + 63 < q0w - 127);
;         if (!skip) {
;           const int dl = qpos - k0 - 4 * h;
;           softmax_pv<1, 0, 4>(qf[hh], Ks + c * (2 * 64 * LSTR), Vs + c * (2 * 64 * LSTR), mref[hh], ls[hh], o[hh][0], o[hh][1],
;                               sl2, dl, true, false, r, h, LSTR, lo);
.LBB0_311:
	s_or_b64 exec, exec, s[4:5]
	v_or_b32_e32 v82, 63, v184
	v_cmp_le_i32_e32 vcc, v184, v210
	v_cmp_ge_i32_e64 s[2:3], v82, v211
	v_sub_u32_e32 v221, v214, v184
	s_and_b64 s[4:5], vcc, s[2:3]
	v_lshlrev_b32_e32 v209, 1, v159
	v_add_u32_e32 v215, v221, v208
	s_and_saveexec_b64 s[2:3], s[4:5]
	s_cbranch_execz .LBB0_315
	v_mov_b32_e32 v230, v215
	s_mov_b32 s6, 2.0
	v_cvt_f32_i32_e32 v82, v230
	s_mov_b32 s7, 0x40400000
	ds_read_b128 v[98:101], v209 offset:36864
	ds_read_b128 v[222:225], v209 offset:41472
	v_fma_f32 v226, -v186, v82, -v220
	v_fma_f32 v84, v186, s6, v226
	v_fma_f32 v85, v186, s7, v226
	s_mov_b32 s6, 0x41000000
	s_mov_b32 s7, 0x41100000
	v_fma_f32 v86, v186, s6, v226
	v_fma_f32 v87, v186, s7, v226
	s_mov_b32 s6, 0x41200000
	s_mov_b32 s7, 0x41300000
	v_fma_f32 v88, v186, s6, v226
	v_fma_f32 v89, v186, s7, v226
	s_mov_b32 s6, 0x41800000
	s_mov_b32 s7, 0x41880000
	v_fma_f32 v90, v186, s6, v226
	v_fma_f32 v91, v186, s7, v226
	s_mov_b32 s6, 0x41900000
	s_mov_b32 s7, 0x41980000
	v_fma_f32 v92, v186, s6, v226
	v_fma_f32 v93, v186, s7, v226
	s_mov_b32 s6, 0x42680000
	s_mov_b32 s7, 0x426c0000
	v_fma_f32 v112, v186, s6, v226
	v_fma_f32 v113, v186, s7, v226
	s_mov_b32 s6, 0x42400000
	v_fma_f32 v82, 0, v186, v226
	v_add_f32_e32 v83, v186, v226
	v_fma_f32 v94, v186, s50, v226
	v_fma_f32 v95, v186, s51, v226
	v_fma_f32 v96, v186, s28, v226
	v_fma_f32 v97, v186, s29, v226
	s_mov_b32 s7, 0x42440000
	v_fma_f32 v110, v186, s30, v226
	v_fma_f32 v111, v186, s31, v226
	s_waitcnt lgkmcnt(1)
	v_mfma_f32_32x32x16_bf16 v[82:97], v[98:101], v[126:129], v[82:97]
	v_fma_f32 v108, v186, s10, v226
	v_fma_f32 v109, v186, s11, v226
	v_fma_f32 v106, v186, s6, v226
	v_fma_f32 v107, v186, s7, v226
	v_fma_f32 v104, v186, s72, v226
	v_fma_f32 v105, v186, s73, v226
	v_fma_f32 v102, v186, s74, v226
	v_fma_f32 v103, v186, s75, v226
	v_fma_f32 v100, v186, s76, v226
	v_fma_f32 v101, v186, s77, v226
	v_fma_f32 v98, v186, s78, v226
	v_fma_f32 v99, v186, s79, v226
	v_add_u32_e32 v231, -1, v230
	v_cmp_gt_u32_e32 vcc, s95, v231
	s_waitcnt lgkmcnt(0)
	v_mfma_f32_32x32x16_bf16 v[98:113], v[222:225], v[126:129], v[98:113]
	ds_read_b128 v[222:225], v209 offset:36896
	s_waitcnt lgkmcnt(0)
	v_mfma_f32_32x32x16_bf16 v[82:97], v[222:225], v[122:125], v[82:97]
	ds_read_b128 v[222:225], v209 offset:41504
	s_waitcnt lgkmcnt(0)
	v_mfma_f32_32x32x16_bf16 v[98:113], v[222:225], v[122:125], v[98:113]
	ds_read_b128 v[222:225], v209 offset:36928
	s_waitcnt lgkmcnt(0)
	v_mfma_f32_32x32x16_bf16 v[82:97], v[222:225], v[118:121], v[82:97]
	ds_read_b128 v[222:225], v209 offset:41536
	s_waitcnt lgkmcnt(0)
	v_mfma_f32_32x32x16_bf16 v[98:113], v[222:225], v[118:121], v[98:113]
	ds_read_b128 v[222:225], v209 offset:36960
	ds_read_b128 v[226:229], v209 offset:41568
	s_waitcnt lgkmcnt(1)
	v_mfma_f32_32x32x16_bf16 v[82:97], v[222:225], v[114:117], v[82:97]
	v_subrev_u32_e32 v222, 33, v230
	v_subrev_u32_e32 v223, 32, v230
	s_waitcnt lgkmcnt(0)
	v_mfma_f32_32x32x16_bf16 v[98:113], v[226:229], v[114:117], v[98:113]
	s_nop 7
	v_cndmask_b32_e32 v83, v199, v83, vcc
	v_cmp_gt_u32_e32 vcc, s95, v230
	s_nop 1
	v_cndmask_b32_e32 v82, v199, v82, vcc
	v_cmp_gt_u32_e32 vcc, s95, v222
	s_nop 1
	v_cndmask_b32_e32 v99, v199, v99, vcc
	v_cmp_gt_u32_e32 vcc, s95, v223
	v_add_u32_e32 v223, -2, v230
	s_nop 0
	v_cndmask_b32_e32 v222, v199, v98, vcc
	v_add_u32_e32 v98, -3, v230
	v_cmp_gt_u32_e32 vcc, s95, v98
	v_subrev_u32_e32 v98, 35, v230
	s_nop 0
	v_cndmask_b32_e32 v85, v199, v85, vcc
	v_cmp_gt_u32_e32 vcc, s95, v223
	v_subrev_u32_e32 v223, 34, v230
	s_nop 0
	v_cndmask_b32_e32 v84, v199, v84, vcc
	v_cmp_gt_u32_e32 vcc, s95, v98
	s_nop 1
	v_cndmask_b32_e32 v98, v199, v101, vcc
	v_cmp_gt_u32_e32 vcc, s95, v223
	v_add_u32_e32 v223, -8, v230
	s_nop 0
	v_cndmask_b32_e32 v101, v199, v100, vcc
	v_add_u32_e32 v100, -9, v230
	v_cmp_gt_u32_e32 vcc, s95, v100
	s_nop 1
	v_cndmask_b32_e32 v224, v199, v87, vcc
	v_cmp_gt_u32_e32 vcc, s95, v223
	v_subrev_u32_e32 v87, 40, v230
	s_nop 0
	v_cndmask_b32_e32 v225, v199, v86, vcc
	v_subrev_u32_e32 v86, 41, v230
	v_cmp_gt_u32_e32 vcc, s95, v86
	v_add_u32_e32 v86, -11, v230
	s_nop 0
	v_cndmask_b32_e32 v100, v199, v103, vcc
	v_cmp_gt_u32_e32 vcc, s95, v87
	v_add_u32_e32 v87, -10, v230
	s_nop 0
	v_cndmask_b32_e32 v102, v199, v102, vcc
	v_cmp_gt_u32_e32 vcc, s95, v86
	v_subrev_u32_e32 v86, 43, v230
	s_nop 0
	v_cndmask_b32_e32 v226, v199, v89, vcc
	v_cmp_gt_u32_e32 vcc, s95, v87
	v_subrev_u32_e32 v87, 42, v230
	v_subrev_u32_e32 v89, 18, v230
	v_cndmask_b32_e32 v227, v199, v88, vcc
	v_cmp_gt_u32_e32 vcc, s95, v86
	v_subrev_u32_e32 v86, 17, v230
	v_subrev_u32_e32 v88, 19, v230
	v_cndmask_b32_e32 v103, v199, v105, vcc
	v_cmp_gt_u32_e32 vcc, s95, v87
	v_add_u32_e32 v87, -16, v230
	s_nop 0
	v_cndmask_b32_e32 v104, v199, v104, vcc
	v_cmp_gt_u32_e32 vcc, s95, v86
	v_subrev_u32_e32 v86, 49, v230
	s_nop 0
	v_cndmask_b32_e32 v105, v199, v91, vcc
	v_cmp_gt_u32_e32 vcc, s95, v87
	v_subrev_u32_e32 v87, 48, v230
	v_subrev_u32_e32 v91, 24, v230
	v_cndmask_b32_e32 v223, v199, v90, vcc
	v_cmp_gt_u32_e32 vcc, s95, v86
	v_subrev_u32_e32 v90, 25, v230
	s_nop 0
	v_cndmask_b32_e32 v86, v199, v107, vcc
	v_cmp_gt_u32_e32 vcc, s95, v87
	s_nop 1
	v_cndmask_b32_e32 v87, v199, v106, vcc
	v_cmp_gt_u32_e32 vcc, s95, v88
	v_subrev_u32_e32 v88, 51, v230
	s_nop 0
	v_cndmask_b32_e32 v106, v199, v93, vcc
	v_cmp_gt_u32_e32 vcc, s95, v89
	v_subrev_u32_e32 v89, 50, v230
	v_subrev_u32_e32 v93, 26, v230
	v_cndmask_b32_e32 v107, v199, v92, vcc
	v_cmp_gt_u32_e32 vcc, s95, v88
	v_subrev_u32_e32 v92, 27, v230
	s_nop 0
	v_cndmask_b32_e32 v88, v199, v109, vcc
	v_cmp_gt_u32_e32 vcc, s95, v89
	s_nop 1
	v_cndmask_b32_e32 v89, v199, v108, vcc
	v_cmp_gt_u32_e32 vcc, s95, v90
	v_subrev_u32_e32 v90, 57, v230
	s_nop 0
	v_cndmask_b32_e32 v95, v199, v95, vcc
	v_cmp_gt_u32_e32 vcc, s95, v91
	v_subrev_u32_e32 v91, 56, v230
	s_nop 0
	v_cndmask_b32_e32 v94, v199, v94, vcc
	v_cmp_gt_u32_e32 vcc, s95, v90
	s_nop 1
	v_cndmask_b32_e32 v90, v199, v111, vcc
	v_cmp_gt_u32_e32 vcc, s95, v91
	s_nop 1
	v_cndmask_b32_e32 v91, v199, v110, vcc
	v_cmp_gt_u32_e32 vcc, s95, v92
	v_subrev_u32_e32 v92, 59, v230
	s_nop 0
	v_cndmask_b32_e32 v97, v199, v97, vcc
	v_cmp_gt_u32_e32 vcc, s95, v93
	v_subrev_u32_e32 v93, 58, v230
	s_nop 0
	v_cndmask_b32_e32 v96, v199, v96, vcc
	v_cmp_gt_u32_e32 vcc, s95, v92
	s_nop 1
	v_cndmask_b32_e32 v92, v199, v113, vcc
	v_cmp_gt_u32_e32 vcc, s95, v93
	s_nop 1
	v_cndmask_b32_e32 v93, v199, v112, vcc
	v_cmp_nge_f32_e32 vcc, s9, v50
	s_cbranch_vccz .LBB0_314
; DI float ex2(float x) { return __builtin_amdgcn_exp2f(x); }
; DI float lg2(float x) { return __builtin_amdgcn_logf(x); }
; template <int MODE, int KS0, int NKS>
; DI void softmax_pv(const bf16x8 (&qf)[4], const u16* Ks, const u16* Vs, float& m, f32x16& ls, f32x16& o0, f32x16& o1,
;                    float sl2, int dl, bool need_mask, bool first, int r, int h, int rs, const int (&lo)[4]) {
;     ...
;   if (__any(first || !(ls[0] <= 1.0e12f))) {
;     float tmax = -INFINITY;
; #pragma unroll
;     for (int i = 0; i < 16; ++i) tmax = fmaxf(tmax, fmaxf(s0[i], s1[i]));
;     tmax = fmaxf(tmax, shx(tmax, r + 32 * h));
;     const float lref = (ls[0] > 1.f) ? lg2(ls[0]) : 0.f;
;     const float delta = first ? tmax : fmaxf(fmaxf(tmax, lref), 0.f);
;     m += delta;
;     const float alpha = ex2(-delta);
; #pragma unroll
;     for (int e = 0; e < 16; ++e) { o0[e] *= alpha; o1[e] *= alpha; ls[e] *= alpha; }
; #pragma unroll
;     for (int i = 0; i < 16; ++i) { s0[i] -= delta; s1[i] -= delta; }
;   }
	v_max_f32_e32 v108, v222, v222
	v_max_f32_e32 v109, v82, v82
	v_max_f32_e32 v108, v109, v108
	v_max_f32_e32 v109, v99, v99
	v_max_f32_e32 v110, v83, v83
	v_max_f32_e32 v109, v110, v109
	s_mov_b32 s6, 0xff800000
	v_max3_f32 v108, v108, s6, v109
	v_max_f32_e32 v109, v101, v101
	v_max_f32_e32 v110, v84, v84
	v_max_f32_e32 v109, v110, v109
	v_max_f32_e32 v110, v98, v98
	v_max_f32_e32 v111, v85, v85
	v_max_f32_e32 v110, v111, v110
	v_max3_f32 v108, v108, v109, v110
	v_max_f32_e32 v109, v102, v102
	v_max_f32_e32 v110, v225, v225
	v_max_f32_e32 v109, v110, v109
	v_max_f32_e32 v110, v100, v100
	v_max_f32_e32 v111, v224, v224
	v_max_f32_e32 v110, v111, v110
	v_max3_f32 v108, v108, v109, v110
	v_max_f32_e32 v109, v104, v104
	v_max_f32_e32 v110, v227, v227
	v_max_f32_e32 v109, v110, v109
	v_max_f32_e32 v110, v103, v103
	v_max_f32_e32 v111, v226, v226
	v_max_f32_e32 v110, v111, v110
	v_max3_f32 v108, v108, v109, v110
	v_max_f32_e32 v109, v87, v87
	v_max_f32_e32 v110, v223, v223
	v_max_f32_e32 v109, v110, v109
	v_max_f32_e32 v110, v86, v86
	v_max_f32_e32 v111, v105, v105
	v_max_f32_e32 v110, v111, v110
	v_max3_f32 v108, v108, v109, v110
	v_max_f32_e32 v109, v89, v89
	v_max_f32_e32 v110, v107, v107
	v_max_f32_e32 v109, v110, v109
	v_max_f32_e32 v110, v88, v88
	v_max_f32_e32 v111, v106, v106
	v_max_f32_e32 v110, v111, v110
	v_max3_f32 v108, v108, v109, v110
	v_max_f32_e32 v109, v91, v91
	v_max_f32_e32 v110, v94, v94
	v_max_f32_e32 v109, v110, v109
	v_max_f32_e32 v110, v90, v90
	v_max_f32_e32 v111, v95, v95
	v_max_f32_e32 v110, v111, v110
	v_max3_f32 v108, v108, v109, v110
	v_max_f32_e32 v109, v93, v93
	v_max_f32_e32 v110, v96, v96
	v_max_f32_e32 v109, v110, v109
	v_max_f32_e32 v110, v92, v92
	v_max_f32_e32 v111, v97, v97
	v_max_f32_e32 v110, v111, v110
	v_max3_f32 v108, v108, v109, v110
	ds_bpermute_b32 v109, v185, v108
	v_log_f32_e32 v110, v50
	v_cmp_lt_f32_e32 vcc, 1.0, v50
	s_waitcnt lgkmcnt(0)
	v_max_f32_e32 v109, v109, v109
	v_max_f32_e32 v108, v108, v109
	v_cndmask_b32_e32 v109, 0, v110, vcc
	v_max3_f32 v109, v108, v109, 0
	v_exp_f32_e64 v108, -v109
	v_add_f32_e32 v220, v220, v109
	v_sub_f32_e32 v82, v82, v109
	v_sub_f32_e32 v83, v83, v109
	v_mul_f32_e32 v80, v80, v108
	v_mul_f32_e32 v81, v81, v108
	v_mul_f32_e32 v78, v78, v108
	v_mul_f32_e32 v79, v79, v108
	v_mul_f32_e32 v76, v76, v108
	v_mul_f32_e32 v77, v77, v108
	v_mul_f32_e32 v74, v74, v108
	v_mul_f32_e32 v75, v75, v108
	v_mul_f32_e32 v72, v72, v108
	v_mul_f32_e32 v73, v73, v108
	v_mul_f32_e32 v70, v70, v108
	v_mul_f32_e32 v71, v71, v108
	v_mul_f32_e32 v68, v68, v108
	v_mul_f32_e32 v69, v69, v108
	v_mul_f32_e32 v66, v66, v108
	v_mul_f32_e32 v67, v67, v108
	v_mul_f32_e32 v48, v48, v108
	v_mul_f32_e32 v49, v49, v108
	v_mul_f32_e32 v46, v46, v108
	v_mul_f32_e32 v47, v47, v108
	v_mul_f32_e32 v44, v44, v108
	v_mul_f32_e32 v45, v45, v108
	v_mul_f32_e32 v42, v42, v108
	v_mul_f32_e32 v43, v43, v108
	v_mul_f32_e32 v40, v40, v108
	v_mul_f32_e32 v41, v41, v108
	v_mul_f32_e32 v38, v38, v108
	v_mul_f32_e32 v39, v39, v108
	v_mul_f32_e32 v36, v36, v108
	v_mul_f32_e32 v37, v37, v108
	v_mul_f32_e32 v34, v34, v108
	v_mul_f32_e32 v35, v35, v108
	v_mul_f32_e32 v64, v64, v108
	v_mul_f32_e32 v65, v65, v108
	v_mul_f32_e32 v62, v62, v108
	v_mul_f32_e32 v63, v63, v108
	v_mul_f32_e32 v60, v60, v108
	v_mul_f32_e32 v61, v61, v108
	v_mul_f32_e32 v58, v58, v108
	v_mul_f32_e32 v59, v59, v108
	v_mul_f32_e32 v56, v56, v108
	v_mul_f32_e32 v57, v57, v108
	v_mul_f32_e32 v54, v54, v108
	v_mul_f32_e32 v55, v55, v108
	v_mul_f32_e32 v52, v52, v108
	v_mul_f32_e32 v53, v53, v108
	v_mul_f32_e32 v50, v50, v108
	v_mul_f32_e32 v51, v51, v108
	v_sub_f32_e32 v84, v84, v109
	v_sub_f32_e32 v85, v85, v109
	v_sub_f32_e32 v225, v225, v109
	v_sub_f32_e32 v224, v224, v109
	v_sub_f32_e32 v227, v227, v109
	v_sub_f32_e32 v226, v226, v109
	v_sub_f32_e32 v223, v223, v109
	v_sub_f32_e32 v105, v105, v109
	v_sub_f32_e32 v107, v107, v109
	v_sub_f32_e32 v106, v106, v109
	v_sub_f32_e32 v94, v94, v109
	v_sub_f32_e32 v95, v95, v109
	v_sub_f32_e32 v96, v96, v109
	v_sub_f32_e32 v97, v97, v109
	v_sub_f32_e32 v222, v222, v109
	v_sub_f32_e32 v99, v99, v109
	v_sub_f32_e32 v101, v101, v109
	v_sub_f32_e32 v98, v98, v109
	v_sub_f32_e32 v102, v102, v109
	v_sub_f32_e32 v100, v100, v109
	v_sub_f32_e32 v104, v104, v109
	v_sub_f32_e32 v103, v103, v109
	v_sub_f32_e32 v87, v87, v109
	v_sub_f32_e32 v86, v86, v109
	v_sub_f32_e32 v89, v89, v109
	v_sub_f32_e32 v88, v88, v109
	v_sub_f32_e32 v91, v91, v109
	v_sub_f32_e32 v90, v90, v109
	v_sub_f32_e32 v93, v93, v109
	v_sub_f32_e32 v92, v92, v109

; DI f32x16 mfma(bf16x8 a, bf16x8 b, f32x16 c) { return __builtin_amdgcn_mfma_f32_32x32x16_bf16(a, b, c, 0, 0, 0); }
; template <int MODE, int KS0, int NKS>
; DI void qk_scores(f32x16& s0, f32x16& s1, const u16* Ks, const bf16x8 (&qf)[4], float sl2, int dl, float mref,
;                   bool need_mask, int r, int h, int rs, const int (&lo)[4]) {
;   asm volatile("" : "+v"(dl));
;   const float nb = -sl2 * (float)dl - mref;
; #pragma unroll
;   for (int i = 0; i < 16; ++i) {
;     const int ci = (i & 3) + 8 * (i >> 2);
;     s0[i] = fmaf(sl2, (float)ci, nb);
;     s1[i] = fmaf(sl2, (float)(ci + 32), nb);
;   }
; #pragma unroll
;   for (int ks = 0; ks < NKS; ++ks) {
;     bf16x8 k0 = ldsv(Ks + lo[KS0 + ks]);
;     bf16x8 k1 = ldsv(Ks + 32 * rs + lo[KS0 + ks]);
;     s0 = mfma(k0, qf[KS0 + ks], s0);
;     s1 = mfma(k1, qf[KS0 + ks], s1);
;   }
;   if (need_mask) {
; #pragma unroll
;     for (int i = 0; i < 16; ++i) {
;       const int ci = (i & 3) + 8 * (i >> 2);
;       bool v0 = (MODE == 0) ? (ci <= dl) : (ci <= dl && ci > dl - 128);
;       bool v1 = (MODE == 0) ? (ci + 32 <= dl) : (ci + 32 <= dl && ci + 32 > dl - 128);
;       s0[i] = v0 ? s0[i] : -INFINITY;
;       s1[i] = v1 ? s1[i] : -INFINITY;
;     }
;   }
; DI void attn_item_B2(const Params& p, int layer, int b, int head0, int qblk, u16* sm, int wv) {
;     ...
;     for (int c = 0; c < 4; ++c) {
;       if (c >= it0) {
;         const int k0 = q0 - 128 + 64 * c;
;         const bool skip = (k0 > q0w + 31) || (k0 + 63 < q0w - 127);
;         if (!skip) {
;           const int dl = qpos - k0 - 4 * h;
;           softmax_pv<1, 0, 4>(qf[hh], Ks + c * (2 * 64 * LSTR), Vs + c * (2 * 64 * LSTR), mref[hh], ls[hh], o[hh][0], o[hh][1],
;                               sl2, dl, true, false, r, h, LSTR, lo);
.LBB0_315:
	s_or_b64 exec, exec, s[2:3]
	v_or_b32_e32 v82, 0x7f, v184
	v_cmp_le_i32_e32 vcc, v219, v210
	v_cmp_ge_i32_e64 s[2:3], v82, v211
	v_sub_u32_e32 v82, v214, v219
	s_and_b64 s[6:7], vcc, s[2:3]
	v_add_u32_e32 v184, v82, v208
	s_and_saveexec_b64 s[2:3], s[6:7]
	s_cbranch_execz .LBB0_319
	v_mov_b32_e32 v219, v184
	s_mov_b32 s44, 2.0
	v_cvt_f32_i32_e32 v82, v219
	s_mov_b32 s45, 0x40400000
	ds_read_b128 v[98:101], v209 offset:55296
	ds_read_b128 v[222:225], v209 offset:59904
	v_fma_f32 v220, -v186, v82, -v220
	v_fma_f32 v84, v186, s44, v220
	v_fma_f32 v85, v186, s45, v220
	s_mov_b32 s44, 0x41000000
	s_mov_b32 s45, 0x41100000
	v_fma_f32 v86, v186, s44, v220
	v_fma_f32 v87, v186, s45, v220
	s_mov_b32 s44, 0x41200000
	s_mov_b32 s45, 0x41300000
	v_fma_f32 v88, v186, s44, v220
	v_fma_f32 v89, v186, s45, v220
	s_mov_b32 s44, 0x41800000
	s_mov_b32 s45, 0x41880000
	v_fma_f32 v90, v186, s44, v220
	v_fma_f32 v91, v186, s45, v220
	s_mov_b32 s44, 0x41900000
	s_mov_b32 s45, 0x41980000
	v_fma_f32 v92, v186, s44, v220
	v_fma_f32 v93, v186, s45, v220
	s_mov_b32 s44, 0x42680000
	s_mov_b32 s45, 0x426c0000
	v_fma_f32 v112, v186, s44, v220
	v_fma_f32 v113, v186, s45, v220
	s_mov_b32 s44, 0x42400000
	v_fma_f32 v82, 0, v186, v220
	v_add_f32_e32 v83, v186, v220
	v_fma_f32 v94, v186, s50, v220
	v_fma_f32 v95, v186, s51, v220
	v_fma_f32 v96, v186, s28, v220
	v_fma_f32 v97, v186, s29, v220
	s_mov_b32 s45, 0x42440000
	v_fma_f32 v110, v186, s30, v220
	v_fma_f32 v111, v186, s31, v220
	s_waitcnt lgkmcnt(1)
	v_mfma_f32_32x32x16_bf16 v[82:97], v[98:101], v[126:129], v[82:97]
	v_fma_f32 v108, v186, s10, v220
	v_fma_f32 v109, v186, s11, v220
	v_fma_f32 v106, v186, s44, v220
	v_fma_f32 v107, v186, s45, v220
	v_fma_f32 v104, v186, s72, v220
	v_fma_f32 v105, v186, s73, v220
	v_fma_f32 v102, v186, s74, v220
	v_fma_f32 v103, v186, s75, v220
	v_fma_f32 v100, v186, s76, v220
	v_fma_f32 v101, v186, s77, v220
	v_fma_f32 v98, v186, s78, v220
	v_fma_f32 v99, v186, s79, v220
	s_waitcnt lgkmcnt(0)
	s_nop 0
	v_mfma_f32_32x32x16_bf16 v[98:113], v[222:225], v[126:129], v[98:113]
	ds_read_b128 v[126:129], v209 offset:55328
	s_waitcnt lgkmcnt(0)
	v_mfma_f32_32x32x16_bf16 v[82:97], v[126:129], v[122:125], v[82:97]
	ds_read_b128 v[126:129], v209 offset:59936
	s_waitcnt lgkmcnt(0)
	v_mfma_f32_32x32x16_bf16 v[98:113], v[126:129], v[122:125], v[98:113]
	ds_read_b128 v[122:125], v209 offset:55360
	v_add_u32_e32 v126, -1, v219
	v_cmp_gt_u32_e32 vcc, s95, v126
	s_waitcnt lgkmcnt(0)
	v_mfma_f32_32x32x16_bf16 v[82:97], v[122:125], v[118:121], v[82:97]
	ds_read_b128 v[122:125], v209 offset:59968
	s_waitcnt lgkmcnt(0)
	v_mfma_f32_32x32x16_bf16 v[98:113], v[122:125], v[118:121], v[98:113]
	ds_read_b128 v[118:121], v209 offset:55392
	ds_read_b128 v[122:125], v209 offset:60000
	s_waitcnt lgkmcnt(1)
	v_mfma_f32_32x32x16_bf16 v[82:97], v[118:121], v[114:117], v[82:97]
	s_waitcnt lgkmcnt(0)
	v_mfma_f32_32x32x16_bf16 v[98:113], v[122:125], v[114:117], v[98:113]
	s_nop 9
	v_cndmask_b32_e32 v118, v199, v83, vcc
	v_cmp_gt_u32_e32 vcc, s95, v219
	v_subrev_u32_e32 v83, 32, v219
	s_nop 0
	v_cndmask_b32_e32 v119, v199, v82, vcc
	v_subrev_u32_e32 v82, 33, v219
	v_cmp_gt_u32_e32 vcc, s95, v82
	v_add_u32_e32 v82, -3, v219
	s_nop 0
	v_cndmask_b32_e32 v99, v199, v99, vcc
	v_cmp_gt_u32_e32 vcc, s95, v83
	v_add_u32_e32 v83, -2, v219
	s_nop 0
	v_cndmask_b32_e32 v114, v199, v98, vcc
	v_cmp_gt_u32_e32 vcc, s95, v82
	v_subrev_u32_e32 v82, 35, v219
	s_nop 0
	v_cndmask_b32_e32 v115, v199, v85, vcc
	v_cmp_gt_u32_e32 vcc, s95, v83
	v_subrev_u32_e32 v83, 34, v219
	v_subrev_u32_e32 v85, 18, v219
	v_cndmask_b32_e32 v116, v199, v84, vcc
	v_cmp_gt_u32_e32 vcc, s95, v82
	v_add_u32_e32 v82, -9, v219
	v_subrev_u32_e32 v84, 19, v219
	v_cndmask_b32_e32 v98, v199, v101, vcc
	v_cmp_gt_u32_e32 vcc, s95, v83
	v_add_u32_e32 v83, -8, v219
	s_nop 0
	v_cndmask_b32_e32 v100, v199, v100, vcc
	v_cmp_gt_u32_e32 vcc, s95, v82
	v_subrev_u32_e32 v82, 41, v219
	s_nop 0
	v_cndmask_b32_e32 v117, v199, v87, vcc
	v_cmp_gt_u32_e32 vcc, s95, v83
	v_subrev_u32_e32 v83, 40, v219
	s_nop 0
	v_cndmask_b32_e32 v120, v199, v86, vcc
	v_cmp_gt_u32_e32 vcc, s95, v82
	v_add_u32_e32 v82, -11, v219
	s_nop 0
	v_cndmask_b32_e32 v86, v199, v103, vcc
	v_cmp_gt_u32_e32 vcc, s95, v83
	v_add_u32_e32 v83, -10, v219
	s_nop 0
	v_cndmask_b32_e32 v87, v199, v102, vcc
	v_cmp_gt_u32_e32 vcc, s95, v82
	v_subrev_u32_e32 v82, 43, v219
	s_nop 0
	v_cndmask_b32_e32 v121, v199, v89, vcc
	v_cmp_gt_u32_e32 vcc, s95, v83
	v_subrev_u32_e32 v83, 42, v219
	s_nop 0
	v_cndmask_b32_e32 v122, v199, v88, vcc
	v_cmp_gt_u32_e32 vcc, s95, v82
	v_subrev_u32_e32 v82, 17, v219
	s_nop 0
	v_cndmask_b32_e32 v88, v199, v105, vcc
	v_cmp_gt_u32_e32 vcc, s95, v83
	v_add_u32_e32 v83, -16, v219
	s_nop 0
	v_cndmask_b32_e32 v89, v199, v104, vcc
	v_cmp_gt_u32_e32 vcc, s95, v82
	v_subrev_u32_e32 v82, 49, v219
	s_nop 0
	v_cndmask_b32_e32 v101, v199, v91, vcc
	v_cmp_gt_u32_e32 vcc, s95, v83
	v_subrev_u32_e32 v83, 48, v219
	v_subrev_u32_e32 v91, 24, v219
	v_cndmask_b32_e32 v103, v199, v90, vcc
	v_cmp_gt_u32_e32 vcc, s95, v82
	v_subrev_u32_e32 v90, 25, v219
	s_nop 0
	v_cndmask_b32_e32 v82, v199, v107, vcc
	v_cmp_gt_u32_e32 vcc, s95, v83
	s_nop 1
	v_cndmask_b32_e32 v83, v199, v106, vcc
	v_cmp_gt_u32_e32 vcc, s95, v84
	v_subrev_u32_e32 v84, 51, v219
	s_nop 0
	v_cndmask_b32_e32 v102, v199, v93, vcc
	v_cmp_gt_u32_e32 vcc, s95, v85
	v_subrev_u32_e32 v85, 50, v219
	v_subrev_u32_e32 v93, 26, v219
	v_cndmask_b32_e32 v104, v199, v92, vcc
	v_cmp_gt_u32_e32 vcc, s95, v84
	v_subrev_u32_e32 v92, 27, v219
	s_nop 0
	v_cndmask_b32_e32 v84, v199, v109, vcc
	v_cmp_gt_u32_e32 vcc, s95, v85
	s_nop 1
	v_cndmask_b32_e32 v85, v199, v108, vcc
	v_cmp_gt_u32_e32 vcc, s95, v90
	v_subrev_u32_e32 v90, 57, v219
	s_nop 0
	v_cndmask_b32_e32 v95, v199, v95, vcc
	v_cmp_gt_u32_e32 vcc, s95, v91
	v_subrev_u32_e32 v91, 56, v219
	s_nop 0
	v_cndmask_b32_e32 v94, v199, v94, vcc
	v_cmp_gt_u32_e32 vcc, s95, v90
	s_nop 1
	v_cndmask_b32_e32 v90, v199, v111, vcc
	v_cmp_gt_u32_e32 vcc, s95, v91
	s_nop 1
	v_cndmask_b32_e32 v91, v199, v110, vcc
	v_cmp_gt_u32_e32 vcc, s95, v92
	v_subrev_u32_e32 v92, 59, v219
	s_nop 0
	v_cndmask_b32_e32 v97, v199, v97, vcc
	v_cmp_gt_u32_e32 vcc, s95, v93
	v_subrev_u32_e32 v93, 58, v219
	s_nop 0
	v_cndmask_b32_e32 v96, v199, v96, vcc
	v_cmp_gt_u32_e32 vcc, s95, v92
	s_nop 1
	v_cndmask_b32_e32 v92, v199, v113, vcc
	v_cmp_gt_u32_e32 vcc, s95, v93
	s_nop 1
	v_cndmask_b32_e32 v93, v199, v112, vcc
	v_cmp_nge_f32_e32 vcc, s9, v50
	s_cbranch_vccz .LBB0_318
; DI float ex2(float x) { return __builtin_amdgcn_exp2f(x); }
; DI float lg2(float x) { return __builtin_amdgcn_logf(x); }
; template <int MODE, int KS0, int NKS>
; DI void softmax_pv(const bf16x8 (&qf)[4], const u16* Ks, const u16* Vs, float& m, f32x16& ls, f32x16& o0, f32x16& o1,
;                    float sl2, int dl, bool need_mask, bool first, int r, int h, int rs, const int (&lo)[4]) {
;     ...
;   if (__any(first || !(ls[0] <= 1.0e12f))) {
;     float tmax = -INFINITY;
; #pragma unroll
;     for (int i = 0; i < 16; ++i) tmax = fmaxf(tmax, fmaxf(s0[i], s1[i]));
;     tmax = fmaxf(tmax, shx(tmax, r + 32 * h));
;     const float lref = (ls[0] > 1.f) ? lg2(ls[0]) : 0.f;
;     const float delta = first ? tmax : fmaxf(fmaxf(tmax, lref), 0.f);
;     m += delta;
;     const float alpha = ex2(-delta);
; #pragma unroll
;     for (int e = 0; e < 16; ++e) { o0[e] *= alpha; o1[e] *= alpha; ls[e] *= alpha; }
; #pragma unroll
;     for (int i = 0; i < 16; ++i) { s0[i] -= delta; s1[i] -= delta; }
;   }
	v_max_f32_e32 v105, v114, v114
	v_max_f32_e32 v106, v119, v119
	v_max_f32_e32 v105, v106, v105
	v_max_f32_e32 v106, v99, v99
	v_max_f32_e32 v107, v118, v118
	v_max_f32_e32 v106, v107, v106
	s_mov_b32 s19, 0xff800000
	v_max3_f32 v105, v105, s19, v106
	v_max_f32_e32 v106, v100, v100
	v_max_f32_e32 v107, v116, v116
	v_max_f32_e32 v106, v107, v106
	v_max_f32_e32 v107, v98, v98
	v_max_f32_e32 v108, v115, v115
	v_max_f32_e32 v107, v108, v107
	v_max3_f32 v105, v105, v106, v107
	v_max_f32_e32 v106, v87, v87
	v_max_f32_e32 v107, v120, v120
	v_max_f32_e32 v106, v107, v106
	v_max_f32_e32 v107, v86, v86
	v_max_f32_e32 v108, v117, v117
	v_max_f32_e32 v107, v108, v107
	v_max3_f32 v105, v105, v106, v107
	v_max_f32_e32 v106, v89, v89
	v_max_f32_e32 v107, v122, v122
	v_max_f32_e32 v106, v107, v106
	v_max_f32_e32 v107, v88, v88
	v_max_f32_e32 v108, v121, v121
	v_max_f32_e32 v107, v108, v107
	v_max3_f32 v105, v105, v106, v107
	v_max_f32_e32 v106, v83, v83
	v_max_f32_e32 v107, v103, v103
	v_max_f32_e32 v106, v107, v106
	v_max_f32_e32 v107, v82, v82
	v_max_f32_e32 v108, v101, v101
	v_max_f32_e32 v107, v108, v107
	v_max3_f32 v105, v105, v106, v107
	v_max_f32_e32 v106, v85, v85
	v_max_f32_e32 v107, v104, v104
	v_max_f32_e32 v106, v107, v106
	v_max_f32_e32 v107, v84, v84
	v_max_f32_e32 v108, v102, v102
	v_max_f32_e32 v107, v108, v107
	v_max3_f32 v105, v105, v106, v107
	v_max_f32_e32 v106, v91, v91
	v_max_f32_e32 v107, v94, v94
	v_max_f32_e32 v106, v107, v106
	v_max_f32_e32 v107, v90, v90
	v_max_f32_e32 v108, v95, v95
	v_max_f32_e32 v107, v108, v107
	v_max3_f32 v105, v105, v106, v107
	v_max_f32_e32 v106, v93, v93
	v_max_f32_e32 v107, v96, v96
	v_max_f32_e32 v106, v107, v106
	v_max_f32_e32 v107, v92, v92
	v_max_f32_e32 v108, v97, v97
	v_max_f32_e32 v107, v108, v107
	v_max3_f32 v105, v105, v106, v107
	ds_bpermute_b32 v106, v185, v105
	v_log_f32_e32 v107, v50
	v_cmp_lt_f32_e32 vcc, 1.0, v50
	s_waitcnt lgkmcnt(0)
	v_max_f32_e32 v106, v106, v106
	v_max_f32_e32 v105, v105, v106
	v_cndmask_b32_e32 v106, 0, v107, vcc
	v_max3_f32 v105, v105, v106, 0
	v_exp_f32_e64 v106, -v105
	v_sub_f32_e32 v119, v119, v105
	v_sub_f32_e32 v118, v118, v105
	v_sub_f32_e32 v116, v116, v105
	v_mul_f32_e32 v80, v80, v106
	v_mul_f32_e32 v81, v81, v106
	v_mul_f32_e32 v78, v78, v106
	v_mul_f32_e32 v79, v79, v106
	v_mul_f32_e32 v76, v76, v106
	v_mul_f32_e32 v77, v77, v106
	v_mul_f32_e32 v74, v74, v106
	v_mul_f32_e32 v75, v75, v106
	v_mul_f32_e32 v72, v72, v106
	v_mul_f32_e32 v73, v73, v106
	v_mul_f32_e32 v70, v70, v106
	v_mul_f32_e32 v71, v71, v106
	v_mul_f32_e32 v68, v68, v106
	v_mul_f32_e32 v69, v69, v106
	v_mul_f32_e32 v66, v66, v106
	v_mul_f32_e32 v67, v67, v106
	v_mul_f32_e32 v48, v48, v106
	v_mul_f32_e32 v49, v49, v106
	v_mul_f32_e32 v46, v46, v106
	v_mul_f32_e32 v47, v47, v106
	v_mul_f32_e32 v44, v44, v106
	v_mul_f32_e32 v45, v45, v106
	v_mul_f32_e32 v42, v42, v106
	v_mul_f32_e32 v43, v43, v106
	v_mul_f32_e32 v40, v40, v106
	v_mul_f32_e32 v41, v41, v106
	v_mul_f32_e32 v38, v38, v106
	v_mul_f32_e32 v39, v39, v106
	v_mul_f32_e32 v36, v36, v106
	v_mul_f32_e32 v37, v37, v106
	v_mul_f32_e32 v34, v34, v106
	v_mul_f32_e32 v35, v35, v106
	v_mul_f32_e32 v64, v64, v106
	v_mul_f32_e32 v65, v65, v106
	v_mul_f32_e32 v62, v62, v106
	v_mul_f32_e32 v63, v63, v106
	v_mul_f32_e32 v60, v60, v106
	v_mul_f32_e32 v61, v61, v106
	v_mul_f32_e32 v58, v58, v106
	v_mul_f32_e32 v59, v59, v106
	v_mul_f32_e32 v56, v56, v106
	v_mul_f32_e32 v57, v57, v106
	v_mul_f32_e32 v54, v54, v106
	v_mul_f32_e32 v55, v55, v106
	v_mul_f32_e32 v52, v52, v106
	v_mul_f32_e32 v53, v53, v106
	v_mul_f32_e32 v50, v50, v106
	v_mul_f32_e32 v51, v51, v106
	v_sub_f32_e32 v115, v115, v105
	v_sub_f32_e32 v120, v120, v105
	v_sub_f32_e32 v117, v117, v105
	v_sub_f32_e32 v122, v122, v105
	v_sub_f32_e32 v121, v121, v105
	v_sub_f32_e32 v103, v103, v105
	v_sub_f32_e32 v101, v101, v105
	v_sub_f32_e32 v104, v104, v105
	v_sub_f32_e32 v102, v102, v105
	v_sub_f32_e32 v94, v94, v105
	v_sub_f32_e32 v95, v95, v105
	v_sub_f32_e32 v96, v96, v105
	v_sub_f32_e32 v97, v97, v105
	v_sub_f32_e32 v114, v114, v105
	v_sub_f32_e32 v99, v99, v105
	v_sub_f32_e32 v100, v100, v105
	v_sub_f32_e32 v98, v98, v105
	v_sub_f32_e32 v87, v87, v105
	v_sub_f32_e32 v86, v86, v105
	v_sub_f32_e32 v89, v89, v105
	v_sub_f32_e32 v88, v88, v105
	v_sub_f32_e32 v83, v83, v105
	v_sub_f32_e32 v82, v82, v105
	v_sub_f32_e32 v85, v85, v105
	v_sub_f32_e32 v84, v84, v105
	v_sub_f32_e32 v91, v91, v105
	v_sub_f32_e32 v90, v90, v105
	v_sub_f32_e32 v93, v93, v105
	v_sub_f32_e32 v92, v92, v105

; DI f32x16 mfma(bf16x8 a, bf16x8 b, f32x16 c) { return __builtin_amdgcn_mfma_f32_32x32x16_bf16(a, b, c, 0, 0, 0); }
; template <int MODE, int KS0, int NKS>
; DI void qk_scores(f32x16& s0, f32x16& s1, const u16* Ks, const bf16x8 (&qf)[4], float sl2, int dl, float mref,
;                   bool need_mask, int r, int h, int rs, const int (&lo)[4]) {
;   asm volatile("" : "+v"(dl));
;   const float nb = -sl2 * (float)dl - mref;
; #pragma unroll
;   for (int i = 0; i < 16; ++i) {
;     const int ci = (i & 3) + 8 * (i >> 2);
;     s0[i] = fmaf(sl2, (float)ci, nb);
;     s1[i] = fmaf(sl2, (float)(ci + 32), nb);
;   }
; #pragma unroll
;   for (int ks = 0; ks < NKS; ++ks) {
;     bf16x8 k0 = ldsv(Ks + lo[KS0 + ks]);
;     bf16x8 k1 = ldsv(Ks + 32 * rs + lo[KS0 + ks]);
;     s0 = mfma(k0, qf[KS0 + ks], s0);
;     s1 = mfma(k1, qf[KS0 + ks], s1);
;   }
; DI void attn_item_B2(const Params& p, int layer, int b, int head0, int qblk, u16* sm, int wv) {
;     ...
;   for (int hh = 0; hh < 2; ++hh) {
;     const int head = head0 + hh;
;     const float sl2 = exp2f(-8.f * (float)(1 + head) / 12.f) * LOG2E;
; #pragma unroll
;     for (int e = 0; e < 16; ++e) { o[hh][0][e] = zf; o[hh][1][e] = zf; ls[hh][e] = onef; }
;     mref[hh] = p.sinks[layer * 8 + head] * LOG2E;
; #pragma unroll
;     for (int c = 0; c < 4; ++c) {
;       if (c >= it0) {
;         const int k0 = q0 - 128 + 64 * c;
;         const bool skip = (k0 > q0w + 31) || (k0 + 63 < q0w - 127);
;         if (!skip) {
;           const int dl = qpos - k0 - 4 * h;
;           softmax_pv<1, 0, 4>(qf[hh], Ks + c * (2 * 64 * LSTR), Vs + c * (2 * 64 * LSTR), mref[hh], ls[hh], o[hh][0], o[hh][1],
;                               sl2, dl, true, false, r, h, LSTR, lo);
.LBB0_319:
	s_or_b64 exec, exec, s[2:3]
	s_nop 10
	global_load_dword v51, v1, s[0:1] offset:4
	s_add_i32 s18, s18, 2
	v_cvt_f32_i32_e32 v52, s18
	s_mov_b32 s2, 0x41400000
	v_mov_b64_e32 v[96:97], v[16:17]
	v_mov_b64_e32 v[94:95], v[14:15]
	v_mul_f32_e32 v52, 0xc1000000, v52
	v_div_scale_f32 v53, s[0:1], s2, s2, v52
	v_rcp_f32_e32 v54, v53
	v_div_scale_f32 v55, vcc, v52, s2, v52
	v_mov_b64_e32 v[92:93], v[12:13]
	v_fma_f32 v56, -v53, v54, 1.0
	v_fmac_f32_e32 v54, v56, v54
	v_mul_f32_e32 v56, v55, v54
	v_fma_f32 v57, -v53, v56, v55
	v_fmac_f32_e32 v56, v57, v54
	v_fma_f32 v53, -v53, v56, v55
	v_div_fmas_f32 v53, v53, v54, v56
	v_div_fixup_f32 v52, v53, s2, v52
	v_cmp_gt_f32_e32 vcc, s94, v52
	s_and_b64 s[0:1], vcc, exec
	s_cselect_b32 s0, 0xffffffc0, 0
	v_cndmask_b32_e32 v53, 0, v187, vcc
	v_add_f32_e32 v52, v52, v53
	v_exp_f32_e32 v52, v52
	v_mov_b64_e32 v[90:91], v[10:11]
	v_mov_b64_e32 v[88:89], v[8:9]
	v_mov_b64_e32 v[86:87], v[6:7]
	v_ldexp_f32 v52, v52, s0
	v_mul_f32_e32 v56, 0x3fb8aa3b, v52
	v_mov_b64_e32 v[84:85], v[4:5]
	v_mov_b64_e32 v[82:83], v[2:3]
	s_waitcnt vmcnt(0)
	v_mul_f32_e32 v51, 0x3fb8aa3b, v51
	s_and_saveexec_b64 s[0:1], s[36:37]
	s_cbranch_execz .LBB0_329
	v_cmp_le_i32_e32 vcc, v212, v210
	v_cmp_ge_i32_e64 s[2:3], v216, v211
	v_mov_b64_e32 v[112:113], v[16:17]
	s_and_b64 s[18:19], vcc, s[2:3]
	v_mov_b64_e32 v[110:111], v[14:15]
	v_mov_b64_e32 v[108:109], v[12:13]
	v_mov_b64_e32 v[106:107], v[10:11]
	v_mov_b64_e32 v[104:105], v[8:9]
	v_mov_b64_e32 v[102:103], v[6:7]
	v_mov_b64_e32 v[100:101], v[4:5]
	v_mov_b64_e32 v[98:99], v[2:3]
	s_and_saveexec_b64 s[2:3], s[18:19]
	s_cbranch_execz .LBB0_324
	v_add3_u32 v3, v214, v213, v208
	s_mov_b32 s18, 2.0
	v_cvt_f32_i32_e32 v8, v3
	s_mov_b32 s19, 0x40400000
	ds_read_b128 v[4:7], v209
	v_fma_f32 v12, -v56, v8, -v51
	v_fma_f32 v84, v56, s18, v12
	v_fma_f32 v85, v56, s19, v12
	s_mov_b32 s18, 0x41000000
	s_mov_b32 s19, 0x41100000
	v_fma_f32 v86, v56, s18, v12
	v_fma_f32 v87, v56, s19, v12
	s_mov_b32 s18, 0x41200000
	s_mov_b32 s19, 0x41300000
	v_fma_f32 v88, v56, s18, v12
	v_fma_f32 v89, v56, s19, v12
	s_mov_b32 s18, 0x41800000
	s_mov_b32 s19, 0x41880000
	v_fma_f32 v90, v56, s18, v12
	v_fma_f32 v91, v56, s19, v12
	s_mov_b32 s18, 0x41900000
	s_mov_b32 s19, 0x41980000
	v_fma_f32 v82, 0, v56, v12
	v_add_f32_e32 v83, v56, v12
	v_fma_f32 v92, v56, s18, v12
	v_fma_f32 v93, v56, s19, v12
	v_fma_f32 v94, v56, s50, v12
	v_fma_f32 v95, v56, s51, v12
	v_fma_f32 v96, v56, s28, v12
	v_fma_f32 v97, v56, s29, v12
	ds_read_b128 v[8:11], v209 offset:4608
	s_mov_b32 s18, 0x42680000
	s_waitcnt lgkmcnt(1)
	v_mfma_f32_32x32x16_bf16 v[82:97], v[4:7], v[142:145], v[82:97]
	ds_read_b128 v[4:7], v209 offset:32
	s_mov_b32 s19, 0x426c0000
	v_fma_f32 v112, v56, s18, v12
	v_fma_f32 v113, v56, s19, v12
	s_mov_b32 s18, 0x42400000
	s_mov_b32 s19, 0x42440000
	v_fma_f32 v110, v56, s30, v12
	v_fma_f32 v111, v56, s31, v12
	v_fma_f32 v108, v56, s10, v12
	v_fma_f32 v109, v56, s11, v12
	v_fma_f32 v106, v56, s18, v12
	v_fma_f32 v107, v56, s19, v12
	v_fma_f32 v104, v56, s72, v12
	v_fma_f32 v105, v56, s73, v12
	v_fma_f32 v102, v56, s74, v12
	v_fma_f32 v103, v56, s75, v12
	v_fma_f32 v100, v56, s76, v12
	v_fma_f32 v101, v56, s77, v12
	v_fma_f32 v98, v56, s78, v12
	v_fma_f32 v99, v56, s79, v12
	s_waitcnt lgkmcnt(0)
	v_mfma_f32_32x32x16_bf16 v[82:97], v[4:7], v[138:141], v[82:97]
	ds_read_b128 v[4:7], v209 offset:4640
	v_add_u32_e32 v12, -1, v3
	v_cmp_gt_u32_e32 vcc, s95, v12
	v_mfma_f32_32x32x16_bf16 v[98:113], v[8:11], v[142:145], v[98:113]
	s_waitcnt lgkmcnt(0)
	v_mfma_f32_32x32x16_bf16 v[98:113], v[4:7], v[138:141], v[98:113]
	ds_read_b128 v[4:7], v209 offset:64
	s_waitcnt lgkmcnt(0)
	v_mfma_f32_32x32x16_bf16 v[82:97], v[4:7], v[134:137], v[82:97]
	ds_read_b128 v[4:7], v209 offset:4672
	s_waitcnt lgkmcnt(0)
	v_mfma_f32_32x32x16_bf16 v[98:113], v[4:7], v[134:137], v[98:113]
	ds_read_b128 v[4:7], v209 offset:96
	ds_read_b128 v[8:11], v209 offset:4704
	s_waitcnt lgkmcnt(1)
	v_mfma_f32_32x32x16_bf16 v[82:97], v[4:7], v[130:133], v[82:97]
	v_subrev_u32_e32 v4, 33, v3
	v_subrev_u32_e32 v5, 32, v3
	s_waitcnt lgkmcnt(0)
; DI float ex2(float x) { return __builtin_amdgcn_exp2f(x); }
; DI float lg2(float x) { return __builtin_amdgcn_logf(x); }
; template <int MODE, int KS0, int NKS>
; DI void qk_scores(f32x16& s0, f32x16& s1, const u16* Ks, const bf16x8 (&qf)[4], float sl2, int dl, float mref,
;                   bool need_mask, int r, int h, int rs, const int (&lo)[4]) {
;     ...
;   if (need_mask) {
; #pragma unroll
;     for (int i = 0; i < 16; ++i) {
;       const int ci = (i & 3) + 8 * (i >> 2);
;       bool v0 = (MODE == 0) ? (ci <= dl) : (ci <= dl && ci > dl - 128);
;       bool v1 = (MODE == 0) ? (ci + 32 <= dl) : (ci + 32 <= dl && ci + 32 > dl - 128);
;       s0[i] = v0 ? s0[i] : -INFINITY;
;       s1[i] = v1 ? s1[i] : -INFINITY;
;     }
;   }
; }
; template <int MODE, int KS0, int NKS>
; DI void softmax_pv(const bf16x8 (&qf)[4], const u16* Ks, const u16* Vs, float& m, f32x16& ls, f32x16& o0, f32x16& o1,
;                    float sl2, int dl, bool need_mask, bool first, int r, int h, int rs, const int (&lo)[4]) {
;   f32x16 s0, s1;
;   qk_scores<MODE, KS0, NKS>(s0, s1, Ks, qf, sl2, dl, m, need_mask, r, h, rs, lo);
;   if (__any(first || !(ls[0] <= 1.0e12f))) {
;     float tmax = -INFINITY;
; #pragma unroll
;     for (int i = 0; i < 16; ++i) tmax = fmaxf(tmax, fmaxf(s0[i], s1[i]));
;     tmax = fmaxf(tmax, shx(tmax, r + 32 * h));
;     const float lref = (ls[0] > 1.f) ? lg2(ls[0]) : 0.f;
;     const float delta = first ? tmax : fmaxf(fmaxf(tmax, lref), 0.f);
;     m += delta;
;     const float alpha = ex2(-delta);
; #pragma unroll
;     for (int e = 0; e < 16; ++e) { o0[e] *= alpha; o1[e] *= alpha; ls[e] *= alpha; }
; #pragma unroll
;     for (int i = 0; i < 16; ++i) { s0[i] -= delta; s1[i] -= delta; }
;   }
	v_mfma_f32_32x32x16_bf16 v[98:113], v[8:11], v[130:133], v[98:113]
	s_nop 7
	v_cndmask_b32_e32 v29, v199, v83, vcc
	v_cmp_gt_u32_e32 vcc, s95, v3
	s_nop 1
	v_cndmask_b32_e32 v30, v199, v82, vcc
	v_cmp_gt_u32_e32 vcc, s95, v4
	v_add_u32_e32 v4, -3, v3
	s_nop 0
	v_cndmask_b32_e32 v59, v199, v99, vcc
	v_cmp_gt_u32_e32 vcc, s95, v5
	v_add_u32_e32 v5, -2, v3
	s_nop 0
	v_cndmask_b32_e32 v64, v199, v98, vcc
	v_cmp_gt_u32_e32 vcc, s95, v4
	v_subrev_u32_e32 v4, 35, v3
	s_nop 0
	v_cndmask_b32_e32 v31, v199, v85, vcc
	v_cmp_gt_u32_e32 vcc, s95, v5
	v_subrev_u32_e32 v5, 34, v3
	s_nop 0
	v_cndmask_b32_e32 v32, v199, v84, vcc
	v_cmp_gt_u32_e32 vcc, s95, v4
	v_add_u32_e32 v4, -9, v3
	s_nop 0
	v_cndmask_b32_e32 v62, v199, v101, vcc
	v_cmp_gt_u32_e32 vcc, s95, v5
	v_add_u32_e32 v5, -8, v3
	s_nop 0
	v_cndmask_b32_e32 v65, v199, v100, vcc
	v_cmp_gt_u32_e32 vcc, s95, v4
	v_subrev_u32_e32 v4, 41, v3
	s_nop 0
	v_cndmask_b32_e32 v33, v199, v87, vcc
	v_cmp_gt_u32_e32 vcc, s95, v5
	v_subrev_u32_e32 v5, 40, v3
	s_nop 0
	v_cndmask_b32_e32 v53, v199, v86, vcc
	v_cmp_gt_u32_e32 vcc, s95, v4
	v_add_u32_e32 v4, -11, v3
	s_nop 0
	v_cndmask_b32_e32 v63, v199, v103, vcc
	v_cmp_gt_u32_e32 vcc, s95, v5
	v_add_u32_e32 v5, -10, v3
	s_nop 0
	v_cndmask_b32_e32 v98, v199, v102, vcc
	v_cmp_gt_u32_e32 vcc, s95, v4
	v_subrev_u32_e32 v4, 43, v3
	s_nop 0
	v_cndmask_b32_e32 v55, v199, v89, vcc
	v_cmp_gt_u32_e32 vcc, s95, v5
	v_subrev_u32_e32 v5, 42, v3
	s_nop 0
	v_cndmask_b32_e32 v82, v199, v88, vcc
	v_cmp_gt_u32_e32 vcc, s95, v4
	v_subrev_u32_e32 v4, 17, v3
	s_nop 0
	v_cndmask_b32_e32 v99, v199, v105, vcc
	v_cmp_gt_u32_e32 vcc, s95, v5
	v_add_u32_e32 v5, -16, v3
	s_nop 0
	v_cndmask_b32_e32 v100, v199, v104, vcc
	v_cmp_gt_u32_e32 vcc, s95, v4
	v_subrev_u32_e32 v4, 49, v3
	s_nop 0
	v_cndmask_b32_e32 v105, v199, v91, vcc
	v_cmp_gt_u32_e32 vcc, s95, v5
	v_subrev_u32_e32 v5, 48, v3
	s_nop 0
	v_cndmask_b32_e32 v52, v199, v90, vcc
	v_cmp_gt_u32_e32 vcc, s95, v4
	v_subrev_u32_e32 v4, 19, v3
	s_nop 0
	v_cndmask_b32_e32 v57, v199, v107, vcc
	v_cmp_gt_u32_e32 vcc, s95, v5
	v_subrev_u32_e32 v5, 18, v3
	s_nop 0
	v_cndmask_b32_e32 v58, v199, v106, vcc
	v_cmp_gt_u32_e32 vcc, s95, v4
	v_subrev_u32_e32 v4, 51, v3
	s_nop 0
	v_cndmask_b32_e32 v106, v199, v93, vcc
	v_cmp_gt_u32_e32 vcc, s95, v5
	v_subrev_u32_e32 v5, 50, v3
	s_nop 0
	v_cndmask_b32_e32 v54, v199, v92, vcc
	v_cmp_gt_u32_e32 vcc, s95, v4
	v_subrev_u32_e32 v4, 25, v3
	s_nop 0
	v_cndmask_b32_e32 v60, v199, v109, vcc
	v_cmp_gt_u32_e32 vcc, s95, v5
	v_subrev_u32_e32 v5, 24, v3
	s_nop 0
	v_cndmask_b32_e32 v61, v199, v108, vcc
	v_cmp_gt_u32_e32 vcc, s95, v4
	v_subrev_u32_e32 v4, 57, v3
	s_nop 0
	v_cndmask_b32_e32 v107, v199, v95, vcc
	v_cmp_gt_u32_e32 vcc, s95, v5
	v_subrev_u32_e32 v5, 56, v3
	s_nop 0
	v_cndmask_b32_e32 v108, v199, v94, vcc
	v_cmp_gt_u32_e32 vcc, s95, v4
	v_subrev_u32_e32 v4, 27, v3
	s_nop 0
	v_cndmask_b32_e32 v101, v199, v111, vcc
	v_cmp_gt_u32_e32 vcc, s95, v5
	v_subrev_u32_e32 v5, 26, v3
	s_nop 0
	v_cndmask_b32_e32 v102, v199, v110, vcc
	v_cmp_gt_u32_e32 vcc, s95, v4
	v_subrev_u32_e32 v4, 59, v3
	v_subrev_u32_e32 v3, 58, v3
	v_cndmask_b32_e32 v109, v199, v97, vcc
	v_cmp_gt_u32_e32 vcc, s95, v5
	s_nop 1
	v_cndmask_b32_e32 v110, v199, v96, vcc
	v_cmp_gt_u32_e32 vcc, s95, v4
	s_nop 1
	v_cndmask_b32_e32 v103, v199, v113, vcc
	v_cmp_gt_u32_e32 vcc, s95, v3
	s_nop 1
	v_cndmask_b32_e32 v104, v199, v112, vcc
	v_cmp_nge_f32_e32 vcc, s9, v18
	s_cbranch_vccz .LBB0_323
	v_max_f32_e32 v3, v64, v64
	v_max_f32_e32 v4, v30, v30
	v_max_f32_e32 v3, v4, v3
	v_max_f32_e32 v4, v59, v59
	v_max_f32_e32 v5, v29, v29
	v_max_f32_e32 v4, v5, v4
	s_mov_b32 s18, 0xff800000
	v_max3_f32 v3, v3, s18, v4
	v_max_f32_e32 v4, v65, v65
	v_max_f32_e32 v5, v32, v32
	v_max_f32_e32 v4, v5, v4
	v_max_f32_e32 v5, v62, v62
	v_max_f32_e32 v6, v31, v31
	v_max_f32_e32 v5, v6, v5
	v_max3_f32 v3, v3, v4, v5
	v_max_f32_e32 v4, v98, v98
	v_max_f32_e32 v5, v53, v53
	v_max_f32_e32 v4, v5, v4
	v_max_f32_e32 v5, v63, v63
	v_max_f32_e32 v6, v33, v33
	v_max_f32_e32 v5, v6, v5
	v_max3_f32 v3, v3, v4, v5
	v_max_f32_e32 v4, v100, v100
	v_max_f32_e32 v5, v82, v82
	v_max_f32_e32 v4, v5, v4
	v_max_f32_e32 v5, v99, v99
	v_max_f32_e32 v6, v55, v55
	v_max_f32_e32 v5, v6, v5
	v_max3_f32 v3, v3, v4, v5
	v_max_f32_e32 v4, v58, v58
	v_max_f32_e32 v5, v52, v52
	v_max_f32_e32 v4, v5, v4
	v_max_f32_e32 v5, v57, v57
	v_max_f32_e32 v6, v105, v105
	v_max_f32_e32 v5, v6, v5
	v_max3_f32 v3, v3, v4, v5
	v_max_f32_e32 v4, v61, v61
	v_max_f32_e32 v5, v54, v54
	v_max_f32_e32 v4, v5, v4
	v_max_f32_e32 v5, v60, v60
	v_max_f32_e32 v6, v106, v106
	v_max_f32_e32 v5, v6, v5
	v_max3_f32 v3, v3, v4, v5
	v_max_f32_e32 v4, v102, v102
	v_max_f32_e32 v5, v108, v108
	v_max_f32_e32 v4, v5, v4
	v_max_f32_e32 v5, v101, v101
	v_max_f32_e32 v6, v107, v107
	v_max_f32_e32 v5, v6, v5
	v_max3_f32 v3, v3, v4, v5
	v_max_f32_e32 v4, v104, v104
	v_max_f32_e32 v5, v110, v110
	v_max_f32_e32 v4, v5, v4
	v_max_f32_e32 v5, v103, v103
	v_max_f32_e32 v6, v109, v109
	v_max_f32_e32 v5, v6, v5
	v_max3_f32 v3, v3, v4, v5
	ds_bpermute_b32 v4, v185, v3
	v_log_f32_e32 v5, v18
	v_cmp_lt_f32_e32 vcc, 1.0, v18
	s_waitcnt lgkmcnt(0)
	v_max_f32_e32 v4, v4, v4
	v_max_f32_e32 v3, v3, v4
	v_cndmask_b32_e32 v4, 0, v5, vcc
	v_max3_f32 v3, v3, v4, 0
	v_exp_f32_e64 v4, -v3
	v_add_f32_e32 v51, v51, v3
	v_sub_f32_e32 v30, v30, v3
	v_sub_f32_e32 v29, v29, v3
	v_mul_f32_e32 v2, v2, v4
	v_mul_f32_e32 v18, v18, v4
	v_sub_f32_e32 v32, v32, v3
	v_sub_f32_e32 v31, v31, v3
	v_sub_f32_e32 v53, v53, v3
	v_sub_f32_e32 v33, v33, v3
	v_sub_f32_e32 v82, v82, v3
	v_sub_f32_e32 v55, v55, v3
	v_sub_f32_e32 v52, v52, v3
	v_sub_f32_e32 v105, v105, v3
	v_sub_f32_e32 v54, v54, v3
	v_sub_f32_e32 v106, v106, v3
	v_sub_f32_e32 v108, v108, v3
	v_sub_f32_e32 v107, v107, v3
	v_sub_f32_e32 v110, v110, v3
	v_sub_f32_e32 v109, v109, v3
	v_sub_f32_e32 v64, v64, v3
	v_sub_f32_e32 v59, v59, v3
	v_sub_f32_e32 v65, v65, v3
	v_sub_f32_e32 v62, v62, v3
	v_sub_f32_e32 v98, v98, v3
	v_sub_f32_e32 v63, v63, v3
	v_sub_f32_e32 v100, v100, v3
	v_sub_f32_e32 v99, v99, v3
	v_sub_f32_e32 v58, v58, v3
	v_sub_f32_e32 v57, v57, v3
	v_sub_f32_e32 v61, v61, v3
	v_sub_f32_e32 v60, v60, v3
	v_sub_f32_e32 v102, v102, v3
	v_sub_f32_e32 v101, v101, v3
	v_sub_f32_e32 v104, v104, v3
	v_sub_f32_e32 v103, v103, v3

; DI f32x16 mfma(bf16x8 a, bf16x8 b, f32x16 c) { return __builtin_amdgcn_mfma_f32_32x32x16_bf16(a, b, c, 0, 0, 0); }
; template <int MODE, int KS0, int NKS>
; DI void qk_scores(f32x16& s0, f32x16& s1, const u16* Ks, const bf16x8 (&qf)[4], float sl2, int dl, float mref,
;                   bool need_mask, int r, int h, int rs, const int (&lo)[4]) {
;   asm volatile("" : "+v"(dl));
;   const float nb = -sl2 * (float)dl - mref;
; #pragma unroll
;   for (int i = 0; i < 16; ++i) {
;     const int ci = (i & 3) + 8 * (i >> 2);
;     s0[i] = fmaf(sl2, (float)ci, nb);
;     s1[i] = fmaf(sl2, (float)(ci + 32), nb);
;   }
; #pragma unroll
;   for (int ks = 0; ks < NKS; ++ks) {
;     bf16x8 k0 = ldsv(Ks + lo[KS0 + ks]);
;     bf16x8 k1 = ldsv(Ks + 32 * rs + lo[KS0 + ks]);
;     s0 = mfma(k0, qf[KS0 + ks], s0);
;     s1 = mfma(k1, qf[KS0 + ks], s1);
;   }
;   if (need_mask) {
; #pragma unroll
;     for (int i = 0; i < 16; ++i) {
;       const int ci = (i & 3) + 8 * (i >> 2);
;       bool v0 = (MODE == 0) ? (ci <= dl) : (ci <= dl && ci > dl - 128);
;       bool v1 = (MODE == 0) ? (ci + 32 <= dl) : (ci + 32 <= dl && ci + 32 > dl - 128);
;       s0[i] = v0 ? s0[i] : -INFINITY;
;       s1[i] = v1 ? s1[i] : -INFINITY;
;     }
;   }
.LBB0_326:
	s_mov_b32 s2, 2.0
	v_cvt_f32_i32_e32 v57, v215
	s_mov_b32 s3, 0x40400000
	ds_read_b128 v[52:55], v209 offset:36864
	ds_read_b128 v[58:61], v209 offset:41472
	v_fma_f32 v62, -v56, v57, -v51
	v_fma_f32 v100, v56, s2, v62
	v_fma_f32 v101, v56, s3, v62
	s_mov_b32 s2, 0x41000000
	s_mov_b32 s3, 0x41100000
	v_fma_f32 v102, v56, s2, v62
	v_fma_f32 v103, v56, s3, v62
	s_mov_b32 s2, 0x41200000
	s_mov_b32 s3, 0x41300000
	v_fma_f32 v104, v56, s2, v62
	v_fma_f32 v105, v56, s3, v62
	s_mov_b32 s2, 0x41800000
	s_mov_b32 s3, 0x41880000
	v_fma_f32 v106, v56, s2, v62
	v_fma_f32 v107, v56, s3, v62
	s_mov_b32 s2, 0x41900000
	s_mov_b32 s3, 0x41980000
	v_fma_f32 v98, 0, v56, v62
	v_add_f32_e32 v99, v56, v62
	v_fma_f32 v108, v56, s2, v62
	v_fma_f32 v109, v56, s3, v62
	v_fma_f32 v110, v56, s50, v62
	v_fma_f32 v111, v56, s51, v62
	v_fma_f32 v112, v56, s28, v62
	v_fma_f32 v113, v56, s29, v62
	s_mov_b32 s2, 0x42680000
	s_mov_b32 s3, 0x426c0000
	s_waitcnt lgkmcnt(1)
	v_mfma_f32_32x32x16_bf16 v[98:113], v[52:55], v[142:145], v[98:113]
	ds_read_b128 v[52:55], v209 offset:36896
	v_fma_f32 v128, v56, s2, v62
	v_fma_f32 v129, v56, s3, v62
	s_mov_b32 s2, 0x42400000
	s_mov_b32 s3, 0x42440000
	v_fma_f32 v126, v56, s30, v62
	v_fma_f32 v127, v56, s31, v62
	v_fma_f32 v124, v56, s10, v62
	v_fma_f32 v125, v56, s11, v62
	v_fma_f32 v122, v56, s2, v62
	v_fma_f32 v123, v56, s3, v62
	v_fma_f32 v120, v56, s72, v62
	v_fma_f32 v121, v56, s73, v62
	v_fma_f32 v118, v56, s74, v62
	v_fma_f32 v119, v56, s75, v62
	v_fma_f32 v116, v56, s76, v62
	v_fma_f32 v117, v56, s77, v62
	v_fma_f32 v114, v56, s78, v62
	v_fma_f32 v115, v56, s79, v62
	s_waitcnt lgkmcnt(0)
	v_mfma_f32_32x32x16_bf16 v[98:113], v[52:55], v[138:141], v[98:113]
	ds_read_b128 v[52:55], v209 offset:41504
	v_add_u32_e32 v57, -1, v215
	v_cmp_gt_u32_e32 vcc, s95, v57
	v_subrev_u32_e32 v57, 35, v215
	v_mfma_f32_32x32x16_bf16 v[114:129], v[58:61], v[142:145], v[114:129]
	s_waitcnt lgkmcnt(0)
	v_mfma_f32_32x32x16_bf16 v[114:129], v[52:55], v[138:141], v[114:129]
	ds_read_b128 v[52:55], v209 offset:36928
	s_waitcnt lgkmcnt(0)
	v_mfma_f32_32x32x16_bf16 v[98:113], v[52:55], v[134:137], v[98:113]
	ds_read_b128 v[52:55], v209 offset:41536
	s_waitcnt lgkmcnt(0)
	v_mfma_f32_32x32x16_bf16 v[114:129], v[52:55], v[134:137], v[114:129]
	ds_read_b128 v[52:55], v209 offset:36960
	ds_read_b128 v[58:61], v209 offset:41568
	s_waitcnt lgkmcnt(1)
	v_mfma_f32_32x32x16_bf16 v[98:113], v[52:55], v[130:133], v[98:113]
	v_subrev_u32_e32 v54, 33, v215
	v_subrev_u32_e32 v55, 32, v215
	s_waitcnt lgkmcnt(0)
	v_mfma_f32_32x32x16_bf16 v[114:129], v[58:61], v[130:133], v[114:129]
	s_nop 7
	v_cndmask_b32_e32 v52, v199, v99, vcc
	v_cmp_gt_u32_e32 vcc, s95, v215
	v_subrev_u32_e32 v58, 34, v215
	v_subrev_u32_e32 v60, 19, v215
	v_cndmask_b32_e32 v53, v199, v98, vcc
	v_cmp_gt_u32_e32 vcc, s95, v54
	v_add_u32_e32 v54, -3, v215
	v_subrev_u32_e32 v61, 18, v215
	v_cndmask_b32_e32 v59, v199, v115, vcc
	v_cmp_gt_u32_e32 vcc, s95, v55
	v_add_u32_e32 v55, -2, v215
	s_nop 0
	v_cndmask_b32_e32 v64, v199, v114, vcc
	v_cmp_gt_u32_e32 vcc, s95, v54
	s_nop 1
	v_cndmask_b32_e32 v54, v199, v101, vcc
	v_cmp_gt_u32_e32 vcc, s95, v55
	v_subrev_u32_e32 v101, 25, v215
	s_nop 0
	v_cndmask_b32_e32 v55, v199, v100, vcc
	v_cmp_gt_u32_e32 vcc, s95, v57
	v_add_u32_e32 v57, -9, v215
	s_nop 0
	v_cndmask_b32_e32 v62, v199, v117, vcc
	v_cmp_gt_u32_e32 vcc, s95, v58
	v_add_u32_e32 v58, -8, v215
	s_nop 0
	v_cndmask_b32_e32 v65, v199, v116, vcc
	v_cmp_gt_u32_e32 vcc, s95, v57
	v_subrev_u32_e32 v57, 41, v215
	s_nop 0
	v_cndmask_b32_e32 v115, v199, v103, vcc
	v_cmp_gt_u32_e32 vcc, s95, v58
	v_subrev_u32_e32 v58, 40, v215
	v_subrev_u32_e32 v103, 27, v215
	v_cndmask_b32_e32 v116, v199, v102, vcc
	v_cmp_gt_u32_e32 vcc, s95, v57
	v_add_u32_e32 v57, -11, v215
	v_subrev_u32_e32 v102, 24, v215
	v_cndmask_b32_e32 v63, v199, v119, vcc
	v_cmp_gt_u32_e32 vcc, s95, v58
	v_add_u32_e32 v58, -10, v215
	s_nop 0
	v_cndmask_b32_e32 v98, v199, v118, vcc
	v_cmp_gt_u32_e32 vcc, s95, v57
	v_subrev_u32_e32 v57, 43, v215
	s_nop 0
	v_cndmask_b32_e32 v117, v199, v105, vcc
	v_cmp_gt_u32_e32 vcc, s95, v58
	v_subrev_u32_e32 v58, 42, v215
	s_nop 0
	v_cndmask_b32_e32 v118, v199, v104, vcc
	v_cmp_gt_u32_e32 vcc, s95, v57
	v_subrev_u32_e32 v57, 17, v215
	v_subrev_u32_e32 v104, 26, v215
	v_cndmask_b32_e32 v99, v199, v121, vcc
	v_cmp_gt_u32_e32 vcc, s95, v58
	v_add_u32_e32 v58, -16, v215
	s_nop 0
	v_cndmask_b32_e32 v100, v199, v120, vcc
	v_cmp_gt_u32_e32 vcc, s95, v57
	v_subrev_u32_e32 v57, 49, v215
	s_nop 0
	v_cndmask_b32_e32 v105, v199, v107, vcc
	v_cmp_gt_u32_e32 vcc, s95, v58
	v_subrev_u32_e32 v58, 48, v215
	s_nop 0
	v_cndmask_b32_e32 v114, v199, v106, vcc
	v_cmp_gt_u32_e32 vcc, s95, v57
	s_nop 1
	v_cndmask_b32_e32 v57, v199, v123, vcc
	v_cmp_gt_u32_e32 vcc, s95, v58
	s_nop 1
	v_cndmask_b32_e32 v58, v199, v122, vcc
	v_cmp_gt_u32_e32 vcc, s95, v60
	v_subrev_u32_e32 v60, 51, v215
	s_nop 0
	v_cndmask_b32_e32 v106, v199, v109, vcc
	v_cmp_gt_u32_e32 vcc, s95, v61
	v_subrev_u32_e32 v61, 50, v215
	s_nop 0
	v_cndmask_b32_e32 v108, v199, v108, vcc
	v_cmp_gt_u32_e32 vcc, s95, v60
	s_nop 1
	v_cndmask_b32_e32 v60, v199, v125, vcc
	v_cmp_gt_u32_e32 vcc, s95, v61
	s_nop 1
	v_cndmask_b32_e32 v61, v199, v124, vcc
	v_cmp_gt_u32_e32 vcc, s95, v101
	v_subrev_u32_e32 v101, 57, v215
	s_nop 0
	v_cndmask_b32_e32 v107, v199, v111, vcc
	v_cmp_gt_u32_e32 vcc, s95, v102
	v_subrev_u32_e32 v102, 56, v215
	s_nop 0
	v_cndmask_b32_e32 v109, v199, v110, vcc
	v_cmp_gt_u32_e32 vcc, s95, v101
	s_nop 1
	v_cndmask_b32_e32 v101, v199, v127, vcc
	v_cmp_gt_u32_e32 vcc, s95, v102
	s_nop 1
	v_cndmask_b32_e32 v102, v199, v126, vcc
	v_cmp_gt_u32_e32 vcc, s95, v103
	v_subrev_u32_e32 v103, 59, v215
	s_nop 0
	v_cndmask_b32_e32 v110, v199, v113, vcc
	v_cmp_gt_u32_e32 vcc, s95, v104
	v_subrev_u32_e32 v104, 58, v215
	s_nop 0
	v_cndmask_b32_e32 v111, v199, v112, vcc
	v_cmp_gt_u32_e32 vcc, s95, v103
	s_nop 1
	v_cndmask_b32_e32 v103, v199, v129, vcc
	v_cmp_gt_u32_e32 vcc, s95, v104
	s_nop 1
	v_cndmask_b32_e32 v104, v199, v128, vcc
	v_cmp_nge_f32_e32 vcc, s9, v18
	s_cbranch_vccz .LBB0_328
; DI float ex2(float x) { return __builtin_amdgcn_exp2f(x); }
; DI float lg2(float x) { return __builtin_amdgcn_logf(x); }
; template <int MODE, int KS0, int NKS>
; DI void softmax_pv(const bf16x8 (&qf)[4], const u16* Ks, const u16* Vs, float& m, f32x16& ls, f32x16& o0, f32x16& o1,
;                    float sl2, int dl, bool need_mask, bool first, int r, int h, int rs, const int (&lo)[4]) {
;     ...
;   if (__any(first || !(ls[0] <= 1.0e12f))) {
;     float tmax = -INFINITY;
; #pragma unroll
;     for (int i = 0; i < 16; ++i) tmax = fmaxf(tmax, fmaxf(s0[i], s1[i]));
;     tmax = fmaxf(tmax, shx(tmax, r + 32 * h));
;     const float lref = (ls[0] > 1.f) ? lg2(ls[0]) : 0.f;
;     const float delta = first ? tmax : fmaxf(fmaxf(tmax, lref), 0.f);
;     m += delta;
;     const float alpha = ex2(-delta);
; #pragma unroll
;     for (int e = 0; e < 16; ++e) { o0[e] *= alpha; o1[e] *= alpha; ls[e] *= alpha; }
; #pragma unroll
;     for (int i = 0; i < 16; ++i) { s0[i] -= delta; s1[i] -= delta; }
;   }
	v_max_f32_e32 v112, v64, v64
	v_max_f32_e32 v113, v53, v53
	v_max_f32_e32 v112, v113, v112
	v_max_f32_e32 v113, v59, v59
	v_max_f32_e32 v119, v52, v52
	v_max_f32_e32 v113, v119, v113
	s_mov_b32 s2, 0xff800000
	v_max3_f32 v112, v112, s2, v113
	v_max_f32_e32 v113, v65, v65
	v_max_f32_e32 v119, v55, v55
	v_max_f32_e32 v113, v119, v113
	v_max_f32_e32 v119, v62, v62
	v_max_f32_e32 v120, v54, v54
	v_max_f32_e32 v119, v120, v119
	v_max3_f32 v112, v112, v113, v119
	v_max_f32_e32 v113, v98, v98
	v_max_f32_e32 v119, v116, v116
	v_max_f32_e32 v113, v119, v113
	v_max_f32_e32 v119, v63, v63
	v_max_f32_e32 v120, v115, v115
	v_max_f32_e32 v119, v120, v119
	v_max3_f32 v112, v112, v113, v119
	v_max_f32_e32 v113, v100, v100
	v_max_f32_e32 v119, v118, v118
	v_max_f32_e32 v113, v119, v113
	v_max_f32_e32 v119, v99, v99
	v_max_f32_e32 v120, v117, v117
	v_max_f32_e32 v119, v120, v119
	v_max3_f32 v112, v112, v113, v119
	v_max_f32_e32 v113, v58, v58
	v_max_f32_e32 v119, v114, v114
	v_max_f32_e32 v113, v119, v113
	v_max_f32_e32 v119, v57, v57
	v_max_f32_e32 v120, v105, v105
	v_max_f32_e32 v119, v120, v119
	v_max3_f32 v112, v112, v113, v119
	v_max_f32_e32 v113, v61, v61
	v_max_f32_e32 v119, v108, v108
	v_max_f32_e32 v113, v119, v113
	v_max_f32_e32 v119, v60, v60
	v_max_f32_e32 v120, v106, v106
	v_max_f32_e32 v119, v120, v119
	v_max3_f32 v112, v112, v113, v119
	v_max_f32_e32 v113, v102, v102
	v_max_f32_e32 v119, v109, v109
	v_max_f32_e32 v113, v119, v113
	v_max_f32_e32 v119, v101, v101
	v_max_f32_e32 v120, v107, v107
	v_max_f32_e32 v119, v120, v119
	v_max3_f32 v112, v112, v113, v119
	v_max_f32_e32 v113, v104, v104
	v_max_f32_e32 v119, v111, v111
	v_max_f32_e32 v113, v119, v113
	v_max_f32_e32 v119, v103, v103
	v_max_f32_e32 v120, v110, v110
	v_max_f32_e32 v119, v120, v119
	v_max3_f32 v112, v112, v113, v119
	ds_bpermute_b32 v113, v185, v112
	v_log_f32_e32 v119, v18
	v_cmp_lt_f32_e32 vcc, 1.0, v18
	s_waitcnt lgkmcnt(0)
	v_max_f32_e32 v113, v113, v113
	v_max_f32_e32 v112, v112, v113
	v_cndmask_b32_e32 v113, 0, v119, vcc
	v_max3_f32 v113, v112, v113, 0
	v_exp_f32_e64 v112, -v113
	v_add_f32_e32 v51, v51, v113
	v_sub_f32_e32 v53, v53, v113
	v_sub_f32_e32 v52, v52, v113
	v_mul_f32_e32 v96, v96, v112
	v_mul_f32_e32 v97, v97, v112
	v_mul_f32_e32 v94, v94, v112
	v_mul_f32_e32 v95, v95, v112
	v_mul_f32_e32 v92, v92, v112
	v_mul_f32_e32 v93, v93, v112
	v_mul_f32_e32 v90, v90, v112
	v_mul_f32_e32 v91, v91, v112
	v_mul_f32_e32 v88, v88, v112
	v_mul_f32_e32 v89, v89, v112
	v_mul_f32_e32 v86, v86, v112
	v_mul_f32_e32 v87, v87, v112
	v_mul_f32_e32 v84, v84, v112
	v_mul_f32_e32 v85, v85, v112
	v_mul_f32_e32 v82, v82, v112
	v_mul_f32_e32 v83, v83, v112
	v_mul_f32_e32 v16, v16, v112
	v_mul_f32_e32 v17, v17, v112
	v_mul_f32_e32 v14, v14, v112
	v_mul_f32_e32 v15, v15, v112
	v_mul_f32_e32 v12, v12, v112
	v_mul_f32_e32 v13, v13, v112
	v_mul_f32_e32 v10, v10, v112
	v_mul_f32_e32 v11, v11, v112
	v_mul_f32_e32 v8, v8, v112
	v_mul_f32_e32 v9, v9, v112
	v_mul_f32_e32 v6, v6, v112
	v_mul_f32_e32 v7, v7, v112
	v_mul_f32_e32 v4, v4, v112
	v_mul_f32_e32 v5, v5, v112
	v_mul_f32_e32 v2, v2, v112
	v_mul_f32_e32 v3, v3, v112
	v_mul_f32_e32 v32, v32, v112
	v_mul_f32_e32 v33, v33, v112
	v_mul_f32_e32 v30, v30, v112
	v_mul_f32_e32 v31, v31, v112
	v_mul_f32_e32 v28, v28, v112
	v_mul_f32_e32 v29, v29, v112
	v_mul_f32_e32 v26, v26, v112
	v_mul_f32_e32 v27, v27, v112
	v_mul_f32_e32 v24, v24, v112
	v_mul_f32_e32 v25, v25, v112
	v_mul_f32_e32 v22, v22, v112
	v_mul_f32_e32 v23, v23, v112
	v_mul_f32_e32 v20, v20, v112
	v_mul_f32_e32 v21, v21, v112
	v_mul_f32_e32 v18, v18, v112
	v_mul_f32_e32 v19, v19, v112
	v_sub_f32_e32 v55, v55, v113
	v_sub_f32_e32 v54, v54, v113
	v_sub_f32_e32 v116, v116, v113
	v_sub_f32_e32 v115, v115, v113
	v_sub_f32_e32 v118, v118, v113
	v_sub_f32_e32 v117, v117, v113
	v_sub_f32_e32 v114, v114, v113
	v_sub_f32_e32 v105, v105, v113
	v_sub_f32_e32 v108, v108, v113
	v_sub_f32_e32 v106, v106, v113
	v_sub_f32_e32 v109, v109, v113
	v_sub_f32_e32 v107, v107, v113
	v_sub_f32_e32 v111, v111, v113
	v_sub_f32_e32 v110, v110, v113
	v_sub_f32_e32 v64, v64, v113
	v_sub_f32_e32 v59, v59, v113
	v_sub_f32_e32 v65, v65, v113
	v_sub_f32_e32 v62, v62, v113
	v_sub_f32_e32 v98, v98, v113
	v_sub_f32_e32 v63, v63, v113
	v_sub_f32_e32 v100, v100, v113
	v_sub_f32_e32 v99, v99, v113
	v_sub_f32_e32 v58, v58, v113
	v_sub_f32_e32 v57, v57, v113
	v_sub_f32_e32 v61, v61, v113
	v_sub_f32_e32 v60, v60, v113
	v_sub_f32_e32 v102, v102, v113
	v_sub_f32_e32 v101, v101, v113
	v_sub_f32_e32 v104, v104, v113
	v_sub_f32_e32 v103, v103, v113

; DI f32x16 mfma(bf16x8 a, bf16x8 b, f32x16 c) { return __builtin_amdgcn_mfma_f32_32x32x16_bf16(a, b, c, 0, 0, 0); }
; template <int MODE, int KS0, int NKS>
; DI void qk_scores(f32x16& s0, f32x16& s1, const u16* Ks, const bf16x8 (&qf)[4], float sl2, int dl, float mref,
;                   bool need_mask, int r, int h, int rs, const int (&lo)[4]) {
;   asm volatile("" : "+v"(dl));
;   const float nb = -sl2 * (float)dl - mref;
; #pragma unroll
;   for (int i = 0; i < 16; ++i) {
;     const int ci = (i & 3) + 8 * (i >> 2);
;     s0[i] = fmaf(sl2, (float)ci, nb);
;     s1[i] = fmaf(sl2, (float)(ci + 32), nb);
;   }
; #pragma unroll
;   for (int ks = 0; ks < NKS; ++ks) {
;     bf16x8 k0 = ldsv(Ks + lo[KS0 + ks]);
;     bf16x8 k1 = ldsv(Ks + 32 * rs + lo[KS0 + ks]);
;     s0 = mfma(k0, qf[KS0 + ks], s0);
;     s1 = mfma(k1, qf[KS0 + ks], s1);
;   }
;   if (need_mask) {
; #pragma unroll
;     for (int i = 0; i < 16; ++i) {
;       const int ci = (i & 3) + 8 * (i >> 2);
;       bool v0 = (MODE == 0) ? (ci <= dl) : (ci <= dl && ci > dl - 128);
;       bool v1 = (MODE == 0) ? (ci + 32 <= dl) : (ci + 32 <= dl && ci + 32 > dl - 128);
;       s0[i] = v0 ? s0[i] : -INFINITY;
;       s1[i] = v1 ? s1[i] : -INFINITY;
;     }
;   }
.LBB0_330:
	v_cmp_le_i32_e32 vcc, v217, v210
	v_cmp_ge_i32_e64 s[2:3], v218, v211
	s_and_b64 s[18:19], vcc, s[2:3]
	s_and_saveexec_b64 s[2:3], s[18:19]
	s_cbranch_execz .LBB0_334
	v_add3_u32 v186, v221, v208, 64
	s_mov_b32 s18, 2.0
	v_cvt_f32_i32_e32 v57, v186
	s_mov_b32 s19, 0x40400000
	ds_read_b128 v[52:55], v209 offset:18432
	ds_read_b128 v[58:61], v209 offset:23040
	v_fma_f32 v62, -v56, v57, -v51
	v_fma_f32 v100, v56, s18, v62
	v_fma_f32 v101, v56, s19, v62
	s_mov_b32 s18, 0x41000000
	s_mov_b32 s19, 0x41100000
	v_fma_f32 v102, v56, s18, v62
	v_fma_f32 v103, v56, s19, v62
	s_mov_b32 s18, 0x41200000
	s_mov_b32 s19, 0x41300000
	v_fma_f32 v104, v56, s18, v62
	v_fma_f32 v105, v56, s19, v62
	s_mov_b32 s18, 0x41800000
	s_mov_b32 s19, 0x41880000
	v_fma_f32 v106, v56, s18, v62
	v_fma_f32 v107, v56, s19, v62
	s_mov_b32 s18, 0x41900000
	s_mov_b32 s19, 0x41980000
	v_fma_f32 v98, 0, v56, v62
	v_add_f32_e32 v99, v56, v62
	v_fma_f32 v108, v56, s18, v62
	v_fma_f32 v109, v56, s19, v62
	v_fma_f32 v110, v56, s50, v62
	v_fma_f32 v111, v56, s51, v62
	v_fma_f32 v112, v56, s28, v62
	v_fma_f32 v113, v56, s29, v62
	s_mov_b32 s18, 0x42680000
	s_mov_b32 s19, 0x426c0000
	s_waitcnt lgkmcnt(1)
	v_mfma_f32_32x32x16_bf16 v[98:113], v[52:55], v[142:145], v[98:113]
	ds_read_b128 v[52:55], v209 offset:18464
	v_fma_f32 v128, v56, s18, v62
	v_fma_f32 v129, v56, s19, v62
	s_mov_b32 s18, 0x42400000
	s_mov_b32 s19, 0x42440000
	v_fma_f32 v126, v56, s30, v62
	v_fma_f32 v127, v56, s31, v62
	v_fma_f32 v124, v56, s10, v62
	v_fma_f32 v125, v56, s11, v62
	v_fma_f32 v122, v56, s18, v62
	v_fma_f32 v123, v56, s19, v62
	v_fma_f32 v120, v56, s72, v62
	v_fma_f32 v121, v56, s73, v62
	v_fma_f32 v118, v56, s74, v62
	v_fma_f32 v119, v56, s75, v62
	v_fma_f32 v116, v56, s76, v62
	v_fma_f32 v117, v56, s77, v62
	v_fma_f32 v114, v56, s78, v62
	v_fma_f32 v115, v56, s79, v62
	s_waitcnt lgkmcnt(0)
	v_mfma_f32_32x32x16_bf16 v[98:113], v[52:55], v[138:141], v[98:113]
	ds_read_b128 v[52:55], v209 offset:23072
	v_add_u32_e32 v57, -1, v186
	v_cmp_gt_u32_e32 vcc, s95, v57
	v_subrev_u32_e32 v57, 35, v186
	v_mfma_f32_32x32x16_bf16 v[114:129], v[58:61], v[142:145], v[114:129]
	s_waitcnt lgkmcnt(0)
	v_mfma_f32_32x32x16_bf16 v[114:129], v[52:55], v[138:141], v[114:129]
	ds_read_b128 v[52:55], v209 offset:18496
	s_waitcnt lgkmcnt(0)
	v_mfma_f32_32x32x16_bf16 v[98:113], v[52:55], v[134:137], v[98:113]
	ds_read_b128 v[52:55], v209 offset:23104
	s_waitcnt lgkmcnt(0)
	v_mfma_f32_32x32x16_bf16 v[114:129], v[52:55], v[134:137], v[114:129]
	ds_read_b128 v[52:55], v209 offset:18528
	ds_read_b128 v[58:61], v209 offset:23136
	s_waitcnt lgkmcnt(1)
	v_mfma_f32_32x32x16_bf16 v[98:113], v[52:55], v[130:133], v[98:113]
	v_subrev_u32_e32 v54, 33, v186
	v_subrev_u32_e32 v55, 32, v186
	s_waitcnt lgkmcnt(0)
	v_mfma_f32_32x32x16_bf16 v[114:129], v[58:61], v[130:133], v[114:129]
	s_nop 7
	v_cndmask_b32_e32 v52, v199, v99, vcc
	v_cmp_gt_u32_e32 vcc, s95, v186
	v_subrev_u32_e32 v58, 34, v186
	v_subrev_u32_e32 v60, 19, v186
	v_cndmask_b32_e32 v53, v199, v98, vcc
	v_cmp_gt_u32_e32 vcc, s95, v54
	v_add_u32_e32 v54, -3, v186
	v_subrev_u32_e32 v61, 18, v186
	v_cndmask_b32_e32 v59, v199, v115, vcc
	v_cmp_gt_u32_e32 vcc, s95, v55
	v_add_u32_e32 v55, -2, v186
	s_nop 0
	v_cndmask_b32_e32 v64, v199, v114, vcc
	v_cmp_gt_u32_e32 vcc, s95, v54
	s_nop 1
	v_cndmask_b32_e32 v54, v199, v101, vcc
	v_cmp_gt_u32_e32 vcc, s95, v55
	v_subrev_u32_e32 v101, 25, v186
	s_nop 0
	v_cndmask_b32_e32 v55, v199, v100, vcc
	v_cmp_gt_u32_e32 vcc, s95, v57
	v_add_u32_e32 v57, -9, v186
	s_nop 0
	v_cndmask_b32_e32 v62, v199, v117, vcc
	v_cmp_gt_u32_e32 vcc, s95, v58
	v_add_u32_e32 v58, -8, v186
	s_nop 0
	v_cndmask_b32_e32 v65, v199, v116, vcc
	v_cmp_gt_u32_e32 vcc, s95, v57
	v_subrev_u32_e32 v57, 41, v186
	s_nop 0
	v_cndmask_b32_e32 v115, v199, v103, vcc
	v_cmp_gt_u32_e32 vcc, s95, v58
	v_subrev_u32_e32 v58, 40, v186
	v_subrev_u32_e32 v103, 27, v186
	v_cndmask_b32_e32 v116, v199, v102, vcc
	v_cmp_gt_u32_e32 vcc, s95, v57
	v_add_u32_e32 v57, -11, v186
	v_subrev_u32_e32 v102, 24, v186
	v_cndmask_b32_e32 v63, v199, v119, vcc
	v_cmp_gt_u32_e32 vcc, s95, v58
	v_add_u32_e32 v58, -10, v186
	s_nop 0
	v_cndmask_b32_e32 v98, v199, v118, vcc
	v_cmp_gt_u32_e32 vcc, s95, v57
	v_subrev_u32_e32 v57, 43, v186
	s_nop 0
	v_cndmask_b32_e32 v117, v199, v105, vcc
	v_cmp_gt_u32_e32 vcc, s95, v58
	v_subrev_u32_e32 v58, 42, v186
	s_nop 0
	v_cndmask_b32_e32 v118, v199, v104, vcc
	v_cmp_gt_u32_e32 vcc, s95, v57
	v_subrev_u32_e32 v57, 17, v186
	v_subrev_u32_e32 v104, 26, v186
	v_cndmask_b32_e32 v99, v199, v121, vcc
	v_cmp_gt_u32_e32 vcc, s95, v58
	v_add_u32_e32 v58, -16, v186
	s_nop 0
	v_cndmask_b32_e32 v100, v199, v120, vcc
	v_cmp_gt_u32_e32 vcc, s95, v57
	v_subrev_u32_e32 v57, 49, v186
	s_nop 0
	v_cndmask_b32_e32 v105, v199, v107, vcc
	v_cmp_gt_u32_e32 vcc, s95, v58
	v_subrev_u32_e32 v58, 48, v186
	s_nop 0
	v_cndmask_b32_e32 v114, v199, v106, vcc
	v_cmp_gt_u32_e32 vcc, s95, v57
	s_nop 1
	v_cndmask_b32_e32 v57, v199, v123, vcc
	v_cmp_gt_u32_e32 vcc, s95, v58
	s_nop 1
	v_cndmask_b32_e32 v58, v199, v122, vcc
	v_cmp_gt_u32_e32 vcc, s95, v60
	v_subrev_u32_e32 v60, 51, v186
	s_nop 0
	v_cndmask_b32_e32 v106, v199, v109, vcc
	v_cmp_gt_u32_e32 vcc, s95, v61
	v_subrev_u32_e32 v61, 50, v186
	s_nop 0
	v_cndmask_b32_e32 v108, v199, v108, vcc
	v_cmp_gt_u32_e32 vcc, s95, v60
	s_nop 1
	v_cndmask_b32_e32 v60, v199, v125, vcc
	v_cmp_gt_u32_e32 vcc, s95, v61
	s_nop 1
	v_cndmask_b32_e32 v61, v199, v124, vcc
	v_cmp_gt_u32_e32 vcc, s95, v101
	v_subrev_u32_e32 v101, 57, v186
	s_nop 0
	v_cndmask_b32_e32 v107, v199, v111, vcc
	v_cmp_gt_u32_e32 vcc, s95, v102
	v_subrev_u32_e32 v102, 56, v186
	s_nop 0
	v_cndmask_b32_e32 v109, v199, v110, vcc
	v_cmp_gt_u32_e32 vcc, s95, v101
	s_nop 1
	v_cndmask_b32_e32 v101, v199, v127, vcc
	v_cmp_gt_u32_e32 vcc, s95, v102
	s_nop 1
	v_cndmask_b32_e32 v102, v199, v126, vcc
	v_cmp_gt_u32_e32 vcc, s95, v103
	v_subrev_u32_e32 v103, 59, v186
	s_nop 0
	v_cndmask_b32_e32 v110, v199, v113, vcc
	v_cmp_gt_u32_e32 vcc, s95, v104
	v_subrev_u32_e32 v104, 58, v186
	s_nop 0
	v_cndmask_b32_e32 v111, v199, v112, vcc
	v_cmp_gt_u32_e32 vcc, s95, v103
	s_nop 1
	v_cndmask_b32_e32 v103, v199, v129, vcc
	v_cmp_gt_u32_e32 vcc, s95, v104
	s_nop 1
	v_cndmask_b32_e32 v104, v199, v128, vcc
	v_cmp_nge_f32_e32 vcc, s9, v18
	s_cbranch_vccz .LBB0_333
; DI float ex2(float x) { return __builtin_amdgcn_exp2f(x); }
; DI float lg2(float x) { return __builtin_amdgcn_logf(x); }
; template <int MODE, int KS0, int NKS>
; DI void softmax_pv(const bf16x8 (&qf)[4], const u16* Ks, const u16* Vs, float& m, f32x16& ls, f32x16& o0, f32x16& o1,
;                    float sl2, int dl, bool need_mask, bool first, int r, int h, int rs, const int (&lo)[4]) {
;     ...
;   if (__any(first || !(ls[0] <= 1.0e12f))) {
;     float tmax = -INFINITY;
; #pragma unroll
;     for (int i = 0; i < 16; ++i) tmax = fmaxf(tmax, fmaxf(s0[i], s1[i]));
;     tmax = fmaxf(tmax, shx(tmax, r + 32 * h));
;     const float lref = (ls[0] > 1.f) ? lg2(ls[0]) : 0.f;
;     const float delta = first ? tmax : fmaxf(fmaxf(tmax, lref), 0.f);
;     m += delta;
;     const float alpha = ex2(-delta);
; #pragma unroll
;     for (int e = 0; e < 16; ++e) { o0[e] *= alpha; o1[e] *= alpha; ls[e] *= alpha; }
; #pragma unroll
;     for (int i = 0; i < 16; ++i) { s0[i] -= delta; s1[i] -= delta; }
;   }
	v_max_f32_e32 v112, v64, v64
	v_max_f32_e32 v113, v53, v53
	v_max_f32_e32 v112, v113, v112
	v_max_f32_e32 v113, v59, v59
	v_max_f32_e32 v119, v52, v52
	v_max_f32_e32 v113, v119, v113
	s_mov_b32 s18, 0xff800000
	v_max3_f32 v112, v112, s18, v113
	v_max_f32_e32 v113, v65, v65
	v_max_f32_e32 v119, v55, v55
	v_max_f32_e32 v113, v119, v113
	v_max_f32_e32 v119, v62, v62
	v_max_f32_e32 v120, v54, v54
	v_max_f32_e32 v119, v120, v119
	v_max3_f32 v112, v112, v113, v119
	v_max_f32_e32 v113, v98, v98
	v_max_f32_e32 v119, v116, v116
	v_max_f32_e32 v113, v119, v113
	v_max_f32_e32 v119, v63, v63
	v_max_f32_e32 v120, v115, v115
	v_max_f32_e32 v119, v120, v119
	v_max3_f32 v112, v112, v113, v119
	v_max_f32_e32 v113, v100, v100
	v_max_f32_e32 v119, v118, v118
	v_max_f32_e32 v113, v119, v113
	v_max_f32_e32 v119, v99, v99
	v_max_f32_e32 v120, v117, v117
	v_max_f32_e32 v119, v120, v119
	v_max3_f32 v112, v112, v113, v119
	v_max_f32_e32 v113, v58, v58
	v_max_f32_e32 v119, v114, v114
	v_max_f32_e32 v113, v119, v113
	v_max_f32_e32 v119, v57, v57
	v_max_f32_e32 v120, v105, v105
	v_max_f32_e32 v119, v120, v119
	v_max3_f32 v112, v112, v113, v119
	v_max_f32_e32 v113, v61, v61
	v_max_f32_e32 v119, v108, v108
	v_max_f32_e32 v113, v119, v113
	v_max_f32_e32 v119, v60, v60
	v_max_f32_e32 v120, v106, v106
	v_max_f32_e32 v119, v120, v119
	v_max3_f32 v112, v112, v113, v119
	v_max_f32_e32 v113, v102, v102
	v_max_f32_e32 v119, v109, v109
	v_max_f32_e32 v113, v119, v113
	v_max_f32_e32 v119, v101, v101
	v_max_f32_e32 v120, v107, v107
	v_max_f32_e32 v119, v120, v119
	v_max3_f32 v112, v112, v113, v119
	v_max_f32_e32 v113, v104, v104
	v_max_f32_e32 v119, v111, v111
	v_max_f32_e32 v113, v119, v113
	v_max_f32_e32 v119, v103, v103
	v_max_f32_e32 v120, v110, v110
	v_max_f32_e32 v119, v120, v119
	v_max3_f32 v112, v112, v113, v119
	ds_bpermute_b32 v113, v185, v112
	v_log_f32_e32 v119, v18
	v_cmp_lt_f32_e32 vcc, 1.0, v18
	s_waitcnt lgkmcnt(0)
	v_max_f32_e32 v113, v113, v113
	v_max_f32_e32 v112, v112, v113
	v_cndmask_b32_e32 v113, 0, v119, vcc
	v_max3_f32 v113, v112, v113, 0
	v_exp_f32_e64 v112, -v113
	v_add_f32_e32 v51, v51, v113
	v_sub_f32_e32 v53, v53, v113
	v_sub_f32_e32 v52, v52, v113
	v_mul_f32_e32 v96, v96, v112
	v_mul_f32_e32 v97, v97, v112
	v_mul_f32_e32 v94, v94, v112
	v_mul_f32_e32 v95, v95, v112
	v_mul_f32_e32 v92, v92, v112
	v_mul_f32_e32 v93, v93, v112
	v_mul_f32_e32 v90, v90, v112
	v_mul_f32_e32 v91, v91, v112
	v_mul_f32_e32 v88, v88, v112
	v_mul_f32_e32 v89, v89, v112
	v_mul_f32_e32 v86, v86, v112
	v_mul_f32_e32 v87, v87, v112
	v_mul_f32_e32 v84, v84, v112
	v_mul_f32_e32 v85, v85, v112
	v_mul_f32_e32 v82, v82, v112
	v_mul_f32_e32 v83, v83, v112
	v_mul_f32_e32 v16, v16, v112
	v_mul_f32_e32 v17, v17, v112
	v_mul_f32_e32 v14, v14, v112
	v_mul_f32_e32 v15, v15, v112
	v_mul_f32_e32 v12, v12, v112
	v_mul_f32_e32 v13, v13, v112
	v_mul_f32_e32 v10, v10, v112
	v_mul_f32_e32 v11, v11, v112
	v_mul_f32_e32 v8, v8, v112
	v_mul_f32_e32 v9, v9, v112
	v_mul_f32_e32 v6, v6, v112
	v_mul_f32_e32 v7, v7, v112
	v_mul_f32_e32 v4, v4, v112
	v_mul_f32_e32 v5, v5, v112
	v_mul_f32_e32 v2, v2, v112
	v_mul_f32_e32 v3, v3, v112
	v_mul_f32_e32 v32, v32, v112
	v_mul_f32_e32 v33, v33, v112
	v_mul_f32_e32 v30, v30, v112
	v_mul_f32_e32 v31, v31, v112
	v_mul_f32_e32 v28, v28, v112
	v_mul_f32_e32 v29, v29, v112
	v_mul_f32_e32 v26, v26, v112
	v_mul_f32_e32 v27, v27, v112
	v_mul_f32_e32 v24, v24, v112
	v_mul_f32_e32 v25, v25, v112
	v_mul_f32_e32 v22, v22, v112
	v_mul_f32_e32 v23, v23, v112
	v_mul_f32_e32 v20, v20, v112
	v_mul_f32_e32 v21, v21, v112
	v_mul_f32_e32 v18, v18, v112
	v_mul_f32_e32 v19, v19, v112
	v_sub_f32_e32 v55, v55, v113
	v_sub_f32_e32 v54, v54, v113
	v_sub_f32_e32 v116, v116, v113
	v_sub_f32_e32 v115, v115, v113
	v_sub_f32_e32 v118, v118, v113
	v_sub_f32_e32 v117, v117, v113
	v_sub_f32_e32 v114, v114, v113
	v_sub_f32_e32 v105, v105, v113
	v_sub_f32_e32 v108, v108, v113
	v_sub_f32_e32 v106, v106, v113
	v_sub_f32_e32 v109, v109, v113
	v_sub_f32_e32 v107, v107, v113
	v_sub_f32_e32 v111, v111, v113
	v_sub_f32_e32 v110, v110, v113
	v_sub_f32_e32 v64, v64, v113
	v_sub_f32_e32 v59, v59, v113
	v_sub_f32_e32 v65, v65, v113
	v_sub_f32_e32 v62, v62, v113
	v_sub_f32_e32 v98, v98, v113
	v_sub_f32_e32 v63, v63, v113
	v_sub_f32_e32 v100, v100, v113
	v_sub_f32_e32 v99, v99, v113
	v_sub_f32_e32 v58, v58, v113
	v_sub_f32_e32 v57, v57, v113
	v_sub_f32_e32 v61, v61, v113
	v_sub_f32_e32 v60, v60, v113
	v_sub_f32_e32 v102, v102, v113
	v_sub_f32_e32 v101, v101, v113
	v_sub_f32_e32 v104, v104, v113
	v_sub_f32_e32 v103, v103, v113

; DI f32x16 mfma(bf16x8 a, bf16x8 b, f32x16 c) { return __builtin_amdgcn_mfma_f32_32x32x16_bf16(a, b, c, 0, 0, 0); }
; template <int MODE, int KS0, int NKS>
; DI void qk_scores(f32x16& s0, f32x16& s1, const u16* Ks, const bf16x8 (&qf)[4], float sl2, int dl, float mref,
;                   bool need_mask, int r, int h, int rs, const int (&lo)[4]) {
;   asm volatile("" : "+v"(dl));
;   const float nb = -sl2 * (float)dl - mref;
; #pragma unroll
;   for (int i = 0; i < 16; ++i) {
;     const int ci = (i & 3) + 8 * (i >> 2);
;     s0[i] = fmaf(sl2, (float)ci, nb);
;     s1[i] = fmaf(sl2, (float)(ci + 32), nb);
;   }
; #pragma unroll
;   for (int ks = 0; ks < NKS; ++ks) {
;     bf16x8 k0 = ldsv(Ks + lo[KS0 + ks]);
;     bf16x8 k1 = ldsv(Ks + 32 * rs + lo[KS0 + ks]);
;     s0 = mfma(k0, qf[KS0 + ks], s0);
;     s1 = mfma(k1, qf[KS0 + ks], s1);
;   }
;   if (need_mask) {
; #pragma unroll
;     for (int i = 0; i < 16; ++i) {
;       const int ci = (i & 3) + 8 * (i >> 2);
;       bool v0 = (MODE == 0) ? (ci <= dl) : (ci <= dl && ci > dl - 128);
;       bool v1 = (MODE == 0) ? (ci + 32 <= dl) : (ci + 32 <= dl && ci + 32 > dl - 128);
;       s0[i] = v0 ? s0[i] : -INFINITY;
;       s1[i] = v1 ? s1[i] : -INFINITY;
;     }
;   }
.LBB0_336:
	s_mov_b32 s2, 2.0
	v_cvt_f32_i32_e32 v57, v184
	s_mov_b32 s3, 0x40400000
	ds_read_b128 v[52:55], v209 offset:55296
	ds_read_b128 v[58:61], v209 offset:59904
	v_fma_f32 v62, -v56, v57, -v51
	v_fma_f32 v100, v56, s2, v62
	v_fma_f32 v101, v56, s3, v62
	s_mov_b32 s2, 0x41000000
	s_mov_b32 s3, 0x41100000
	v_fma_f32 v102, v56, s2, v62
	v_fma_f32 v103, v56, s3, v62
	s_mov_b32 s2, 0x41200000
	s_mov_b32 s3, 0x41300000
	v_fma_f32 v104, v56, s2, v62
	v_fma_f32 v105, v56, s3, v62
	s_mov_b32 s2, 0x41800000
	s_mov_b32 s3, 0x41880000
	v_fma_f32 v106, v56, s2, v62
	v_fma_f32 v107, v56, s3, v62
	s_mov_b32 s2, 0x41900000
	s_mov_b32 s3, 0x41980000
	v_fma_f32 v98, 0, v56, v62
	v_add_f32_e32 v99, v56, v62
	v_fma_f32 v108, v56, s2, v62
	v_fma_f32 v109, v56, s3, v62
	v_fma_f32 v110, v56, s50, v62
	v_fma_f32 v111, v56, s51, v62
	v_fma_f32 v112, v56, s28, v62
	v_fma_f32 v113, v56, s29, v62
	s_mov_b32 s2, 0x42680000
	s_mov_b32 s3, 0x426c0000
	s_waitcnt lgkmcnt(1)
	v_mfma_f32_32x32x16_bf16 v[98:113], v[52:55], v[142:145], v[98:113]
	ds_read_b128 v[52:55], v209 offset:55328
	v_fma_f32 v128, v56, s2, v62
	v_fma_f32 v129, v56, s3, v62
	s_mov_b32 s2, 0x42400000
	s_mov_b32 s3, 0x42440000
	v_fma_f32 v126, v56, s30, v62
	v_fma_f32 v127, v56, s31, v62
	v_fma_f32 v124, v56, s10, v62
	v_fma_f32 v125, v56, s11, v62
	v_fma_f32 v122, v56, s2, v62
	v_fma_f32 v123, v56, s3, v62
	v_fma_f32 v120, v56, s72, v62
	v_fma_f32 v121, v56, s73, v62
	v_fma_f32 v118, v56, s74, v62
	v_fma_f32 v119, v56, s75, v62
	v_fma_f32 v116, v56, s76, v62
	v_fma_f32 v117, v56, s77, v62
	v_fma_f32 v114, v56, s78, v62
	v_fma_f32 v115, v56, s79, v62
	s_waitcnt lgkmcnt(0)
	v_mfma_f32_32x32x16_bf16 v[98:113], v[52:55], v[138:141], v[98:113]
	ds_read_b128 v[52:55], v209 offset:59936
	v_add_u32_e32 v51, -1, v184
	v_cmp_gt_u32_e32 vcc, s95, v51
	v_subrev_u32_e32 v51, 33, v184
	v_subrev_u32_e32 v63, 25, v184
	v_subrev_u32_e32 v64, 24, v184
	v_subrev_u32_e32 v65, 27, v184
	v_mfma_f32_32x32x16_bf16 v[114:129], v[58:61], v[142:145], v[114:129]
	s_waitcnt lgkmcnt(0)
	v_mfma_f32_32x32x16_bf16 v[114:129], v[52:55], v[138:141], v[114:129]
	ds_read_b128 v[52:55], v209 offset:55360
	s_waitcnt lgkmcnt(0)
	v_mfma_f32_32x32x16_bf16 v[98:113], v[52:55], v[134:137], v[98:113]
	ds_read_b128 v[52:55], v209 offset:59968
	s_waitcnt lgkmcnt(0)
	v_mfma_f32_32x32x16_bf16 v[114:129], v[52:55], v[134:137], v[114:129]
	ds_read_b128 v[52:55], v209 offset:55392
	ds_read_b128 v[56:59], v209 offset:60000
	s_waitcnt lgkmcnt(1)
	v_mfma_f32_32x32x16_bf16 v[98:113], v[52:55], v[130:133], v[98:113]
	v_subrev_u32_e32 v52, 32, v184
	v_subrev_u32_e32 v54, 19, v184
	v_subrev_u32_e32 v55, 18, v184
	s_waitcnt lgkmcnt(0)
	v_mfma_f32_32x32x16_bf16 v[114:129], v[56:59], v[130:133], v[114:129]
	s_nop 6
	v_cndmask_b32_e32 v99, v199, v99, vcc
	v_cmp_gt_u32_e32 vcc, s95, v184
	s_nop 1
	v_cndmask_b32_e32 v134, v199, v98, vcc
	v_cmp_gt_u32_e32 vcc, s95, v51
	v_add_u32_e32 v51, -3, v184
	v_subrev_u32_e32 v98, 26, v184
	v_cndmask_b32_e32 v53, v199, v115, vcc
	v_cmp_gt_u32_e32 vcc, s95, v52
	v_add_u32_e32 v52, -2, v184
	s_nop 0
	v_cndmask_b32_e32 v58, v199, v114, vcc
	v_cmp_gt_u32_e32 vcc, s95, v51
	v_subrev_u32_e32 v51, 35, v184
	s_nop 0
	v_cndmask_b32_e32 v101, v199, v101, vcc
	v_cmp_gt_u32_e32 vcc, s95, v52
	v_subrev_u32_e32 v52, 34, v184
	s_nop 0
	v_cndmask_b32_e32 v114, v199, v100, vcc
	v_cmp_gt_u32_e32 vcc, s95, v51
	v_add_u32_e32 v51, -9, v184
	s_nop 0
	v_cndmask_b32_e32 v56, v199, v117, vcc
	v_cmp_gt_u32_e32 vcc, s95, v52
	v_add_u32_e32 v52, -8, v184
	s_nop 0
	v_cndmask_b32_e32 v59, v199, v116, vcc
	v_cmp_gt_u32_e32 vcc, s95, v51
	v_subrev_u32_e32 v51, 41, v184
	s_nop 0
	v_cndmask_b32_e32 v115, v199, v103, vcc
	v_cmp_gt_u32_e32 vcc, s95, v52
	v_subrev_u32_e32 v52, 40, v184
	s_nop 0
	v_cndmask_b32_e32 v116, v199, v102, vcc
	v_cmp_gt_u32_e32 vcc, s95, v51
	v_add_u32_e32 v51, -11, v184
	s_nop 0
	v_cndmask_b32_e32 v57, v199, v119, vcc
	v_cmp_gt_u32_e32 vcc, s95, v52
	v_add_u32_e32 v52, -10, v184
	s_nop 0
	v_cndmask_b32_e32 v60, v199, v118, vcc
	v_cmp_gt_u32_e32 vcc, s95, v51
	v_subrev_u32_e32 v51, 43, v184
	s_nop 0
	v_cndmask_b32_e32 v117, v199, v105, vcc
	v_cmp_gt_u32_e32 vcc, s95, v52
	v_subrev_u32_e32 v52, 42, v184
	s_nop 0
	v_cndmask_b32_e32 v118, v199, v104, vcc
	v_cmp_gt_u32_e32 vcc, s95, v51
	v_subrev_u32_e32 v51, 17, v184
	s_nop 0
	v_cndmask_b32_e32 v61, v199, v121, vcc
	v_cmp_gt_u32_e32 vcc, s95, v52
	v_add_u32_e32 v52, -16, v184
	s_nop 0
	v_cndmask_b32_e32 v62, v199, v120, vcc
	v_cmp_gt_u32_e32 vcc, s95, v51
	v_subrev_u32_e32 v51, 49, v184
	s_nop 0
	v_cndmask_b32_e32 v100, v199, v107, vcc
	v_cmp_gt_u32_e32 vcc, s95, v52
	v_subrev_u32_e32 v52, 48, v184
	s_nop 0
	v_cndmask_b32_e32 v104, v199, v106, vcc
	v_cmp_gt_u32_e32 vcc, s95, v51
	s_nop 1
	v_cndmask_b32_e32 v51, v199, v123, vcc
	v_cmp_gt_u32_e32 vcc, s95, v52
	s_nop 1
	v_cndmask_b32_e32 v52, v199, v122, vcc
	v_cmp_gt_u32_e32 vcc, s95, v54
	v_subrev_u32_e32 v54, 51, v184
	s_nop 0
	v_cndmask_b32_e32 v102, v199, v109, vcc
	v_cmp_gt_u32_e32 vcc, s95, v55
	v_subrev_u32_e32 v55, 50, v184
	s_nop 0
	v_cndmask_b32_e32 v105, v199, v108, vcc
	v_cmp_gt_u32_e32 vcc, s95, v54
	s_nop 1
	v_cndmask_b32_e32 v54, v199, v125, vcc
	v_cmp_gt_u32_e32 vcc, s95, v55
	s_nop 1
	v_cndmask_b32_e32 v55, v199, v124, vcc
	v_cmp_gt_u32_e32 vcc, s95, v63
	v_subrev_u32_e32 v63, 57, v184
	s_nop 0
	v_cndmask_b32_e32 v103, v199, v111, vcc
	v_cmp_gt_u32_e32 vcc, s95, v64
	v_subrev_u32_e32 v64, 56, v184
	s_nop 0
	v_cndmask_b32_e32 v106, v199, v110, vcc
	v_cmp_gt_u32_e32 vcc, s95, v63
	s_nop 1
	v_cndmask_b32_e32 v63, v199, v127, vcc
	v_cmp_gt_u32_e32 vcc, s95, v64
	s_nop 1
	v_cndmask_b32_e32 v64, v199, v126, vcc
	v_cmp_gt_u32_e32 vcc, s95, v65
	v_subrev_u32_e32 v65, 59, v184
	s_nop 0
	v_cndmask_b32_e32 v107, v199, v113, vcc
	v_cmp_gt_u32_e32 vcc, s95, v98
	v_subrev_u32_e32 v98, 58, v184
	s_nop 0
	v_cndmask_b32_e32 v108, v199, v112, vcc
	v_cmp_gt_u32_e32 vcc, s95, v65
	s_nop 1
	v_cndmask_b32_e32 v65, v199, v129, vcc
	v_cmp_gt_u32_e32 vcc, s95, v98
	s_nop 1
	v_cndmask_b32_e32 v98, v199, v128, vcc
	v_cmp_nge_f32_e32 vcc, s9, v18
	s_cbranch_vccz .LBB0_338
; DI float ex2(float x) { return __builtin_amdgcn_exp2f(x); }
; DI float lg2(float x) { return __builtin_amdgcn_logf(x); }
; template <int MODE, int KS0, int NKS>
; DI void softmax_pv(const bf16x8 (&qf)[4], const u16* Ks, const u16* Vs, float& m, f32x16& ls, f32x16& o0, f32x16& o1,
;                    float sl2, int dl, bool need_mask, bool first, int r, int h, int rs, const int (&lo)[4]) {
;     ...
;   if (__any(first || !(ls[0] <= 1.0e12f))) {
;     float tmax = -INFINITY;
; #pragma unroll
;     for (int i = 0; i < 16; ++i) tmax = fmaxf(tmax, fmaxf(s0[i], s1[i]));
;     tmax = fmaxf(tmax, shx(tmax, r + 32 * h));
;     const float lref = (ls[0] > 1.f) ? lg2(ls[0]) : 0.f;
;     const float delta = first ? tmax : fmaxf(fmaxf(tmax, lref), 0.f);
;     m += delta;
;     const float alpha = ex2(-delta);
; #pragma unroll
;     for (int e = 0; e < 16; ++e) { o0[e] *= alpha; o1[e] *= alpha; ls[e] *= alpha; }
; #pragma unroll
;     for (int i = 0; i < 16; ++i) { s0[i] -= delta; s1[i] -= delta; }
;   }
	v_max_f32_e32 v109, v58, v58
	v_max_f32_e32 v110, v134, v134
	v_max_f32_e32 v109, v110, v109
	v_max_f32_e32 v110, v53, v53
	v_max_f32_e32 v111, v99, v99
	v_max_f32_e32 v110, v111, v110
	s_mov_b32 s2, 0xff800000
	v_max3_f32 v109, v109, s2, v110
	v_max_f32_e32 v110, v59, v59
	v_max_f32_e32 v111, v114, v114
	v_max_f32_e32 v110, v111, v110
	v_max_f32_e32 v111, v56, v56
	v_max_f32_e32 v112, v101, v101
	v_max_f32_e32 v111, v112, v111
	v_max3_f32 v109, v109, v110, v111
	v_max_f32_e32 v110, v60, v60
	v_max_f32_e32 v111, v116, v116
	v_max_f32_e32 v110, v111, v110
	v_max_f32_e32 v111, v57, v57
	v_max_f32_e32 v112, v115, v115
	v_max_f32_e32 v111, v112, v111
	v_max3_f32 v109, v109, v110, v111
	v_max_f32_e32 v110, v62, v62
	v_max_f32_e32 v111, v118, v118
	v_max_f32_e32 v110, v111, v110
	v_max_f32_e32 v111, v61, v61
	v_max_f32_e32 v112, v117, v117
	v_max_f32_e32 v111, v112, v111
	v_max3_f32 v109, v109, v110, v111
	v_max_f32_e32 v110, v52, v52
	v_max_f32_e32 v111, v104, v104
	v_max_f32_e32 v110, v111, v110
	v_max_f32_e32 v111, v51, v51
	v_max_f32_e32 v112, v100, v100
	v_max_f32_e32 v111, v112, v111
	v_max3_f32 v109, v109, v110, v111
	v_max_f32_e32 v110, v55, v55
	v_max_f32_e32 v111, v105, v105
	v_max_f32_e32 v110, v111, v110
	v_max_f32_e32 v111, v54, v54
	v_max_f32_e32 v112, v102, v102
	v_max_f32_e32 v111, v112, v111
	v_max3_f32 v109, v109, v110, v111
	v_max_f32_e32 v110, v64, v64
	v_max_f32_e32 v111, v106, v106
	v_max_f32_e32 v110, v111, v110
	v_max_f32_e32 v111, v63, v63
	v_max_f32_e32 v112, v103, v103
	v_max_f32_e32 v111, v112, v111
	v_max3_f32 v109, v109, v110, v111
	v_max_f32_e32 v110, v98, v98
	v_max_f32_e32 v111, v108, v108
	v_max_f32_e32 v110, v111, v110
	v_max_f32_e32 v111, v65, v65
	v_max_f32_e32 v112, v107, v107
	v_max_f32_e32 v111, v112, v111
	v_max3_f32 v109, v109, v110, v111
	ds_bpermute_b32 v110, v185, v109
	v_log_f32_e32 v111, v18
	v_cmp_lt_f32_e32 vcc, 1.0, v18
	s_waitcnt lgkmcnt(0)
	v_max_f32_e32 v110, v110, v110
	v_max_f32_e32 v109, v109, v110
	v_cndmask_b32_e32 v110, 0, v111, vcc
	v_max3_f32 v109, v109, v110, 0
	v_exp_f32_e64 v110, -v109
	v_sub_f32_e32 v134, v134, v109
	v_sub_f32_e32 v99, v99, v109
	v_sub_f32_e32 v114, v114, v109
	v_mul_f32_e32 v96, v96, v110
	v_mul_f32_e32 v97, v97, v110
	v_mul_f32_e32 v94, v94, v110
	v_mul_f32_e32 v95, v95, v110
	v_mul_f32_e32 v92, v92, v110
	v_mul_f32_e32 v93, v93, v110
	v_mul_f32_e32 v90, v90, v110
	v_mul_f32_e32 v91, v91, v110
	v_mul_f32_e32 v88, v88, v110
	v_mul_f32_e32 v89, v89, v110
	v_mul_f32_e32 v86, v86, v110
	v_mul_f32_e32 v87, v87, v110
	v_mul_f32_e32 v84, v84, v110
	v_mul_f32_e32 v85, v85, v110
	v_mul_f32_e32 v82, v82, v110
	v_mul_f32_e32 v83, v83, v110
	v_mul_f32_e32 v16, v16, v110
	v_mul_f32_e32 v17, v17, v110
	v_mul_f32_e32 v14, v14, v110
	v_mul_f32_e32 v15, v15, v110
	v_mul_f32_e32 v12, v12, v110
	v_mul_f32_e32 v13, v13, v110
	v_mul_f32_e32 v10, v10, v110
	v_mul_f32_e32 v11, v11, v110
	v_mul_f32_e32 v8, v8, v110
	v_mul_f32_e32 v9, v9, v110
	v_mul_f32_e32 v6, v6, v110
	v_mul_f32_e32 v7, v7, v110
	v_mul_f32_e32 v4, v4, v110
	v_mul_f32_e32 v5, v5, v110
	v_mul_f32_e32 v2, v2, v110
	v_mul_f32_e32 v3, v3, v110
	v_mul_f32_e32 v32, v32, v110
	v_mul_f32_e32 v33, v33, v110
	v_mul_f32_e32 v30, v30, v110
	v_mul_f32_e32 v31, v31, v110
	v_mul_f32_e32 v28, v28, v110
	v_mul_f32_e32 v29, v29, v110
	v_mul_f32_e32 v26, v26, v110
	v_mul_f32_e32 v27, v27, v110
	v_mul_f32_e32 v24, v24, v110
	v_mul_f32_e32 v25, v25, v110
	v_mul_f32_e32 v22, v22, v110
	v_mul_f32_e32 v23, v23, v110
	v_mul_f32_e32 v20, v20, v110
	v_mul_f32_e32 v21, v21, v110
	v_mul_f32_e32 v18, v18, v110
	v_mul_f32_e32 v19, v19, v110
	v_sub_f32_e32 v101, v101, v109
	v_sub_f32_e32 v116, v116, v109
	v_sub_f32_e32 v115, v115, v109
	v_sub_f32_e32 v118, v118, v109
	v_sub_f32_e32 v117, v117, v109
	v_sub_f32_e32 v104, v104, v109
	v_sub_f32_e32 v100, v100, v109
	v_sub_f32_e32 v105, v105, v109
	v_sub_f32_e32 v102, v102, v109
	v_sub_f32_e32 v106, v106, v109
	v_sub_f32_e32 v103, v103, v109
	v_sub_f32_e32 v108, v108, v109
	v_sub_f32_e32 v107, v107, v109
	v_sub_f32_e32 v58, v58, v109
	v_sub_f32_e32 v53, v53, v109
	v_sub_f32_e32 v59, v59, v109
	v_sub_f32_e32 v56, v56, v109
	v_sub_f32_e32 v60, v60, v109
	v_sub_f32_e32 v57, v57, v109
	v_sub_f32_e32 v62, v62, v109
	v_sub_f32_e32 v61, v61, v109
	v_sub_f32_e32 v52, v52, v109
	v_sub_f32_e32 v51, v51, v109
	v_sub_f32_e32 v55, v55, v109
	v_sub_f32_e32 v54, v54, v109
	v_sub_f32_e32 v64, v64, v109
	v_sub_f32_e32 v63, v63, v109
	v_sub_f32_e32 v98, v98, v109
	v_sub_f32_e32 v65, v65, v109

; DI float bflo(unsigned v) { return __uint_as_float(v << 16); }
; DI float bfhi(unsigned v) { return __uint_as_float(v & 0xffff0000u); }
; DI float silu(float g) { return g * __builtin_amdgcn_rcpf(1.f + ex2(-g * LOG2E)); }
; DI void store_y(const f32x16& oa, const f32x16& ob, float mult, const float* sg, const u32x2 (&gv)[8], u16* yrow0, float* stg,
;                 int lane, int r, int h) {
; #pragma unroll
;   for (int dt = 0; dt < 2; ++dt)
; #pragma unroll
;     for (int g = 0; g < 4; ++g) {
;       f32x4 v;
;       v[0] = (dt ? ob[4 * g] : oa[4 * g]) * mult; v[1] = (dt ? ob[4 * g + 1] : oa[4 * g + 1]) * mult;
;       v[2] = (dt ? ob[4 * g + 2] : oa[4 * g + 2]) * mult; v[3] = (dt ? ob[4 * g + 3] : oa[4 * g + 3]) * mult;
;       *(f32x4*)(stg + r * 68 + 32 * dt + 8 * g + 4 * h) = v;
;     }
;   const int kc = lane & 15;
;   f32x4 sv = {1.f, 1.f, 1.f, 1.f};
;   if (sg) sv = *(const f32x4*)(sg + kc * 4);
; #pragma unroll
;   for (int t = 0; t < 8; ++t) {
;     const int row = (lane >> 4) + 4 * t;
;     const f32x4 v = *(const f32x4*)(stg + row * 68 + kc * 4);
;     float y0 = v[0] * sv[0] * silu(bflo(gv[t][0]));
;     float y1 = v[1] * sv[1] * silu(bfhi(gv[t][0]));
;     float y2 = v[2] * sv[2] * silu(bflo(gv[t][1]));
;     float y3 = v[3] * sv[3] * silu(bfhi(gv[t][1]));
;     u32x2 yo = {pk2(y0, y1), pk2(y2, y3)};
;     *(u32x2*)(yrow0 + (size_t)row * DM + kc * 4) = yo;
;   }
; }
; DI void attn_item_B2(const Params& p, int layer, int b, int head0, int qblk, u16* sm, int wv) {
;     ...
;   __syncthreads();
; #pragma unroll
;   for (int hh = 0; hh < 2; ++hh)
;     store_y(o[hh][0], o[hh][1], 1.f / ls[hh][0], nullptr, gate[hh], p.y + ((size_t)b * SEQ + q0w) * DM + 256 + (head0 + hh) * 64,
;             (float*)sm + 9216 + w * 2176, lane, r, h);
.LBB0_339:
	s_or_b64 exec, exec, s[0:1]
	v_readlane_b32 s0, v250, 9
	v_readlane_b32 s1, v250, 10
	s_nop 8
	v_mul_u32_u24_e32 v22, 0x110, v205
	v_lshl_add_u64 v[20:21], v[182:183], 0, s[0:1]
	s_movk_i32 s0, 0x2200
	v_mul_lo_u32 v19, v204, s0
	v_add3_u32 v51, v19, v22, v0
	v_div_scale_f32 v22, s[0:1], v50, v50, 1.0
	v_rcp_f32_e32 v23, v22
	s_barrier
	v_lshlrev_b64 v[20:21], 11, v[20:21]
	v_fma_f32 v24, -v22, v23, 1.0
	v_fmac_f32_e32 v23, v24, v23
	v_div_scale_f32 v24, vcc, 1.0, v50, 1.0
	v_mul_f32_e32 v25, v24, v23
	v_fma_f32 v26, -v22, v25, v24
	v_fmac_f32_e32 v25, v26, v23
	v_fma_f32 v22, -v22, v25, v24
	v_div_fmas_f32 v22, v22, v23, v25
	v_div_fixup_f32 v26, v22, v50, 1.0
	v_mul_f32_e32 v22, v66, v26
	v_mul_f32_e32 v23, v67, v26
	v_mul_f32_e32 v24, v68, v26
	v_mul_f32_e32 v25, v69, v26
	ds_write_b128 v51, v[22:25] offset:36864
	v_mul_f32_e32 v22, v70, v26
	v_mul_f32_e32 v23, v71, v26
	v_mul_f32_e32 v24, v72, v26
	v_mul_f32_e32 v25, v73, v26
	ds_write_b128 v51, v[22:25] offset:36896
	v_mul_f32_e32 v22, v74, v26
	v_mul_f32_e32 v23, v75, v26
	v_mul_f32_e32 v24, v76, v26
	v_mul_f32_e32 v25, v77, v26
	ds_write_b128 v51, v[22:25] offset:36928
	v_mul_f32_e32 v22, v78, v26
	v_mul_f32_e32 v23, v79, v26
	v_mul_f32_e32 v24, v80, v26
	v_mul_f32_e32 v25, v81, v26
	ds_write_b128 v51, v[22:25] offset:36960
	v_mul_f32_e32 v22, v34, v26
	v_mul_f32_e32 v23, v35, v26
	v_mul_f32_e32 v24, v36, v26
	v_mul_f32_e32 v25, v37, v26
	ds_write_b128 v51, v[22:25] offset:36992
	v_mul_f32_e32 v22, v38, v26
	v_mul_f32_e32 v23, v39, v26
	v_mul_f32_e32 v24, v40, v26
	v_mul_f32_e32 v25, v41, v26
	ds_write_b128 v51, v[22:25] offset:37024
	v_mul_f32_e32 v22, v42, v26
	v_mul_f32_e32 v23, v43, v26
	v_mul_f32_e32 v24, v44, v26
	v_mul_f32_e32 v25, v45, v26
	v_lshl_add_u64 v[20:21], s[90:91], 0, v[20:21]
	ds_write_b128 v51, v[22:25] offset:37056
	v_mul_f32_e32 v22, v46, v26
	v_mul_f32_e32 v23, v47, v26
	v_mul_f32_e32 v24, v48, v26
	v_mul_f32_e32 v25, v49, v26
	v_lshlrev_b32_e32 v26, 16, v180
	v_lshl_add_u64 v[28:29], s[42:43], 1, v[20:21]
	ds_write_b128 v51, v[22:25] offset:37088
	v_mov_b32_e32 v159, v1
	v_and_b32_e32 v27, 0xffff0000, v180
	v_mul_f32_e32 v22, 0xbfb8aa3b, v26
	v_lshlrev_b32_e32 v30, 16, v181
	v_and_b32_e32 v31, 0xffff0000, v181
	v_lshl_add_u64 v[36:37], v[28:29], 0, v[158:159]
	v_exp_f32_e32 v28, v22
	v_mul_f32_e32 v22, 0xbfb8aa3b, v27
	v_mul_f32_e32 v32, 0xbfb8aa3b, v30
	v_mul_f32_e32 v33, 0xbfb8aa3b, v31
	v_exp_f32_e32 v29, v22
	v_exp_f32_e32 v32, v32
	v_exp_f32_e32 v33, v33
	v_lshl_or_b32 v0, v207, 2, v19
	s_movk_i32 s0, 0x110
	v_mad_u32_u24 v19, v206, s0, v0
	v_add_f32_e32 v28, 1.0, v28
	v_add_f32_e32 v29, 1.0, v29
	v_add_f32_e32 v32, 1.0, v32
	v_add_f32_e32 v33, 1.0, v33
	ds_read_b128 v[22:25], v19 offset:36864
	v_rcp_f32_e32 v28, v28
	v_rcp_f32_e32 v29, v29
	v_rcp_f32_e32 v32, v32
	v_rcp_f32_e32 v33, v33
	v_lshlrev_b32_e32 v0, 11, v206
	v_mul_f32_e32 v34, v28, v26
	v_mul_f32_e32 v35, v29, v27
	ds_read_b128 v[26:29], v19 offset:37952
	v_mul_f32_e32 v30, v32, v30
	v_mul_f32_e32 v31, v33, v31
	s_waitcnt lgkmcnt(1)
	v_mul_f32_e32 v22, v34, v22
	v_mul_f32_e32 v23, v35, v23
	v_mul_f32_e32 v24, v30, v24
	v_mul_f32_e32 v25, v31, v25
	v_cvt_pk_bf16_f32 v22, v22, v23
	v_cvt_pk_bf16_f32 v23, v24, v25
	v_lshlrev_b32_e32 v24, 16, v176
	v_and_b32_e32 v25, 0xffff0000, v176
	v_mul_f32_e32 v30, 0xbfb8aa3b, v24
	v_lshlrev_b32_e32 v34, 16, v177
	v_and_b32_e32 v35, 0xffff0000, v177
	v_exp_f32_e32 v32, v30
	v_mul_f32_e32 v30, 0xbfb8aa3b, v25
	v_mul_f32_e32 v38, 0xbfb8aa3b, v34
	v_mul_f32_e32 v39, 0xbfb8aa3b, v35
	v_exp_f32_e32 v33, v30
	v_exp_f32_e32 v38, v38
	v_exp_f32_e32 v39, v39
	v_add_f32_e32 v32, 1.0, v32
	v_add_f32_e32 v33, 1.0, v33
	v_add_f32_e32 v38, 1.0, v38
	v_add_f32_e32 v39, 1.0, v39
	v_rcp_f32_e32 v32, v32
	v_rcp_f32_e32 v33, v33
	v_rcp_f32_e32 v38, v38
	v_rcp_f32_e32 v39, v39
	v_lshl_add_u64 v[30:31], v[36:37], 0, v[0:1]
	global_store_dwordx2 v[30:31], v[22:23], off offset:512
	v_mul_f32_e32 v22, v32, v24
	v_mul_f32_e32 v23, v33, v25
	v_mul_f32_e32 v24, v38, v34
	v_mul_f32_e32 v25, v39, v35
	s_waitcnt lgkmcnt(0)
	v_mul_f32_e32 v22, v22, v26
	v_mul_f32_e32 v23, v23, v27
	v_mul_f32_e32 v24, v24, v28
	v_mul_f32_e32 v25, v25, v29
	v_cvt_pk_bf16_f32 v22, v22, v23
	v_cvt_pk_bf16_f32 v23, v24, v25
	v_or_b32_e32 v24, 0x2000, v0
	v_mov_b32_e32 v25, v1
	v_lshl_add_u64 v[26:27], v[36:37], 0, v[24:25]
	global_store_dwordx2 v[26:27], v[22:23], off offset:512
	v_lshlrev_b32_e32 v22, 16, v174
	v_and_b32_e32 v23, 0xffff0000, v174
	v_mul_f32_e32 v26, 0xbfb8aa3b, v22
	v_lshlrev_b32_e32 v34, 16, v175
	v_exp_f32_e32 v30, v26
	v_mul_f32_e32 v26, 0xbfb8aa3b, v23
	v_and_b32_e32 v35, 0xffff0000, v175
	v_mul_f32_e32 v32, 0xbfb8aa3b, v34
	v_exp_f32_e32 v31, v26
	v_exp_f32_e32 v32, v32
	v_mul_f32_e32 v33, 0xbfb8aa3b, v35
	v_exp_f32_e32 v33, v33
	v_add_f32_e32 v30, 1.0, v30
	v_add_f32_e32 v31, 1.0, v31
	v_add_f32_e32 v32, 1.0, v32
	ds_read_b128 v[26:29], v19 offset:39040
	v_rcp_f32_e32 v30, v30
	v_rcp_f32_e32 v31, v31
	v_rcp_f32_e32 v38, v32
	v_add_f32_e32 v32, 1.0, v33
	v_rcp_f32_e32 v39, v32
	v_mul_f32_e32 v22, v30, v22
	v_mul_f32_e32 v23, v31, v23
	v_lshlrev_b32_e32 v40, 16, v173
	s_waitcnt lgkmcnt(0)
; DI float bflo(unsigned v) { return __uint_as_float(v << 16); }
; DI float bfhi(unsigned v) { return __uint_as_float(v & 0xffff0000u); }
; DI float silu(float g) { return g * __builtin_amdgcn_rcpf(1.f + ex2(-g * LOG2E)); }
; DI void store_y(const f32x16& oa, const f32x16& ob, float mult, const float* sg, const u32x2 (&gv)[8], u16* yrow0, float* stg,
;                 int lane, int r, int h) {
;     ...
; #pragma unroll
;   for (int t = 0; t < 8; ++t) {
;     const int row = (lane >> 4) + 4 * t;
;     const f32x4 v = *(const f32x4*)(stg + row * 68 + kc * 4);
;     float y0 = v[0] * sv[0] * silu(bflo(gv[t][0]));
;     float y1 = v[1] * sv[1] * silu(bfhi(gv[t][0]));
;     float y2 = v[2] * sv[2] * silu(bflo(gv[t][1]));
;     float y3 = v[3] * sv[3] * silu(bfhi(gv[t][1]));
;     u32x2 yo = {pk2(y0, y1), pk2(y2, y3)};
;     *(u32x2*)(yrow0 + (size_t)row * DM + kc * 4) = yo;
;   }
	v_mul_f32_e32 v22, v22, v26
	v_mul_f32_e32 v23, v23, v27
	v_mul_f32_e32 v26, v38, v34
	v_mul_f32_e32 v27, v39, v35
	v_and_b32_e32 v41, 0xffff0000, v173
	v_mul_f32_e32 v26, v26, v28
	v_mul_f32_e32 v27, v27, v29
	v_mul_f32_e32 v42, 0xbfb8aa3b, v40
	v_cvt_pk_bf16_f32 v29, v26, v27
	v_lshlrev_b32_e32 v26, 16, v172
	v_and_b32_e32 v27, 0xffff0000, v172
	v_mul_f32_e32 v34, 0xbfb8aa3b, v26
	v_exp_f32_e32 v38, v34
	v_mul_f32_e32 v34, 0xbfb8aa3b, v27
	v_mul_f32_e32 v43, 0xbfb8aa3b, v41
	v_exp_f32_e32 v39, v34
	v_exp_f32_e32 v42, v42
	v_exp_f32_e32 v43, v43
	v_add_f32_e32 v38, 1.0, v38
	v_add_f32_e32 v39, 1.0, v39
	v_add_f32_e32 v42, 1.0, v42
	v_add_f32_e32 v43, 1.0, v43
	ds_read_b128 v[30:33], v19 offset:40128
	v_rcp_f32_e32 v38, v38
	v_rcp_f32_e32 v39, v39
	v_rcp_f32_e32 v42, v42
	v_rcp_f32_e32 v43, v43
	v_cvt_pk_bf16_f32 v28, v22, v23
	v_or_b32_e32 v22, 0x4000, v0
	v_mov_b32_e32 v23, v1
	v_lshl_add_u64 v[34:35], v[36:37], 0, v[22:23]
	global_store_dwordx2 v[34:35], v[28:29], off offset:512
	v_mul_f32_e32 v26, v38, v26
	v_mul_f32_e32 v27, v39, v27
	v_mul_f32_e32 v28, v42, v40
	v_mul_f32_e32 v29, v43, v41
	s_waitcnt lgkmcnt(0)
	v_mul_f32_e32 v26, v26, v30
	v_mul_f32_e32 v27, v27, v31
	v_mul_f32_e32 v28, v28, v32
	v_mul_f32_e32 v29, v29, v33
	v_cvt_pk_bf16_f32 v26, v26, v27
	v_cvt_pk_bf16_f32 v27, v28, v29
	v_or_b32_e32 v28, 0x6000, v0
	v_mov_b32_e32 v29, v1
	v_lshl_add_u64 v[30:31], v[36:37], 0, v[28:29]
	global_store_dwordx2 v[30:31], v[26:27], off offset:512
	v_lshlrev_b32_e32 v26, 16, v170
	v_and_b32_e32 v27, 0xffff0000, v170
	v_mul_f32_e32 v30, 0xbfb8aa3b, v26
	v_lshlrev_b32_e32 v42, 16, v171
	v_exp_f32_e32 v34, v30
	v_mul_f32_e32 v30, 0xbfb8aa3b, v27
	v_and_b32_e32 v43, 0xffff0000, v171
	v_mul_f32_e32 v38, 0xbfb8aa3b, v42
	v_exp_f32_e32 v35, v30
	v_exp_f32_e32 v38, v38
	v_mul_f32_e32 v39, 0xbfb8aa3b, v43
	v_exp_f32_e32 v39, v39
	v_add_f32_e32 v34, 1.0, v34
	v_add_f32_e32 v35, 1.0, v35
	v_add_f32_e32 v38, 1.0, v38
	ds_read_b128 v[30:33], v19 offset:41216
	v_rcp_f32_e32 v34, v34
	v_rcp_f32_e32 v35, v35
	v_rcp_f32_e32 v44, v38
	v_add_f32_e32 v38, 1.0, v39
	v_rcp_f32_e32 v45, v38
	v_mul_f32_e32 v26, v34, v26
	v_mul_f32_e32 v27, v35, v27
	ds_read_b128 v[38:41], v19 offset:42304
	s_waitcnt lgkmcnt(1)
	v_mul_f32_e32 v26, v26, v30
	v_mul_f32_e32 v27, v27, v31
	v_mul_f32_e32 v30, v44, v42
	v_mul_f32_e32 v31, v45, v43
	v_lshlrev_b32_e32 v44, 16, v169
	v_mul_f32_e32 v30, v30, v32
	v_mul_f32_e32 v31, v31, v33
	v_and_b32_e32 v45, 0xffff0000, v169
	v_cvt_pk_bf16_f32 v33, v30, v31
	v_lshlrev_b32_e32 v30, 16, v168
	v_and_b32_e32 v31, 0xffff0000, v168
	v_mul_f32_e32 v34, 0xbfb8aa3b, v30
	v_exp_f32_e32 v42, v34
	v_mul_f32_e32 v34, 0xbfb8aa3b, v31
	v_mul_f32_e32 v46, 0xbfb8aa3b, v44
	v_mul_f32_e32 v47, 0xbfb8aa3b, v45
	v_exp_f32_e32 v43, v34
	v_exp_f32_e32 v46, v46
	v_exp_f32_e32 v47, v47
	v_add_f32_e32 v42, 1.0, v42
	v_add_f32_e32 v43, 1.0, v43
	v_add_f32_e32 v46, 1.0, v46
	v_add_f32_e32 v47, 1.0, v47
	v_rcp_f32_e32 v42, v42
	v_rcp_f32_e32 v43, v43
	v_rcp_f32_e32 v46, v46
	v_rcp_f32_e32 v47, v47
	v_cvt_pk_bf16_f32 v32, v26, v27
	v_or_b32_e32 v26, 0x8000, v0
	v_mov_b32_e32 v27, v1
	v_lshl_add_u64 v[34:35], v[36:37], 0, v[26:27]
	global_store_dwordx2 v[34:35], v[32:33], off offset:512
	v_mul_f32_e32 v30, v42, v30
	v_mul_f32_e32 v31, v43, v31
	v_mul_f32_e32 v32, v46, v44
	v_mul_f32_e32 v33, v47, v45
	s_waitcnt lgkmcnt(0)
	v_mul_f32_e32 v30, v30, v38
	v_mul_f32_e32 v31, v31, v39
	v_mul_f32_e32 v32, v32, v40
	v_mul_f32_e32 v33, v33, v41
	v_cvt_pk_bf16_f32 v30, v30, v31
	v_cvt_pk_bf16_f32 v31, v32, v33
	v_or_b32_e32 v32, 0xa000, v0
	v_mov_b32_e32 v33, v1
	v_lshl_add_u64 v[34:35], v[36:37], 0, v[32:33]
	v_lshlrev_b32_e32 v46, 16, v167
	global_store_dwordx2 v[34:35], v[30:31], off offset:512
	v_lshlrev_b32_e32 v30, 16, v166
	v_and_b32_e32 v31, 0xffff0000, v166
	v_and_b32_e32 v47, 0xffff0000, v167
	v_mul_f32_e32 v42, 0xbfb8aa3b, v46
	v_mul_f32_e32 v34, 0xbfb8aa3b, v30
	v_mul_f32_e32 v35, 0xbfb8aa3b, v31
	v_exp_f32_e32 v42, v42
	v_mul_f32_e32 v43, 0xbfb8aa3b, v47
	v_exp_f32_e32 v34, v34
	v_exp_f32_e32 v35, v35
	v_exp_f32_e32 v43, v43
	v_add_f32_e32 v42, 1.0, v42
	v_add_f32_e32 v34, 1.0, v34
	v_add_f32_e32 v35, 1.0, v35
	v_rcp_f32_e32 v48, v42
	v_add_f32_e32 v42, 1.0, v43
	v_rcp_f32_e32 v34, v34
	v_rcp_f32_e32 v35, v35
	v_rcp_f32_e32 v49, v42
	ds_read_b128 v[38:41], v19 offset:43392
	ds_read_b128 v[42:45], v19 offset:44480
	v_mul_f32_e32 v30, v34, v30
	v_mul_f32_e32 v31, v35, v31
	v_mul_f32_e32 v34, v48, v46
	v_mul_f32_e32 v35, v49, v47
	v_lshlrev_b32_e32 v48, 16, v165
	v_and_b32_e32 v49, 0xffff0000, v165
	v_mul_f32_e32 v50, 0xbfb8aa3b, v48
	s_waitcnt lgkmcnt(1)
	v_mul_f32_e32 v34, v34, v40
	v_mul_f32_e32 v35, v35, v41
	v_exp_f32_e32 v50, v50
	v_mul_f32_e32 v52, 0xbfb8aa3b, v49
	v_mul_f32_e32 v30, v30, v38
	v_mul_f32_e32 v31, v31, v39
	v_cvt_pk_bf16_f32 v39, v34, v35
	v_lshlrev_b32_e32 v34, 16, v164
	v_exp_f32_e32 v53, v52
	v_and_b32_e32 v35, 0xffff0000, v164
	v_mul_f32_e32 v40, 0xbfb8aa3b, v34
	v_exp_f32_e32 v46, v40
	v_mul_f32_e32 v40, 0xbfb8aa3b, v35
	v_exp_f32_e32 v47, v40
	v_add_f32_e32 v50, 1.0, v50
	v_rcp_f32_e32 v52, v50
	v_add_f32_e32 v50, 1.0, v53
	v_rcp_f32_e32 v53, v50
	v_cvt_pk_bf16_f32 v38, v30, v31
	v_or_b32_e32 v30, 0xc000, v0
	v_mov_b32_e32 v31, v1
	v_add_f32_e32 v46, 1.0, v46
	v_add_f32_e32 v47, 1.0, v47
	v_lshl_add_u64 v[40:41], v[36:37], 0, v[30:31]
	v_rcp_f32_e32 v46, v46
	v_rcp_f32_e32 v47, v47
	global_store_dwordx2 v[40:41], v[38:39], off offset:512
	v_mul_f32_e32 v38, v52, v48
	v_mul_f32_e32 v39, v53, v49
	v_lshl_add_u64 v[20:21], s[40:41], 1, v[20:21]
	s_waitcnt lgkmcnt(0)
; DI float bflo(unsigned v) { return __uint_as_float(v << 16); }
; DI float bfhi(unsigned v) { return __uint_as_float(v & 0xffff0000u); }
; DI float silu(float g) { return g * __builtin_amdgcn_rcpf(1.f + ex2(-g * LOG2E)); }
; DI void store_y(const f32x16& oa, const f32x16& ob, float mult, const float* sg, const u32x2 (&gv)[8], u16* yrow0, float* stg,
;                 int lane, int r, int h) {
; #pragma unroll
;   for (int dt = 0; dt < 2; ++dt)
; #pragma unroll
;     for (int g = 0; g < 4; ++g) {
;       f32x4 v;
;       v[0] = (dt ? ob[4 * g] : oa[4 * g]) * mult; v[1] = (dt ? ob[4 * g + 1] : oa[4 * g + 1]) * mult;
;       v[2] = (dt ? ob[4 * g + 2] : oa[4 * g + 2]) * mult; v[3] = (dt ? ob[4 * g + 3] : oa[4 * g + 3]) * mult;
;       *(f32x4*)(stg + r * 68 + 32 * dt + 8 * g + 4 * h) = v;
;     }
;   const int kc = lane & 15;
;   f32x4 sv = {1.f, 1.f, 1.f, 1.f};
;   if (sg) sv = *(const f32x4*)(sg + kc * 4);
; #pragma unroll
;   for (int t = 0; t < 8; ++t) {
;     const int row = (lane >> 4) + 4 * t;
;     const f32x4 v = *(const f32x4*)(stg + row * 68 + kc * 4);
;     float y0 = v[0] * sv[0] * silu(bflo(gv[t][0]));
;     float y1 = v[1] * sv[1] * silu(bfhi(gv[t][0]));
;     float y2 = v[2] * sv[2] * silu(bflo(gv[t][1]));
;     float y3 = v[3] * sv[3] * silu(bfhi(gv[t][1]));
;     u32x2 yo = {pk2(y0, y1), pk2(y2, y3)};
;     *(u32x2*)(yrow0 + (size_t)row * DM + kc * 4) = yo;
;   }
; DI void attn_item_B2(const Params& p, int layer, int b, int head0, int qblk, u16* sm, int wv) {
;     ...
;   __syncthreads();
; #pragma unroll
;   for (int hh = 0; hh < 2; ++hh)
;     store_y(o[hh][0], o[hh][1], 1.f / ls[hh][0], nullptr, gate[hh], p.y + ((size_t)b * SEQ + q0w) * DM + 256 + (head0 + hh) * 64,
;             (float*)sm + 9216 + w * 2176, lane, r, h);
	v_mul_f32_e32 v38, v38, v44
	v_mul_f32_e32 v39, v39, v45
	v_mul_f32_e32 v34, v46, v34
	v_mul_f32_e32 v35, v47, v35
	v_cvt_pk_bf16_f32 v41, v38, v39
	v_div_scale_f32 v38, s[0:1], v18, v18, 1.0
	v_rcp_f32_e32 v39, v38
	v_mul_f32_e32 v34, v34, v42
	v_mul_f32_e32 v35, v35, v43
	v_readlane_b32 s41, v250, 28
	v_cvt_pk_bf16_f32 v40, v34, v35
	v_or_b32_e32 v34, 0xe000, v0
	v_mov_b32_e32 v35, v1
	v_lshl_add_u64 v[36:37], v[36:37], 0, v[34:35]
	global_store_dwordx2 v[36:37], v[40:41], off offset:512
	v_fma_f32 v36, -v38, v39, 1.0
	v_fmac_f32_e32 v39, v36, v39
	v_div_scale_f32 v36, vcc, 1.0, v18, 1.0
	v_mul_f32_e32 v37, v36, v39
	v_fma_f32 v40, -v38, v37, v36
	v_fmac_f32_e32 v37, v40, v39
	v_fma_f32 v36, -v38, v37, v36
	v_div_fmas_f32 v36, v36, v39, v37
	v_div_fixup_f32 v18, v36, v18, 1.0
	v_mul_f32_e32 v2, v2, v18
	v_mul_f32_e32 v3, v3, v18
	v_mul_f32_e32 v4, v4, v18
	v_mul_f32_e32 v5, v5, v18
	ds_write_b128 v51, v[2:5] offset:36992
	v_mul_f32_e32 v2, v6, v18
	v_mul_f32_e32 v3, v7, v18
	v_mul_f32_e32 v4, v8, v18
	v_mul_f32_e32 v5, v9, v18
	ds_write_b128 v51, v[2:5] offset:37024
	v_mul_f32_e32 v2, v10, v18
	v_mul_f32_e32 v3, v11, v18
	v_mul_f32_e32 v4, v12, v18
	v_mul_f32_e32 v5, v13, v18
	ds_write_b128 v51, v[2:5] offset:37056
	v_mul_f32_e32 v2, v14, v18
	v_mul_f32_e32 v3, v15, v18
	v_mul_f32_e32 v4, v16, v18
	v_mul_f32_e32 v5, v17, v18
	v_lshlrev_b32_e32 v8, 16, v162
	ds_write_b128 v51, v[2:5] offset:37088
	v_and_b32_e32 v9, 0xffff0000, v162
	v_mul_f32_e32 v4, 0xbfb8aa3b, v8
	v_lshlrev_b32_e32 v12, 16, v163
	v_and_b32_e32 v13, 0xffff0000, v163
	v_exp_f32_e32 v10, v4
	v_mul_f32_e32 v4, 0xbfb8aa3b, v9
	v_mul_f32_e32 v14, 0xbfb8aa3b, v12
	v_mul_f32_e32 v15, 0xbfb8aa3b, v13
	v_mul_f32_e32 v36, v82, v18
	v_mul_f32_e32 v37, v83, v18
	v_mul_f32_e32 v38, v84, v18
	v_mul_f32_e32 v39, v85, v18
	v_exp_f32_e32 v11, v4
	v_exp_f32_e32 v14, v14
	v_exp_f32_e32 v15, v15
	ds_write_b128 v51, v[36:39] offset:36864
	v_mul_f32_e32 v36, v86, v18
	v_mul_f32_e32 v37, v87, v18
	v_mul_f32_e32 v38, v88, v18
	v_mul_f32_e32 v39, v89, v18
	ds_write_b128 v51, v[36:39] offset:36896
	v_mul_f32_e32 v36, v90, v18
	v_mul_f32_e32 v37, v91, v18
	v_mul_f32_e32 v38, v92, v18
	v_mul_f32_e32 v39, v93, v18
	ds_write_b128 v51, v[36:39] offset:36928
	v_mul_f32_e32 v36, v94, v18
	v_mul_f32_e32 v37, v95, v18
	v_mul_f32_e32 v38, v96, v18
	v_mul_f32_e32 v39, v97, v18
	ds_write_b128 v51, v[36:39] offset:36960
	v_add_f32_e32 v10, 1.0, v10
	v_add_f32_e32 v11, 1.0, v11
	v_add_f32_e32 v14, 1.0, v14
	v_add_f32_e32 v15, 1.0, v15
	ds_read_b128 v[4:7], v19 offset:36864
	v_rcp_f32_e32 v10, v10
	v_rcp_f32_e32 v11, v11
	v_rcp_f32_e32 v14, v14
	v_rcp_f32_e32 v15, v15
	v_lshl_add_u64 v[2:3], v[20:21], 0, v[158:159]
	v_mul_f32_e32 v16, v10, v8
	v_mul_f32_e32 v17, v11, v9
	ds_read_b128 v[8:11], v19 offset:37952
	v_mul_f32_e32 v12, v14, v12
	v_mul_f32_e32 v13, v15, v13
	s_waitcnt lgkmcnt(1)
	v_mul_f32_e32 v4, v16, v4
	v_mul_f32_e32 v5, v17, v5
	v_mul_f32_e32 v6, v12, v6
	v_mul_f32_e32 v7, v13, v7
	v_cvt_pk_bf16_f32 v4, v4, v5
	v_cvt_pk_bf16_f32 v5, v6, v7
	v_lshlrev_b32_e32 v6, 16, v160
	v_and_b32_e32 v7, 0xffff0000, v160
	v_mul_f32_e32 v12, 0xbfb8aa3b, v6
	v_exp_f32_e32 v14, v12
	v_mul_f32_e32 v12, 0xbfb8aa3b, v7
	v_exp_f32_e32 v15, v12
	v_lshl_add_u64 v[12:13], v[2:3], 0, v[0:1]
	v_add_f32_e32 v0, 1.0, v14
	v_lshlrev_b32_e32 v16, 16, v161
	v_rcp_f32_e32 v14, v0
	v_add_f32_e32 v0, 1.0, v15
	v_and_b32_e32 v17, 0xffff0000, v161
	v_mul_f32_e32 v15, 0xbfb8aa3b, v16
	v_exp_f32_e32 v18, v15
	v_mul_f32_e32 v15, 0xbfb8aa3b, v17
	v_exp_f32_e32 v21, v15
	v_rcp_f32_e32 v15, v0
	v_add_f32_e32 v0, 1.0, v18
	v_rcp_f32_e32 v20, v0
	v_add_f32_e32 v0, 1.0, v21
	v_rcp_f32_e32 v21, v0
	global_store_dwordx2 v[12:13], v[4:5], off offset:512
	v_mul_f32_e32 v4, v14, v6
	v_mul_f32_e32 v5, v15, v7
	v_lshlrev_b32_e32 v12, 16, v157
	v_mul_f32_e32 v6, v20, v16
	v_mul_f32_e32 v7, v21, v17
	s_waitcnt lgkmcnt(0)
	v_mul_f32_e32 v4, v4, v8
	v_mul_f32_e32 v5, v5, v9
	v_mul_f32_e32 v6, v6, v10
	v_mul_f32_e32 v7, v7, v11
	v_lshlrev_b32_e32 v8, 16, v156
	v_cvt_pk_bf16_f32 v4, v4, v5
	v_cvt_pk_bf16_f32 v5, v6, v7
	v_lshl_add_u64 v[6:7], v[2:3], 0, v[24:25]
	v_and_b32_e32 v9, 0xffff0000, v156
	v_mul_f32_e32 v0, 0xbfb8aa3b, v8
	global_store_dwordx2 v[6:7], v[4:5], off offset:512
	v_exp_f32_e32 v0, v0
	v_mul_f32_e32 v4, 0xbfb8aa3b, v9
	v_exp_f32_e32 v11, v4
	v_and_b32_e32 v13, 0xffff0000, v157
	v_add_f32_e32 v0, 1.0, v0
	v_rcp_f32_e32 v10, v0
	v_add_f32_e32 v0, 1.0, v11
	v_mul_f32_e32 v11, 0xbfb8aa3b, v12
	v_exp_f32_e32 v14, v11
	v_mul_f32_e32 v11, 0xbfb8aa3b, v13
	v_exp_f32_e32 v15, v11
	v_rcp_f32_e32 v11, v0
	v_add_f32_e32 v0, 1.0, v14
	v_rcp_f32_e32 v14, v0
	v_add_f32_e32 v0, 1.0, v15
	ds_read_b128 v[4:7], v19 offset:39040
	v_rcp_f32_e32 v15, v0
	v_mul_f32_e32 v16, v10, v8
	v_mul_f32_e32 v17, v11, v9
	ds_read_b128 v[8:11], v19 offset:40128
	v_mul_f32_e32 v12, v14, v12
	v_mul_f32_e32 v13, v15, v13
	s_waitcnt lgkmcnt(1)
; DI float bflo(unsigned v) { return __uint_as_float(v << 16); }
; DI float bfhi(unsigned v) { return __uint_as_float(v & 0xffff0000u); }
; DI float silu(float g) { return g * __builtin_amdgcn_rcpf(1.f + ex2(-g * LOG2E)); }
; DI void store_y(const f32x16& oa, const f32x16& ob, float mult, const float* sg, const u32x2 (&gv)[8], u16* yrow0, float* stg,
;                 int lane, int r, int h) {
;     ...
; #pragma unroll
;   for (int t = 0; t < 8; ++t) {
;     const int row = (lane >> 4) + 4 * t;
;     const f32x4 v = *(const f32x4*)(stg + row * 68 + kc * 4);
;     float y0 = v[0] * sv[0] * silu(bflo(gv[t][0]));
;     float y1 = v[1] * sv[1] * silu(bfhi(gv[t][0]));
;     float y2 = v[2] * sv[2] * silu(bflo(gv[t][1]));
;     float y3 = v[3] * sv[3] * silu(bfhi(gv[t][1]));
;     u32x2 yo = {pk2(y0, y1), pk2(y2, y3)};
;     *(u32x2*)(yrow0 + (size_t)row * DM + kc * 4) = yo;
;   }
	v_mul_f32_e32 v4, v16, v4
	v_mul_f32_e32 v5, v17, v5
	v_mul_f32_e32 v6, v12, v6
	v_mul_f32_e32 v7, v13, v7
	v_cvt_pk_bf16_f32 v4, v4, v5
	v_cvt_pk_bf16_f32 v5, v6, v7
	v_lshlrev_b32_e32 v6, 16, v154
	v_and_b32_e32 v7, 0xffff0000, v154
	v_mul_f32_e32 v0, 0xbfb8aa3b, v6
	v_exp_f32_e32 v0, v0
	v_mul_f32_e32 v12, 0xbfb8aa3b, v7
	v_exp_f32_e32 v15, v12
	v_lshlrev_b32_e32 v16, 16, v155
	v_add_f32_e32 v0, 1.0, v0
	v_rcp_f32_e32 v14, v0
	v_add_f32_e32 v0, 1.0, v15
	v_and_b32_e32 v17, 0xffff0000, v155
	v_mul_f32_e32 v15, 0xbfb8aa3b, v16
	v_exp_f32_e32 v18, v15
	v_mul_f32_e32 v15, 0xbfb8aa3b, v17
	v_exp_f32_e32 v21, v15
	v_rcp_f32_e32 v15, v0
	v_add_f32_e32 v0, 1.0, v18
	v_rcp_f32_e32 v20, v0
	v_add_f32_e32 v0, 1.0, v21
	v_rcp_f32_e32 v21, v0
	v_lshl_add_u64 v[12:13], v[2:3], 0, v[22:23]
	global_store_dwordx2 v[12:13], v[4:5], off offset:512
	v_mul_f32_e32 v4, v14, v6
	v_mul_f32_e32 v5, v15, v7
	v_mul_f32_e32 v6, v20, v16
	v_mul_f32_e32 v7, v21, v17
	s_waitcnt lgkmcnt(0)
	v_mul_f32_e32 v4, v4, v8
	v_mul_f32_e32 v5, v5, v9
	v_mul_f32_e32 v6, v6, v10
	v_mul_f32_e32 v7, v7, v11
	v_lshlrev_b32_e32 v8, 16, v152
	v_cvt_pk_bf16_f32 v4, v4, v5
	v_cvt_pk_bf16_f32 v5, v6, v7
	v_lshl_add_u64 v[6:7], v[2:3], 0, v[28:29]
	v_and_b32_e32 v9, 0xffff0000, v152
	v_mul_f32_e32 v0, 0xbfb8aa3b, v8
	global_store_dwordx2 v[6:7], v[4:5], off offset:512
	v_exp_f32_e32 v0, v0
	v_mul_f32_e32 v4, 0xbfb8aa3b, v9
	v_exp_f32_e32 v11, v4
	v_lshlrev_b32_e32 v12, 16, v153
	v_add_f32_e32 v0, 1.0, v0
	v_rcp_f32_e32 v10, v0
	v_add_f32_e32 v0, 1.0, v11
	v_and_b32_e32 v13, 0xffff0000, v153
	v_mul_f32_e32 v11, 0xbfb8aa3b, v12
	v_exp_f32_e32 v14, v11
	v_mul_f32_e32 v11, 0xbfb8aa3b, v13
	v_exp_f32_e32 v15, v11
	v_rcp_f32_e32 v11, v0
	v_add_f32_e32 v0, 1.0, v14
	v_rcp_f32_e32 v14, v0
	v_add_f32_e32 v0, 1.0, v15
	ds_read_b128 v[4:7], v19 offset:41216
	v_rcp_f32_e32 v15, v0
	v_mul_f32_e32 v16, v10, v8
	v_mul_f32_e32 v17, v11, v9
	ds_read_b128 v[8:11], v19 offset:42304
	v_mul_f32_e32 v12, v14, v12
	v_mul_f32_e32 v13, v15, v13
	s_waitcnt lgkmcnt(1)
	v_mul_f32_e32 v4, v16, v4
	v_mul_f32_e32 v5, v17, v5
	v_mul_f32_e32 v6, v12, v6
	v_mul_f32_e32 v7, v13, v7
	v_cvt_pk_bf16_f32 v4, v4, v5
	v_cvt_pk_bf16_f32 v5, v6, v7
	v_lshlrev_b32_e32 v6, 16, v150
	v_and_b32_e32 v7, 0xffff0000, v150
	v_mul_f32_e32 v0, 0xbfb8aa3b, v6
	v_exp_f32_e32 v0, v0
	v_mul_f32_e32 v12, 0xbfb8aa3b, v7
	v_exp_f32_e32 v15, v12
	v_lshlrev_b32_e32 v16, 16, v151
	v_add_f32_e32 v0, 1.0, v0
	v_rcp_f32_e32 v14, v0
	v_add_f32_e32 v0, 1.0, v15
	v_and_b32_e32 v17, 0xffff0000, v151
	v_mul_f32_e32 v15, 0xbfb8aa3b, v16
	v_exp_f32_e32 v18, v15
	v_mul_f32_e32 v15, 0xbfb8aa3b, v17
	v_exp_f32_e32 v21, v15
	v_rcp_f32_e32 v15, v0
	v_add_f32_e32 v0, 1.0, v18
	v_rcp_f32_e32 v20, v0
	v_add_f32_e32 v0, 1.0, v21
	v_rcp_f32_e32 v21, v0
	v_lshl_add_u64 v[12:13], v[2:3], 0, v[26:27]
	global_store_dwordx2 v[12:13], v[4:5], off offset:512
	v_mul_f32_e32 v4, v14, v6
	v_mul_f32_e32 v5, v15, v7
	v_mul_f32_e32 v6, v20, v16
	v_mul_f32_e32 v7, v21, v17
	s_waitcnt lgkmcnt(0)
	v_mul_f32_e32 v4, v4, v8
	v_mul_f32_e32 v5, v5, v9
	v_mul_f32_e32 v6, v6, v10
	v_mul_f32_e32 v7, v7, v11
	v_lshlrev_b32_e32 v8, 16, v148
	v_cvt_pk_bf16_f32 v4, v4, v5
	v_cvt_pk_bf16_f32 v5, v6, v7
	v_lshl_add_u64 v[6:7], v[2:3], 0, v[32:33]
	v_and_b32_e32 v9, 0xffff0000, v148
	v_mul_f32_e32 v0, 0xbfb8aa3b, v8
	global_store_dwordx2 v[6:7], v[4:5], off offset:512
	v_exp_f32_e32 v0, v0
	v_mul_f32_e32 v4, 0xbfb8aa3b, v9
	v_exp_f32_e32 v11, v4
	v_lshlrev_b32_e32 v12, 16, v149
	v_add_f32_e32 v0, 1.0, v0
	v_rcp_f32_e32 v10, v0
	v_add_f32_e32 v0, 1.0, v11
	v_and_b32_e32 v13, 0xffff0000, v149
	v_mul_f32_e32 v11, 0xbfb8aa3b, v12
	v_exp_f32_e32 v14, v11
	v_mul_f32_e32 v11, 0xbfb8aa3b, v13
	v_exp_f32_e32 v15, v11
	v_rcp_f32_e32 v11, v0
	v_add_f32_e32 v0, 1.0, v14
	v_rcp_f32_e32 v14, v0
	v_add_f32_e32 v0, 1.0, v15
	ds_read_b128 v[4:7], v19 offset:43392
	v_rcp_f32_e32 v15, v0
	v_mul_f32_e32 v16, v10, v8
	v_mul_f32_e32 v17, v11, v9
	ds_read_b128 v[8:11], v19 offset:44480
	v_mul_f32_e32 v12, v14, v12
	v_mul_f32_e32 v13, v15, v13
	s_waitcnt lgkmcnt(1)
	v_mul_f32_e32 v4, v16, v4
	v_mul_f32_e32 v5, v17, v5
	v_mul_f32_e32 v6, v12, v6
	v_mul_f32_e32 v7, v13, v7
	v_cvt_pk_bf16_f32 v4, v4, v5
	v_cvt_pk_bf16_f32 v5, v6, v7
	v_lshlrev_b32_e32 v6, 16, v146
	v_and_b32_e32 v7, 0xffff0000, v146
	v_mul_f32_e32 v0, 0xbfb8aa3b, v6
	v_exp_f32_e32 v0, v0
	v_mul_f32_e32 v12, 0xbfb8aa3b, v7
	v_exp_f32_e32 v15, v12
	v_lshlrev_b32_e32 v16, 16, v147
	v_add_f32_e32 v0, 1.0, v0
	v_rcp_f32_e32 v14, v0
	v_add_f32_e32 v0, 1.0, v15
	v_and_b32_e32 v17, 0xffff0000, v147
	v_mul_f32_e32 v15, 0xbfb8aa3b, v16
	v_exp_f32_e32 v18, v15
	v_mul_f32_e32 v15, 0xbfb8aa3b, v17
	v_exp_f32_e32 v19, v15
	v_rcp_f32_e32 v15, v0
	v_add_f32_e32 v0, 1.0, v18
	v_rcp_f32_e32 v18, v0
	v_add_f32_e32 v0, 1.0, v19
	v_rcp_f32_e32 v19, v0
	v_lshl_add_u64 v[12:13], v[2:3], 0, v[30:31]
	global_store_dwordx2 v[12:13], v[4:5], off offset:512
	v_mul_f32_e32 v4, v14, v6
	v_mul_f32_e32 v5, v15, v7
	v_mul_f32_e32 v6, v18, v16
	v_mul_f32_e32 v7, v19, v17
	s_waitcnt lgkmcnt(0)
	v_mul_f32_e32 v4, v4, v8
	v_mul_f32_e32 v5, v5, v9
	v_mul_f32_e32 v6, v6, v10
	v_mul_f32_e32 v7, v7, v11
	v_cvt_pk_bf16_f32 v4, v4, v5
	v_cvt_pk_bf16_f32 v5, v6, v7
	v_lshl_add_u64 v[2:3], v[2:3], 0, v[34:35]
	global_store_dwordx2 v[2:3], v[4:5], off offset:512
	s_or_b64 exec, exec, s[38:39]
	s_andn2_saveexec_b64 s[0:1], s[64:65]
	s_cbranch_execz .LBB0_196
	s_branch .LBB0_254

; DI float bflo(unsigned v) { return __uint_as_float(v << 16); }
; DI float bfhi(unsigned v) { return __uint_as_float(v & 0xffff0000u); }
; template <int EPI>
; DI void gemm_tile(const Params& p, int layer, int mt, int nt, u16* sm, int wv) {
;     ...
;     __syncthreads();
;     float* stg = (float*)(sm + (wm * 2 + wn) * (128 * LSTR));
;     const int kc = lane & 15;
; #pragma unroll
;     for (int hh = 0; hh < 2; ++hh) {
; #pragma unroll
;       for (int i2 = 0; i2 < 4; ++i2)
; #pragma unroll
;         for (int j = 0; j < 4; ++j)
;           *(f32x4*)(stg + (16 * i2 + fr) * 68 + 16 * j + 4 * fq) = acc[4 * hh + i2][j];
;       const size_t mrow0 = (size_t)(m0 + wm * 128 + 64 * hh);
;       u16* xrow = p.xg + mrow0 * DM + n0 + wn * 64 + kc * 4;
;       u16* x2row = (u16*)p.x2 + mrow0 * DM + n0 + wn * 64 + kc * 4;
;       u32x2 xb[16];
; #pragma unroll
;       for (int t = 0; t < 16; ++t) xb[t] = __builtin_nontemporal_load((const u32x2*)(xrow + (size_t)((lane >> 4) + 4 * t) * DM));
; #pragma unroll
;       for (int t = 0; t < 16; ++t) {
;         const int row = (lane >> 4) + 4 * t;
;         const f32x4 a4 = *(const f32x4*)(stg + row * 68 + kc * 4);
;         const float v0 = bflo(xb[t][0]) + a4[0], v1 = bfhi(xb[t][0]) + a4[1], v2 = bflo(xb[t][1]) + a4[2], v3 = bfhi(xb[t][1]) + a4[3];
;         float sq = v0 * v0 + v1 * v1 + v2 * v2 + v3 * v3;
;         u32x2 pv = {pk2(v0, v1), pk2(v2, v3)};
;         if (has_next) *(u32x2*)(xrow + (size_t)row * DM) = pv;
;         else *(u32x2*)(x2row + (size_t)row * DM) = pv;
.LBB0_399:
	v_mbcnt_lo_u32_b32 v185, -1, 0
	v_mbcnt_hi_u32_b32 v185, -1, v185
	s_lshl_b64 s[2:3], s[2:3], 1
	v_add_u32_e32 v0, s33, v185
	v_bfe_u32 v181, v0, 6, 1
	s_waitcnt vmcnt(9)
	v_bfe_u32 v66, v0, 6, 21
	v_and_b32_e32 v0, 0xffffff80, v0
	v_lshl_add_u32 v68, s4, 8, v0
	v_and_b32_e32 v180, 15, v185
	v_mul_u32_u24_e32 v66, 0x4800, v66
	v_ashrrev_i32_e32 v69, 31, v68
	v_and_or_b32 v182, v185, 48, v66
	v_lshl_or_b32 v184, v180, 4, v66
	s_movk_i32 s4, 0x110
	v_lshlrev_b64 v[66:67], 11, v[68:69]
	v_mad_u32_u24 v0, v180, s4, v182
	s_waitcnt vmcnt(7)
	v_lshl_add_u64 v[70:71], s[60:61], 0, v[66:67]
	s_barrier
	ds_write_b128 v0, v[174:177]
	ds_write_b128 v0, v[170:173] offset:64
	ds_write_b128 v0, v[166:169] offset:128
	ds_write_b128 v0, v[162:165] offset:192
	ds_write_b128 v0, v[158:161] offset:4352
	ds_write_b128 v0, v[154:157] offset:4416
	ds_write_b128 v0, v[150:153] offset:4480
	ds_write_b128 v0, v[146:149] offset:4544
	ds_write_b128 v0, v[142:145] offset:8704
	ds_write_b128 v0, v[138:141] offset:8768
	ds_write_b128 v0, v[134:137] offset:8832
	ds_write_b128 v0, v[130:133] offset:8896
	ds_write_b128 v0, v[126:129] offset:13056
	ds_write_b128 v0, v[122:125] offset:13120
	ds_write_b128 v0, v[118:121] offset:13184
	ds_write_b128 v0, v[114:117] offset:13248
	v_lshl_add_u64 v[70:71], v[70:71], 0, s[2:3]
	v_lshlrev_b32_e32 v0, 7, v181
	v_lshl_add_u64 v[66:67], s[82:83], 0, v[66:67]
	v_bfe_u32 v183, v185, 4, 2
	v_lshl_add_u64 v[70:71], v[70:71], 0, v[0:1]
	s_waitcnt vmcnt(1)
	v_lshlrev_b32_e32 v104, 3, v180
	v_mov_b32_e32 v105, v1
	v_lshl_add_u64 v[66:67], v[66:67], 0, s[2:3]
	v_lshlrev_b32_e32 v186, 10, v183
	s_waitcnt vmcnt(0)
	v_lshl_add_u64 v[110:111], v[70:71], 0, v[104:105]
	v_lshl_add_u64 v[134:135], v[66:67], 0, v[0:1]
	v_lshlrev_b32_e32 v0, 11, v183
	v_lshl_add_u64 v[66:67], v[110:111], 0, v[0:1]
	v_or_b32_e32 v0, 0x1000, v186
	v_lshlrev_b32_e32 v70, 1, v0
	v_mov_b32_e32 v71, v1
	v_lshl_add_u64 v[72:73], v[110:111], 0, v[70:71]
	v_or_b32_e32 v0, 0x2000, v186
	global_load_dwordx2 v[132:133], v[72:73], off nt
	v_lshlrev_b32_e32 v72, 1, v0
	v_mov_b32_e32 v73, v1
	v_lshl_add_u64 v[74:75], v[110:111], 0, v[72:73]
	v_or_b32_e32 v0, 0x3000, v186
	global_load_dwordx2 v[130:131], v[74:75], off nt
	v_lshlrev_b32_e32 v74, 1, v0
	v_mov_b32_e32 v75, v1
	v_or_b32_e32 v0, 0x4000, v186
	v_lshl_add_u64 v[76:77], v[110:111], 0, v[74:75]
	v_lshlrev_b32_e32 v80, 1, v0
	v_mov_b32_e32 v81, v1
	global_load_dwordx2 v[128:129], v[76:77], off nt
	v_lshl_add_u64 v[76:77], v[110:111], 0, v[80:81]
	v_or_b32_e32 v0, 0x5000, v186
	global_load_dwordx2 v[126:127], v[76:77], off nt
	v_lshlrev_b32_e32 v76, 1, v0
	v_mov_b32_e32 v77, v1
	v_lshl_add_u64 v[78:79], v[110:111], 0, v[76:77]
	v_or_b32_e32 v0, 0x6000, v186
	global_load_dwordx2 v[124:125], v[78:79], off nt
	v_lshlrev_b32_e32 v78, 1, v0
	v_mov_b32_e32 v79, v1
	v_lshl_add_u64 v[82:83], v[110:111], 0, v[78:79]
	v_or_b32_e32 v0, 0x7000, v186
	global_load_dwordx2 v[122:123], v[82:83], off nt
	v_lshlrev_b32_e32 v82, 1, v0
	v_mov_b32_e32 v83, v1
	v_or_b32_e32 v0, 0x8000, v186
	v_lshl_add_u64 v[84:85], v[110:111], 0, v[82:83]
	v_lshlrev_b32_e32 v88, 1, v0
	v_mov_b32_e32 v89, v1
	global_load_dwordx2 v[120:121], v[84:85], off nt
	v_lshl_add_u64 v[84:85], v[110:111], 0, v[88:89]
	v_or_b32_e32 v0, 0x9000, v186
	global_load_dwordx2 v[118:119], v[84:85], off nt
	v_lshlrev_b32_e32 v84, 1, v0
	v_mov_b32_e32 v85, v1
	v_lshl_add_u64 v[86:87], v[110:111], 0, v[84:85]
	v_or_b32_e32 v0, 0xa000, v186
	global_load_dwordx2 v[116:117], v[86:87], off nt
	v_lshlrev_b32_e32 v86, 1, v0
	v_mov_b32_e32 v87, v1
	v_lshl_add_u64 v[90:91], v[110:111], 0, v[86:87]
	v_or_b32_e32 v0, 0xb000, v186
	global_load_dwordx2 v[114:115], v[90:91], off nt
	v_lshlrev_b32_e32 v90, 1, v0
	v_mov_b32_e32 v91, v1
	v_or_b32_e32 v0, 0xc000, v186
	v_lshl_add_u64 v[92:93], v[110:111], 0, v[90:91]
	v_lshlrev_b32_e32 v96, 1, v0
	v_mov_b32_e32 v97, v1
	global_load_dwordx2 v[112:113], v[92:93], off nt
	v_lshl_add_u64 v[92:93], v[110:111], 0, v[96:97]
	v_or_b32_e32 v0, 0xd000, v186
	global_load_dwordx2 v[108:109], v[92:93], off nt
	v_lshlrev_b32_e32 v92, 1, v0
	v_mov_b32_e32 v93, v1
	v_lshl_add_u64 v[94:95], v[110:111], 0, v[92:93]
	v_or_b32_e32 v0, 0xe000, v186
	global_load_dwordx2 v[140:141], v[66:67], off nt
	global_load_dwordx2 v[106:107], v[94:95], off nt
	v_lshlrev_b32_e32 v94, 1, v0
	v_mov_b32_e32 v95, v1
	v_lshl_add_u64 v[98:99], v[110:111], 0, v[94:95]
	v_or_b32_e32 v0, 0xf000, v186
	global_load_dwordx2 v[102:103], v[98:99], off nt
	v_lshlrev_b32_e32 v98, 1, v0
	v_mov_b32_e32 v99, v1
	v_lshl_add_u64 v[100:101], v[110:111], 0, v[98:99]
	global_load_dwordx2 v[100:101], v[100:101], off nt
	v_mad_u32_u24 v0, v183, s4, v184
	ds_read_b128 v[136:139], v0
	v_lshl_add_u64 v[134:135], v[134:135], 0, v[104:105]
	s_mov_b64 s[4:5], -1
	s_and_b64 vcc, exec, s[70:71]
	v_lshlrev_b32_e32 v0, 1, v186
	s_waitcnt vmcnt(3)
	v_lshlrev_b32_e32 v104, 16, v140
	v_and_b32_e32 v105, 0xffff0000, v140
	s_waitcnt lgkmcnt(0)
	v_add_f32_e32 v104, v136, v104
	v_add_f32_e32 v105, v137, v105
	v_lshlrev_b32_e32 v136, 16, v141
	v_and_b32_e32 v137, 0xffff0000, v141
	v_add_f32_e32 v136, v138, v136
	v_add_f32_e32 v137, v139, v137
	v_cvt_pk_bf16_f32 v138, v104, v105
	v_cvt_pk_bf16_f32 v139, v136, v137
	s_cbranch_vccz .LBB0_401
	v_lshl_add_u64 v[140:141], v[134:135], 0, v[0:1]
	global_store_dwordx2 v[140:141], v[138:139], off
	s_mov_b64 s[4:5], 0

; DI float bflo(unsigned v) { return __uint_as_float(v << 16); }
; DI float bfhi(unsigned v) { return __uint_as_float(v & 0xffff0000u); }
; template <int EPI>
; DI void gemm_tile(const Params& p, int layer, int mt, int nt, u16* sm, int wv) {
;     ...
;       for (int t = 0; t < 16; ++t) {
;         const int row = (lane >> 4) + 4 * t;
;         const f32x4 a4 = *(const f32x4*)(stg + row * 68 + kc * 4);
;         const float v0 = bflo(xb[t][0]) + a4[0], v1 = bfhi(xb[t][0]) + a4[1], v2 = bflo(xb[t][1]) + a4[2], v3 = bfhi(xb[t][1]) + a4[3];
;         float sq = v0 * v0 + v1 * v1 + v2 * v2 + v3 * v3;
;         u32x2 pv = {pk2(v0, v1), pk2(v2, v3)};
;         if (has_next) *(u32x2*)(xrow + (size_t)row * DM) = pv;
;         else *(u32x2*)(x2row + (size_t)row * DM) = pv;
;         sq += shx(sq, lane, 1); sq += shx(sq, lane, 2); sq += shx(sq, lane, 4); sq += shx(sq, lane, 8);
;         if (kc == 0) atomicAdd(ssn + mrow0 + row, sq);
.LBB0_403:
	v_and_b32_e32 v66, 63, v185
	v_lshlrev_b32_e32 v71, 2, v66
	v_mul_f32_e32 v66, v104, v104
	v_mul_f32_e32 v67, v105, v105
	v_mul_f32_e32 v104, v136, v136
	v_mul_f32_e32 v105, v137, v137
	v_add_f32_e32 v66, v66, v67
	v_add_f32_e32 v66, v104, v66
	v_xor_b32_e32 v138, 4, v71
	v_add_f32_e32 v66, v105, v66
	s_nop 1
	v_mov_b32_dpp v67, v66 quad_perm:[1,0,3,2] row_mask:0xf bank_mask:0xf
	v_xor_b32_e32 v137, 8, v71
	v_xor_b32_e32 v139, 16, v71
	v_xor_b32_e32 v136, 32, v71
	v_cmp_eq_u32_e64 s[36:37], 0, v180
	s_waitcnt lgkmcnt(0)
	v_add_f32_e32 v66, v66, v67
	s_nop 1
	v_mov_b32_dpp v67, v66 quad_perm:[2,3,0,1] row_mask:0xf bank_mask:0xf
	v_lshl_add_u64 v[104:105], v[68:69], 2, s[0:1]
	s_waitcnt lgkmcnt(0)
	v_add_f32_e32 v66, v66, v67
	s_nop 1
	v_mov_b32_dpp v67, v66 row_half_mirror row_mask:0xf bank_mask:0xf
	s_waitcnt lgkmcnt(0)
	v_add_f32_e32 v67, v66, v67
	s_nop 1
	v_mov_b32_dpp v71, v67 row_mirror row_mask:0xf bank_mask:0xf
	v_lshlrev_b32_e32 v66, 2, v183
	v_add_f32_e32 v146, v67, v71
	v_cmp_eq_u32_e64 s[4:5], 0, v180
	s_nop 1
	v_cndmask_b32_e64 v147, v147, v146, s[4:5]
.LBB0_405:
	v_mul_u32_u24_e32 v67, 0x110, v183
	v_add_u32_e32 v69, v67, v184
	ds_read_b128 v[140:143], v69 offset:1088
	v_lshlrev_b32_e32 v144, 16, v132
	v_and_b32_e32 v145, 0xffff0000, v132
	v_lshlrev_b32_e32 v132, 16, v133
	v_and_b32_e32 v133, 0xffff0000, v133
	s_waitcnt lgkmcnt(0)
	v_add_f32_e32 v140, v140, v144
	v_add_f32_e32 v141, v141, v145
	v_add_f32_e32 v142, v142, v132
	v_add_f32_e32 v143, v143, v133
	v_mul_f32_e32 v132, v140, v140
	v_mul_f32_e32 v133, v141, v141
	v_mul_f32_e32 v144, v142, v142
	v_mul_f32_e32 v145, v143, v143
	v_add_f32_e32 v67, v132, v133
	v_add_f32_e32 v67, v144, v67
	v_add_f32_e32 v67, v145, v67
	s_nop 1
	v_mov_b32_dpp v71, v67 quad_perm:[1,0,3,2] row_mask:0xf bank_mask:0xf
	v_or_b32_e32 v132, 4, v183
	v_cndmask_b32_e64 v111, v135, v111, s[34:35]
	v_cndmask_b32_e64 v110, v134, v110, s[34:35]
	v_lshlrev_b32_e32 v134, 11, v132
	s_waitcnt lgkmcnt(0)
	v_add_f32_e32 v67, v67, v71
	s_nop 1
	v_mov_b32_dpp v71, v67 quad_perm:[2,3,0,1] row_mask:0xf bank_mask:0xf
	v_mov_b32_e32 v135, v1
	v_cvt_pk_bf16_f32 v140, v140, v141
	v_cvt_pk_bf16_f32 v141, v142, v143
	v_lshl_add_u64 v[134:135], v[110:111], 0, v[134:135]
	s_waitcnt lgkmcnt(0)
	v_add_f32_e32 v67, v67, v71
	s_nop 1
	v_mov_b32_dpp v71, v67 row_half_mirror row_mask:0xf bank_mask:0xf
	global_store_dwordx2 v[134:135], v[140:141], off
	s_waitcnt lgkmcnt(0)
	v_add_f32_e32 v67, v67, v71
	s_nop 1
	v_mov_b32_dpp v71, v67 row_mirror row_mask:0xf bank_mask:0xf
	v_add_f32_e32 v146, v67, v71
	v_cmp_eq_u32_e64 s[4:5], 1, v180
	s_nop 1
	v_cndmask_b32_e64 v147, v147, v146, s[4:5]
.LBB0_407:
	ds_read_b128 v[140:143], v69 offset:2176
	v_lshlrev_b32_e32 v134, 16, v130
	v_and_b32_e32 v135, 0xffff0000, v130
	v_lshlrev_b32_e32 v130, 16, v131
	v_and_b32_e32 v131, 0xffff0000, v131
	s_waitcnt lgkmcnt(0)
	v_add_f32_e32 v134, v140, v134
	v_add_f32_e32 v135, v141, v135
	v_add_f32_e32 v140, v142, v130
	v_add_f32_e32 v141, v143, v131
	v_mul_f32_e32 v130, v134, v134
	v_mul_f32_e32 v131, v135, v135
	v_mul_f32_e32 v142, v140, v140
	v_mul_f32_e32 v143, v141, v141
	v_add_f32_e32 v67, v130, v131
	v_add_f32_e32 v67, v142, v67
	v_add_f32_e32 v67, v143, v67
	s_nop 1
	v_mov_b32_dpp v71, v67 quad_perm:[1,0,3,2] row_mask:0xf bank_mask:0xf
	v_or_b32_e32 v130, 8, v183
	v_cvt_pk_bf16_f32 v134, v134, v135
	v_cvt_pk_bf16_f32 v135, v140, v141
	v_lshlrev_b32_e32 v140, 11, v130
	s_waitcnt lgkmcnt(0)
	v_add_f32_e32 v67, v67, v71
	s_nop 1
	v_mov_b32_dpp v71, v67 quad_perm:[2,3,0,1] row_mask:0xf bank_mask:0xf
	v_mov_b32_e32 v141, v1
	v_lshl_add_u64 v[140:141], v[110:111], 0, v[140:141]
	global_store_dwordx2 v[140:141], v[134:135], off
	s_waitcnt lgkmcnt(0)
	v_add_f32_e32 v67, v67, v71
	s_nop 1
	v_mov_b32_dpp v71, v67 row_half_mirror row_mask:0xf bank_mask:0xf
	s_waitcnt lgkmcnt(0)
	v_add_f32_e32 v67, v67, v71
	s_nop 1
	v_mov_b32_dpp v71, v67 row_mirror row_mask:0xf bank_mask:0xf
	v_add_f32_e32 v146, v67, v71
	v_cmp_eq_u32_e64 s[4:5], 2, v180
	s_nop 1
	v_cndmask_b32_e64 v147, v147, v146, s[4:5]
.LBB0_409:
	ds_read_b128 v[140:143], v69 offset:3264
	v_lshlrev_b32_e32 v134, 16, v128
	v_and_b32_e32 v135, 0xffff0000, v128
	v_lshlrev_b32_e32 v128, 16, v129
	v_and_b32_e32 v129, 0xffff0000, v129
	s_waitcnt lgkmcnt(0)
	v_add_f32_e32 v134, v140, v134
	v_add_f32_e32 v135, v141, v135
	v_add_f32_e32 v140, v142, v128
	v_add_f32_e32 v141, v143, v129
	v_mul_f32_e32 v128, v134, v134
	v_mul_f32_e32 v129, v135, v135
	v_mul_f32_e32 v142, v140, v140
	v_mul_f32_e32 v143, v141, v141
	v_add_f32_e32 v67, v128, v129
	v_add_f32_e32 v67, v142, v67
	v_add_f32_e32 v67, v143, v67
	s_nop 1
	v_mov_b32_dpp v71, v67 quad_perm:[1,0,3,2] row_mask:0xf bank_mask:0xf
	v_or_b32_e32 v128, 12, v183
	v_cvt_pk_bf16_f32 v134, v134, v135
	v_cvt_pk_bf16_f32 v135, v140, v141
	v_lshlrev_b32_e32 v140, 11, v128
	s_waitcnt lgkmcnt(0)
	v_add_f32_e32 v67, v67, v71
	s_nop 1
	v_mov_b32_dpp v71, v67 quad_perm:[2,3,0,1] row_mask:0xf bank_mask:0xf
	v_mov_b32_e32 v141, v1
	v_lshl_add_u64 v[140:141], v[110:111], 0, v[140:141]
	global_store_dwordx2 v[140:141], v[134:135], off
	s_waitcnt lgkmcnt(0)
	v_add_f32_e32 v67, v67, v71
	s_nop 1
	v_mov_b32_dpp v71, v67 row_half_mirror row_mask:0xf bank_mask:0xf
	s_waitcnt lgkmcnt(0)
	v_add_f32_e32 v67, v67, v71
	s_nop 1
	v_mov_b32_dpp v71, v67 row_mirror row_mask:0xf bank_mask:0xf
	v_add_f32_e32 v146, v67, v71
	v_cmp_eq_u32_e64 s[4:5], 3, v180
	s_nop 1
	v_cndmask_b32_e64 v147, v147, v146, s[4:5]
; DI float bflo(unsigned v) { return __uint_as_float(v << 16); }
; DI float bfhi(unsigned v) { return __uint_as_float(v & 0xffff0000u); }
; template <int EPI>
; DI void gemm_tile(const Params& p, int layer, int mt, int nt, u16* sm, int wv) {
;     ...
;       for (int t = 0; t < 16; ++t) {
;         const int row = (lane >> 4) + 4 * t;
;         const f32x4 a4 = *(const f32x4*)(stg + row * 68 + kc * 4);
;         const float v0 = bflo(xb[t][0]) + a4[0], v1 = bfhi(xb[t][0]) + a4[1], v2 = bflo(xb[t][1]) + a4[2], v3 = bfhi(xb[t][1]) + a4[3];
;         float sq = v0 * v0 + v1 * v1 + v2 * v2 + v3 * v3;
;         u32x2 pv = {pk2(v0, v1), pk2(v2, v3)};
;         if (has_next) *(u32x2*)(xrow + (size_t)row * DM) = pv;
;         else *(u32x2*)(x2row + (size_t)row * DM) = pv;
;         sq += shx(sq, lane, 1); sq += shx(sq, lane, 2); sq += shx(sq, lane, 4); sq += shx(sq, lane, 8);
;         if (kc == 0) atomicAdd(ssn + mrow0 + row, sq);
.LBB0_411:
	ds_read_b128 v[140:143], v69 offset:4352
	v_lshlrev_b32_e32 v134, 16, v126
	v_and_b32_e32 v135, 0xffff0000, v126
	v_lshlrev_b32_e32 v126, 16, v127
	v_and_b32_e32 v127, 0xffff0000, v127
	s_waitcnt lgkmcnt(0)
	v_add_f32_e32 v134, v140, v134
	v_add_f32_e32 v135, v141, v135
	v_add_f32_e32 v140, v142, v126
	v_add_f32_e32 v141, v143, v127
	v_mul_f32_e32 v126, v134, v134
	v_mul_f32_e32 v127, v135, v135
	v_mul_f32_e32 v142, v140, v140
	v_mul_f32_e32 v143, v141, v141
	v_add_f32_e32 v67, v126, v127
	v_add_f32_e32 v67, v142, v67
	v_add_f32_e32 v67, v143, v67
	s_nop 1
	v_mov_b32_dpp v71, v67 quad_perm:[1,0,3,2] row_mask:0xf bank_mask:0xf
	v_or_b32_e32 v126, 16, v183
	v_cvt_pk_bf16_f32 v134, v134, v135
	v_cvt_pk_bf16_f32 v135, v140, v141
	v_lshlrev_b32_e32 v140, 11, v126
	s_waitcnt lgkmcnt(0)
	v_add_f32_e32 v67, v67, v71
	s_nop 1
	v_mov_b32_dpp v71, v67 quad_perm:[2,3,0,1] row_mask:0xf bank_mask:0xf
	v_mov_b32_e32 v141, v1
	v_lshl_add_u64 v[140:141], v[110:111], 0, v[140:141]
	global_store_dwordx2 v[140:141], v[134:135], off
	s_waitcnt lgkmcnt(0)
	v_add_f32_e32 v67, v67, v71
	s_nop 1
	v_mov_b32_dpp v71, v67 row_half_mirror row_mask:0xf bank_mask:0xf
	s_waitcnt lgkmcnt(0)
	v_add_f32_e32 v67, v67, v71
	s_nop 1
	v_mov_b32_dpp v71, v67 row_mirror row_mask:0xf bank_mask:0xf
	v_add_f32_e32 v146, v67, v71
	v_cmp_eq_u32_e64 s[4:5], 4, v180
	s_nop 1
	v_cndmask_b32_e64 v147, v147, v146, s[4:5]
.LBB0_413:
	ds_read_b128 v[140:143], v69 offset:5440
	v_lshlrev_b32_e32 v134, 16, v124
	v_and_b32_e32 v135, 0xffff0000, v124
	v_lshlrev_b32_e32 v124, 16, v125
	v_and_b32_e32 v125, 0xffff0000, v125
	s_waitcnt lgkmcnt(0)
	v_add_f32_e32 v134, v140, v134
	v_add_f32_e32 v135, v141, v135
	v_add_f32_e32 v140, v142, v124
	v_add_f32_e32 v141, v143, v125
	v_mul_f32_e32 v124, v134, v134
	v_mul_f32_e32 v125, v135, v135
	v_mul_f32_e32 v142, v140, v140
	v_mul_f32_e32 v143, v141, v141
	v_add_f32_e32 v67, v124, v125
	v_add_f32_e32 v67, v142, v67
	v_add_f32_e32 v67, v143, v67
	s_nop 1
	v_mov_b32_dpp v71, v67 quad_perm:[1,0,3,2] row_mask:0xf bank_mask:0xf
	v_or_b32_e32 v124, 20, v183
	v_cvt_pk_bf16_f32 v134, v134, v135
	v_cvt_pk_bf16_f32 v135, v140, v141
	v_lshlrev_b32_e32 v140, 11, v124
	s_waitcnt lgkmcnt(0)
	v_add_f32_e32 v67, v67, v71
	s_nop 1
	v_mov_b32_dpp v71, v67 quad_perm:[2,3,0,1] row_mask:0xf bank_mask:0xf
	v_mov_b32_e32 v141, v1
	v_lshl_add_u64 v[140:141], v[110:111], 0, v[140:141]
	global_store_dwordx2 v[140:141], v[134:135], off
	s_waitcnt lgkmcnt(0)
	v_add_f32_e32 v67, v67, v71
	s_nop 1
	v_mov_b32_dpp v71, v67 row_half_mirror row_mask:0xf bank_mask:0xf
	s_waitcnt lgkmcnt(0)
	v_add_f32_e32 v67, v67, v71
	s_nop 1
	v_mov_b32_dpp v71, v67 row_mirror row_mask:0xf bank_mask:0xf
	v_add_f32_e32 v146, v67, v71
	v_cmp_eq_u32_e64 s[4:5], 5, v180
	s_nop 1
	v_cndmask_b32_e64 v147, v147, v146, s[4:5]
.LBB0_415:
	ds_read_b128 v[140:143], v69 offset:6528
	v_lshlrev_b32_e32 v134, 16, v122
	v_and_b32_e32 v135, 0xffff0000, v122
	v_lshlrev_b32_e32 v122, 16, v123
	v_and_b32_e32 v123, 0xffff0000, v123
	s_waitcnt lgkmcnt(0)
	v_add_f32_e32 v134, v140, v134
	v_add_f32_e32 v135, v141, v135
	v_add_f32_e32 v140, v142, v122
	v_add_f32_e32 v141, v143, v123
	v_mul_f32_e32 v122, v134, v134
	v_mul_f32_e32 v123, v135, v135
	v_mul_f32_e32 v142, v140, v140
	v_mul_f32_e32 v143, v141, v141
	v_add_f32_e32 v67, v122, v123
	v_add_f32_e32 v67, v142, v67
	v_add_f32_e32 v67, v143, v67
	s_nop 1
	v_mov_b32_dpp v71, v67 quad_perm:[1,0,3,2] row_mask:0xf bank_mask:0xf
	v_or_b32_e32 v122, 24, v183
	v_cvt_pk_bf16_f32 v134, v134, v135
	v_cvt_pk_bf16_f32 v135, v140, v141
	v_lshlrev_b32_e32 v140, 11, v122
	s_waitcnt lgkmcnt(0)
	v_add_f32_e32 v67, v67, v71
	s_nop 1
	v_mov_b32_dpp v71, v67 quad_perm:[2,3,0,1] row_mask:0xf bank_mask:0xf
	v_mov_b32_e32 v141, v1
	v_lshl_add_u64 v[140:141], v[110:111], 0, v[140:141]
	global_store_dwordx2 v[140:141], v[134:135], off
	s_waitcnt lgkmcnt(0)
	v_add_f32_e32 v67, v67, v71
	s_nop 1
	v_mov_b32_dpp v71, v67 row_half_mirror row_mask:0xf bank_mask:0xf
	s_waitcnt lgkmcnt(0)
	v_add_f32_e32 v67, v67, v71
	s_nop 1
	v_mov_b32_dpp v71, v67 row_mirror row_mask:0xf bank_mask:0xf
	v_add_f32_e32 v146, v67, v71
	v_cmp_eq_u32_e64 s[4:5], 6, v180
	s_nop 1
	v_cndmask_b32_e64 v147, v147, v146, s[4:5]
.LBB0_417:
	ds_read_b128 v[140:143], v69 offset:7616
	v_lshlrev_b32_e32 v134, 16, v120
	v_and_b32_e32 v135, 0xffff0000, v120
	v_lshlrev_b32_e32 v120, 16, v121
	v_and_b32_e32 v121, 0xffff0000, v121
	s_waitcnt lgkmcnt(0)
	v_add_f32_e32 v134, v140, v134
	v_add_f32_e32 v135, v141, v135
	v_add_f32_e32 v140, v142, v120
	v_add_f32_e32 v141, v143, v121
	v_mul_f32_e32 v120, v134, v134
	v_mul_f32_e32 v121, v135, v135
	v_mul_f32_e32 v142, v140, v140
	v_mul_f32_e32 v143, v141, v141
	v_add_f32_e32 v67, v120, v121
	v_add_f32_e32 v67, v142, v67
	v_add_f32_e32 v67, v143, v67
	s_nop 1
	v_mov_b32_dpp v71, v67 quad_perm:[1,0,3,2] row_mask:0xf bank_mask:0xf
	v_or_b32_e32 v120, 28, v183
	v_cvt_pk_bf16_f32 v134, v134, v135
	v_cvt_pk_bf16_f32 v135, v140, v141
	v_lshlrev_b32_e32 v140, 11, v120
	s_waitcnt lgkmcnt(0)
	v_add_f32_e32 v67, v67, v71
	s_nop 1
	v_mov_b32_dpp v71, v67 quad_perm:[2,3,0,1] row_mask:0xf bank_mask:0xf
	v_mov_b32_e32 v141, v1
	v_lshl_add_u64 v[140:141], v[110:111], 0, v[140:141]
	global_store_dwordx2 v[140:141], v[134:135], off
	s_waitcnt lgkmcnt(0)
	v_add_f32_e32 v67, v67, v71
	s_nop 1
	v_mov_b32_dpp v71, v67 row_half_mirror row_mask:0xf bank_mask:0xf
	s_waitcnt lgkmcnt(0)
	v_add_f32_e32 v67, v67, v71
	s_nop 1
	v_mov_b32_dpp v71, v67 row_mirror row_mask:0xf bank_mask:0xf
	v_add_f32_e32 v146, v67, v71
	v_cmp_eq_u32_e64 s[4:5], 7, v180
	s_nop 1
	v_cndmask_b32_e64 v147, v147, v146, s[4:5]
; DI float bflo(unsigned v) { return __uint_as_float(v << 16); }
; DI float bfhi(unsigned v) { return __uint_as_float(v & 0xffff0000u); }
; template <int EPI>
; DI void gemm_tile(const Params& p, int layer, int mt, int nt, u16* sm, int wv) {
;     ...
;       for (int t = 0; t < 16; ++t) {
;         const int row = (lane >> 4) + 4 * t;
;         const f32x4 a4 = *(const f32x4*)(stg + row * 68 + kc * 4);
;         const float v0 = bflo(xb[t][0]) + a4[0], v1 = bfhi(xb[t][0]) + a4[1], v2 = bflo(xb[t][1]) + a4[2], v3 = bfhi(xb[t][1]) + a4[3];
;         float sq = v0 * v0 + v1 * v1 + v2 * v2 + v3 * v3;
;         u32x2 pv = {pk2(v0, v1), pk2(v2, v3)};
;         if (has_next) *(u32x2*)(xrow + (size_t)row * DM) = pv;
;         else *(u32x2*)(x2row + (size_t)row * DM) = pv;
;         sq += shx(sq, lane, 1); sq += shx(sq, lane, 2); sq += shx(sq, lane, 4); sq += shx(sq, lane, 8);
;         if (kc == 0) atomicAdd(ssn + mrow0 + row, sq);
.LBB0_419:
	ds_read_b128 v[140:143], v69 offset:8704
	v_lshlrev_b32_e32 v134, 16, v118
	v_and_b32_e32 v135, 0xffff0000, v118
	v_lshlrev_b32_e32 v118, 16, v119
	v_and_b32_e32 v119, 0xffff0000, v119
	s_waitcnt lgkmcnt(0)
	v_add_f32_e32 v134, v140, v134
	v_add_f32_e32 v135, v141, v135
	v_add_f32_e32 v140, v142, v118
	v_add_f32_e32 v141, v143, v119
	v_mul_f32_e32 v118, v134, v134
	v_mul_f32_e32 v119, v135, v135
	v_mul_f32_e32 v142, v140, v140
	v_mul_f32_e32 v143, v141, v141
	v_add_f32_e32 v67, v118, v119
	v_add_f32_e32 v67, v142, v67
	v_add_f32_e32 v67, v143, v67
	s_nop 1
	v_mov_b32_dpp v71, v67 quad_perm:[1,0,3,2] row_mask:0xf bank_mask:0xf
	v_or_b32_e32 v118, 32, v183
	v_cvt_pk_bf16_f32 v134, v134, v135
	v_cvt_pk_bf16_f32 v135, v140, v141
	v_lshlrev_b32_e32 v140, 11, v118
	s_waitcnt lgkmcnt(0)
	v_add_f32_e32 v67, v67, v71
	s_nop 1
	v_mov_b32_dpp v71, v67 quad_perm:[2,3,0,1] row_mask:0xf bank_mask:0xf
	v_mov_b32_e32 v141, v1
	v_lshl_add_u64 v[140:141], v[110:111], 0, v[140:141]
	global_store_dwordx2 v[140:141], v[134:135], off
	s_waitcnt lgkmcnt(0)
	v_add_f32_e32 v67, v67, v71
	s_nop 1
	v_mov_b32_dpp v71, v67 row_half_mirror row_mask:0xf bank_mask:0xf
	s_waitcnt lgkmcnt(0)
	v_add_f32_e32 v67, v67, v71
	s_nop 1
	v_mov_b32_dpp v71, v67 row_mirror row_mask:0xf bank_mask:0xf
	v_add_f32_e32 v146, v67, v71
	v_cmp_eq_u32_e64 s[4:5], 8, v180
	s_nop 1
	v_cndmask_b32_e64 v147, v147, v146, s[4:5]
.LBB0_421:
	ds_read_b128 v[140:143], v69 offset:9792
	v_lshlrev_b32_e32 v134, 16, v116
	v_and_b32_e32 v135, 0xffff0000, v116
	v_lshlrev_b32_e32 v116, 16, v117
	v_and_b32_e32 v117, 0xffff0000, v117
	s_waitcnt lgkmcnt(0)
	v_add_f32_e32 v134, v140, v134
	v_add_f32_e32 v135, v141, v135
	v_add_f32_e32 v140, v142, v116
	v_add_f32_e32 v141, v143, v117
	v_mul_f32_e32 v116, v134, v134
	v_mul_f32_e32 v117, v135, v135
	v_mul_f32_e32 v142, v140, v140
	v_mul_f32_e32 v143, v141, v141
	v_add_f32_e32 v67, v116, v117
	v_add_f32_e32 v67, v142, v67
	v_add_f32_e32 v67, v143, v67
	s_nop 1
	v_mov_b32_dpp v71, v67 quad_perm:[1,0,3,2] row_mask:0xf bank_mask:0xf
	v_or_b32_e32 v116, 36, v183
	v_cvt_pk_bf16_f32 v134, v134, v135
	v_cvt_pk_bf16_f32 v135, v140, v141
	v_lshlrev_b32_e32 v140, 11, v116
	s_waitcnt lgkmcnt(0)
	v_add_f32_e32 v67, v67, v71
	s_nop 1
	v_mov_b32_dpp v71, v67 quad_perm:[2,3,0,1] row_mask:0xf bank_mask:0xf
	v_mov_b32_e32 v141, v1
	v_lshl_add_u64 v[140:141], v[110:111], 0, v[140:141]
	global_store_dwordx2 v[140:141], v[134:135], off
	s_waitcnt lgkmcnt(0)
	v_add_f32_e32 v67, v67, v71
	s_nop 1
	v_mov_b32_dpp v71, v67 row_half_mirror row_mask:0xf bank_mask:0xf
	s_waitcnt lgkmcnt(0)
	v_add_f32_e32 v67, v67, v71
	s_nop 1
	v_mov_b32_dpp v71, v67 row_mirror row_mask:0xf bank_mask:0xf
	v_add_f32_e32 v146, v67, v71
	v_cmp_eq_u32_e64 s[4:5], 9, v180
	s_nop 1
	v_cndmask_b32_e64 v147, v147, v146, s[4:5]
.LBB0_423:
	ds_read_b128 v[140:143], v69 offset:10880
	v_lshlrev_b32_e32 v134, 16, v114
	v_and_b32_e32 v135, 0xffff0000, v114
	v_lshlrev_b32_e32 v114, 16, v115
	v_and_b32_e32 v115, 0xffff0000, v115
	s_waitcnt lgkmcnt(0)
	v_add_f32_e32 v134, v140, v134
	v_add_f32_e32 v135, v141, v135
	v_add_f32_e32 v140, v142, v114
	v_add_f32_e32 v141, v143, v115
	v_mul_f32_e32 v114, v134, v134
	v_mul_f32_e32 v115, v135, v135
	v_mul_f32_e32 v142, v140, v140
	v_mul_f32_e32 v143, v141, v141
	v_add_f32_e32 v67, v114, v115
	v_add_f32_e32 v67, v142, v67
	v_add_f32_e32 v67, v143, v67
	s_nop 1
	v_mov_b32_dpp v71, v67 quad_perm:[1,0,3,2] row_mask:0xf bank_mask:0xf
	v_or_b32_e32 v114, 40, v183
	v_cvt_pk_bf16_f32 v134, v134, v135
	v_cvt_pk_bf16_f32 v135, v140, v141
	v_lshlrev_b32_e32 v140, 11, v114
	s_waitcnt lgkmcnt(0)
	v_add_f32_e32 v67, v67, v71
	s_nop 1
	v_mov_b32_dpp v71, v67 quad_perm:[2,3,0,1] row_mask:0xf bank_mask:0xf
	v_mov_b32_e32 v141, v1
	v_lshl_add_u64 v[140:141], v[110:111], 0, v[140:141]
	global_store_dwordx2 v[140:141], v[134:135], off
	s_waitcnt lgkmcnt(0)
	v_add_f32_e32 v67, v67, v71
	s_nop 1
	v_mov_b32_dpp v71, v67 row_half_mirror row_mask:0xf bank_mask:0xf
	s_waitcnt lgkmcnt(0)
	v_add_f32_e32 v67, v67, v71
	s_nop 1
	v_mov_b32_dpp v71, v67 row_mirror row_mask:0xf bank_mask:0xf
	v_add_f32_e32 v146, v67, v71
	v_cmp_eq_u32_e64 s[4:5], 10, v180
	s_nop 1
	v_cndmask_b32_e64 v147, v147, v146, s[4:5]
.LBB0_425:
	ds_read_b128 v[140:143], v69 offset:11968
	v_lshlrev_b32_e32 v134, 16, v112
	v_and_b32_e32 v135, 0xffff0000, v112
	v_lshlrev_b32_e32 v112, 16, v113
	v_and_b32_e32 v113, 0xffff0000, v113
	s_waitcnt lgkmcnt(0)
	v_add_f32_e32 v134, v140, v134
	v_add_f32_e32 v135, v141, v135
	v_add_f32_e32 v140, v142, v112
	v_add_f32_e32 v141, v143, v113
	v_mul_f32_e32 v112, v134, v134
	v_mul_f32_e32 v113, v135, v135
	v_mul_f32_e32 v142, v140, v140
	v_mul_f32_e32 v143, v141, v141
	v_add_f32_e32 v67, v112, v113
	v_add_f32_e32 v67, v142, v67
	v_add_f32_e32 v67, v143, v67
	s_nop 1
	v_mov_b32_dpp v71, v67 quad_perm:[1,0,3,2] row_mask:0xf bank_mask:0xf
	v_or_b32_e32 v112, 44, v183
	v_cvt_pk_bf16_f32 v134, v134, v135
	v_cvt_pk_bf16_f32 v135, v140, v141
	v_lshlrev_b32_e32 v140, 11, v112
	s_waitcnt lgkmcnt(0)
	v_add_f32_e32 v67, v67, v71
	s_nop 1
	v_mov_b32_dpp v71, v67 quad_perm:[2,3,0,1] row_mask:0xf bank_mask:0xf
	v_mov_b32_e32 v141, v1
	v_lshl_add_u64 v[140:141], v[110:111], 0, v[140:141]
	global_store_dwordx2 v[140:141], v[134:135], off
	s_waitcnt lgkmcnt(0)
	v_add_f32_e32 v67, v67, v71
	s_nop 1
	v_mov_b32_dpp v71, v67 row_half_mirror row_mask:0xf bank_mask:0xf
	s_waitcnt lgkmcnt(0)
	v_add_f32_e32 v67, v67, v71
	s_nop 1
	v_mov_b32_dpp v71, v67 row_mirror row_mask:0xf bank_mask:0xf
	v_add_f32_e32 v146, v67, v71
	v_cmp_eq_u32_e64 s[4:5], 11, v180
	s_nop 1
	v_cndmask_b32_e64 v147, v147, v146, s[4:5]
; DI float bflo(unsigned v) { return __uint_as_float(v << 16); }
; DI float bfhi(unsigned v) { return __uint_as_float(v & 0xffff0000u); }
; template <int EPI>
; DI void gemm_tile(const Params& p, int layer, int mt, int nt, u16* sm, int wv) {
;     ...
;       for (int t = 0; t < 16; ++t) {
;         const int row = (lane >> 4) + 4 * t;
;         const f32x4 a4 = *(const f32x4*)(stg + row * 68 + kc * 4);
;         const float v0 = bflo(xb[t][0]) + a4[0], v1 = bfhi(xb[t][0]) + a4[1], v2 = bflo(xb[t][1]) + a4[2], v3 = bfhi(xb[t][1]) + a4[3];
;         float sq = v0 * v0 + v1 * v1 + v2 * v2 + v3 * v3;
;         u32x2 pv = {pk2(v0, v1), pk2(v2, v3)};
;         if (has_next) *(u32x2*)(xrow + (size_t)row * DM) = pv;
;         else *(u32x2*)(x2row + (size_t)row * DM) = pv;
;         sq += shx(sq, lane, 1); sq += shx(sq, lane, 2); sq += shx(sq, lane, 4); sq += shx(sq, lane, 8);
;         if (kc == 0) atomicAdd(ssn + mrow0 + row, sq);
.LBB0_427:
	ds_read_b128 v[140:143], v69 offset:13056
	v_lshlrev_b32_e32 v134, 16, v108
	v_and_b32_e32 v135, 0xffff0000, v108
	v_lshlrev_b32_e32 v108, 16, v109
	v_and_b32_e32 v109, 0xffff0000, v109
	s_waitcnt lgkmcnt(0)
	v_add_f32_e32 v134, v140, v134
	v_add_f32_e32 v135, v141, v135
	v_add_f32_e32 v140, v142, v108
	v_add_f32_e32 v141, v143, v109
	v_mul_f32_e32 v108, v134, v134
	v_mul_f32_e32 v109, v135, v135
	v_mul_f32_e32 v142, v140, v140
	v_mul_f32_e32 v143, v141, v141
	v_add_f32_e32 v67, v108, v109
	v_add_f32_e32 v67, v142, v67
	v_add_f32_e32 v67, v143, v67
	s_nop 1
	v_mov_b32_dpp v71, v67 quad_perm:[1,0,3,2] row_mask:0xf bank_mask:0xf
	v_or_b32_e32 v108, 48, v183
	v_cvt_pk_bf16_f32 v134, v134, v135
	v_cvt_pk_bf16_f32 v135, v140, v141
	v_lshlrev_b32_e32 v140, 11, v108
	s_waitcnt lgkmcnt(0)
	v_add_f32_e32 v67, v67, v71
	s_nop 1
	v_mov_b32_dpp v71, v67 quad_perm:[2,3,0,1] row_mask:0xf bank_mask:0xf
	v_mov_b32_e32 v141, v1
	v_lshl_add_u64 v[140:141], v[110:111], 0, v[140:141]
	global_store_dwordx2 v[140:141], v[134:135], off
	s_waitcnt lgkmcnt(0)
	v_add_f32_e32 v67, v67, v71
	s_nop 1
	v_mov_b32_dpp v71, v67 row_half_mirror row_mask:0xf bank_mask:0xf
	s_waitcnt lgkmcnt(0)
	v_add_f32_e32 v67, v67, v71
	s_nop 1
	v_mov_b32_dpp v71, v67 row_mirror row_mask:0xf bank_mask:0xf
	v_add_f32_e32 v146, v67, v71
	v_cmp_eq_u32_e64 s[4:5], 12, v180
	s_nop 1
	v_cndmask_b32_e64 v147, v147, v146, s[4:5]
.LBB0_429:
	ds_read_b128 v[140:143], v69 offset:14144
	s_waitcnt vmcnt(14)
	v_lshlrev_b32_e32 v134, 16, v106
	v_and_b32_e32 v135, 0xffff0000, v106
	v_lshlrev_b32_e32 v106, 16, v107
	v_and_b32_e32 v107, 0xffff0000, v107
	s_waitcnt lgkmcnt(0)
	v_add_f32_e32 v134, v140, v134
	v_add_f32_e32 v135, v141, v135
	v_add_f32_e32 v140, v142, v106
	v_add_f32_e32 v141, v143, v107
	v_mul_f32_e32 v106, v134, v134
	v_mul_f32_e32 v107, v135, v135
	v_mul_f32_e32 v142, v140, v140
	v_mul_f32_e32 v143, v141, v141
	v_add_f32_e32 v67, v106, v107
	v_add_f32_e32 v67, v142, v67
	v_add_f32_e32 v67, v143, v67
	s_nop 1
	v_mov_b32_dpp v71, v67 quad_perm:[1,0,3,2] row_mask:0xf bank_mask:0xf
	v_or_b32_e32 v106, 52, v183
	v_cvt_pk_bf16_f32 v134, v134, v135
	v_cvt_pk_bf16_f32 v135, v140, v141
	v_lshlrev_b32_e32 v140, 11, v106
	s_waitcnt lgkmcnt(0)
	v_add_f32_e32 v67, v67, v71
	s_nop 1
	v_mov_b32_dpp v71, v67 quad_perm:[2,3,0,1] row_mask:0xf bank_mask:0xf
	v_mov_b32_e32 v141, v1
	v_lshl_add_u64 v[140:141], v[110:111], 0, v[140:141]
	global_store_dwordx2 v[140:141], v[134:135], off
	s_waitcnt lgkmcnt(0)
	v_add_f32_e32 v67, v67, v71
	s_nop 1
	v_mov_b32_dpp v71, v67 row_half_mirror row_mask:0xf bank_mask:0xf
	s_waitcnt lgkmcnt(0)
	v_add_f32_e32 v67, v67, v71
	s_nop 1
	v_mov_b32_dpp v71, v67 row_mirror row_mask:0xf bank_mask:0xf
	v_add_f32_e32 v146, v67, v71
	v_cmp_eq_u32_e64 s[4:5], 13, v180
	s_nop 1
	v_cndmask_b32_e64 v147, v147, v146, s[4:5]
.LBB0_431:
	ds_read_b128 v[140:143], v69 offset:15232
	s_waitcnt vmcnt(14)
	v_lshlrev_b32_e32 v134, 16, v102
	v_and_b32_e32 v135, 0xffff0000, v102
	v_lshlrev_b32_e32 v102, 16, v103
	v_and_b32_e32 v103, 0xffff0000, v103
	s_waitcnt lgkmcnt(0)
	v_add_f32_e32 v134, v140, v134
	v_add_f32_e32 v135, v141, v135
	v_add_f32_e32 v140, v142, v102
	v_add_f32_e32 v141, v143, v103
	v_mul_f32_e32 v102, v134, v134
	v_mul_f32_e32 v103, v135, v135
	v_mul_f32_e32 v142, v140, v140
	v_mul_f32_e32 v143, v141, v141
	v_add_f32_e32 v67, v102, v103
	v_add_f32_e32 v67, v142, v67
	v_add_f32_e32 v67, v143, v67
	s_nop 1
	v_mov_b32_dpp v71, v67 quad_perm:[1,0,3,2] row_mask:0xf bank_mask:0xf
	v_or_b32_e32 v103, 56, v183
	v_cvt_pk_bf16_f32 v134, v134, v135
	v_cvt_pk_bf16_f32 v135, v140, v141
	v_lshlrev_b32_e32 v140, 11, v103
	s_waitcnt lgkmcnt(0)
	v_add_f32_e32 v67, v67, v71
	s_nop 1
	v_mov_b32_dpp v71, v67 quad_perm:[2,3,0,1] row_mask:0xf bank_mask:0xf
	v_mov_b32_e32 v141, v1
	v_lshl_add_u64 v[140:141], v[110:111], 0, v[140:141]
	global_store_dwordx2 v[140:141], v[134:135], off
	s_waitcnt lgkmcnt(0)
	v_add_f32_e32 v67, v67, v71
	s_nop 1
	v_mov_b32_dpp v71, v67 row_half_mirror row_mask:0xf bank_mask:0xf
	s_waitcnt lgkmcnt(0)
	v_add_f32_e32 v67, v67, v71
	s_nop 1
	v_mov_b32_dpp v71, v67 row_mirror row_mask:0xf bank_mask:0xf
	v_add_f32_e32 v146, v67, v71
	v_cmp_eq_u32_e64 s[4:5], 14, v180
	s_nop 1
	v_cndmask_b32_e64 v147, v147, v146, s[4:5]
; DI float bflo(unsigned v) { return __uint_as_float(v << 16); }
; DI float bfhi(unsigned v) { return __uint_as_float(v & 0xffff0000u); }
; template <int EPI>
; DI void gemm_tile(const Params& p, int layer, int mt, int nt, u16* sm, int wv) {
;     ...
; #pragma unroll
;     for (int hh = 0; hh < 2; ++hh) {
; #pragma unroll
;       for (int i2 = 0; i2 < 4; ++i2)
; #pragma unroll
;         for (int j = 0; j < 4; ++j)
;           *(f32x4*)(stg + (16 * i2 + fr) * 68 + 16 * j + 4 * fq) = acc[4 * hh + i2][j];
;       const size_t mrow0 = (size_t)(m0 + wm * 128 + 64 * hh);
;       u16* xrow = p.xg + mrow0 * DM + n0 + wn * 64 + kc * 4;
;       u16* x2row = (u16*)p.x2 + mrow0 * DM + n0 + wn * 64 + kc * 4;
;       u32x2 xb[16];
; #pragma unroll
;       for (int t = 0; t < 16; ++t) xb[t] = __builtin_nontemporal_load((const u32x2*)(xrow + (size_t)((lane >> 4) + 4 * t) * DM));
; #pragma unroll
;       for (int t = 0; t < 16; ++t) {
;         const int row = (lane >> 4) + 4 * t;
;         const f32x4 a4 = *(const f32x4*)(stg + row * 68 + kc * 4);
;         const float v0 = bflo(xb[t][0]) + a4[0], v1 = bfhi(xb[t][0]) + a4[1], v2 = bflo(xb[t][1]) + a4[2], v3 = bfhi(xb[t][1]) + a4[3];
;         float sq = v0 * v0 + v1 * v1 + v2 * v2 + v3 * v3;
;         u32x2 pv = {pk2(v0, v1), pk2(v2, v3)};
;         if (has_next) *(u32x2*)(xrow + (size_t)row * DM) = pv;
;         else *(u32x2*)(x2row + (size_t)row * DM) = pv;
;         sq += shx(sq, lane, 1); sq += shx(sq, lane, 2); sq += shx(sq, lane, 4); sq += shx(sq, lane, 8);
;         if (kc == 0) atomicAdd(ssn + mrow0 + row, sq);
.LBB0_433:
	ds_read_b128 v[140:143], v69 offset:16320
	s_waitcnt vmcnt(14)
	v_lshlrev_b32_e32 v134, 16, v100
	v_and_b32_e32 v135, 0xffff0000, v100
	v_lshlrev_b32_e32 v100, 16, v101
	v_and_b32_e32 v101, 0xffff0000, v101
	s_waitcnt lgkmcnt(0)
	v_add_f32_e32 v134, v140, v134
	v_add_f32_e32 v135, v141, v135
	v_add_f32_e32 v100, v142, v100
	v_add_f32_e32 v101, v143, v101
	v_mul_f32_e32 v140, v134, v134
	v_mul_f32_e32 v141, v135, v135
	v_mul_f32_e32 v142, v100, v100
	v_mul_f32_e32 v143, v101, v101
	v_add_f32_e32 v67, v140, v141
	v_add_f32_e32 v67, v142, v67
	v_add_f32_e32 v67, v143, v67
	s_nop 1
	v_mov_b32_dpp v71, v67 quad_perm:[1,0,3,2] row_mask:0xf bank_mask:0xf
	v_or_b32_e32 v102, 60, v183
	v_cvt_pk_bf16_f32 v134, v134, v135
	v_cvt_pk_bf16_f32 v135, v100, v101
	v_lshlrev_b32_e32 v100, 11, v102
	s_waitcnt lgkmcnt(0)
	v_add_f32_e32 v67, v67, v71
	s_nop 1
	v_mov_b32_dpp v71, v67 quad_perm:[2,3,0,1] row_mask:0xf bank_mask:0xf
	v_mov_b32_e32 v101, v1
	v_lshl_add_u64 v[100:101], v[110:111], 0, v[100:101]
	global_store_dwordx2 v[100:101], v[134:135], off
	s_waitcnt lgkmcnt(0)
	v_add_f32_e32 v67, v67, v71
	s_nop 1
	v_mov_b32_dpp v71, v67 row_half_mirror row_mask:0xf bank_mask:0xf
	s_waitcnt lgkmcnt(0)
	v_add_f32_e32 v67, v67, v71
	s_nop 1
	v_mov_b32_dpp v71, v67 row_mirror row_mask:0xf bank_mask:0xf
	v_add_f32_e32 v146, v67, v71
	v_cmp_eq_u32_e64 s[4:5], 15, v180
	s_nop 1
	v_cndmask_b32_e64 v147, v147, v146, s[4:5]
.LBB0_435:
	v_lshl_add_u32 v148, v180, 4, v66
	v_mov_b32_e32 v149, v1
	v_lshl_add_u64 v[148:149], v[104:105], 0, v[148:149]
	global_atomic_add_f32 v[148:149], v147, off
	v_mul_u32_u24_e32 v73, 0x110, v180
	v_add_u32_e32 v73, v182, v73
	ds_write_b128 v73, v[62:65]
	ds_write_b128 v73, v[58:61] offset:64
	ds_write_b128 v73, v[54:57] offset:128
	ds_write_b128 v73, v[50:53] offset:192
	ds_write_b128 v73, v[46:49] offset:4352
	ds_write_b128 v73, v[42:45] offset:4416
	ds_write_b128 v73, v[38:41] offset:4480
	ds_write_b128 v73, v[34:37] offset:4544
	ds_write_b128 v73, v[30:33] offset:8704
	ds_write_b128 v73, v[26:29] offset:8768
	ds_write_b128 v73, v[22:25] offset:8832
	ds_write_b128 v73, v[18:21] offset:8896
	ds_write_b128 v73, v[10:13] offset:13056
	ds_write_b128 v73, v[6:9] offset:13120
	ds_write_b128 v73, v[2:5] offset:13184
	ds_write_b128 v73, v[14:17] offset:13248
	v_or_b32_e32 v4, 64, v68
	v_ashrrev_i32_e32 v5, 31, v4
	v_lshlrev_b64 v[2:3], 11, v[4:5]
	v_lshlrev_b32_e32 v67, 6, v181
	v_lshl_add_u64 v[6:7], s[60:61], 0, v[2:3]
	s_waitcnt lgkmcnt(14)
	v_lshlrev_b32_e32 v71, 2, v180
	v_lshl_add_u64 v[6:7], v[6:7], 0, s[2:3]
	v_lshlrev_b32_e32 v8, 1, v67
	v_mov_b32_e32 v9, v1
	v_lshl_add_u64 v[6:7], v[6:7], 0, v[8:9]
	v_lshlrev_b32_e32 v38, 1, v71
	v_mov_b32_e32 v39, v1
	v_lshl_add_u64 v[2:3], s[82:83], 0, v[2:3]
	v_lshl_add_u64 v[10:11], v[6:7], 0, v[38:39]
	v_lshl_add_u64 v[2:3], v[2:3], 0, s[2:3]
	v_mov_b32_e32 v71, v1
	v_lshl_add_u64 v[40:41], v[2:3], 0, v[8:9]
	v_lshl_add_u64 v[2:3], v[10:11], 0, v[70:71]
	v_mov_b32_e32 v73, v1
	global_load_dwordx2 v[34:35], v[2:3], off nt
	v_lshl_add_u64 v[2:3], v[10:11], 0, v[72:73]
	v_mov_b32_e32 v75, v1
	global_load_dwordx2 v[32:33], v[2:3], off nt
	v_lshl_add_u64 v[2:3], v[10:11], 0, v[74:75]
	v_mov_b32_e32 v81, v1
	global_load_dwordx2 v[30:31], v[2:3], off nt
	v_lshl_add_u64 v[2:3], v[10:11], 0, v[80:81]
	v_mov_b32_e32 v77, v1
	global_load_dwordx2 v[28:29], v[2:3], off nt
	v_lshl_add_u64 v[2:3], v[10:11], 0, v[76:77]
	v_mov_b32_e32 v79, v1
	global_load_dwordx2 v[26:27], v[2:3], off nt
	v_lshl_add_u64 v[2:3], v[10:11], 0, v[78:79]
	v_mov_b32_e32 v83, v1
	global_load_dwordx2 v[24:25], v[2:3], off nt
	v_lshl_add_u64 v[2:3], v[10:11], 0, v[82:83]
	v_mov_b32_e32 v89, v1
	global_load_dwordx2 v[22:23], v[2:3], off nt
	v_lshl_add_u64 v[2:3], v[10:11], 0, v[88:89]
	v_mov_b32_e32 v85, v1
	global_load_dwordx2 v[20:21], v[2:3], off nt
	v_lshl_add_u64 v[2:3], v[10:11], 0, v[84:85]
	v_mov_b32_e32 v87, v1
	global_load_dwordx2 v[18:19], v[2:3], off nt
	v_lshl_add_u64 v[2:3], v[10:11], 0, v[86:87]
	v_mov_b32_e32 v91, v1
	global_load_dwordx2 v[16:17], v[2:3], off nt
	v_lshl_add_u64 v[2:3], v[10:11], 0, v[90:91]
	v_mov_b32_e32 v97, v1
	v_lshl_add_u64 v[36:37], v[10:11], 0, v[0:1]
	global_load_dwordx2 v[14:15], v[2:3], off nt
	v_lshl_add_u64 v[2:3], v[10:11], 0, v[96:97]
	v_mov_b32_e32 v93, v1
	global_load_dwordx2 v[44:45], v[36:37], off nt
	global_load_dwordx2 v[12:13], v[2:3], off nt
	v_lshl_add_u64 v[2:3], v[10:11], 0, v[92:93]
	v_mov_b32_e32 v95, v1
	global_load_dwordx2 v[8:9], v[2:3], off nt
	v_lshl_add_u64 v[2:3], v[10:11], 0, v[94:95]
	v_mov_b32_e32 v99, v1
	global_load_dwordx2 v[6:7], v[2:3], off nt
	v_lshl_add_u64 v[2:3], v[10:11], 0, v[98:99]
	global_load_dwordx2 v[2:3], v[2:3], off nt
	v_lshl_add_u64 v[38:39], v[40:41], 0, v[38:39]
	ds_read_b128 v[40:43], v69
	s_mov_b64 s[2:3], -1
	s_andn2_b64 vcc, exec, s[70:71]
	s_waitcnt vmcnt(4)
	v_lshlrev_b32_e32 v46, 16, v44
	v_and_b32_e32 v47, 0xffff0000, v44
	v_lshlrev_b32_e32 v44, 16, v45
	v_and_b32_e32 v45, 0xffff0000, v45
	s_waitcnt lgkmcnt(0)
	v_add_f32_e32 v40, v40, v46
	v_add_f32_e32 v41, v41, v47
	v_add_f32_e32 v42, v42, v44
	v_add_f32_e32 v43, v43, v45
	v_cvt_pk_bf16_f32 v44, v40, v41
	v_cvt_pk_bf16_f32 v45, v42, v43
	s_cbranch_vccnz .LBB0_437
	v_lshl_add_u64 v[46:47], v[38:39], 0, v[0:1]
	s_mov_b64 s[2:3], 0
	global_store_dwordx2 v[46:47], v[44:45], off

; DI float bflo(unsigned v) { return __uint_as_float(v << 16); }
; DI float bfhi(unsigned v) { return __uint_as_float(v & 0xffff0000u); }
; template <int EPI>
; DI void gemm_tile(const Params& p, int layer, int mt, int nt, u16* sm, int wv) {
;     ...
;       for (int t = 0; t < 16; ++t) {
;         const int row = (lane >> 4) + 4 * t;
;         const f32x4 a4 = *(const f32x4*)(stg + row * 68 + kc * 4);
;         const float v0 = bflo(xb[t][0]) + a4[0], v1 = bfhi(xb[t][0]) + a4[1], v2 = bflo(xb[t][1]) + a4[2], v3 = bfhi(xb[t][1]) + a4[3];
;         float sq = v0 * v0 + v1 * v1 + v2 * v2 + v3 * v3;
;         u32x2 pv = {pk2(v0, v1), pk2(v2, v3)};
;         if (has_next) *(u32x2*)(xrow + (size_t)row * DM) = pv;
;         else *(u32x2*)(x2row + (size_t)row * DM) = pv;
;         sq += shx(sq, lane, 1); sq += shx(sq, lane, 2); sq += shx(sq, lane, 4); sq += shx(sq, lane, 8);
;         if (kc == 0) atomicAdd(ssn + mrow0 + row, sq);
.LBB0_439:
	v_mul_f32_e32 v36, v40, v40
	v_mul_f32_e32 v37, v41, v41
	v_mul_f32_e32 v40, v42, v42
	v_mul_f32_e32 v41, v43, v43
	v_add_f32_e32 v0, v36, v37
	v_add_f32_e32 v0, v40, v0
	v_add_f32_e32 v0, v41, v0
	s_nop 1
	v_mov_b32_dpp v36, v0 quad_perm:[1,0,3,2] row_mask:0xf bank_mask:0xf
	s_waitcnt lgkmcnt(0)
	v_add_f32_e32 v0, v0, v36
	s_nop 1
	v_mov_b32_dpp v36, v0 quad_perm:[2,3,0,1] row_mask:0xf bank_mask:0xf
	s_waitcnt lgkmcnt(0)
	v_add_f32_e32 v0, v0, v36
	s_nop 1
	v_mov_b32_dpp v36, v0 row_half_mirror row_mask:0xf bank_mask:0xf
	s_waitcnt lgkmcnt(0)
	v_add_f32_e32 v0, v0, v36
	s_nop 1
	v_mov_b32_dpp v36, v0 row_mirror row_mask:0xf bank_mask:0xf
	v_add_f32_e32 v146, v0, v36
	v_cmp_eq_u32_e64 s[2:3], 0, v180
	s_nop 1
	v_cndmask_b32_e64 v147, v147, v146, s[2:3]
.LBB0_441:
	ds_read_b128 v[40:43], v69 offset:1088
	s_waitcnt lgkmcnt(1)
	v_lshlrev_b32_e32 v36, 16, v34
	v_and_b32_e32 v37, 0xffff0000, v34
	v_lshlrev_b32_e32 v34, 16, v35
	v_and_b32_e32 v35, 0xffff0000, v35
	s_waitcnt lgkmcnt(0)
	v_add_f32_e32 v36, v40, v36
	v_add_f32_e32 v37, v41, v37
	v_add_f32_e32 v34, v42, v34
	v_add_f32_e32 v35, v43, v35
	v_mul_f32_e32 v40, v36, v36
	v_mul_f32_e32 v41, v37, v37
	v_mul_f32_e32 v42, v34, v34
	v_mul_f32_e32 v43, v35, v35
	v_add_f32_e32 v40, v40, v41
	v_lshlrev_b32_e32 v0, 10, v132
	v_add_f32_e32 v40, v42, v40
	v_add_f32_e32 v40, v43, v40
	v_cndmask_b32_e64 v11, v39, v11, s[34:35]
	v_cndmask_b32_e64 v10, v38, v10, s[34:35]
	v_lshlrev_b32_e32 v0, 1, v0
	v_cvt_pk_bf16_f32 v36, v36, v37
	v_cvt_pk_bf16_f32 v37, v34, v35
	v_lshl_add_u64 v[34:35], v[10:11], 0, v[0:1]
	s_nop 1
	v_mov_b32_dpp v0, v40 quad_perm:[1,0,3,2] row_mask:0xf bank_mask:0xf
	global_store_dwordx2 v[34:35], v[36:37], off
	v_lshl_add_u64 v[4:5], v[4:5], 2, s[0:1]
	s_waitcnt lgkmcnt(0)
	v_add_f32_e32 v0, v40, v0
	s_nop 1
	v_mov_b32_dpp v34, v0 quad_perm:[2,3,0,1] row_mask:0xf bank_mask:0xf
	s_waitcnt lgkmcnt(0)
	v_add_f32_e32 v0, v0, v34
	s_nop 1
	v_mov_b32_dpp v34, v0 row_half_mirror row_mask:0xf bank_mask:0xf
	s_waitcnt lgkmcnt(0)
	v_add_f32_e32 v0, v0, v34
	s_nop 1
	v_mov_b32_dpp v34, v0 row_mirror row_mask:0xf bank_mask:0xf
	v_add_f32_e32 v146, v0, v34
	v_cmp_eq_u32_e64 s[2:3], 1, v180
	s_nop 1
	v_cndmask_b32_e64 v147, v147, v146, s[2:3]
.LBB0_443:
	s_waitcnt lgkmcnt(0)
	ds_read_b128 v[34:37], v69 offset:2176
	v_lshlrev_b32_e32 v38, 16, v32
	v_and_b32_e32 v39, 0xffff0000, v32
	v_lshlrev_b32_e32 v32, 16, v33
	v_and_b32_e32 v33, 0xffff0000, v33
	s_waitcnt lgkmcnt(0)
	v_add_f32_e32 v34, v34, v38
	v_add_f32_e32 v35, v35, v39
	v_add_f32_e32 v32, v36, v32
	v_add_f32_e32 v33, v37, v33
	v_mul_f32_e32 v36, v34, v34
	v_mul_f32_e32 v37, v35, v35
	v_mul_f32_e32 v38, v32, v32
	v_mul_f32_e32 v39, v33, v33
	v_add_f32_e32 v36, v36, v37
	v_lshlrev_b32_e32 v0, 10, v130
	v_add_f32_e32 v36, v38, v36
	v_add_f32_e32 v36, v39, v36
	v_lshlrev_b32_e32 v0, 1, v0
	v_cvt_pk_bf16_f32 v34, v34, v35
	v_cvt_pk_bf16_f32 v35, v32, v33
	v_lshl_add_u64 v[32:33], v[10:11], 0, v[0:1]
	s_nop 1
	v_mov_b32_dpp v0, v36 quad_perm:[1,0,3,2] row_mask:0xf bank_mask:0xf
	global_store_dwordx2 v[32:33], v[34:35], off
	s_waitcnt lgkmcnt(0)
	v_add_f32_e32 v0, v36, v0
	s_nop 1
	v_mov_b32_dpp v32, v0 quad_perm:[2,3,0,1] row_mask:0xf bank_mask:0xf
	s_waitcnt lgkmcnt(0)
	v_add_f32_e32 v0, v0, v32
	s_nop 1
	v_mov_b32_dpp v32, v0 row_half_mirror row_mask:0xf bank_mask:0xf
	s_waitcnt lgkmcnt(0)
	v_add_f32_e32 v0, v0, v32
	s_nop 1
	v_mov_b32_dpp v32, v0 row_mirror row_mask:0xf bank_mask:0xf
	v_add_f32_e32 v146, v0, v32
	v_cmp_eq_u32_e64 s[2:3], 2, v180
	s_nop 1
	v_cndmask_b32_e64 v147, v147, v146, s[2:3]
.LBB0_445:
	s_waitcnt lgkmcnt(0)
	ds_read_b128 v[32:35], v69 offset:3264
	v_lshlrev_b32_e32 v36, 16, v30
	v_and_b32_e32 v37, 0xffff0000, v30
	v_lshlrev_b32_e32 v30, 16, v31
	v_and_b32_e32 v31, 0xffff0000, v31
	s_waitcnt lgkmcnt(0)
	v_add_f32_e32 v32, v32, v36
	v_add_f32_e32 v33, v33, v37
	v_add_f32_e32 v30, v34, v30
	v_add_f32_e32 v31, v35, v31
	v_mul_f32_e32 v34, v32, v32
	v_mul_f32_e32 v35, v33, v33
	v_mul_f32_e32 v36, v30, v30
	v_mul_f32_e32 v37, v31, v31
	v_add_f32_e32 v34, v34, v35
	v_lshlrev_b32_e32 v0, 10, v128
	v_add_f32_e32 v34, v36, v34
	v_add_f32_e32 v34, v37, v34
	v_lshlrev_b32_e32 v0, 1, v0
	v_cvt_pk_bf16_f32 v32, v32, v33
	v_cvt_pk_bf16_f32 v33, v30, v31
	v_lshl_add_u64 v[30:31], v[10:11], 0, v[0:1]
	s_nop 1
	v_mov_b32_dpp v0, v34 quad_perm:[1,0,3,2] row_mask:0xf bank_mask:0xf
	global_store_dwordx2 v[30:31], v[32:33], off
	s_waitcnt lgkmcnt(0)
	v_add_f32_e32 v0, v34, v0
	s_nop 1
	v_mov_b32_dpp v30, v0 quad_perm:[2,3,0,1] row_mask:0xf bank_mask:0xf
	s_waitcnt lgkmcnt(0)
	v_add_f32_e32 v0, v0, v30
	s_nop 1
	v_mov_b32_dpp v30, v0 row_half_mirror row_mask:0xf bank_mask:0xf
	s_waitcnt lgkmcnt(0)
	v_add_f32_e32 v0, v0, v30
	s_nop 1
	v_mov_b32_dpp v30, v0 row_mirror row_mask:0xf bank_mask:0xf
	v_add_f32_e32 v146, v0, v30
	v_cmp_eq_u32_e64 s[2:3], 3, v180
	s_nop 1
	v_cndmask_b32_e64 v147, v147, v146, s[2:3]
.LBB0_447:
	s_waitcnt lgkmcnt(0)
	ds_read_b128 v[30:33], v69 offset:4352
	v_lshlrev_b32_e32 v34, 16, v28
	v_and_b32_e32 v35, 0xffff0000, v28
	v_lshlrev_b32_e32 v28, 16, v29
	v_and_b32_e32 v29, 0xffff0000, v29
	s_waitcnt lgkmcnt(0)
	v_add_f32_e32 v30, v30, v34
	v_add_f32_e32 v31, v31, v35
	v_add_f32_e32 v28, v32, v28
	v_add_f32_e32 v29, v33, v29
	v_mul_f32_e32 v32, v30, v30
	v_mul_f32_e32 v33, v31, v31
	v_mul_f32_e32 v34, v28, v28
	v_mul_f32_e32 v35, v29, v29
	v_add_f32_e32 v32, v32, v33
	v_lshlrev_b32_e32 v0, 10, v126
	v_add_f32_e32 v32, v34, v32
	v_add_f32_e32 v32, v35, v32
	v_lshlrev_b32_e32 v0, 1, v0
	v_cvt_pk_bf16_f32 v30, v30, v31
	v_cvt_pk_bf16_f32 v31, v28, v29
	v_lshl_add_u64 v[28:29], v[10:11], 0, v[0:1]
	s_nop 1
	v_mov_b32_dpp v0, v32 quad_perm:[1,0,3,2] row_mask:0xf bank_mask:0xf
	global_store_dwordx2 v[28:29], v[30:31], off
	s_waitcnt lgkmcnt(0)
	v_add_f32_e32 v0, v32, v0
	s_nop 1
	v_mov_b32_dpp v28, v0 quad_perm:[2,3,0,1] row_mask:0xf bank_mask:0xf
	s_waitcnt lgkmcnt(0)
	v_add_f32_e32 v0, v0, v28
	s_nop 1
	v_mov_b32_dpp v28, v0 row_half_mirror row_mask:0xf bank_mask:0xf
	s_waitcnt lgkmcnt(0)
	v_add_f32_e32 v0, v0, v28
	s_nop 1
	v_mov_b32_dpp v28, v0 row_mirror row_mask:0xf bank_mask:0xf
	v_add_f32_e32 v146, v0, v28
	v_cmp_eq_u32_e64 s[2:3], 4, v180
	s_nop 1
	v_cndmask_b32_e64 v147, v147, v146, s[2:3]
; DI float bflo(unsigned v) { return __uint_as_float(v << 16); }
; DI float bfhi(unsigned v) { return __uint_as_float(v & 0xffff0000u); }
; template <int EPI>
; DI void gemm_tile(const Params& p, int layer, int mt, int nt, u16* sm, int wv) {
;     ...
;       for (int t = 0; t < 16; ++t) {
;         const int row = (lane >> 4) + 4 * t;
;         const f32x4 a4 = *(const f32x4*)(stg + row * 68 + kc * 4);
;         const float v0 = bflo(xb[t][0]) + a4[0], v1 = bfhi(xb[t][0]) + a4[1], v2 = bflo(xb[t][1]) + a4[2], v3 = bfhi(xb[t][1]) + a4[3];
;         float sq = v0 * v0 + v1 * v1 + v2 * v2 + v3 * v3;
;         u32x2 pv = {pk2(v0, v1), pk2(v2, v3)};
;         if (has_next) *(u32x2*)(xrow + (size_t)row * DM) = pv;
;         else *(u32x2*)(x2row + (size_t)row * DM) = pv;
;         sq += shx(sq, lane, 1); sq += shx(sq, lane, 2); sq += shx(sq, lane, 4); sq += shx(sq, lane, 8);
;         if (kc == 0) atomicAdd(ssn + mrow0 + row, sq);
.LBB0_449:
	s_waitcnt lgkmcnt(0)
	ds_read_b128 v[28:31], v69 offset:5440
	v_lshlrev_b32_e32 v32, 16, v26
	v_and_b32_e32 v33, 0xffff0000, v26
	v_lshlrev_b32_e32 v26, 16, v27
	v_and_b32_e32 v27, 0xffff0000, v27
	s_waitcnt lgkmcnt(0)
	v_add_f32_e32 v28, v28, v32
	v_add_f32_e32 v29, v29, v33
	v_add_f32_e32 v26, v30, v26
	v_add_f32_e32 v27, v31, v27
	v_mul_f32_e32 v30, v28, v28
	v_mul_f32_e32 v31, v29, v29
	v_mul_f32_e32 v32, v26, v26
	v_mul_f32_e32 v33, v27, v27
	v_add_f32_e32 v30, v30, v31
	v_lshlrev_b32_e32 v0, 10, v124
	v_add_f32_e32 v30, v32, v30
	v_add_f32_e32 v30, v33, v30
	v_lshlrev_b32_e32 v0, 1, v0
	v_cvt_pk_bf16_f32 v28, v28, v29
	v_cvt_pk_bf16_f32 v29, v26, v27
	v_lshl_add_u64 v[26:27], v[10:11], 0, v[0:1]
	s_nop 1
	v_mov_b32_dpp v0, v30 quad_perm:[1,0,3,2] row_mask:0xf bank_mask:0xf
	global_store_dwordx2 v[26:27], v[28:29], off
	s_waitcnt lgkmcnt(0)
	v_add_f32_e32 v0, v30, v0
	s_nop 1
	v_mov_b32_dpp v26, v0 quad_perm:[2,3,0,1] row_mask:0xf bank_mask:0xf
	s_waitcnt lgkmcnt(0)
	v_add_f32_e32 v0, v0, v26
	s_nop 1
	v_mov_b32_dpp v26, v0 row_half_mirror row_mask:0xf bank_mask:0xf
	s_waitcnt lgkmcnt(0)
	v_add_f32_e32 v0, v0, v26
	s_nop 1
	v_mov_b32_dpp v26, v0 row_mirror row_mask:0xf bank_mask:0xf
	v_add_f32_e32 v146, v0, v26
	v_cmp_eq_u32_e64 s[2:3], 5, v180
	s_nop 1
	v_cndmask_b32_e64 v147, v147, v146, s[2:3]
.LBB0_451:
	s_waitcnt lgkmcnt(0)
	ds_read_b128 v[26:29], v69 offset:6528
	v_lshlrev_b32_e32 v30, 16, v24
	v_and_b32_e32 v31, 0xffff0000, v24
	v_lshlrev_b32_e32 v24, 16, v25
	v_and_b32_e32 v25, 0xffff0000, v25
	s_waitcnt lgkmcnt(0)
	v_add_f32_e32 v26, v26, v30
	v_add_f32_e32 v27, v27, v31
	v_add_f32_e32 v24, v28, v24
	v_add_f32_e32 v25, v29, v25
	v_mul_f32_e32 v28, v26, v26
	v_mul_f32_e32 v29, v27, v27
	v_mul_f32_e32 v30, v24, v24
	v_mul_f32_e32 v31, v25, v25
	v_add_f32_e32 v28, v28, v29
	v_lshlrev_b32_e32 v0, 10, v122
	v_add_f32_e32 v28, v30, v28
	v_add_f32_e32 v28, v31, v28
	v_lshlrev_b32_e32 v0, 1, v0
	v_cvt_pk_bf16_f32 v26, v26, v27
	v_cvt_pk_bf16_f32 v27, v24, v25
	v_lshl_add_u64 v[24:25], v[10:11], 0, v[0:1]
	s_nop 1
	v_mov_b32_dpp v0, v28 quad_perm:[1,0,3,2] row_mask:0xf bank_mask:0xf
	global_store_dwordx2 v[24:25], v[26:27], off
	s_waitcnt lgkmcnt(0)
	v_add_f32_e32 v0, v28, v0
	s_nop 1
	v_mov_b32_dpp v24, v0 quad_perm:[2,3,0,1] row_mask:0xf bank_mask:0xf
	s_waitcnt lgkmcnt(0)
	v_add_f32_e32 v0, v0, v24
	s_nop 1
	v_mov_b32_dpp v24, v0 row_half_mirror row_mask:0xf bank_mask:0xf
	s_waitcnt lgkmcnt(0)
	v_add_f32_e32 v0, v0, v24
	s_nop 1
	v_mov_b32_dpp v24, v0 row_mirror row_mask:0xf bank_mask:0xf
	v_add_f32_e32 v146, v0, v24
	v_cmp_eq_u32_e64 s[2:3], 6, v180
	s_nop 1
	v_cndmask_b32_e64 v147, v147, v146, s[2:3]
.LBB0_453:
	s_waitcnt lgkmcnt(0)
	ds_read_b128 v[24:27], v69 offset:7616
	v_lshlrev_b32_e32 v28, 16, v22
	v_and_b32_e32 v29, 0xffff0000, v22
	v_lshlrev_b32_e32 v22, 16, v23
	v_and_b32_e32 v23, 0xffff0000, v23
	s_waitcnt lgkmcnt(0)
	v_add_f32_e32 v24, v24, v28
	v_add_f32_e32 v25, v25, v29
	v_add_f32_e32 v22, v26, v22
	v_add_f32_e32 v23, v27, v23
	v_mul_f32_e32 v26, v24, v24
	v_mul_f32_e32 v27, v25, v25
	v_mul_f32_e32 v28, v22, v22
	v_mul_f32_e32 v29, v23, v23
	v_add_f32_e32 v26, v26, v27
	v_lshlrev_b32_e32 v0, 10, v120
	v_add_f32_e32 v26, v28, v26
	v_add_f32_e32 v26, v29, v26
	v_lshlrev_b32_e32 v0, 1, v0
	v_cvt_pk_bf16_f32 v24, v24, v25
	v_cvt_pk_bf16_f32 v25, v22, v23
	v_lshl_add_u64 v[22:23], v[10:11], 0, v[0:1]
	s_nop 1
	v_mov_b32_dpp v0, v26 quad_perm:[1,0,3,2] row_mask:0xf bank_mask:0xf
	global_store_dwordx2 v[22:23], v[24:25], off
	s_waitcnt lgkmcnt(0)
	v_add_f32_e32 v0, v26, v0
	s_nop 1
	v_mov_b32_dpp v22, v0 quad_perm:[2,3,0,1] row_mask:0xf bank_mask:0xf
	s_waitcnt lgkmcnt(0)
	v_add_f32_e32 v0, v0, v22
	s_nop 1
	v_mov_b32_dpp v22, v0 row_half_mirror row_mask:0xf bank_mask:0xf
	s_waitcnt lgkmcnt(0)
	v_add_f32_e32 v0, v0, v22
	s_nop 1
	v_mov_b32_dpp v22, v0 row_mirror row_mask:0xf bank_mask:0xf
	v_add_f32_e32 v146, v0, v22
	v_cmp_eq_u32_e64 s[2:3], 7, v180
	s_nop 1
	v_cndmask_b32_e64 v147, v147, v146, s[2:3]
.LBB0_455:
	s_waitcnt lgkmcnt(0)
	ds_read_b128 v[22:25], v69 offset:8704
	v_lshlrev_b32_e32 v26, 16, v20
	v_and_b32_e32 v27, 0xffff0000, v20
	v_lshlrev_b32_e32 v20, 16, v21
	v_and_b32_e32 v21, 0xffff0000, v21
	s_waitcnt lgkmcnt(0)
	v_add_f32_e32 v22, v22, v26
	v_add_f32_e32 v23, v23, v27
	v_add_f32_e32 v20, v24, v20
	v_add_f32_e32 v21, v25, v21
	v_mul_f32_e32 v24, v22, v22
	v_mul_f32_e32 v25, v23, v23
	v_mul_f32_e32 v26, v20, v20
	v_mul_f32_e32 v27, v21, v21
	v_add_f32_e32 v24, v24, v25
	v_lshlrev_b32_e32 v0, 10, v118
	v_add_f32_e32 v24, v26, v24
	v_add_f32_e32 v24, v27, v24
	v_lshlrev_b32_e32 v0, 1, v0
	v_cvt_pk_bf16_f32 v22, v22, v23
	v_cvt_pk_bf16_f32 v23, v20, v21
	v_lshl_add_u64 v[20:21], v[10:11], 0, v[0:1]
	s_nop 1
	v_mov_b32_dpp v0, v24 quad_perm:[1,0,3,2] row_mask:0xf bank_mask:0xf
	global_store_dwordx2 v[20:21], v[22:23], off
	s_waitcnt lgkmcnt(0)
	v_add_f32_e32 v0, v24, v0
	s_nop 1
	v_mov_b32_dpp v20, v0 quad_perm:[2,3,0,1] row_mask:0xf bank_mask:0xf
	s_waitcnt lgkmcnt(0)
	v_add_f32_e32 v0, v0, v20
	s_nop 1
	v_mov_b32_dpp v20, v0 row_half_mirror row_mask:0xf bank_mask:0xf
	s_waitcnt lgkmcnt(0)
	v_add_f32_e32 v0, v0, v20
	s_nop 1
	v_mov_b32_dpp v20, v0 row_mirror row_mask:0xf bank_mask:0xf
	v_add_f32_e32 v146, v0, v20
	v_cmp_eq_u32_e64 s[2:3], 8, v180
	s_nop 1
	v_cndmask_b32_e64 v147, v147, v146, s[2:3]
; DI float bflo(unsigned v) { return __uint_as_float(v << 16); }
; DI float bfhi(unsigned v) { return __uint_as_float(v & 0xffff0000u); }
; template <int EPI>
; DI void gemm_tile(const Params& p, int layer, int mt, int nt, u16* sm, int wv) {
;     ...
;       for (int t = 0; t < 16; ++t) {
;         const int row = (lane >> 4) + 4 * t;
;         const f32x4 a4 = *(const f32x4*)(stg + row * 68 + kc * 4);
;         const float v0 = bflo(xb[t][0]) + a4[0], v1 = bfhi(xb[t][0]) + a4[1], v2 = bflo(xb[t][1]) + a4[2], v3 = bfhi(xb[t][1]) + a4[3];
;         float sq = v0 * v0 + v1 * v1 + v2 * v2 + v3 * v3;
;         u32x2 pv = {pk2(v0, v1), pk2(v2, v3)};
;         if (has_next) *(u32x2*)(xrow + (size_t)row * DM) = pv;
;         else *(u32x2*)(x2row + (size_t)row * DM) = pv;
;         sq += shx(sq, lane, 1); sq += shx(sq, lane, 2); sq += shx(sq, lane, 4); sq += shx(sq, lane, 8);
;         if (kc == 0) atomicAdd(ssn + mrow0 + row, sq);
.LBB0_457:
	s_waitcnt lgkmcnt(0)
	ds_read_b128 v[20:23], v69 offset:9792
	v_lshlrev_b32_e32 v24, 16, v18
	v_and_b32_e32 v25, 0xffff0000, v18
	v_lshlrev_b32_e32 v18, 16, v19
	v_and_b32_e32 v19, 0xffff0000, v19
	s_waitcnt lgkmcnt(0)
	v_add_f32_e32 v20, v20, v24
	v_add_f32_e32 v21, v21, v25
	v_add_f32_e32 v18, v22, v18
	v_add_f32_e32 v19, v23, v19
	v_mul_f32_e32 v22, v20, v20
	v_mul_f32_e32 v23, v21, v21
	v_mul_f32_e32 v24, v18, v18
	v_mul_f32_e32 v25, v19, v19
	v_add_f32_e32 v22, v22, v23
	v_lshlrev_b32_e32 v0, 10, v116
	v_add_f32_e32 v22, v24, v22
	v_add_f32_e32 v22, v25, v22
	v_lshlrev_b32_e32 v0, 1, v0
	v_cvt_pk_bf16_f32 v20, v20, v21
	v_cvt_pk_bf16_f32 v21, v18, v19
	v_lshl_add_u64 v[18:19], v[10:11], 0, v[0:1]
	s_nop 1
	v_mov_b32_dpp v0, v22 quad_perm:[1,0,3,2] row_mask:0xf bank_mask:0xf
	global_store_dwordx2 v[18:19], v[20:21], off
	s_waitcnt lgkmcnt(0)
	v_add_f32_e32 v0, v22, v0
	s_nop 1
	v_mov_b32_dpp v18, v0 quad_perm:[2,3,0,1] row_mask:0xf bank_mask:0xf
	s_waitcnt lgkmcnt(0)
	v_add_f32_e32 v0, v0, v18
	s_nop 1
	v_mov_b32_dpp v18, v0 row_half_mirror row_mask:0xf bank_mask:0xf
	s_waitcnt lgkmcnt(0)
	v_add_f32_e32 v0, v0, v18
	s_nop 1
	v_mov_b32_dpp v18, v0 row_mirror row_mask:0xf bank_mask:0xf
	v_add_f32_e32 v146, v0, v18
	v_cmp_eq_u32_e64 s[2:3], 9, v180
	s_nop 1
	v_cndmask_b32_e64 v147, v147, v146, s[2:3]
.LBB0_459:
	s_waitcnt lgkmcnt(0)
	ds_read_b128 v[18:21], v69 offset:10880
	v_lshlrev_b32_e32 v22, 16, v16
	v_and_b32_e32 v23, 0xffff0000, v16
	v_lshlrev_b32_e32 v16, 16, v17
	v_and_b32_e32 v17, 0xffff0000, v17
	s_waitcnt lgkmcnt(0)
	v_add_f32_e32 v18, v18, v22
	v_add_f32_e32 v19, v19, v23
	v_add_f32_e32 v16, v20, v16
	v_add_f32_e32 v17, v21, v17
	v_mul_f32_e32 v20, v18, v18
	v_mul_f32_e32 v21, v19, v19
	v_mul_f32_e32 v22, v16, v16
	v_mul_f32_e32 v23, v17, v17
	v_add_f32_e32 v20, v20, v21
	v_lshlrev_b32_e32 v0, 10, v114
	v_add_f32_e32 v20, v22, v20
	v_add_f32_e32 v20, v23, v20
	v_lshlrev_b32_e32 v0, 1, v0
	v_cvt_pk_bf16_f32 v18, v18, v19
	v_cvt_pk_bf16_f32 v19, v16, v17
	v_lshl_add_u64 v[16:17], v[10:11], 0, v[0:1]
	s_nop 1
	v_mov_b32_dpp v0, v20 quad_perm:[1,0,3,2] row_mask:0xf bank_mask:0xf
	global_store_dwordx2 v[16:17], v[18:19], off
	s_waitcnt lgkmcnt(0)
	v_add_f32_e32 v0, v20, v0
	s_nop 1
	v_mov_b32_dpp v16, v0 quad_perm:[2,3,0,1] row_mask:0xf bank_mask:0xf
	s_waitcnt lgkmcnt(0)
	v_add_f32_e32 v0, v0, v16
	s_nop 1
	v_mov_b32_dpp v16, v0 row_half_mirror row_mask:0xf bank_mask:0xf
	s_waitcnt lgkmcnt(0)
	v_add_f32_e32 v0, v0, v16
	s_nop 1
	v_mov_b32_dpp v16, v0 row_mirror row_mask:0xf bank_mask:0xf
	v_add_f32_e32 v146, v0, v16
	v_cmp_eq_u32_e64 s[2:3], 10, v180
	s_nop 1
	v_cndmask_b32_e64 v147, v147, v146, s[2:3]
.LBB0_461:
	s_waitcnt lgkmcnt(0)
	ds_read_b128 v[16:19], v69 offset:11968
	v_lshlrev_b32_e32 v20, 16, v14
	v_and_b32_e32 v21, 0xffff0000, v14
	v_lshlrev_b32_e32 v14, 16, v15
	v_and_b32_e32 v15, 0xffff0000, v15
	s_waitcnt lgkmcnt(0)
	v_add_f32_e32 v16, v16, v20
	v_add_f32_e32 v17, v17, v21
	v_add_f32_e32 v14, v18, v14
	v_add_f32_e32 v15, v19, v15
	v_mul_f32_e32 v18, v16, v16
	v_mul_f32_e32 v19, v17, v17
	v_mul_f32_e32 v20, v14, v14
	v_mul_f32_e32 v21, v15, v15
	v_add_f32_e32 v18, v18, v19
	v_lshlrev_b32_e32 v0, 10, v112
	v_add_f32_e32 v18, v20, v18
	v_add_f32_e32 v18, v21, v18
	v_lshlrev_b32_e32 v0, 1, v0
	v_cvt_pk_bf16_f32 v16, v16, v17
	v_cvt_pk_bf16_f32 v17, v14, v15
	v_lshl_add_u64 v[14:15], v[10:11], 0, v[0:1]
	s_nop 1
	v_mov_b32_dpp v0, v18 quad_perm:[1,0,3,2] row_mask:0xf bank_mask:0xf
	global_store_dwordx2 v[14:15], v[16:17], off
	s_waitcnt lgkmcnt(0)
	v_add_f32_e32 v0, v18, v0
	s_nop 1
	v_mov_b32_dpp v14, v0 quad_perm:[2,3,0,1] row_mask:0xf bank_mask:0xf
	s_waitcnt lgkmcnt(0)
	v_add_f32_e32 v0, v0, v14
	s_nop 1
	v_mov_b32_dpp v14, v0 row_half_mirror row_mask:0xf bank_mask:0xf
	s_waitcnt lgkmcnt(0)
	v_add_f32_e32 v0, v0, v14
	s_nop 1
	v_mov_b32_dpp v14, v0 row_mirror row_mask:0xf bank_mask:0xf
	v_add_f32_e32 v146, v0, v14
	v_cmp_eq_u32_e64 s[2:3], 11, v180
	s_nop 1
	v_cndmask_b32_e64 v147, v147, v146, s[2:3]
.LBB0_463:
	s_waitcnt lgkmcnt(0)
	ds_read_b128 v[14:17], v69 offset:13056
	s_waitcnt vmcnt(14)
	v_lshlrev_b32_e32 v18, 16, v12
	v_and_b32_e32 v19, 0xffff0000, v12
	v_lshlrev_b32_e32 v12, 16, v13
	v_and_b32_e32 v13, 0xffff0000, v13
	s_waitcnt lgkmcnt(0)
	v_add_f32_e32 v14, v14, v18
	v_add_f32_e32 v15, v15, v19
	v_add_f32_e32 v12, v16, v12
	v_add_f32_e32 v13, v17, v13
	v_mul_f32_e32 v16, v14, v14
	v_mul_f32_e32 v17, v15, v15
	v_mul_f32_e32 v18, v12, v12
	v_mul_f32_e32 v19, v13, v13
	v_add_f32_e32 v16, v16, v17
	v_lshlrev_b32_e32 v0, 10, v108
	v_add_f32_e32 v16, v18, v16
	v_add_f32_e32 v16, v19, v16
	v_lshlrev_b32_e32 v0, 1, v0
	v_cvt_pk_bf16_f32 v14, v14, v15
	v_cvt_pk_bf16_f32 v15, v12, v13
	v_lshl_add_u64 v[12:13], v[10:11], 0, v[0:1]
	s_nop 1
	v_mov_b32_dpp v0, v16 quad_perm:[1,0,3,2] row_mask:0xf bank_mask:0xf
	global_store_dwordx2 v[12:13], v[14:15], off
	s_waitcnt lgkmcnt(0)
	v_add_f32_e32 v0, v16, v0
	s_nop 1
	v_mov_b32_dpp v12, v0 quad_perm:[2,3,0,1] row_mask:0xf bank_mask:0xf
	s_waitcnt lgkmcnt(0)
	v_add_f32_e32 v0, v0, v12
	s_nop 1
	v_mov_b32_dpp v12, v0 row_half_mirror row_mask:0xf bank_mask:0xf
	s_waitcnt lgkmcnt(0)
	v_add_f32_e32 v0, v0, v12
	s_nop 1
	v_mov_b32_dpp v12, v0 row_mirror row_mask:0xf bank_mask:0xf
	v_add_f32_e32 v146, v0, v12
	v_cmp_eq_u32_e64 s[2:3], 12, v180
	s_nop 1
	v_cndmask_b32_e64 v147, v147, v146, s[2:3]
; DI float bflo(unsigned v) { return __uint_as_float(v << 16); }
; DI float bfhi(unsigned v) { return __uint_as_float(v & 0xffff0000u); }
; template <int EPI>
; DI void gemm_tile(const Params& p, int layer, int mt, int nt, u16* sm, int wv) {
;     ...
;       for (int t = 0; t < 16; ++t) {
;         const int row = (lane >> 4) + 4 * t;
;         const f32x4 a4 = *(const f32x4*)(stg + row * 68 + kc * 4);
;         const float v0 = bflo(xb[t][0]) + a4[0], v1 = bfhi(xb[t][0]) + a4[1], v2 = bflo(xb[t][1]) + a4[2], v3 = bfhi(xb[t][1]) + a4[3];
;         float sq = v0 * v0 + v1 * v1 + v2 * v2 + v3 * v3;
;         u32x2 pv = {pk2(v0, v1), pk2(v2, v3)};
;         if (has_next) *(u32x2*)(xrow + (size_t)row * DM) = pv;
;         else *(u32x2*)(x2row + (size_t)row * DM) = pv;
;         sq += shx(sq, lane, 1); sq += shx(sq, lane, 2); sq += shx(sq, lane, 4); sq += shx(sq, lane, 8);
;         if (kc == 0) atomicAdd(ssn + mrow0 + row, sq);
.LBB0_465:
	s_waitcnt lgkmcnt(0)
	ds_read_b128 v[12:15], v69 offset:14144
	s_waitcnt vmcnt(14)
	v_lshlrev_b32_e32 v16, 16, v8
	v_and_b32_e32 v17, 0xffff0000, v8
	v_lshlrev_b32_e32 v8, 16, v9
	v_and_b32_e32 v9, 0xffff0000, v9
	s_waitcnt lgkmcnt(0)
	v_add_f32_e32 v12, v12, v16
	v_add_f32_e32 v13, v13, v17
	v_add_f32_e32 v8, v14, v8
	v_add_f32_e32 v9, v15, v9
	v_mul_f32_e32 v14, v12, v12
	v_mul_f32_e32 v15, v13, v13
	v_mul_f32_e32 v16, v8, v8
	v_mul_f32_e32 v17, v9, v9
	v_add_f32_e32 v14, v14, v15
	v_lshlrev_b32_e32 v0, 10, v106
	v_add_f32_e32 v14, v16, v14
	v_add_f32_e32 v14, v17, v14
	v_lshlrev_b32_e32 v0, 1, v0
	v_cvt_pk_bf16_f32 v12, v12, v13
	v_cvt_pk_bf16_f32 v13, v8, v9
	v_lshl_add_u64 v[8:9], v[10:11], 0, v[0:1]
	s_nop 1
	v_mov_b32_dpp v0, v14 quad_perm:[1,0,3,2] row_mask:0xf bank_mask:0xf
	global_store_dwordx2 v[8:9], v[12:13], off
	s_waitcnt lgkmcnt(0)
	v_add_f32_e32 v0, v14, v0
	s_nop 1
	v_mov_b32_dpp v8, v0 quad_perm:[2,3,0,1] row_mask:0xf bank_mask:0xf
	s_waitcnt lgkmcnt(0)
	v_add_f32_e32 v0, v0, v8
	s_nop 1
	v_mov_b32_dpp v8, v0 row_half_mirror row_mask:0xf bank_mask:0xf
	s_waitcnt lgkmcnt(0)
	v_add_f32_e32 v0, v0, v8
	s_nop 1
	v_mov_b32_dpp v8, v0 row_mirror row_mask:0xf bank_mask:0xf
	v_add_f32_e32 v146, v0, v8
	v_cmp_eq_u32_e64 s[2:3], 13, v180
	s_nop 1
	v_cndmask_b32_e64 v147, v147, v146, s[2:3]
.LBB0_467:
	ds_read_b128 v[12:15], v69 offset:15232
	s_waitcnt vmcnt(14) lgkmcnt(1)
	v_lshlrev_b32_e32 v8, 16, v6
	v_and_b32_e32 v9, 0xffff0000, v6
	v_lshlrev_b32_e32 v6, 16, v7
	v_and_b32_e32 v7, 0xffff0000, v7
	s_waitcnt lgkmcnt(0)
	v_add_f32_e32 v8, v12, v8
	v_add_f32_e32 v9, v13, v9
	v_add_f32_e32 v6, v14, v6
	v_add_f32_e32 v7, v15, v7
	v_mul_f32_e32 v12, v8, v8
	v_mul_f32_e32 v13, v9, v9
	v_mul_f32_e32 v14, v6, v6
	v_mul_f32_e32 v15, v7, v7
	v_add_f32_e32 v12, v12, v13
	v_lshlrev_b32_e32 v0, 10, v103
	v_add_f32_e32 v12, v14, v12
	v_add_f32_e32 v12, v15, v12
	v_lshlrev_b32_e32 v0, 1, v0
	v_cvt_pk_bf16_f32 v8, v8, v9
	v_cvt_pk_bf16_f32 v9, v6, v7
	v_lshl_add_u64 v[6:7], v[10:11], 0, v[0:1]
	s_nop 1
	v_mov_b32_dpp v0, v12 quad_perm:[1,0,3,2] row_mask:0xf bank_mask:0xf
	global_store_dwordx2 v[6:7], v[8:9], off
	s_waitcnt lgkmcnt(0)
	v_add_f32_e32 v0, v12, v0
	s_nop 1
	v_mov_b32_dpp v6, v0 quad_perm:[2,3,0,1] row_mask:0xf bank_mask:0xf
	s_waitcnt lgkmcnt(0)
	v_add_f32_e32 v0, v0, v6
	s_nop 1
	v_mov_b32_dpp v6, v0 row_half_mirror row_mask:0xf bank_mask:0xf
	s_waitcnt lgkmcnt(0)
	v_add_f32_e32 v0, v0, v6
	s_nop 1
	v_mov_b32_dpp v6, v0 row_mirror row_mask:0xf bank_mask:0xf
	v_add_f32_e32 v146, v0, v6
	v_cmp_eq_u32_e64 s[2:3], 14, v180
	s_nop 1
	v_cndmask_b32_e64 v147, v147, v146, s[2:3]
.LBB0_469:
	s_waitcnt lgkmcnt(0)
	ds_read_b128 v[6:9], v69 offset:16320
	s_waitcnt vmcnt(14)
	v_lshlrev_b32_e32 v12, 16, v2
	v_and_b32_e32 v13, 0xffff0000, v2
	v_lshlrev_b32_e32 v2, 16, v3
	v_and_b32_e32 v3, 0xffff0000, v3
	s_waitcnt lgkmcnt(0)
	v_add_f32_e32 v6, v6, v12
	v_add_f32_e32 v7, v7, v13
	v_add_f32_e32 v2, v8, v2
	v_add_f32_e32 v3, v9, v3
	v_mul_f32_e32 v8, v6, v6
	v_mul_f32_e32 v9, v7, v7
	v_mul_f32_e32 v12, v2, v2
	v_mul_f32_e32 v13, v3, v3
	v_add_f32_e32 v8, v8, v9
	v_lshlrev_b32_e32 v0, 10, v102
	v_add_f32_e32 v8, v12, v8
	v_add_f32_e32 v8, v13, v8
	v_lshlrev_b32_e32 v0, 1, v0
	v_cvt_pk_bf16_f32 v6, v6, v7
	v_cvt_pk_bf16_f32 v7, v2, v3
	v_lshl_add_u64 v[2:3], v[10:11], 0, v[0:1]
	s_nop 1
	v_mov_b32_dpp v0, v8 quad_perm:[1,0,3,2] row_mask:0xf bank_mask:0xf
	global_store_dwordx2 v[2:3], v[6:7], off
	s_waitcnt lgkmcnt(0)
	v_add_f32_e32 v0, v8, v0
	s_nop 1
	v_mov_b32_dpp v2, v0 quad_perm:[2,3,0,1] row_mask:0xf bank_mask:0xf
	s_waitcnt lgkmcnt(0)
	v_add_f32_e32 v0, v0, v2
	s_nop 1
	v_mov_b32_dpp v2, v0 row_half_mirror row_mask:0xf bank_mask:0xf
	s_waitcnt lgkmcnt(0)
	v_add_f32_e32 v0, v0, v2
	s_nop 1
	v_mov_b32_dpp v2, v0 row_mirror row_mask:0xf bank_mask:0xf
	v_add_f32_e32 v146, v0, v2
	v_cmp_eq_u32_e64 s[2:3], 15, v180
	s_nop 1
	v_cndmask_b32_e64 v147, v147, v146, s[2:3]
	v_lshl_add_u32 v148, v180, 4, v66
	v_mov_b32_e32 v149, v1
	v_lshl_add_u64 v[148:149], v[4:5], 0, v[148:149]
	global_atomic_add_f32 v[148:149], v147, off
	s_branch .LBB0_394

; DI float bflo(unsigned v) { return __uint_as_float(v << 16); }
; DI float bfhi(unsigned v) { return __uint_as_float(v & 0xffff0000u); }
; __global__ void __launch_bounds__(256, 2) hymba_mega(Params p) {
;     ...
;     for (int row0 = (bid * 4 + (tid >> 6)) * 4; row0 < MTOK; row0 += nb * 16) {
;       f32x4 xv[4][4];
;       float rs[4];
; #pragma unroll
;       for (int q = 0; q < 4; ++q) {
;         rs[q] = ssf[row0 + q];
; #pragma unroll
;         for (int j = 0; j < 4; ++j) {
;           const u32x2 xb = __builtin_nontemporal_load((const u32x2*)((const u16*)p.x2 + (size_t)(row0 + q) * DM + j * 256 + lane * 4));
;           xv[q][j][0] = bflo(xb[0]); xv[q][j][1] = bfhi(xb[0]); xv[q][j][2] = bflo(xb[1]); xv[q][j][3] = bfhi(xb[1]);
;         }
;       }
; #pragma unroll
;       for (int q = 0; q < 4; ++q) {
;         const float rq = __builtin_amdgcn_rsqf(rs[q] * (1.f / DM) + EPS);
.LBB0_524:
	global_load_dwordx4 v[16:19], v[22:23], off
	global_load_dwordx2 v[62:63], v[26:27], off offset:-4096 nt
	global_load_dwordx2 v[60:61], v[26:27], off offset:-3584 nt
	global_load_dwordx2 v[58:59], v[26:27], off offset:-3072 nt
	global_load_dwordx2 v[56:57], v[26:27], off offset:-2560 nt
	global_load_dwordx2 v[54:55], v[26:27], off offset:-2048 nt
	global_load_dwordx2 v[52:53], v[26:27], off offset:-1536 nt
	global_load_dwordx2 v[50:51], v[26:27], off offset:-1024 nt
	global_load_dwordx2 v[48:49], v[26:27], off offset:-512 nt
	global_load_dwordx2 v[46:47], v[26:27], off nt
	global_load_dwordx2 v[44:45], v[26:27], off offset:512 nt
	global_load_dwordx2 v[42:43], v[26:27], off offset:1024 nt
	global_load_dwordx2 v[36:37], v[26:27], off offset:1536 nt
	global_load_dwordx2 v[34:35], v[26:27], off offset:2048 nt
	global_load_dwordx2 v[32:33], v[26:27], off offset:2560 nt
	global_load_dwordx2 v[30:31], v[26:27], off offset:3072 nt
	global_load_dwordx2 v[28:29], v[26:27], off offset:3584 nt
	v_add_co_u32_e32 v38, vcc, s8, v24
	v_add_u32_e32 v20, s12, v20
	s_nop 0
	v_addc_co_u32_e32 v39, vcc, 0, v25, vcc
	v_add_co_u32_e32 v40, vcc, s9, v24
	v_lshl_add_u64 v[22:23], v[22:23], 0, s[0:1]
	s_nop 0
	v_addc_co_u32_e32 v41, vcc, 0, v25, vcc
	v_add_co_u32_e32 v94, vcc, s10, v24
	v_lshl_add_u64 v[26:27], v[26:27], 0, s[4:5]
	s_nop 0
	v_addc_co_u32_e32 v95, vcc, 0, v25, vcc
	v_cmp_lt_i32_e32 vcc, s11, v20
	s_or_b64 s[6:7], vcc, s[6:7]
	s_waitcnt vmcnt(16)
	v_fmamk_f32 v16, v16, 0x3a800000, v21
	v_fmamk_f32 v17, v17, 0x3a800000, v21
	v_fmamk_f32 v19, v19, 0x3a800000, v21
	v_rsq_f32_e32 v16, v16
	s_waitcnt vmcnt(15)
	v_lshlrev_b32_e32 v64, 16, v62
	v_and_b32_e32 v65, 0xffff0000, v62
	v_lshlrev_b32_e32 v62, 16, v63
	v_and_b32_e32 v63, 0xffff0000, v63
	s_waitcnt vmcnt(8)
	v_lshlrev_b32_e32 v80, 16, v48
	v_and_b32_e32 v81, 0xffff0000, v48
	v_fmamk_f32 v48, v18, 0x3a800000, v21
	v_rsq_f32_e32 v18, v17
	v_lshlrev_b32_e32 v66, 16, v60
	s_waitcnt vmcnt(3)
	v_lshlrev_b32_e32 v100, 16, v34
	v_and_b32_e32 v101, 0xffff0000, v34
	s_waitcnt vmcnt(1)
	v_lshlrev_b32_e32 v108, 16, v30
	v_and_b32_e32 v109, 0xffff0000, v30
	s_waitcnt vmcnt(0)
; __global__ void __launch_bounds__(256, 2) hymba_mega(Params p) {
;     ...
; #pragma unroll
;       for (int q = 0; q < 4; ++q) {
;         const float rq = __builtin_amdgcn_rsqf(rs[q] * (1.f / DM) + EPS);
; #pragma unroll
;         for (int j = 0; j < 4; ++j) {
;           f32x4 v = xv[q][j];
;           v[0] *= rq * gv[j][0]; v[1] *= rq * gv[j][1]; v[2] *= rq * gv[j][2]; v[3] *= rq * gv[j][3];
;           __builtin_nontemporal_store(v, (f32x4*)(p.out + (size_t)(row0 + q) * DM + j * 256 + lane * 4));
;         }
;       }
	v_lshlrev_b32_e32 v112, 16, v28
	v_and_b32_e32 v113, 0xffff0000, v28
	v_rsq_f32_e32 v28, v48
	v_rsq_f32_e32 v30, v19
	v_lshlrev_b32_e32 v102, 16, v35
	v_and_b32_e32 v103, 0xffff0000, v35
	v_lshlrev_b32_e32 v104, 16, v32
	v_and_b32_e32 v105, 0xffff0000, v32
	v_lshlrev_b32_e32 v106, 16, v33
	v_and_b32_e32 v107, 0xffff0000, v33
	v_mul_f32_e32 v32, v16, v12
	v_mul_f32_e32 v33, v16, v13
	v_mul_f32_e32 v34, v16, v14
	v_mul_f32_e32 v35, v16, v15
	v_and_b32_e32 v67, 0xffff0000, v60
	v_lshlrev_b32_e32 v60, 16, v61
	v_and_b32_e32 v61, 0xffff0000, v61
	v_lshlrev_b32_e32 v68, 16, v58
	v_and_b32_e32 v69, 0xffff0000, v58
	v_lshlrev_b32_e32 v58, 16, v59
	v_and_b32_e32 v59, 0xffff0000, v59
	v_lshlrev_b32_e32 v70, 16, v56
	v_and_b32_e32 v71, 0xffff0000, v56
	v_lshlrev_b32_e32 v56, 16, v57
	v_and_b32_e32 v57, 0xffff0000, v57
	v_lshlrev_b32_e32 v72, 16, v54
	v_and_b32_e32 v73, 0xffff0000, v54
	v_lshlrev_b32_e32 v54, 16, v55
	v_and_b32_e32 v55, 0xffff0000, v55
	v_lshlrev_b32_e32 v74, 16, v52
	v_and_b32_e32 v75, 0xffff0000, v52
	v_lshlrev_b32_e32 v52, 16, v53
	v_and_b32_e32 v53, 0xffff0000, v53
	v_lshlrev_b32_e32 v76, 16, v50
	v_and_b32_e32 v77, 0xffff0000, v50
	v_lshlrev_b32_e32 v78, 16, v51
	v_and_b32_e32 v79, 0xffff0000, v51
	v_lshlrev_b32_e32 v82, 16, v49
	v_and_b32_e32 v83, 0xffff0000, v49
	v_lshlrev_b32_e32 v84, 16, v46
	v_and_b32_e32 v85, 0xffff0000, v46
	v_lshlrev_b32_e32 v86, 16, v47
	v_and_b32_e32 v87, 0xffff0000, v47
	v_lshlrev_b32_e32 v88, 16, v44
	v_and_b32_e32 v89, 0xffff0000, v44
	v_lshlrev_b32_e32 v90, 16, v45
	v_and_b32_e32 v91, 0xffff0000, v45
	v_lshlrev_b32_e32 v92, 16, v42
	v_and_b32_e32 v93, 0xffff0000, v42
	v_lshlrev_b32_e32 v96, 16, v43
	v_and_b32_e32 v97, 0xffff0000, v43
	v_lshlrev_b32_e32 v98, 16, v36
	v_and_b32_e32 v99, 0xffff0000, v36
	v_lshlrev_b32_e32 v36, 16, v37
	v_and_b32_e32 v37, 0xffff0000, v37
	v_lshlrev_b32_e32 v110, 16, v31
	v_and_b32_e32 v111, 0xffff0000, v31
	v_lshlrev_b32_e32 v114, 16, v29
	v_and_b32_e32 v115, 0xffff0000, v29
	v_mul_f32_e32 v42, v16, v8
	v_mul_f32_e32 v43, v16, v9
	v_mul_f32_e32 v44, v16, v10
	v_mul_f32_e32 v45, v16, v11
	v_mul_f32_e32 v46, v16, v4
	v_mul_f32_e32 v47, v16, v5
	v_mul_f32_e32 v48, v16, v6
	v_mul_f32_e32 v49, v16, v7
	v_mul_f32_e32 v50, v16, v0
	v_mul_f32_e32 v51, v16, v1
	v_mul_f32_e32 v116, v16, v2
	v_mul_f32_e32 v117, v16, v3
	v_mul_f32_e32 v118, v18, v12
	v_mul_f32_e32 v119, v18, v13
	v_mul_f32_e32 v120, v18, v14
	v_mul_f32_e32 v121, v18, v15
	v_mul_f32_e32 v122, v18, v8
	v_mul_f32_e32 v123, v18, v9
	v_mul_f32_e32 v124, v18, v10
	v_mul_f32_e32 v125, v18, v11
	v_mul_f32_e32 v126, v18, v4
	v_mul_f32_e32 v127, v18, v5
	v_mul_f32_e32 v128, v18, v6
	v_mul_f32_e32 v129, v18, v7
	v_mul_f32_e32 v130, v18, v0
	v_mul_f32_e32 v131, v18, v1
	v_mul_f32_e32 v132, v18, v2
	v_mul_f32_e32 v133, v18, v3
	v_mul_f32_e32 v134, v28, v12
	v_mul_f32_e32 v135, v28, v13
	v_mul_f32_e32 v136, v28, v14
	v_mul_f32_e32 v137, v28, v15
	v_mul_f32_e32 v138, v28, v8
	v_mul_f32_e32 v139, v28, v9
	v_mul_f32_e32 v140, v28, v10
	v_mul_f32_e32 v141, v28, v11
	v_mul_f32_e32 v142, v28, v4
	v_mul_f32_e32 v143, v28, v5
	v_mul_f32_e32 v144, v28, v6
	v_mul_f32_e32 v145, v28, v7
	v_mul_f32_e32 v146, v28, v0
	v_mul_f32_e32 v147, v28, v1
	v_mul_f32_e32 v148, v28, v2
	v_mul_f32_e32 v149, v28, v3
	v_mul_f32_e32 v150, v30, v12
	v_mul_f32_e32 v151, v30, v13
	v_mul_f32_e32 v152, v30, v14
	v_mul_f32_e32 v153, v30, v15
	v_mul_f32_e32 v154, v30, v8
	v_mul_f32_e32 v155, v30, v9
	v_mul_f32_e32 v156, v30, v10
	v_mul_f32_e32 v157, v30, v11
	v_mul_f32_e32 v158, v30, v4
	v_mul_f32_e32 v159, v30, v5
	v_mul_f32_e32 v160, v30, v6
	v_mul_f32_e32 v161, v30, v7
	v_mul_f32_e32 v162, v30, v0
	v_mul_f32_e32 v163, v30, v1
	v_mul_f32_e32 v164, v30, v2
	v_mul_f32_e32 v165, v30, v3
	v_mul_f32_e32 v16, v32, v64
	v_mul_f32_e32 v17, v33, v65
	v_mul_f32_e32 v18, v34, v62
	v_mul_f32_e32 v19, v35, v63
	v_mul_f32_e32 v28, v42, v66
	v_mul_f32_e32 v29, v43, v67
	v_mul_f32_e32 v30, v44, v60
	v_mul_f32_e32 v31, v45, v61
	v_mul_f32_e32 v32, v46, v68
	v_mul_f32_e32 v33, v47, v69
	v_mul_f32_e32 v34, v48, v58
	v_mul_f32_e32 v35, v49, v59
	v_mul_f32_e32 v42, v50, v70
	v_mul_f32_e32 v43, v51, v71
	v_mul_f32_e32 v44, v116, v56
	v_mul_f32_e32 v45, v117, v57
	v_mul_f32_e32 v46, v118, v72
	v_mul_f32_e32 v47, v119, v73
	v_mul_f32_e32 v48, v120, v54
	v_mul_f32_e32 v49, v121, v55
	v_mul_f32_e32 v50, v122, v74
	v_mul_f32_e32 v51, v123, v75
	v_mul_f32_e32 v52, v124, v52
	v_mul_f32_e32 v53, v125, v53
	v_mul_f32_e32 v54, v126, v76
	v_mul_f32_e32 v55, v127, v77
	v_mul_f32_e32 v56, v128, v78
	v_mul_f32_e32 v57, v129, v79
	v_mul_f32_e32 v58, v130, v80
	v_mul_f32_e32 v59, v131, v81
	v_mul_f32_e32 v60, v132, v82
	v_mul_f32_e32 v61, v133, v83
	v_mul_f32_e32 v62, v134, v84
	v_mul_f32_e32 v63, v135, v85
	v_mul_f32_e32 v64, v136, v86
	v_mul_f32_e32 v65, v137, v87
	v_mul_f32_e32 v66, v138, v88
	v_mul_f32_e32 v67, v139, v89
	v_mul_f32_e32 v68, v140, v90
	v_mul_f32_e32 v69, v141, v91
	v_mul_f32_e32 v70, v142, v92
	v_mul_f32_e32 v71, v143, v93
	v_mul_f32_e32 v72, v144, v96
	v_mul_f32_e32 v73, v145, v97
	v_mul_f32_e32 v74, v146, v98
	v_mul_f32_e32 v75, v147, v99
	v_mul_f32_e32 v76, v148, v36
	v_mul_f32_e32 v77, v149, v37
	v_mul_f32_e32 v78, v150, v100
	v_mul_f32_e32 v79, v151, v101
	v_mul_f32_e32 v80, v152, v102
	v_mul_f32_e32 v81, v153, v103
	v_mul_f32_e32 v82, v154, v104
	v_mul_f32_e32 v83, v155, v105
	v_mul_f32_e32 v84, v156, v106
	v_mul_f32_e32 v85, v157, v107
	v_mul_f32_e32 v86, v158, v108
	v_mul_f32_e32 v87, v159, v109
	v_mul_f32_e32 v88, v160, v110
	v_mul_f32_e32 v89, v161, v111
	v_mul_f32_e32 v90, v162, v112
	v_mul_f32_e32 v91, v163, v113
	v_mul_f32_e32 v92, v164, v114
	v_mul_f32_e32 v93, v165, v115
	global_store_dwordx4 v[24:25], v[16:19], off nt
	global_store_dwordx4 v[24:25], v[28:31], off offset:1024 nt
	global_store_dwordx4 v[24:25], v[32:35], off offset:2048 nt
	global_store_dwordx4 v[24:25], v[42:45], off offset:3072 nt
	global_store_dwordx4 v[40:41], v[46:49], off offset:-4096 nt
	global_store_dwordx4 v[38:39], v[50:53], off offset:1024 nt
	global_store_dwordx4 v[38:39], v[54:57], off offset:2048 nt
	global_store_dwordx4 v[38:39], v[58:61], off offset:3072 nt
	global_store_dwordx4 v[40:41], v[62:65], off nt
	global_store_dwordx4 v[40:41], v[66:69], off offset:1024 nt
	global_store_dwordx4 v[40:41], v[70:73], off offset:2048 nt
	global_store_dwordx4 v[40:41], v[74:77], off offset:3072 nt
	global_store_dwordx4 v[94:95], v[78:81], off nt
	global_store_dwordx4 v[94:95], v[82:85], off offset:1024 nt
	global_store_dwordx4 v[94:95], v[86:89], off offset:2048 nt
	global_store_dwordx4 v[94:95], v[90:93], off offset:3072 nt
	v_lshl_add_u64 v[24:25], v[24:25], 0, s[2:3]
	s_andn2_b64 exec, exec, s[6:7]
	s_cbranch_execnz .LBB0_524
